# GEMM LDS tile image changed to 8-row x 128-byte sub-tiles (chunk XOR swizzle): each LDS-DMA wave-instruction fetches 8 whole cache lines; per-k fragment read bases
# baseline (speedup 1.0000x reference)
.LBB0_162:
	v_ashrrev_i32_e32 v7, 31, v14
	v_lshrrev_b32_e32 v7, 26, v7
	v_add_u32_e32 v7, v14, v7
	v_ashrrev_i32_e32 v15, 6, v7
	v_bfe_i32 v7, v14, 27, 1
	v_lshlrev_b32_e32 v6, 4, v14
	v_lshrrev_b32_e32 v7, 22, v7
	v_add_u32_e32 v7, v6, v7
	v_and_b32_e32 v7, 0xfffffc00, v7
	v_sub_u32_e32 v7, v6, v7
	v_lshrrev_b32_e32 v8, 4, v7
	v_bitop3_b32 v8, v8, v7, 32 bitop3:0x6c
	v_ashrrev_i32_e32 v7, 31, v7
	v_lshrrev_b32_e32 v7, 26, v7
	v_add_u32_e32 v7, v8, v7
	v_ashrrev_i32_e32 v16, 6, v7
	v_lshlrev_b32_e32 v9, 3, v15
	v_mul_i32_i24_e32 v10, 64, v16
	v_and_b32_e32 v9, -16, v9
	v_sub_u32_e32 v8, v8, v10
	v_mov_b32_e32 v10, 1
	v_add_u32_e32 v7, v16, v9
	v_lshlrev_b32_e32 v9, 5, v15
	v_ashrrev_i16_sdwa v8, v10, sext(v8) dst_sel:DWORD dst_unused:UNUSED_PAD src0_sel:DWORD src1_sel:BYTE_0
	v_and_b32_e32 v9, 32, v9
	v_bfe_i32 v17, v8, 0, 16
	v_and_b32_e32 v12, 3, v16
	s_mov_b32 s5, 0x1fffe0
	v_add_lshl_u32 v9, v9, v17, 1
	v_add_u32_e32 v6, 0x2000, v6
	v_lshlrev_b32_e32 v8, 1, v7
	v_lshrrev_b32_e32 v11, 2, v7
	v_and_or_b32 v12, v7, s5, v12
	v_lshl_add_u32 v130, v7, 11, v9
	v_ashrrev_i32_e32 v7, 31, v6
	v_lshrrev_b32_e32 v7, 22, v7
	v_add_u32_e32 v7, v6, v7
	v_ashrrev_i32_e32 v18, 10, v7
	v_mul_i32_i24_e32 v7, 0x400, v18
	v_sub_u32_e32 v6, v6, v7
	v_and_b32_e32 v8, 24, v8
	v_and_b32_e32 v11, 4, v11
	v_lshrrev_b32_e32 v7, 4, v6
	v_or3_b32 v8, v12, v11, v8
	v_bitop3_b32 v6, v7, v6, 32 bitop3:0x6c
	v_lshl_add_u32 v132, v8, 11, v9
	v_ashrrev_i32_e32 v8, 31, v6
	v_lshrrev_b32_e32 v8, 26, v8
	v_add_u32_e32 v8, v6, v8
	v_lshlrev_b32_e32 v7, 3, v18
	v_ashrrev_i32_e32 v19, 6, v8
	v_and_b32_e32 v8, 0xc0, v8
	v_and_b32_e32 v7, -16, v7
	v_sub_u32_e32 v6, v6, v8
	s_ashr_i32 s4, s16, 6
	v_add_u32_e32 v7, v19, v7
	v_ashrrev_i16_sdwa v6, v10, sext(v6) dst_sel:DWORD dst_unused:UNUSED_PAD src0_sel:DWORD src1_sel:BYTE_0
	v_lshlrev_b32_e32 v9, 5, v18
	v_bfe_i32 v20, v6, 0, 16
	v_lshlrev_b32_e32 v6, 1, v7
	v_lshrrev_b32_e32 v8, 2, v7
	v_and_b32_e32 v10, 3, v19
	s_lshl_b32 s47, s4, 10
	v_and_b32_e32 v9, 32, v9
	v_and_b32_e32 v6, 24, v6
	v_and_b32_e32 v8, 4, v8
	v_and_or_b32 v10, v7, s5, v10
	s_add_i32 s57, s47, 0
	v_or3_b32 v6, v10, v8, v6
	v_add_lshl_u32 v8, v9, v20, 1
	s_add_i32 m0, s57, 0x10000
	v_readfirstlane_b32 s14, v4
	v_readfirstlane_b32 s15, v5
	v_lshl_add_u32 v136, v6, 11, v8
	v_lshl_add_u32 v134, v7, 11, v8
	s_add_i32 s62, s57, 0x2000
	s_add_i32 s63, s57, 0x4000
	s_add_i32 s64, s57, 0x6000
	v_lshrrev_b32_e32 v242, 6, v1
	v_and_b32_e32 v243, 63, v1
	v_lshlrev_b32_e32 v245, 4, v243
	v_lshrrev_b32_e32 v244, 5, v243
	v_lshlrev_b32_e32 v244, 5, v244
	v_xor_b32_e32 v245, v245, v244
	v_lshrrev_b32_e32 v244, 1, v242
	v_lshlrev_b32_e32 v244, 4, v244
	v_lshrrev_b32_e32 v243, 6, v245
	v_add_u32_e32 v244, v244, v243
	v_and_b32_e32 v245, 63, v245
	v_and_b32_e32 v242, 1, v242
	v_lshl_add_u32 v245, v242, 6, v245
	v_mul_u32_u24_e32 v244, 0x800, v244
	v_add_u32_e32 v240, v244, v245
	v_lshrrev_b32_e32 v242, 6, v1
	v_and_b32_e32 v243, 63, v1
	v_lshrrev_b32_e32 v244, 3, v243
	v_lshl_add_u32 v244, v242, 3, v244
	v_lshrrev_b32_e32 v245, 4, v243
	v_and_b32_e32 v245, 3, v245
	v_lshlrev_b32_e32 v245, 1, v245
	v_and_b32_e32 v243, 7, v243
	v_xor_b32_e32 v245, v243, v245
	v_lshlrev_b32_e32 v245, 4, v245
	v_mul_u32_u24_e32 v244, 0x800, v244
	v_add_u32_e32 v241, v244, v245
	v_sub_u32_e32 v130, v130, v240
	v_add_u32_e32 v130, v130, v241
	v_lshrrev_b32_e32 v242, 6, v1
	v_and_b32_e32 v243, 63, v1
	v_lshlrev_b32_e32 v245, 4, v243
	v_lshrrev_b32_e32 v244, 5, v243
	v_lshlrev_b32_e32 v244, 5, v244
	v_xor_b32_e32 v245, v245, v244
	v_add_u32_e32 v242, 8, v242
	v_lshrrev_b32_e32 v244, 1, v242
	v_lshlrev_b32_e32 v244, 4, v244
	v_lshrrev_b32_e32 v243, 6, v245
	v_add_u32_e32 v244, v244, v243
	v_and_b32_e32 v245, 63, v245
	v_and_b32_e32 v242, 1, v242
	v_lshl_add_u32 v245, v242, 6, v245
	v_mul_u32_u24_e32 v244, 0x800, v244
	v_add_u32_e32 v240, v244, v245
	v_lshrrev_b32_e32 v242, 6, v1
	v_and_b32_e32 v243, 63, v1
	v_lshrrev_b32_e32 v244, 3, v243
	v_lshl_add_u32 v244, v242, 3, v244
	v_add_u32_e32 v244, 64, v244
	v_lshrrev_b32_e32 v245, 4, v243
	v_and_b32_e32 v245, 3, v245
	v_lshlrev_b32_e32 v245, 1, v245
	v_and_b32_e32 v243, 7, v243
	v_xor_b32_e32 v245, v243, v245
	v_lshlrev_b32_e32 v245, 4, v245
	v_mul_u32_u24_e32 v244, 0x800, v244
	v_add_u32_e32 v241, v244, v245
	v_sub_u32_e32 v134, v134, v240
	v_add_u32_e32 v134, v134, v241
	v_lshrrev_b32_e32 v242, 6, v1
	v_and_b32_e32 v243, 63, v1
	v_lshlrev_b32_e32 v245, 4, v243
	v_lshrrev_b32_e32 v244, 5, v243
	v_lshlrev_b32_e32 v244, 5, v244
	v_xor_b32_e32 v245, v245, v244
	v_lshrrev_b32_e32 v244, 1, v242
	v_lshlrev_b32_e32 v244, 4, v244
	v_lshrrev_b32_e32 v243, 6, v245
	v_add_u32_e32 v244, v244, v243
	v_and_b32_e32 v245, 63, v245
	v_and_b32_e32 v242, 1, v242
	v_lshl_add_u32 v245, v242, 6, v245
	v_and_b32_e32 v242, 31, v244
	v_sub_u32_e32 v244, v244, v242
	v_and_b32_e32 v243, 3, v242
	v_add_u32_e32 v244, v244, v243
	v_lshrrev_b32_e32 v243, 4, v242
	v_lshl_add_u32 v244, v243, 2, v244
	v_and_b32_e32 v243, 15, v242
	v_lshrrev_b32_e32 v243, 2, v243
	v_lshl_add_u32 v244, v243, 3, v244
	v_mul_u32_u24_e32 v244, 0x800, v244
	v_add_u32_e32 v240, v244, v245
	v_lshrrev_b32_e32 v242, 6, v1
	v_and_b32_e32 v243, 63, v1
	v_lshrrev_b32_e32 v244, 3, v243
	v_lshl_add_u32 v244, v242, 3, v244
	v_lshrrev_b32_e32 v245, 4, v243
	v_and_b32_e32 v245, 3, v245
	v_lshlrev_b32_e32 v245, 1, v245
	v_and_b32_e32 v243, 7, v243
	v_xor_b32_e32 v245, v243, v245
	v_lshlrev_b32_e32 v245, 4, v245
	v_and_b32_e32 v242, 31, v244
	v_sub_u32_e32 v244, v244, v242
	v_and_b32_e32 v243, 3, v242
	v_add_u32_e32 v244, v244, v243
	v_lshrrev_b32_e32 v243, 4, v242
	v_lshl_add_u32 v244, v243, 2, v244
	v_and_b32_e32 v243, 15, v242
	v_lshrrev_b32_e32 v243, 2, v243
	v_lshl_add_u32 v244, v243, 3, v244
	v_mul_u32_u24_e32 v244, 0x800, v244
	v_add_u32_e32 v241, v244, v245
	v_sub_u32_e32 v132, v132, v240
	v_add_u32_e32 v132, v132, v241
	v_lshrrev_b32_e32 v242, 6, v1
	v_and_b32_e32 v243, 63, v1
	v_lshlrev_b32_e32 v245, 4, v243
	v_lshrrev_b32_e32 v244, 5, v243
	v_lshlrev_b32_e32 v244, 5, v244
	v_xor_b32_e32 v245, v245, v244
	v_add_u32_e32 v242, 8, v242
	v_lshrrev_b32_e32 v244, 1, v242
	v_lshlrev_b32_e32 v244, 4, v244
	v_lshrrev_b32_e32 v243, 6, v245
	v_add_u32_e32 v244, v244, v243
	v_and_b32_e32 v245, 63, v245
	v_and_b32_e32 v242, 1, v242
	v_lshl_add_u32 v245, v242, 6, v245
	v_and_b32_e32 v242, 31, v244
	v_sub_u32_e32 v244, v244, v242
	v_and_b32_e32 v243, 3, v242
	v_add_u32_e32 v244, v244, v243
	v_lshrrev_b32_e32 v243, 4, v242
	v_lshl_add_u32 v244, v243, 2, v244
	v_and_b32_e32 v243, 15, v242
	v_lshrrev_b32_e32 v243, 2, v243
	v_lshl_add_u32 v244, v243, 3, v244
	v_mul_u32_u24_e32 v244, 0x800, v244
	v_add_u32_e32 v240, v244, v245
	v_lshrrev_b32_e32 v242, 6, v1
	v_and_b32_e32 v243, 63, v1
	v_lshrrev_b32_e32 v244, 3, v243
	v_lshl_add_u32 v244, v242, 3, v244
	v_add_u32_e32 v244, 64, v244
	v_lshrrev_b32_e32 v245, 4, v243
	v_and_b32_e32 v245, 3, v245
	v_lshlrev_b32_e32 v245, 1, v245
	v_and_b32_e32 v243, 7, v243
	v_xor_b32_e32 v245, v243, v245
	v_lshlrev_b32_e32 v245, 4, v245
	v_and_b32_e32 v242, 31, v244
	v_sub_u32_e32 v244, v244, v242
	v_and_b32_e32 v243, 3, v242
	v_add_u32_e32 v244, v244, v243
	v_lshrrev_b32_e32 v243, 4, v242
	v_lshl_add_u32 v244, v243, 2, v244
	v_and_b32_e32 v243, 15, v242
	v_lshrrev_b32_e32 v243, 2, v243
	v_lshl_add_u32 v244, v243, 3, v244
	v_mul_u32_u24_e32 v244, 0x800, v244
	v_add_u32_e32 v241, v244, v245
	v_sub_u32_e32 v136, v136, v240
	v_add_u32_e32 v136, v136, v241
	global_load_lds_dwordx4 v132, s[14:15]
	s_add_i32 m0, s57, 0x12000
	s_ashr_i32 s5, s16, 8
	global_load_lds_dwordx4 v136, s[14:15]
	s_mov_b64 s[14:15], 0x40000
	v_lshl_add_u64 v[6:7], v[4:5], 0, s[14:15]
	s_add_i32 m0, s57, 0x14000
	v_readfirstlane_b32 s18, v6
	v_readfirstlane_b32 s19, v7
	v_lshl_add_u64 v[6:7], v[2:3], 0, s[14:15]
	v_mov_b32_e32 v139, 0
	v_mov_b32_e32 v133, v139
	v_mov_b32_e32 v137, v139
	v_mov_b32_e32 v131, v139
	global_load_lds_dwordx4 v132, s[18:19]
	s_add_i32 m0, s57, 0x16000
	v_mov_b32_e32 v135, v139
	global_load_lds_dwordx4 v136, s[18:19]
	v_readfirstlane_b32 s18, v2
	v_readfirstlane_b32 s19, v3
	s_mov_b32 m0, s57
	s_cmp_eq_u32 s5, 1
	s_mov_b32 s17, 0
	v_lshl_add_u64 v[12:13], v[4:5], 0, v[132:133]
	v_lshl_add_u64 v[10:11], v[4:5], 0, v[136:137]
	global_load_lds_dwordx4 v130, s[18:19]
	s_mov_b32 m0, s62
	v_lshl_add_u64 v[8:9], v[2:3], 0, v[134:135]
	global_load_lds_dwordx4 v134, s[18:19]
	v_readfirstlane_b32 s18, v6
	v_readfirstlane_b32 s19, v7
	s_mov_b32 m0, s63
	v_lshl_add_u64 v[6:7], v[2:3], 0, v[130:131]
	s_nop 2
	global_load_lds_dwordx4 v130, s[18:19]
	s_mov_b32 m0, s64
	s_nop 0
	global_load_lds_dwordx4 v134, s[18:19]
	s_cselect_b64 s[18:19], -1, 0
	s_cmp_lg_u32 s5, 1
	s_cbranch_scc1 .LBB0_164
	s_barrier
.LBB0_164:
	s_mov_b64 s[20:21], 0x80
	s_add_i32 m0, s57, 0x18000
	v_lshl_add_u64 v[12:13], v[12:13], 0, s[20:21]
	s_waitcnt vmcnt(2)
	s_barrier
	global_load_lds_dwordx4 v[12:13], off
	v_lshl_add_u64 v[10:11], v[10:11], 0, s[20:21]
	s_add_i32 m0, s57, 0x1a000
	s_add_i32 s65, s57, 0x8000
	global_load_lds_dwordx4 v[10:11], off
	v_lshl_add_u64 v[6:7], v[6:7], 0, s[20:21]
	s_mov_b32 m0, s65
	s_add_i32 s66, s57, 0xa000
	global_load_lds_dwordx4 v[6:7], off
	v_lshl_add_u64 v[6:7], v[8:9], 0, s[20:21]
	s_mov_b32 m0, s66
	s_mov_b64 s[22:23], 0x40080
	global_load_lds_dwordx4 v[6:7], off
	v_lshl_add_u64 v[6:7], v[4:5], 0, s[22:23]
	s_add_i32 m0, s57, 0x1c000
	v_lshl_add_u64 v[8:9], v[6:7], 0, v[132:133]
	global_load_lds_dwordx4 v[8:9], off
	v_lshl_add_u64 v[6:7], v[6:7], 0, v[136:137]
	s_add_i32 m0, s57, 0x1e000
	v_and_b32_e32 v140, 15, v14
	global_load_lds_dwordx4 v[6:7], off
	v_bfe_u32 v6, v14, 4, 2
	v_lshlrev_b32_e32 v7, 4, v6
	v_lshlrev_b32_e32 v9, 2, v14
	s_and_b32 s7, s4, 3
	s_lshl_b32 s67, s5, 6
	v_lshl_or_b32 v8, v140, 6, v7
	s_lshl_b32 s5, s5, 13
	v_and_b32_e32 v9, 32, v9
	v_bitop3_b32 v10, v8, s5, v9 bitop3:0xde
	s_lshl_b32 s68, s7, 5
	s_lshl_b32 s5, s7, 12
	s_cmpk_lt_u32 s16, 0x100
	s_cselect_b64 s[24:25], -1, 0
	s_lshl_b32 s4, s4, 6
	v_bitop3_b32 v141, v8, s5, v9 bitop3:0xde
	v_and_or_b32 v158, s4, 64, v7
	v_cmp_eq_u32_e64 s[4:5], 0, v6
	v_lshl_or_b32 v159, v6, 3, s68
	v_lshlrev_b32_e32 v6, 14, v18
	v_and_b32_e32 v6, 0xffff8000, v6
	v_lshl_add_u32 v6, v19, 11, v6
	v_and_b32_e32 v7, 1, v18
	v_lshl_or_b32 v6, v7, 6, v6
	v_lshl_add_u32 v142, v20, 1, v6
	v_lshlrev_b32_e32 v6, 14, v15
	v_and_b32_e32 v6, 0xffff8000, v6
	v_lshl_add_u32 v6, v16, 11, v6
	v_and_b32_e32 v7, 1, v15
	s_waitcnt vmcnt(6)
	v_lshl_or_b32 v6, v7, 6, v6
	s_add_i32 s76, 0, 0x10000
	v_lshl_add_u32 v144, v17, 1, v6
	s_mov_b32 s44, 0xfffc0080
	s_add_i32 s80, s76, s47
	v_mbcnt_lo_u32_b32 v6, -1, 0
	s_lshl_b32 s16, s7, 2
	v_mov_b32_e32 v143, v139
	v_mov_b32_e32 v145, v139
	s_movk_i32 s69, 0x177
	s_add_i32 s72, 0, 0x20020
	s_add_i32 s73, 0, 0x20018
	s_add_i32 s74, 0, 0x2002c
	s_add_i32 s75, 0, 0x20000
	s_mov_b64 s[28:29], 0x100
	s_mov_b32 s45, -1
	s_add_i32 s77, 0, 0x14000
	v_add_u32_e32 v160, 0, v10
	s_add_i32 s78, s57, 0xc000
	s_add_i32 s79, s57, 0xe000
	s_add_i32 s81, s80, 0x2000
	s_add_i32 s82, 0, 0x20010
	s_add_i32 s83, 0, 0x20024
	s_movk_i32 s84, 0x7fff
	s_mov_b32 s46, 0xbfb8aa3b
	v_mbcnt_hi_u32_b32 v161, -1, v6
	s_mov_b32 s85, s17
	v_mov_b64_e32 v[148:149], v[4:5]
	v_mov_b64_e32 v[146:147], v[2:3]
	s_barrier
	v_lshrrev_b32_e32 v242, 6, v1
	v_and_b32_e32 v243, 63, v1
	v_lshlrev_b32_e32 v245, 4, v243
	v_lshrrev_b32_e32 v244, 5, v243
	v_lshlrev_b32_e32 v244, 5, v244
	v_xor_b32_e32 v245, v245, v244
	v_lshrrev_b32_e32 v244, 1, v242
	v_lshlrev_b32_e32 v244, 4, v244
	v_lshrrev_b32_e32 v243, 6, v245
	v_add_u32_e32 v244, v244, v243
	v_and_b32_e32 v245, 63, v245
	v_and_b32_e32 v242, 1, v242
	v_lshl_add_u32 v245, v242, 6, v245
	v_mul_u32_u24_e32 v244, 0x800, v244
	v_add_u32_e32 v240, v244, v245
	v_lshrrev_b32_e32 v242, 6, v1
	v_and_b32_e32 v243, 63, v1
	v_lshrrev_b32_e32 v244, 3, v243
	v_lshl_add_u32 v244, v242, 3, v244
	v_lshrrev_b32_e32 v245, 4, v243
	v_and_b32_e32 v245, 3, v245
	v_lshlrev_b32_e32 v245, 1, v245
	v_and_b32_e32 v243, 7, v243
	v_xor_b32_e32 v245, v243, v245
	v_lshlrev_b32_e32 v245, 4, v245
	v_mul_u32_u24_e32 v244, 0x800, v244
	v_add_u32_e32 v241, v244, v245
	v_sub_u32_e32 v144, v144, v240
	v_add_u32_e32 v144, v144, v241
	v_lshrrev_b32_e32 v242, 6, v1
	v_and_b32_e32 v243, 63, v1
	v_lshlrev_b32_e32 v245, 4, v243
	v_lshrrev_b32_e32 v244, 5, v243
	v_lshlrev_b32_e32 v244, 5, v244
	v_xor_b32_e32 v245, v245, v244
	v_add_u32_e32 v242, 8, v242
	v_lshrrev_b32_e32 v244, 1, v242
	v_lshlrev_b32_e32 v244, 4, v244
	v_lshrrev_b32_e32 v243, 6, v245
	v_add_u32_e32 v244, v244, v243
	v_and_b32_e32 v245, 63, v245
	v_and_b32_e32 v242, 1, v242
	v_lshl_add_u32 v245, v242, 6, v245
	v_mul_u32_u24_e32 v244, 0x800, v244
	v_add_u32_e32 v240, v244, v245
	v_lshrrev_b32_e32 v242, 6, v1
	v_and_b32_e32 v243, 63, v1
	v_lshrrev_b32_e32 v244, 3, v243
	v_lshl_add_u32 v244, v242, 3, v244
	v_add_u32_e32 v244, 64, v244
	v_lshrrev_b32_e32 v245, 4, v243
	v_and_b32_e32 v245, 3, v245
	v_lshlrev_b32_e32 v245, 1, v245
	v_and_b32_e32 v243, 7, v243
	v_xor_b32_e32 v245, v243, v245
	v_lshlrev_b32_e32 v245, 4, v245
	v_mul_u32_u24_e32 v244, 0x800, v244
	v_add_u32_e32 v241, v244, v245
	v_sub_u32_e32 v142, v142, v240
	v_add_u32_e32 v142, v142, v241
	v_and_b32_e32 v240, 63, v1
	v_and_b32_e32 v241, 15, v240
	v_lshrrev_b32_e32 v242, 4, v240
	v_lshlrev_b32_e32 v243, 6, v241
	v_lshl_add_u32 v243, v242, 4, v243
	v_lshrrev_b32_e32 v244, 3, v241
	v_lshlrev_b32_e32 v245, 5, v244
	v_xor_b32_e32 v243, v243, v245
	v_sub_u32_e32 v160, v160, v243
	v_lshlrev_b32_e32 v244, 10, v244
	v_and_b32_e32 v245, 7, v241
	v_lshl_add_u32 v244, v245, 7, v244
	v_add_u32_e32 v160, v160, v244
	v_lshrrev_b32_e32 v245, 1, v245
	v_lshlrev_b32_e32 v245, 1, v245
	v_add_u32_e32 v244, 4, v242
	v_xor_b32_e32 v244, v244, v245
	v_lshl_add_u32 v238, v244, 4, v160
	v_xor_b32_e32 v244, v242, v245
	v_lshl_add_u32 v160, v244, 4, v160
	v_and_b32_e32 v240, 63, v1
	v_and_b32_e32 v241, 15, v240
	v_lshrrev_b32_e32 v242, 4, v240
	v_lshlrev_b32_e32 v243, 6, v241
	v_lshl_add_u32 v243, v242, 4, v243
	v_lshrrev_b32_e32 v244, 3, v241
	v_lshlrev_b32_e32 v245, 5, v244
	v_xor_b32_e32 v243, v243, v245
	v_sub_u32_e32 v141, v141, v243
	v_lshlrev_b32_e32 v244, 10, v244
	v_and_b32_e32 v245, 7, v241
	v_lshl_add_u32 v244, v245, 7, v244
	v_add_u32_e32 v141, v141, v244
	v_lshrrev_b32_e32 v245, 1, v245
	v_lshlrev_b32_e32 v245, 1, v245
	v_add_u32_e32 v244, 4, v242
	v_xor_b32_e32 v244, v244, v245
	v_lshl_add_u32 v239, v244, 4, v141
	v_xor_b32_e32 v244, v242, v245
	v_lshl_add_u32 v141, v244, 4, v141
	s_branch .LBB0_167

.Lmy_nb_0:
	s_nop 0
	v_readfirstlane_b32 s86, v152
	v_readfirstlane_b32 s87, v153
	v_readfirstlane_b32 s88, v150
	v_readfirstlane_b32 s89, v151
	v_readfirstlane_b32 s90, v146
	v_readfirstlane_b32 s91, v147
	v_readfirstlane_b32 s92, v148
	v_readfirstlane_b32 s93, v149
	v_readfirstlane_b32 s100, v154
	v_readfirstlane_b32 s101, v138
	v_add_u32_e32 v230, s76, v141
	v_add_u32_e32 v234, s76, v239
	v_add_u32_e32 v231, s77, v141
	v_add_u32_e32 v235, s77, v239
	v_add_u32_e32 v232, 0x18000, v141
	v_add_u32_e32 v236, 0x18000, v239
	v_add_u32_e32 v233, 0x1c000, v141
	v_add_u32_e32 v237, 0x1c000, v239
	s_add_u32 s98, s86, 0xfffc0080
	s_addc_u32 s99, s87, -1
	s_cmp_eq_u32 s7, s100
	s_cselect_b64 s[94:95], s[90:91], s[98:99]
	s_cselect_b64 s[96:97], s[92:93], s[88:89]
	s_add_i32 s51, s7, 2
	s_mov_b32 m0, s78
	ds_read_b128 v[164:167], v230
	global_load_lds_dwordx4 v144, s[86:87]
	s_mov_b32 m0, s79
	ds_read_b128 v[168:171], v234
	global_load_lds_dwordx4 v142, s[86:87]
	ds_read_b128 v[172:175], v230 offset:2048
	ds_read_b128 v[176:179], v234 offset:2048
	ds_read_b128 v[180:183], v231
	ds_read_b128 v[184:187], v235
	ds_read_b128 v[188:191], v231 offset:2048
	ds_read_b128 v[192:195], v235 offset:2048
	ds_read_b128 v[196:199], v160
	ds_read_b128 v[200:203], v238
	ds_read_b128 v[204:207], v160 offset:2048
	ds_read_b128 v[208:211], v238 offset:2048
	ds_read_b128 v[212:215], v160 offset:4096
	ds_read_b128 v[216:219], v238 offset:4096
	ds_read_b128 v[220:223], v160 offset:6144
	ds_read_b128 v[224:227], v238 offset:6144
	s_waitcnt vmcnt(8)
	s_waitcnt lgkmcnt(0)
	s_setprio 1
	s_barrier
	v_mfma_f32_16x16x32_bf16 v[122:125], v[164:167], v[196:199], 0
	v_mfma_f32_16x16x32_bf16 v[118:121], v[172:175], v[196:199], 0
	v_mfma_f32_16x16x32_bf16 v[110:113], v[164:167], v[204:207], 0
	v_mfma_f32_16x16x32_bf16 v[102:105], v[172:175], v[204:207], 0
	v_mfma_f32_16x16x32_bf16 v[94:97], v[164:167], v[212:215], 0
	v_mfma_f32_16x16x32_bf16 v[86:89], v[172:175], v[212:215], 0
	v_mfma_f32_16x16x32_bf16 v[78:81], v[164:167], v[220:223], 0
	v_mfma_f32_16x16x32_bf16 v[70:73], v[172:175], v[220:223], 0
	v_mfma_f32_16x16x32_bf16 v[122:125], v[168:171], v[200:203], v[122:125]
	v_mfma_f32_16x16x32_bf16 v[118:121], v[176:179], v[200:203], v[118:121]
	v_mfma_f32_16x16x32_bf16 v[110:113], v[168:171], v[208:211], v[110:113]
	v_mfma_f32_16x16x32_bf16 v[102:105], v[176:179], v[208:211], v[102:105]
	v_mfma_f32_16x16x32_bf16 v[94:97], v[168:171], v[216:219], v[94:97]
	v_mfma_f32_16x16x32_bf16 v[86:89], v[176:179], v[216:219], v[86:89]
	v_mfma_f32_16x16x32_bf16 v[78:81], v[168:171], v[224:227], v[78:81]
	v_mfma_f32_16x16x32_bf16 v[70:73], v[176:179], v[224:227], v[70:73]
	v_mfma_f32_16x16x32_bf16 v[126:129], v[180:183], v[196:199], 0
	v_mfma_f32_16x16x32_bf16 v[114:117], v[188:191], v[196:199], 0
	v_mfma_f32_16x16x32_bf16 v[106:109], v[180:183], v[204:207], 0
	v_mfma_f32_16x16x32_bf16 v[98:101], v[188:191], v[204:207], 0
	v_mfma_f32_16x16x32_bf16 v[90:93], v[180:183], v[212:215], 0
	v_mfma_f32_16x16x32_bf16 v[82:85], v[188:191], v[212:215], 0
	v_mfma_f32_16x16x32_bf16 v[74:77], v[180:183], v[220:223], 0
	v_mfma_f32_16x16x32_bf16 v[66:69], v[188:191], v[220:223], 0
	v_mfma_f32_16x16x32_bf16 v[126:129], v[184:187], v[200:203], v[126:129]
	v_mfma_f32_16x16x32_bf16 v[114:117], v[192:195], v[200:203], v[114:117]
	v_mfma_f32_16x16x32_bf16 v[106:109], v[184:187], v[208:211], v[106:109]
	v_mfma_f32_16x16x32_bf16 v[98:101], v[192:195], v[208:211], v[98:101]
	v_mfma_f32_16x16x32_bf16 v[90:93], v[184:187], v[216:219], v[90:93]
	v_mfma_f32_16x16x32_bf16 v[82:85], v[192:195], v[216:219], v[82:85]
	v_mfma_f32_16x16x32_bf16 v[74:77], v[184:187], v[224:227], v[74:77]
	v_mfma_f32_16x16x32_bf16 v[66:69], v[192:195], v[224:227], v[66:69]
	s_barrier
	s_setprio 0
	s_add_u32 s98, s96, 0x40000
	s_addc_u32 s99, s97, 0
	s_mov_b32 m0, s80
	ds_read_b128 v[196:199], v160 offset:16384
	global_load_lds_dwordx4 v132, s[96:97]
	s_mov_b32 m0, s81
	s_add_i32 s7, s77, s47
	global_load_lds_dwordx4 v136, s[96:97]
	s_mov_b32 m0, s7
	ds_read_b128 v[200:203], v238 offset:16384
	global_load_lds_dwordx4 v132, s[98:99]
	s_add_i32 m0, s7, 0x2000
	ds_read_b128 v[204:207], v160 offset:18432
	global_load_lds_dwordx4 v136, s[98:99]
	s_mov_b32 m0, s57
	ds_read_b128 v[208:211], v238 offset:18432
	global_load_lds_dwordx4 v130, s[94:95]
	s_mov_b32 m0, s62
	ds_read_b128 v[212:215], v160 offset:20480
	global_load_lds_dwordx4 v134, s[94:95]
	ds_read_b128 v[216:219], v238 offset:20480
	ds_read_b128 v[220:223], v160 offset:22528
	ds_read_b128 v[224:227], v238 offset:22528
	s_waitcnt vmcnt(8)
	s_waitcnt lgkmcnt(0)
	s_setprio 1
	s_barrier
	v_mfma_f32_16x16x32_bf16 v[62:65], v[164:167], v[196:199], 0
	v_mfma_f32_16x16x32_bf16 v[54:57], v[172:175], v[196:199], 0
	v_mfma_f32_16x16x32_bf16 v[46:49], v[164:167], v[204:207], 0
	v_mfma_f32_16x16x32_bf16 v[38:41], v[172:175], v[204:207], 0
	v_mfma_f32_16x16x32_bf16 v[30:33], v[164:167], v[212:215], 0
	v_mfma_f32_16x16x32_bf16 v[22:25], v[172:175], v[212:215], 0
	v_mfma_f32_16x16x32_bf16 v[14:17], v[164:167], v[220:223], 0
	v_mfma_f32_16x16x32_bf16 v[6:9], v[172:175], v[220:223], 0
	v_mfma_f32_16x16x32_bf16 v[62:65], v[168:171], v[200:203], v[62:65]
	v_mfma_f32_16x16x32_bf16 v[54:57], v[176:179], v[200:203], v[54:57]
	v_mfma_f32_16x16x32_bf16 v[46:49], v[168:171], v[208:211], v[46:49]
	v_mfma_f32_16x16x32_bf16 v[38:41], v[176:179], v[208:211], v[38:41]
	v_mfma_f32_16x16x32_bf16 v[30:33], v[168:171], v[216:219], v[30:33]
	v_mfma_f32_16x16x32_bf16 v[22:25], v[176:179], v[216:219], v[22:25]
	v_mfma_f32_16x16x32_bf16 v[14:17], v[168:171], v[224:227], v[14:17]
	v_mfma_f32_16x16x32_bf16 v[6:9], v[176:179], v[224:227], v[6:9]
	v_mfma_f32_16x16x32_bf16 v[58:61], v[180:183], v[196:199], 0
	v_mfma_f32_16x16x32_bf16 v[50:53], v[188:191], v[196:199], 0
	v_mfma_f32_16x16x32_bf16 v[42:45], v[180:183], v[204:207], 0
	v_mfma_f32_16x16x32_bf16 v[34:37], v[188:191], v[204:207], 0
	v_mfma_f32_16x16x32_bf16 v[26:29], v[180:183], v[212:215], 0
	v_mfma_f32_16x16x32_bf16 v[18:21], v[188:191], v[212:215], 0
	v_mfma_f32_16x16x32_bf16 v[10:13], v[180:183], v[220:223], 0
	v_mfma_f32_16x16x32_bf16 v[2:5], v[188:191], v[220:223], 0
	v_mfma_f32_16x16x32_bf16 v[58:61], v[184:187], v[200:203], v[58:61]
	v_mfma_f32_16x16x32_bf16 v[50:53], v[192:195], v[200:203], v[50:53]
	v_mfma_f32_16x16x32_bf16 v[42:45], v[184:187], v[208:211], v[42:45]
	v_mfma_f32_16x16x32_bf16 v[34:37], v[192:195], v[208:211], v[34:37]
	v_mfma_f32_16x16x32_bf16 v[26:29], v[184:187], v[216:219], v[26:29]
	v_mfma_f32_16x16x32_bf16 v[18:21], v[192:195], v[216:219], v[18:21]
	v_mfma_f32_16x16x32_bf16 v[10:13], v[184:187], v[224:227], v[10:13]
	v_mfma_f32_16x16x32_bf16 v[2:5], v[192:195], v[224:227], v[2:5]
	s_barrier
	s_setprio 0
	s_add_u32 s98, s94, 0x40000
	s_addc_u32 s99, s95, 0
	s_add_i32 s7, 0, 0x18000
	s_add_i32 s55, 0, 0x1c000
	s_mov_b32 m0, s63
	ds_read_b128 v[164:167], v232
	global_load_lds_dwordx4 v130, s[98:99]
	s_mov_b32 m0, s64
	ds_read_b128 v[168:171], v236
	global_load_lds_dwordx4 v134, s[98:99]
	ds_read_b128 v[172:175], v232 offset:2048
	ds_read_b128 v[176:179], v236 offset:2048
	ds_read_b128 v[180:183], v233
	ds_read_b128 v[184:187], v237
	ds_read_b128 v[188:191], v233 offset:2048
	ds_read_b128 v[192:195], v237 offset:2048
	ds_read_b128 v[196:199], v160 offset:32768
	ds_read_b128 v[200:203], v238 offset:32768
	ds_read_b128 v[204:207], v160 offset:34816
	ds_read_b128 v[208:211], v238 offset:34816
	ds_read_b128 v[212:215], v160 offset:36864
	ds_read_b128 v[216:219], v238 offset:36864
	ds_read_b128 v[220:223], v160 offset:38912
	ds_read_b128 v[224:227], v238 offset:38912
	s_waitcnt vmcnt(8)
	s_waitcnt lgkmcnt(0)
	s_setprio 1
	s_barrier
	v_mfma_f32_16x16x32_bf16 v[122:125], v[164:167], v[196:199], v[122:125]
	v_mfma_f32_16x16x32_bf16 v[118:121], v[172:175], v[196:199], v[118:121]
	v_mfma_f32_16x16x32_bf16 v[110:113], v[164:167], v[204:207], v[110:113]
	v_mfma_f32_16x16x32_bf16 v[102:105], v[172:175], v[204:207], v[102:105]
	v_mfma_f32_16x16x32_bf16 v[94:97], v[164:167], v[212:215], v[94:97]
	v_mfma_f32_16x16x32_bf16 v[86:89], v[172:175], v[212:215], v[86:89]
	v_mfma_f32_16x16x32_bf16 v[78:81], v[164:167], v[220:223], v[78:81]
	v_mfma_f32_16x16x32_bf16 v[70:73], v[172:175], v[220:223], v[70:73]
	v_mfma_f32_16x16x32_bf16 v[122:125], v[168:171], v[200:203], v[122:125]
	v_mfma_f32_16x16x32_bf16 v[118:121], v[176:179], v[200:203], v[118:121]
	v_mfma_f32_16x16x32_bf16 v[110:113], v[168:171], v[208:211], v[110:113]
	v_mfma_f32_16x16x32_bf16 v[102:105], v[176:179], v[208:211], v[102:105]
	v_mfma_f32_16x16x32_bf16 v[94:97], v[168:171], v[216:219], v[94:97]
	v_mfma_f32_16x16x32_bf16 v[86:89], v[176:179], v[216:219], v[86:89]
	v_mfma_f32_16x16x32_bf16 v[78:81], v[168:171], v[224:227], v[78:81]
	v_mfma_f32_16x16x32_bf16 v[70:73], v[176:179], v[224:227], v[70:73]
	v_mfma_f32_16x16x32_bf16 v[126:129], v[180:183], v[196:199], v[126:129]
	v_mfma_f32_16x16x32_bf16 v[114:117], v[188:191], v[196:199], v[114:117]
	v_mfma_f32_16x16x32_bf16 v[106:109], v[180:183], v[204:207], v[106:109]
	v_mfma_f32_16x16x32_bf16 v[98:101], v[188:191], v[204:207], v[98:101]
	v_mfma_f32_16x16x32_bf16 v[90:93], v[180:183], v[212:215], v[90:93]
	v_mfma_f32_16x16x32_bf16 v[82:85], v[188:191], v[212:215], v[82:85]
	v_mfma_f32_16x16x32_bf16 v[74:77], v[180:183], v[220:223], v[74:77]
	v_mfma_f32_16x16x32_bf16 v[66:69], v[188:191], v[220:223], v[66:69]
	v_mfma_f32_16x16x32_bf16 v[126:129], v[184:187], v[200:203], v[126:129]
	v_mfma_f32_16x16x32_bf16 v[114:117], v[192:195], v[200:203], v[114:117]
	v_mfma_f32_16x16x32_bf16 v[106:109], v[184:187], v[208:211], v[106:109]
	v_mfma_f32_16x16x32_bf16 v[98:101], v[192:195], v[208:211], v[98:101]
	v_mfma_f32_16x16x32_bf16 v[90:93], v[184:187], v[216:219], v[90:93]
	v_mfma_f32_16x16x32_bf16 v[82:85], v[192:195], v[216:219], v[82:85]
	v_mfma_f32_16x16x32_bf16 v[74:77], v[184:187], v[224:227], v[74:77]
	v_mfma_f32_16x16x32_bf16 v[66:69], v[192:195], v[224:227], v[66:69]
	s_barrier
	s_setprio 0
	s_add_u32 s96, s96, 0x80
	s_addc_u32 s97, s97, 0
	s_add_u32 s98, s96, 0x40000
	s_addc_u32 s99, s97, 0
	s_add_u32 s94, s94, 0x80
	s_addc_u32 s95, s95, 0
	s_add_i32 s7, s7, s47
	s_mov_b32 m0, s7
	ds_read_b128 v[196:199], v160 offset:49152
	global_load_lds_dwordx4 v132, s[96:97]
	s_add_i32 m0, s7, 0x2000
	s_add_i32 s7, s55, s47
	global_load_lds_dwordx4 v136, s[96:97]
	s_mov_b32 m0, s7
	ds_read_b128 v[200:203], v238 offset:49152
	global_load_lds_dwordx4 v132, s[98:99]
	s_add_i32 m0, s7, 0x2000
	ds_read_b128 v[204:207], v160 offset:51200
	global_load_lds_dwordx4 v136, s[98:99]
	s_mov_b32 m0, s65
	ds_read_b128 v[208:211], v238 offset:51200
	global_load_lds_dwordx4 v130, s[94:95]
	s_mov_b32 m0, s66
	ds_read_b128 v[212:215], v160 offset:53248
	global_load_lds_dwordx4 v134, s[94:95]
	ds_read_b128 v[216:219], v238 offset:53248
	ds_read_b128 v[220:223], v160 offset:55296
	ds_read_b128 v[224:227], v238 offset:55296
	s_waitcnt vmcnt(8)
	s_waitcnt lgkmcnt(0)
	s_setprio 1
	s_barrier
	v_mfma_f32_16x16x32_bf16 v[62:65], v[164:167], v[196:199], v[62:65]
	v_mfma_f32_16x16x32_bf16 v[54:57], v[172:175], v[196:199], v[54:57]
	v_mfma_f32_16x16x32_bf16 v[46:49], v[164:167], v[204:207], v[46:49]
	v_mfma_f32_16x16x32_bf16 v[38:41], v[172:175], v[204:207], v[38:41]
	v_mfma_f32_16x16x32_bf16 v[30:33], v[164:167], v[212:215], v[30:33]
	v_mfma_f32_16x16x32_bf16 v[22:25], v[172:175], v[212:215], v[22:25]
	v_mfma_f32_16x16x32_bf16 v[14:17], v[164:167], v[220:223], v[14:17]
	v_mfma_f32_16x16x32_bf16 v[6:9], v[172:175], v[220:223], v[6:9]
	v_mfma_f32_16x16x32_bf16 v[62:65], v[168:171], v[200:203], v[62:65]
	v_mfma_f32_16x16x32_bf16 v[54:57], v[176:179], v[200:203], v[54:57]
	v_mfma_f32_16x16x32_bf16 v[46:49], v[168:171], v[208:211], v[46:49]
	v_mfma_f32_16x16x32_bf16 v[38:41], v[176:179], v[208:211], v[38:41]
	v_mfma_f32_16x16x32_bf16 v[30:33], v[168:171], v[216:219], v[30:33]
	v_mfma_f32_16x16x32_bf16 v[22:25], v[176:179], v[216:219], v[22:25]
	v_mfma_f32_16x16x32_bf16 v[14:17], v[168:171], v[224:227], v[14:17]
	v_mfma_f32_16x16x32_bf16 v[6:9], v[176:179], v[224:227], v[6:9]
	v_mfma_f32_16x16x32_bf16 v[58:61], v[180:183], v[196:199], v[58:61]
	v_mfma_f32_16x16x32_bf16 v[50:53], v[188:191], v[196:199], v[50:53]
	v_mfma_f32_16x16x32_bf16 v[42:45], v[180:183], v[204:207], v[42:45]
	v_mfma_f32_16x16x32_bf16 v[34:37], v[188:191], v[204:207], v[34:37]
	v_mfma_f32_16x16x32_bf16 v[26:29], v[180:183], v[212:215], v[26:29]
	v_mfma_f32_16x16x32_bf16 v[18:21], v[188:191], v[212:215], v[18:21]
	v_mfma_f32_16x16x32_bf16 v[10:13], v[180:183], v[220:223], v[10:13]
	v_mfma_f32_16x16x32_bf16 v[2:5], v[188:191], v[220:223], v[2:5]
	v_mfma_f32_16x16x32_bf16 v[58:61], v[184:187], v[200:203], v[58:61]
	v_mfma_f32_16x16x32_bf16 v[50:53], v[192:195], v[200:203], v[50:53]
	v_mfma_f32_16x16x32_bf16 v[42:45], v[184:187], v[208:211], v[42:45]
	v_mfma_f32_16x16x32_bf16 v[34:37], v[192:195], v[208:211], v[34:37]
	v_mfma_f32_16x16x32_bf16 v[26:29], v[184:187], v[216:219], v[26:29]
	v_mfma_f32_16x16x32_bf16 v[18:21], v[192:195], v[216:219], v[18:21]
	v_mfma_f32_16x16x32_bf16 v[10:13], v[184:187], v[224:227], v[10:13]
	v_mfma_f32_16x16x32_bf16 v[2:5], v[192:195], v[224:227], v[2:5]
	s_barrier
	s_setprio 0
	s_mov_b32 s7, s51
	s_add_u32 s88, s88, 0x100
	s_addc_u32 s89, s89, 0
	s_add_u32 s86, s86, 0x100
	s_addc_u32 s87, s87, 0
	s_cmp_ge_i32 s51, s101
	s_cbranch_scc1 .Lmy_kexit_0
.LBB0_171:
	s_add_u32 s98, s86, 0xfffc0080
	s_addc_u32 s99, s87, -1
	s_cmp_eq_u32 s7, s100
	s_cselect_b64 s[94:95], s[90:91], s[98:99]
	s_cselect_b64 s[96:97], s[92:93], s[88:89]
	s_add_i32 s51, s7, 2
	s_mov_b32 m0, s78
	ds_read_b128 v[164:167], v230
	global_load_lds_dwordx4 v144, s[86:87]
	s_mov_b32 m0, s79
	ds_read_b128 v[168:171], v234
	global_load_lds_dwordx4 v142, s[86:87]
	ds_read_b128 v[172:175], v230 offset:2048
	ds_read_b128 v[176:179], v234 offset:2048
	ds_read_b128 v[180:183], v231
	ds_read_b128 v[184:187], v235
	ds_read_b128 v[188:191], v231 offset:2048
	ds_read_b128 v[192:195], v235 offset:2048
	ds_read_b128 v[196:199], v160
	ds_read_b128 v[200:203], v238
	ds_read_b128 v[204:207], v160 offset:2048
	ds_read_b128 v[208:211], v238 offset:2048
	ds_read_b128 v[212:215], v160 offset:4096
	ds_read_b128 v[216:219], v238 offset:4096
	ds_read_b128 v[220:223], v160 offset:6144
	ds_read_b128 v[224:227], v238 offset:6144
	s_waitcnt vmcnt(8)
	s_waitcnt lgkmcnt(0)
	s_setprio 1
	s_barrier
	v_mfma_f32_16x16x32_bf16 v[122:125], v[164:167], v[196:199], v[122:125]
	v_mfma_f32_16x16x32_bf16 v[118:121], v[172:175], v[196:199], v[118:121]
	v_mfma_f32_16x16x32_bf16 v[110:113], v[164:167], v[204:207], v[110:113]
	v_mfma_f32_16x16x32_bf16 v[102:105], v[172:175], v[204:207], v[102:105]
	v_mfma_f32_16x16x32_bf16 v[94:97], v[164:167], v[212:215], v[94:97]
	v_mfma_f32_16x16x32_bf16 v[86:89], v[172:175], v[212:215], v[86:89]
	v_mfma_f32_16x16x32_bf16 v[78:81], v[164:167], v[220:223], v[78:81]
	v_mfma_f32_16x16x32_bf16 v[70:73], v[172:175], v[220:223], v[70:73]
	v_mfma_f32_16x16x32_bf16 v[122:125], v[168:171], v[200:203], v[122:125]
	v_mfma_f32_16x16x32_bf16 v[118:121], v[176:179], v[200:203], v[118:121]
	v_mfma_f32_16x16x32_bf16 v[110:113], v[168:171], v[208:211], v[110:113]
	v_mfma_f32_16x16x32_bf16 v[102:105], v[176:179], v[208:211], v[102:105]
	v_mfma_f32_16x16x32_bf16 v[94:97], v[168:171], v[216:219], v[94:97]
	v_mfma_f32_16x16x32_bf16 v[86:89], v[176:179], v[216:219], v[86:89]
	v_mfma_f32_16x16x32_bf16 v[78:81], v[168:171], v[224:227], v[78:81]
	v_mfma_f32_16x16x32_bf16 v[70:73], v[176:179], v[224:227], v[70:73]
	v_mfma_f32_16x16x32_bf16 v[126:129], v[180:183], v[196:199], v[126:129]
	v_mfma_f32_16x16x32_bf16 v[114:117], v[188:191], v[196:199], v[114:117]
	v_mfma_f32_16x16x32_bf16 v[106:109], v[180:183], v[204:207], v[106:109]
	v_mfma_f32_16x16x32_bf16 v[98:101], v[188:191], v[204:207], v[98:101]
	v_mfma_f32_16x16x32_bf16 v[90:93], v[180:183], v[212:215], v[90:93]
	v_mfma_f32_16x16x32_bf16 v[82:85], v[188:191], v[212:215], v[82:85]
	v_mfma_f32_16x16x32_bf16 v[74:77], v[180:183], v[220:223], v[74:77]
	v_mfma_f32_16x16x32_bf16 v[66:69], v[188:191], v[220:223], v[66:69]
	v_mfma_f32_16x16x32_bf16 v[126:129], v[184:187], v[200:203], v[126:129]
	v_mfma_f32_16x16x32_bf16 v[114:117], v[192:195], v[200:203], v[114:117]
	v_mfma_f32_16x16x32_bf16 v[106:109], v[184:187], v[208:211], v[106:109]
	v_mfma_f32_16x16x32_bf16 v[98:101], v[192:195], v[208:211], v[98:101]
	v_mfma_f32_16x16x32_bf16 v[90:93], v[184:187], v[216:219], v[90:93]
	v_mfma_f32_16x16x32_bf16 v[82:85], v[192:195], v[216:219], v[82:85]
	v_mfma_f32_16x16x32_bf16 v[74:77], v[184:187], v[224:227], v[74:77]
	v_mfma_f32_16x16x32_bf16 v[66:69], v[192:195], v[224:227], v[66:69]
	s_barrier
	s_setprio 0
	s_add_u32 s98, s96, 0x40000
	s_addc_u32 s99, s97, 0
	s_mov_b32 m0, s80
	ds_read_b128 v[196:199], v160 offset:16384
	global_load_lds_dwordx4 v132, s[96:97]
	s_mov_b32 m0, s81
	s_add_i32 s7, s77, s47
	global_load_lds_dwordx4 v136, s[96:97]
	s_mov_b32 m0, s7
	ds_read_b128 v[200:203], v238 offset:16384
	global_load_lds_dwordx4 v132, s[98:99]
	s_add_i32 m0, s7, 0x2000
	ds_read_b128 v[204:207], v160 offset:18432
	global_load_lds_dwordx4 v136, s[98:99]
	s_mov_b32 m0, s57
	ds_read_b128 v[208:211], v238 offset:18432
	global_load_lds_dwordx4 v130, s[94:95]
	s_mov_b32 m0, s62
	ds_read_b128 v[212:215], v160 offset:20480
	global_load_lds_dwordx4 v134, s[94:95]
	ds_read_b128 v[216:219], v238 offset:20480
	ds_read_b128 v[220:223], v160 offset:22528
	ds_read_b128 v[224:227], v238 offset:22528
	s_waitcnt vmcnt(8)
	s_waitcnt lgkmcnt(0)
	s_setprio 1
	s_barrier
	v_mfma_f32_16x16x32_bf16 v[62:65], v[164:167], v[196:199], v[62:65]
	v_mfma_f32_16x16x32_bf16 v[54:57], v[172:175], v[196:199], v[54:57]
	v_mfma_f32_16x16x32_bf16 v[46:49], v[164:167], v[204:207], v[46:49]
	v_mfma_f32_16x16x32_bf16 v[38:41], v[172:175], v[204:207], v[38:41]
	v_mfma_f32_16x16x32_bf16 v[30:33], v[164:167], v[212:215], v[30:33]
	v_mfma_f32_16x16x32_bf16 v[22:25], v[172:175], v[212:215], v[22:25]
	v_mfma_f32_16x16x32_bf16 v[14:17], v[164:167], v[220:223], v[14:17]
	v_mfma_f32_16x16x32_bf16 v[6:9], v[172:175], v[220:223], v[6:9]
	v_mfma_f32_16x16x32_bf16 v[62:65], v[168:171], v[200:203], v[62:65]
	v_mfma_f32_16x16x32_bf16 v[54:57], v[176:179], v[200:203], v[54:57]
	v_mfma_f32_16x16x32_bf16 v[46:49], v[168:171], v[208:211], v[46:49]
	v_mfma_f32_16x16x32_bf16 v[38:41], v[176:179], v[208:211], v[38:41]
	v_mfma_f32_16x16x32_bf16 v[30:33], v[168:171], v[216:219], v[30:33]
	v_mfma_f32_16x16x32_bf16 v[22:25], v[176:179], v[216:219], v[22:25]
	v_mfma_f32_16x16x32_bf16 v[14:17], v[168:171], v[224:227], v[14:17]
	v_mfma_f32_16x16x32_bf16 v[6:9], v[176:179], v[224:227], v[6:9]
	v_mfma_f32_16x16x32_bf16 v[58:61], v[180:183], v[196:199], v[58:61]
	v_mfma_f32_16x16x32_bf16 v[50:53], v[188:191], v[196:199], v[50:53]
	v_mfma_f32_16x16x32_bf16 v[42:45], v[180:183], v[204:207], v[42:45]
	v_mfma_f32_16x16x32_bf16 v[34:37], v[188:191], v[204:207], v[34:37]
	v_mfma_f32_16x16x32_bf16 v[26:29], v[180:183], v[212:215], v[26:29]
	v_mfma_f32_16x16x32_bf16 v[18:21], v[188:191], v[212:215], v[18:21]
	v_mfma_f32_16x16x32_bf16 v[10:13], v[180:183], v[220:223], v[10:13]
	v_mfma_f32_16x16x32_bf16 v[2:5], v[188:191], v[220:223], v[2:5]
	v_mfma_f32_16x16x32_bf16 v[58:61], v[184:187], v[200:203], v[58:61]
	v_mfma_f32_16x16x32_bf16 v[50:53], v[192:195], v[200:203], v[50:53]
	v_mfma_f32_16x16x32_bf16 v[42:45], v[184:187], v[208:211], v[42:45]
	v_mfma_f32_16x16x32_bf16 v[34:37], v[192:195], v[208:211], v[34:37]
	v_mfma_f32_16x16x32_bf16 v[26:29], v[184:187], v[216:219], v[26:29]
	v_mfma_f32_16x16x32_bf16 v[18:21], v[192:195], v[216:219], v[18:21]
	v_mfma_f32_16x16x32_bf16 v[10:13], v[184:187], v[224:227], v[10:13]
	v_mfma_f32_16x16x32_bf16 v[2:5], v[192:195], v[224:227], v[2:5]
	s_barrier
	s_setprio 0
	s_add_u32 s98, s94, 0x40000
	s_addc_u32 s99, s95, 0
	s_add_i32 s7, 0, 0x18000
	s_add_i32 s55, 0, 0x1c000
	s_mov_b32 m0, s63
	ds_read_b128 v[164:167], v232
	global_load_lds_dwordx4 v130, s[98:99]
	s_mov_b32 m0, s64
	ds_read_b128 v[168:171], v236
	global_load_lds_dwordx4 v134, s[98:99]
	ds_read_b128 v[172:175], v232 offset:2048
	ds_read_b128 v[176:179], v236 offset:2048
	ds_read_b128 v[180:183], v233
	ds_read_b128 v[184:187], v237
	ds_read_b128 v[188:191], v233 offset:2048
	ds_read_b128 v[192:195], v237 offset:2048
	ds_read_b128 v[196:199], v160 offset:32768
	ds_read_b128 v[200:203], v238 offset:32768
	ds_read_b128 v[204:207], v160 offset:34816
	ds_read_b128 v[208:211], v238 offset:34816
	ds_read_b128 v[212:215], v160 offset:36864
	ds_read_b128 v[216:219], v238 offset:36864
	ds_read_b128 v[220:223], v160 offset:38912
	ds_read_b128 v[224:227], v238 offset:38912
	s_waitcnt vmcnt(8)
	s_waitcnt lgkmcnt(0)
	s_setprio 1
	s_barrier
	v_mfma_f32_16x16x32_bf16 v[122:125], v[164:167], v[196:199], v[122:125]
	v_mfma_f32_16x16x32_bf16 v[118:121], v[172:175], v[196:199], v[118:121]
	v_mfma_f32_16x16x32_bf16 v[110:113], v[164:167], v[204:207], v[110:113]
	v_mfma_f32_16x16x32_bf16 v[102:105], v[172:175], v[204:207], v[102:105]
	v_mfma_f32_16x16x32_bf16 v[94:97], v[164:167], v[212:215], v[94:97]
	v_mfma_f32_16x16x32_bf16 v[86:89], v[172:175], v[212:215], v[86:89]
	v_mfma_f32_16x16x32_bf16 v[78:81], v[164:167], v[220:223], v[78:81]
	v_mfma_f32_16x16x32_bf16 v[70:73], v[172:175], v[220:223], v[70:73]
	v_mfma_f32_16x16x32_bf16 v[122:125], v[168:171], v[200:203], v[122:125]
	v_mfma_f32_16x16x32_bf16 v[118:121], v[176:179], v[200:203], v[118:121]
	v_mfma_f32_16x16x32_bf16 v[110:113], v[168:171], v[208:211], v[110:113]
	v_mfma_f32_16x16x32_bf16 v[102:105], v[176:179], v[208:211], v[102:105]
	v_mfma_f32_16x16x32_bf16 v[94:97], v[168:171], v[216:219], v[94:97]
	v_mfma_f32_16x16x32_bf16 v[86:89], v[176:179], v[216:219], v[86:89]
	v_mfma_f32_16x16x32_bf16 v[78:81], v[168:171], v[224:227], v[78:81]
	v_mfma_f32_16x16x32_bf16 v[70:73], v[176:179], v[224:227], v[70:73]
	v_mfma_f32_16x16x32_bf16 v[126:129], v[180:183], v[196:199], v[126:129]
	v_mfma_f32_16x16x32_bf16 v[114:117], v[188:191], v[196:199], v[114:117]
	v_mfma_f32_16x16x32_bf16 v[106:109], v[180:183], v[204:207], v[106:109]
	v_mfma_f32_16x16x32_bf16 v[98:101], v[188:191], v[204:207], v[98:101]
	v_mfma_f32_16x16x32_bf16 v[90:93], v[180:183], v[212:215], v[90:93]
	v_mfma_f32_16x16x32_bf16 v[82:85], v[188:191], v[212:215], v[82:85]
	v_mfma_f32_16x16x32_bf16 v[74:77], v[180:183], v[220:223], v[74:77]
	v_mfma_f32_16x16x32_bf16 v[66:69], v[188:191], v[220:223], v[66:69]
	v_mfma_f32_16x16x32_bf16 v[126:129], v[184:187], v[200:203], v[126:129]
	v_mfma_f32_16x16x32_bf16 v[114:117], v[192:195], v[200:203], v[114:117]
	v_mfma_f32_16x16x32_bf16 v[106:109], v[184:187], v[208:211], v[106:109]
	v_mfma_f32_16x16x32_bf16 v[98:101], v[192:195], v[208:211], v[98:101]
	v_mfma_f32_16x16x32_bf16 v[90:93], v[184:187], v[216:219], v[90:93]
	v_mfma_f32_16x16x32_bf16 v[82:85], v[192:195], v[216:219], v[82:85]
	v_mfma_f32_16x16x32_bf16 v[74:77], v[184:187], v[224:227], v[74:77]
	v_mfma_f32_16x16x32_bf16 v[66:69], v[192:195], v[224:227], v[66:69]
	s_barrier
	s_setprio 0
	s_add_u32 s96, s96, 0x80
	s_addc_u32 s97, s97, 0
	s_add_u32 s98, s96, 0x40000
	s_addc_u32 s99, s97, 0
	s_add_u32 s94, s94, 0x80
	s_addc_u32 s95, s95, 0
	s_add_i32 s7, s7, s47
	s_mov_b32 m0, s7
	ds_read_b128 v[196:199], v160 offset:49152
	global_load_lds_dwordx4 v132, s[96:97]
	s_add_i32 m0, s7, 0x2000
	s_add_i32 s7, s55, s47
	global_load_lds_dwordx4 v136, s[96:97]
	s_mov_b32 m0, s7
	ds_read_b128 v[200:203], v238 offset:49152
	global_load_lds_dwordx4 v132, s[98:99]
	s_add_i32 m0, s7, 0x2000
	ds_read_b128 v[204:207], v160 offset:51200
	global_load_lds_dwordx4 v136, s[98:99]
	s_mov_b32 m0, s65
	ds_read_b128 v[208:211], v238 offset:51200
	global_load_lds_dwordx4 v130, s[94:95]
	s_mov_b32 m0, s66
	ds_read_b128 v[212:215], v160 offset:53248
	global_load_lds_dwordx4 v134, s[94:95]
	ds_read_b128 v[216:219], v238 offset:53248
	ds_read_b128 v[220:223], v160 offset:55296
	ds_read_b128 v[224:227], v238 offset:55296
	s_waitcnt vmcnt(8)
	s_waitcnt lgkmcnt(0)
	s_setprio 1
	s_barrier
	v_mfma_f32_16x16x32_bf16 v[62:65], v[164:167], v[196:199], v[62:65]
	v_mfma_f32_16x16x32_bf16 v[54:57], v[172:175], v[196:199], v[54:57]
	v_mfma_f32_16x16x32_bf16 v[46:49], v[164:167], v[204:207], v[46:49]
	v_mfma_f32_16x16x32_bf16 v[38:41], v[172:175], v[204:207], v[38:41]
	v_mfma_f32_16x16x32_bf16 v[30:33], v[164:167], v[212:215], v[30:33]
	v_mfma_f32_16x16x32_bf16 v[22:25], v[172:175], v[212:215], v[22:25]
	v_mfma_f32_16x16x32_bf16 v[14:17], v[164:167], v[220:223], v[14:17]
	v_mfma_f32_16x16x32_bf16 v[6:9], v[172:175], v[220:223], v[6:9]
	v_mfma_f32_16x16x32_bf16 v[62:65], v[168:171], v[200:203], v[62:65]
	v_mfma_f32_16x16x32_bf16 v[54:57], v[176:179], v[200:203], v[54:57]
	v_mfma_f32_16x16x32_bf16 v[46:49], v[168:171], v[208:211], v[46:49]
	v_mfma_f32_16x16x32_bf16 v[38:41], v[176:179], v[208:211], v[38:41]
	v_mfma_f32_16x16x32_bf16 v[30:33], v[168:171], v[216:219], v[30:33]
	v_mfma_f32_16x16x32_bf16 v[22:25], v[176:179], v[216:219], v[22:25]
	v_mfma_f32_16x16x32_bf16 v[14:17], v[168:171], v[224:227], v[14:17]
	v_mfma_f32_16x16x32_bf16 v[6:9], v[176:179], v[224:227], v[6:9]
	v_mfma_f32_16x16x32_bf16 v[58:61], v[180:183], v[196:199], v[58:61]
	v_mfma_f32_16x16x32_bf16 v[50:53], v[188:191], v[196:199], v[50:53]
	v_mfma_f32_16x16x32_bf16 v[42:45], v[180:183], v[204:207], v[42:45]
	v_mfma_f32_16x16x32_bf16 v[34:37], v[188:191], v[204:207], v[34:37]
	v_mfma_f32_16x16x32_bf16 v[26:29], v[180:183], v[212:215], v[26:29]
	v_mfma_f32_16x16x32_bf16 v[18:21], v[188:191], v[212:215], v[18:21]
	v_mfma_f32_16x16x32_bf16 v[10:13], v[180:183], v[220:223], v[10:13]
	v_mfma_f32_16x16x32_bf16 v[2:5], v[188:191], v[220:223], v[2:5]
	v_mfma_f32_16x16x32_bf16 v[58:61], v[184:187], v[200:203], v[58:61]
	v_mfma_f32_16x16x32_bf16 v[50:53], v[192:195], v[200:203], v[50:53]
	v_mfma_f32_16x16x32_bf16 v[42:45], v[184:187], v[208:211], v[42:45]
	v_mfma_f32_16x16x32_bf16 v[34:37], v[192:195], v[208:211], v[34:37]
	v_mfma_f32_16x16x32_bf16 v[26:29], v[184:187], v[216:219], v[26:29]
	v_mfma_f32_16x16x32_bf16 v[18:21], v[192:195], v[216:219], v[18:21]
	v_mfma_f32_16x16x32_bf16 v[10:13], v[184:187], v[224:227], v[10:13]
	v_mfma_f32_16x16x32_bf16 v[2:5], v[192:195], v[224:227], v[2:5]
	s_barrier
	s_setprio 0
	s_mov_b32 s7, s51
	s_add_u32 s88, s88, 0x100
	s_addc_u32 s89, s89, 0
	s_add_u32 s86, s86, 0x100
	s_addc_u32 s87, s87, 0
	s_cmp_ge_i32 s51, s101
	s_cbranch_scc0 .LBB0_171

.LBB0_295:
	v_ashrrev_i32_e32 v5, 31, v12
	v_lshrrev_b32_e32 v5, 26, v5
	v_add_u32_e32 v5, v12, v5
	v_ashrrev_i32_e32 v13, 6, v5
	v_bfe_i32 v5, v12, 27, 1
	v_lshlrev_b32_e32 v4, 4, v12
	v_lshrrev_b32_e32 v5, 22, v5
	v_add_u32_e32 v5, v4, v5
	v_and_b32_e32 v5, 0xfffffc00, v5
	v_sub_u32_e32 v5, v4, v5
	v_lshrrev_b32_e32 v6, 4, v5
	v_bitop3_b32 v6, v6, v5, 32 bitop3:0x6c
	v_ashrrev_i32_e32 v5, 31, v5
	v_lshrrev_b32_e32 v5, 26, v5
	v_lshlrev_b32_e32 v7, 3, v13
	v_add_u32_e32 v5, v6, v5
	v_and_b32_e32 v7, -16, v7
	v_ashrrev_i32_e32 v14, 6, v5
	v_add_u32_e32 v5, v14, v7
	v_lshlrev_b32_e32 v7, 5, v13
	v_and_b32_e32 v15, 32, v7
	v_mul_i32_i24_e32 v7, 64, v14
	v_sub_u32_e32 v6, v6, v7
	v_mov_b32_e32 v7, 1
	v_ashrrev_i16_sdwa v6, v7, sext(v6) dst_sel:DWORD dst_unused:UNUSED_PAD src0_sel:DWORD src1_sel:BYTE_0
	v_lshlrev_b32_e32 v8, 1, v5
	v_lshrrev_b32_e32 v9, 2, v5
	v_and_b32_e32 v10, 3, v14
	s_mov_b32 s9, 0xffffe0
	v_bfe_i32 v16, v6, 0, 16
	v_and_b32_e32 v8, 24, v8
	v_and_b32_e32 v9, 4, v9
	v_and_or_b32 v10, v5, s9, v10
	s_movk_i32 s8, 0xb00
	v_add_u32_e32 v6, v15, v16
	v_or3_b32 v8, v10, v9, v8
	v_mul_lo_u32 v5, v5, s8
	v_add_lshl_u32 v130, v6, v5, 1
	v_mul_u32_u24_e32 v5, 0xb00, v8
	v_add_u32_e32 v4, 0x2000, v4
	v_add_lshl_u32 v132, v5, v6, 1
	v_ashrrev_i32_e32 v5, 31, v4
	v_lshrrev_b32_e32 v5, 22, v5
	v_add_u32_e32 v5, v4, v5
	v_ashrrev_i32_e32 v17, 10, v5
	v_mul_i32_i24_e32 v5, 0x400, v17
	v_sub_u32_e32 v4, v4, v5
	v_lshrrev_b32_e32 v5, 4, v4
	v_bitop3_b32 v4, v5, v4, 32 bitop3:0x6c
	v_ashrrev_i32_e32 v6, 31, v4
	v_lshrrev_b32_e32 v6, 26, v6
	v_lshlrev_b32_e32 v5, 3, v17
	v_add_u32_e32 v6, v4, v6
	v_and_b32_e32 v5, -16, v5
	v_ashrrev_i32_e32 v19, 6, v6
	v_and_b32_e32 v6, 0xc0, v6
	v_add_u32_e32 v5, v19, v5
	v_lshlrev_b32_e32 v8, 5, v17
	v_sub_u32_e32 v4, v4, v6
	s_ashr_i32 s5, s4, 6
	v_and_b32_e32 v18, 32, v8
	v_ashrrev_i16_sdwa v4, v7, sext(v4) dst_sel:DWORD dst_unused:UNUSED_PAD src0_sel:DWORD src1_sel:BYTE_0
	v_lshlrev_b32_e32 v6, 1, v5
	v_lshrrev_b32_e32 v7, 2, v5
	v_and_b32_e32 v8, 3, v19
	v_bfe_i32 v20, v4, 0, 16
	v_and_b32_e32 v6, 24, v6
	v_and_b32_e32 v7, 4, v7
	v_and_or_b32 v8, v5, s9, v8
	s_lshl_b32 s54, s5, 10
	v_add_u32_e32 v4, v18, v20
	v_or3_b32 v6, v8, v7, v6
	v_mul_lo_u32 v5, v5, s8
	s_add_i32 s55, s54, 0
	v_add_lshl_u32 v134, v4, v5, 1
	v_mul_u32_u24_e32 v5, 0xb00, v6
	s_add_i32 m0, s55, 0x10000
	v_readfirstlane_b32 s16, v2
	v_readfirstlane_b32 s17, v3
	v_add_lshl_u32 v136, v5, v4, 1
	s_add_i32 s56, s55, 0x2000
	s_add_i32 s57, s55, 0x4000
	s_add_i32 s58, s55, 0x6000
	s_ashr_i32 s9, s4, 8
	v_lshrrev_b32_e32 v242, 6, v1
	v_and_b32_e32 v243, 63, v1
	v_lshlrev_b32_e32 v245, 4, v243
	v_lshrrev_b32_e32 v244, 5, v243
	v_lshlrev_b32_e32 v244, 5, v244
	v_xor_b32_e32 v245, v245, v244
	v_lshrrev_b32_e32 v244, 1, v242
	v_lshlrev_b32_e32 v244, 4, v244
	v_lshrrev_b32_e32 v243, 6, v245
	v_add_u32_e32 v244, v244, v243
	v_and_b32_e32 v245, 63, v245
	v_and_b32_e32 v242, 1, v242
	v_lshl_add_u32 v245, v242, 6, v245
	v_mul_u32_u24_e32 v244, 0x1600, v244
	v_add_u32_e32 v240, v244, v245
	v_lshrrev_b32_e32 v242, 6, v1
	v_and_b32_e32 v243, 63, v1
	v_lshrrev_b32_e32 v244, 3, v243
	v_lshl_add_u32 v244, v242, 3, v244
	v_lshrrev_b32_e32 v245, 4, v243
	v_and_b32_e32 v245, 3, v245
	v_lshlrev_b32_e32 v245, 1, v245
	v_and_b32_e32 v243, 7, v243
	v_xor_b32_e32 v245, v243, v245
	v_lshlrev_b32_e32 v245, 4, v245
	v_mul_u32_u24_e32 v244, 0x1600, v244
	v_add_u32_e32 v241, v244, v245
	v_sub_u32_e32 v130, v130, v240
	v_add_u32_e32 v130, v130, v241
	v_lshrrev_b32_e32 v242, 6, v1
	v_and_b32_e32 v243, 63, v1
	v_lshlrev_b32_e32 v245, 4, v243
	v_lshrrev_b32_e32 v244, 5, v243
	v_lshlrev_b32_e32 v244, 5, v244
	v_xor_b32_e32 v245, v245, v244
	v_add_u32_e32 v242, 8, v242
	v_lshrrev_b32_e32 v244, 1, v242
	v_lshlrev_b32_e32 v244, 4, v244
	v_lshrrev_b32_e32 v243, 6, v245
	v_add_u32_e32 v244, v244, v243
	v_and_b32_e32 v245, 63, v245
	v_and_b32_e32 v242, 1, v242
	v_lshl_add_u32 v245, v242, 6, v245
	v_mul_u32_u24_e32 v244, 0x1600, v244
	v_add_u32_e32 v240, v244, v245
	v_lshrrev_b32_e32 v242, 6, v1
	v_and_b32_e32 v243, 63, v1
	v_lshrrev_b32_e32 v244, 3, v243
	v_lshl_add_u32 v244, v242, 3, v244
	v_add_u32_e32 v244, 64, v244
	v_lshrrev_b32_e32 v245, 4, v243
	v_and_b32_e32 v245, 3, v245
	v_lshlrev_b32_e32 v245, 1, v245
	v_and_b32_e32 v243, 7, v243
	v_xor_b32_e32 v245, v243, v245
	v_lshlrev_b32_e32 v245, 4, v245
	v_mul_u32_u24_e32 v244, 0x1600, v244
	v_add_u32_e32 v241, v244, v245
	v_sub_u32_e32 v134, v134, v240
	v_add_u32_e32 v134, v134, v241
	v_lshrrev_b32_e32 v242, 6, v1
	v_and_b32_e32 v243, 63, v1
	v_lshlrev_b32_e32 v245, 4, v243
	v_lshrrev_b32_e32 v244, 5, v243
	v_lshlrev_b32_e32 v244, 5, v244
	v_xor_b32_e32 v245, v245, v244
	v_lshrrev_b32_e32 v244, 1, v242
	v_lshlrev_b32_e32 v244, 4, v244
	v_lshrrev_b32_e32 v243, 6, v245
	v_add_u32_e32 v244, v244, v243
	v_and_b32_e32 v245, 63, v245
	v_and_b32_e32 v242, 1, v242
	v_lshl_add_u32 v245, v242, 6, v245
	v_and_b32_e32 v242, 31, v244
	v_sub_u32_e32 v244, v244, v242
	v_and_b32_e32 v243, 3, v242
	v_add_u32_e32 v244, v244, v243
	v_lshrrev_b32_e32 v243, 4, v242
	v_lshl_add_u32 v244, v243, 2, v244
	v_and_b32_e32 v243, 15, v242
	v_lshrrev_b32_e32 v243, 2, v243
	v_lshl_add_u32 v244, v243, 3, v244
	v_mul_u32_u24_e32 v244, 0x1600, v244
	v_add_u32_e32 v240, v244, v245
	v_lshrrev_b32_e32 v242, 6, v1
	v_and_b32_e32 v243, 63, v1
	v_lshrrev_b32_e32 v244, 3, v243
	v_lshl_add_u32 v244, v242, 3, v244
	v_lshrrev_b32_e32 v245, 4, v243
	v_and_b32_e32 v245, 3, v245
	v_lshlrev_b32_e32 v245, 1, v245
	v_and_b32_e32 v243, 7, v243
	v_xor_b32_e32 v245, v243, v245
	v_lshlrev_b32_e32 v245, 4, v245
	v_and_b32_e32 v242, 31, v244
	v_sub_u32_e32 v244, v244, v242
	v_and_b32_e32 v243, 3, v242
	v_add_u32_e32 v244, v244, v243
	v_lshrrev_b32_e32 v243, 4, v242
	v_lshl_add_u32 v244, v243, 2, v244
	v_and_b32_e32 v243, 15, v242
	v_lshrrev_b32_e32 v243, 2, v243
	v_lshl_add_u32 v244, v243, 3, v244
	v_mul_u32_u24_e32 v244, 0x1600, v244
	v_add_u32_e32 v241, v244, v245
	v_sub_u32_e32 v132, v132, v240
	v_add_u32_e32 v132, v132, v241
	v_lshrrev_b32_e32 v242, 6, v1
	v_and_b32_e32 v243, 63, v1
	v_lshlrev_b32_e32 v245, 4, v243
	v_lshrrev_b32_e32 v244, 5, v243
	v_lshlrev_b32_e32 v244, 5, v244
	v_xor_b32_e32 v245, v245, v244
	v_add_u32_e32 v242, 8, v242
	v_lshrrev_b32_e32 v244, 1, v242
	v_lshlrev_b32_e32 v244, 4, v244
	v_lshrrev_b32_e32 v243, 6, v245
	v_add_u32_e32 v244, v244, v243
	v_and_b32_e32 v245, 63, v245
	v_and_b32_e32 v242, 1, v242
	v_lshl_add_u32 v245, v242, 6, v245
	v_and_b32_e32 v242, 31, v244
	v_sub_u32_e32 v244, v244, v242
	v_and_b32_e32 v243, 3, v242
	v_add_u32_e32 v244, v244, v243
	v_lshrrev_b32_e32 v243, 4, v242
	v_lshl_add_u32 v244, v243, 2, v244
	v_and_b32_e32 v243, 15, v242
	v_lshrrev_b32_e32 v243, 2, v243
	v_lshl_add_u32 v244, v243, 3, v244
	v_mul_u32_u24_e32 v244, 0x1600, v244
	v_add_u32_e32 v240, v244, v245
	v_lshrrev_b32_e32 v242, 6, v1
	v_and_b32_e32 v243, 63, v1
	v_lshrrev_b32_e32 v244, 3, v243
	v_lshl_add_u32 v244, v242, 3, v244
	v_add_u32_e32 v244, 64, v244
	v_lshrrev_b32_e32 v245, 4, v243
	v_and_b32_e32 v245, 3, v245
	v_lshlrev_b32_e32 v245, 1, v245
	v_and_b32_e32 v243, 7, v243
	v_xor_b32_e32 v245, v243, v245
	v_lshlrev_b32_e32 v245, 4, v245
	v_and_b32_e32 v242, 31, v244
	v_sub_u32_e32 v244, v244, v242
	v_and_b32_e32 v243, 3, v242
	v_add_u32_e32 v244, v244, v243
	v_lshrrev_b32_e32 v243, 4, v242
	v_lshl_add_u32 v244, v243, 2, v244
	v_and_b32_e32 v243, 15, v242
	v_lshrrev_b32_e32 v243, 2, v243
	v_lshl_add_u32 v244, v243, 3, v244
	v_mul_u32_u24_e32 v244, 0x1600, v244
	v_add_u32_e32 v241, v244, v245
	v_sub_u32_e32 v136, v136, v240
	v_add_u32_e32 v136, v136, v241
	global_load_lds_dwordx4 v132, s[16:17]
	s_add_i32 m0, s55, 0x12000
	v_mov_b32_e32 v139, 0
	global_load_lds_dwordx4 v136, s[16:17]
	s_mov_b64 s[16:17], 0xb0000
	v_lshl_add_u64 v[4:5], v[2:3], 0, s[16:17]
	s_add_i32 m0, s55, 0x14000
	v_readfirstlane_b32 s18, v4
	v_readfirstlane_b32 s19, v5
	v_lshl_add_u64 v[4:5], v[152:153], 0, s[16:17]
	v_mov_b32_e32 v133, v139
	v_mov_b32_e32 v137, v139
	v_mov_b32_e32 v131, v139
	v_mov_b32_e32 v135, v139
	global_load_lds_dwordx4 v132, s[18:19]
	s_add_i32 m0, s55, 0x16000
	s_cmp_eq_u32 s9, 1
	global_load_lds_dwordx4 v136, s[18:19]
	v_readfirstlane_b32 s18, v152
	v_readfirstlane_b32 s19, v153
	s_mov_b32 m0, s55
	s_mov_b32 s59, 0
	v_lshl_add_u64 v[10:11], v[2:3], 0, v[132:133]
	v_lshl_add_u64 v[8:9], v[2:3], 0, v[136:137]
	v_lshl_add_u64 v[6:7], v[152:153], 0, v[134:135]
	global_load_lds_dwordx4 v130, s[18:19]
	s_mov_b32 m0, s56
	s_nop 0
	global_load_lds_dwordx4 v134, s[18:19]
	v_readfirstlane_b32 s18, v4
	v_readfirstlane_b32 s19, v5
	s_mov_b32 m0, s57
	v_lshl_add_u64 v[4:5], v[152:153], 0, v[130:131]
	s_nop 2
	global_load_lds_dwordx4 v130, s[18:19]
	s_mov_b32 m0, s58
	s_nop 0
	global_load_lds_dwordx4 v134, s[18:19]
	s_cselect_b64 s[18:19], -1, 0
	s_cmp_lg_u32 s9, 1
	s_cbranch_scc1 .LBB0_297
	s_barrier
.LBB0_297:
	s_and_b32 s44, s5, 3
	s_lshl_b32 s60, s9, 6
	s_lshl_b32 s9, s9, 13
	s_lshl_b32 s61, s44, 5
	s_lshl_b32 s24, s44, 12
	s_add_u32 s62, s38, 0x51a2000
	s_mov_b64 s[20:21], 0x80
	s_addc_u32 s63, s39, 0
	s_add_i32 m0, s55, 0x18000
	v_lshl_add_u64 v[10:11], v[10:11], 0, s[20:21]
	s_waitcnt vmcnt(2)
	s_barrier
	global_load_lds_dwordx4 v[10:11], off
	v_lshl_add_u64 v[8:9], v[8:9], 0, s[20:21]
	s_add_i32 m0, s55, 0x1a000
	s_add_i32 s64, s55, 0x8000
	global_load_lds_dwordx4 v[8:9], off
	v_lshl_add_u64 v[4:5], v[4:5], 0, s[20:21]
	s_mov_b32 m0, s64
	s_add_i32 s65, s55, 0xa000
	global_load_lds_dwordx4 v[4:5], off
	v_lshl_add_u64 v[4:5], v[6:7], 0, s[20:21]
	s_mov_b32 m0, s65
	s_mov_b64 s[22:23], 0xb0080
	global_load_lds_dwordx4 v[4:5], off
	v_lshl_add_u64 v[4:5], v[2:3], 0, s[22:23]
	s_add_i32 m0, s55, 0x1c000
	v_lshl_add_u64 v[6:7], v[4:5], 0, v[132:133]
	global_load_lds_dwordx4 v[6:7], off
	v_lshl_add_u64 v[4:5], v[4:5], 0, v[136:137]
	s_add_i32 m0, s55, 0x1e000
	v_and_b32_e32 v140, 15, v12
	global_load_lds_dwordx4 v[4:5], off
	v_bfe_u32 v4, v12, 4, 2
	v_lshlrev_b32_e32 v5, 4, v4
	v_lshlrev_b32_e32 v7, 2, v12
	v_lshl_or_b32 v6, v140, 6, v5
	v_and_b32_e32 v7, 32, v7
	s_cmpk_lt_u32 s4, 0x100
	v_bitop3_b32 v160, v6, s24, v7 bitop3:0xde
	s_cselect_b64 s[24:25], -1, 0
	s_lshl_b32 s4, s5, 6
	v_bitop3_b32 v8, v6, s9, v7 bitop3:0xde
	s_movk_i32 s9, 0x80
	s_and_b64 s[28:29], exec, s[6:7]
	s_cselect_b32 s66, s9, 0x280
	s_lshl_b32 s9, s44, 2
	v_and_or_b32 v161, s4, 64, v5
	v_cmp_eq_u32_e64 s[4:5], 0, v4
	s_add_u32 s67, s62, s9
	v_lshl_or_b32 v162, v4, 3, s61
	v_lshrrev_b32_e32 v5, 1, v17
	v_mul_lo_u32 v4, v19, s8
	s_mov_b32 s9, 0xb000
	v_mad_u64_u32 v[4:5], s[28:29], v5, s9, v[4:5]
	v_or_b32_e32 v4, v4, v18
	v_add_lshl_u32 v138, v4, v20, 1
	v_lshrrev_b32_e32 v5, 1, v13
	v_mul_lo_u32 v4, v14, s8
	v_mad_u64_u32 v[4:5], s[8:9], v5, s9, v[4:5]
	v_or_b32_e32 v4, v4, v15
	s_waitcnt vmcnt(6)
	v_lshl_add_u64 v[142:143], v[138:139], 0, s[22:23]
	v_add_lshl_u32 v138, v4, v16, 1
	v_cndmask_b32_e64 v4, 0, 1, s[6:7]
	v_cmp_ne_u32_e64 s[6:7], 1, v4
	v_mbcnt_lo_u32_b32 v4, -1, 0
	s_addc_u32 s68, s63, 0
	v_lshl_add_u64 v[144:145], v[138:139], 0, s[22:23]
	s_mov_b64 s[28:29], 0x100
	s_add_i32 s69, 0, 0x10000
	s_add_i32 s72, 0, 0x14000
	v_add_u32_e32 v163, 0, v8
	s_movk_i32 s73, 0x7fff
	s_mov_b32 s44, 0xbfb8aa3b
	v_mbcnt_hi_u32_b32 v164, -1, v4
	s_barrier
	v_lshrrev_b32_e32 v242, 6, v1
	v_and_b32_e32 v243, 63, v1
	v_lshlrev_b32_e32 v245, 4, v243
	v_lshrrev_b32_e32 v244, 5, v243
	v_lshlrev_b32_e32 v244, 5, v244
	v_xor_b32_e32 v245, v245, v244
	v_lshrrev_b32_e32 v244, 1, v242
	v_lshlrev_b32_e32 v244, 4, v244
	v_lshrrev_b32_e32 v243, 6, v245
	v_add_u32_e32 v244, v244, v243
	v_and_b32_e32 v245, 63, v245
	v_and_b32_e32 v242, 1, v242
	v_lshl_add_u32 v245, v242, 6, v245
	v_mul_u32_u24_e32 v244, 0x1600, v244
	v_add_u32_e32 v240, v244, v245
	v_lshrrev_b32_e32 v242, 6, v1
	v_and_b32_e32 v243, 63, v1
	v_lshrrev_b32_e32 v244, 3, v243
	v_lshl_add_u32 v244, v242, 3, v244
	v_lshrrev_b32_e32 v245, 4, v243
	v_and_b32_e32 v245, 3, v245
	v_lshlrev_b32_e32 v245, 1, v245
	v_and_b32_e32 v243, 7, v243
	v_xor_b32_e32 v245, v243, v245
	v_lshlrev_b32_e32 v245, 4, v245
	v_mul_u32_u24_e32 v244, 0x1600, v244
	v_add_u32_e32 v241, v244, v245
	v_sub_u32_e32 v144, v144, v240
	v_add_u32_e32 v144, v144, v241
	v_lshrrev_b32_e32 v242, 6, v1
	v_and_b32_e32 v243, 63, v1
	v_lshlrev_b32_e32 v245, 4, v243
	v_lshrrev_b32_e32 v244, 5, v243
	v_lshlrev_b32_e32 v244, 5, v244
	v_xor_b32_e32 v245, v245, v244
	v_add_u32_e32 v242, 8, v242
	v_lshrrev_b32_e32 v244, 1, v242
	v_lshlrev_b32_e32 v244, 4, v244
	v_lshrrev_b32_e32 v243, 6, v245
	v_add_u32_e32 v244, v244, v243
	v_and_b32_e32 v245, 63, v245
	v_and_b32_e32 v242, 1, v242
	v_lshl_add_u32 v245, v242, 6, v245
	v_mul_u32_u24_e32 v244, 0x1600, v244
	v_add_u32_e32 v240, v244, v245
	v_lshrrev_b32_e32 v242, 6, v1
	v_and_b32_e32 v243, 63, v1
	v_lshrrev_b32_e32 v244, 3, v243
	v_lshl_add_u32 v244, v242, 3, v244
	v_add_u32_e32 v244, 64, v244
	v_lshrrev_b32_e32 v245, 4, v243
	v_and_b32_e32 v245, 3, v245
	v_lshlrev_b32_e32 v245, 1, v245
	v_and_b32_e32 v243, 7, v243
	v_xor_b32_e32 v245, v243, v245
	v_lshlrev_b32_e32 v245, 4, v245
	v_mul_u32_u24_e32 v244, 0x1600, v244
	v_add_u32_e32 v241, v244, v245
	v_sub_u32_e32 v142, v142, v240
	v_add_u32_e32 v142, v142, v241
	v_and_b32_e32 v240, 63, v1
	v_and_b32_e32 v241, 15, v240
	v_lshrrev_b32_e32 v242, 4, v240
	v_lshlrev_b32_e32 v243, 6, v241
	v_lshl_add_u32 v243, v242, 4, v243
	v_lshrrev_b32_e32 v244, 3, v241
	v_lshlrev_b32_e32 v245, 5, v244
	v_xor_b32_e32 v243, v243, v245
	v_sub_u32_e32 v163, v163, v243
	v_lshlrev_b32_e32 v244, 10, v244
	v_and_b32_e32 v245, 7, v241
	v_lshl_add_u32 v244, v245, 7, v244
	v_add_u32_e32 v163, v163, v244
	v_lshrrev_b32_e32 v245, 1, v245
	v_lshlrev_b32_e32 v245, 1, v245
	v_add_u32_e32 v244, 4, v242
	v_xor_b32_e32 v244, v244, v245
	v_lshl_add_u32 v238, v244, 4, v163
	v_xor_b32_e32 v244, v242, v245
	v_lshl_add_u32 v163, v244, 4, v163
	v_and_b32_e32 v240, 63, v1
	v_and_b32_e32 v241, 15, v240
	v_lshrrev_b32_e32 v242, 4, v240
	v_lshlrev_b32_e32 v243, 6, v241
	v_lshl_add_u32 v243, v242, 4, v243
	v_lshrrev_b32_e32 v244, 3, v241
	v_lshlrev_b32_e32 v245, 5, v244
	v_xor_b32_e32 v243, v243, v245
	v_sub_u32_e32 v160, v160, v243
	v_lshlrev_b32_e32 v244, 10, v244
	v_and_b32_e32 v245, 7, v241
	v_lshl_add_u32 v244, v245, 7, v244
	v_add_u32_e32 v160, v160, v244
	v_lshrrev_b32_e32 v245, 1, v245
	v_lshlrev_b32_e32 v245, 1, v245
	v_add_u32_e32 v244, 4, v242
	v_xor_b32_e32 v244, v244, v245
	v_lshl_add_u32 v239, v244, 4, v160
	v_xor_b32_e32 v244, v242, v245
	v_lshl_add_u32 v160, v244, 4, v160
	s_branch .LBB0_300

.Lmy_nb_1:
	s_nop 0
	v_readfirstlane_b32 s86, v152
	v_readfirstlane_b32 s87, v153
	v_readfirstlane_b32 s88, v154
	v_readfirstlane_b32 s89, v155
	v_readfirstlane_b32 s90, v148
	v_readfirstlane_b32 s91, v149
	v_readfirstlane_b32 s92, v150
	v_readfirstlane_b32 s93, v151
	v_readfirstlane_b32 s100, v138
	v_readfirstlane_b32 s101, v141
	v_add_u32_e32 v230, s69, v160
	v_add_u32_e32 v234, s69, v239
	v_add_u32_e32 v231, s72, v160
	v_add_u32_e32 v235, s72, v239
	v_add_u32_e32 v232, 0x18000, v160
	v_add_u32_e32 v236, 0x18000, v239
	v_add_u32_e32 v233, 0x1c000, v160
	v_add_u32_e32 v237, 0x1c000, v239
	s_add_u32 s98, s86, 0x100
	s_addc_u32 s99, s87, 0
	s_cmp_eq_u32 s8, s100
	s_cselect_b64 s[94:95], s[90:91], s[98:99]
	s_cselect_b64 s[96:97], s[92:93], s[88:89]
	s_add_i32 s9, s8, 2
	s_add_i32 m0, s55, 0xc000
	ds_read_b128 v[166:169], v230
	global_load_lds_dwordx4 v144, s[86:87]
	s_add_i32 m0, s55, 0xe000
	ds_read_b128 v[170:173], v234
	global_load_lds_dwordx4 v142, s[86:87]
	ds_read_b128 v[174:177], v230 offset:2048
	ds_read_b128 v[178:181], v234 offset:2048
	ds_read_b128 v[182:185], v231
	ds_read_b128 v[186:189], v235
	ds_read_b128 v[190:193], v231 offset:2048
	ds_read_b128 v[194:197], v235 offset:2048
	ds_read_b128 v[198:201], v163
	ds_read_b128 v[202:205], v238
	ds_read_b128 v[206:209], v163 offset:2048
	ds_read_b128 v[210:213], v238 offset:2048
	ds_read_b128 v[214:217], v163 offset:4096
	ds_read_b128 v[218:221], v238 offset:4096
	ds_read_b128 v[222:225], v163 offset:6144
	ds_read_b128 v[226:229], v238 offset:6144
	s_waitcnt vmcnt(8)
	s_waitcnt lgkmcnt(0)
	s_setprio 1
	s_barrier
	v_mfma_f32_16x16x32_bf16 v[122:125], v[166:169], v[198:201], 0
	v_mfma_f32_16x16x32_bf16 v[118:121], v[174:177], v[198:201], 0
	v_mfma_f32_16x16x32_bf16 v[110:113], v[166:169], v[206:209], 0
	v_mfma_f32_16x16x32_bf16 v[102:105], v[174:177], v[206:209], 0
	v_mfma_f32_16x16x32_bf16 v[94:97], v[166:169], v[214:217], 0
	v_mfma_f32_16x16x32_bf16 v[86:89], v[174:177], v[214:217], 0
	v_mfma_f32_16x16x32_bf16 v[78:81], v[166:169], v[222:225], 0
	v_mfma_f32_16x16x32_bf16 v[70:73], v[174:177], v[222:225], 0
	v_mfma_f32_16x16x32_bf16 v[122:125], v[170:173], v[202:205], v[122:125]
	v_mfma_f32_16x16x32_bf16 v[118:121], v[178:181], v[202:205], v[118:121]
	v_mfma_f32_16x16x32_bf16 v[110:113], v[170:173], v[210:213], v[110:113]
	v_mfma_f32_16x16x32_bf16 v[102:105], v[178:181], v[210:213], v[102:105]
	v_mfma_f32_16x16x32_bf16 v[94:97], v[170:173], v[218:221], v[94:97]
	v_mfma_f32_16x16x32_bf16 v[86:89], v[178:181], v[218:221], v[86:89]
	v_mfma_f32_16x16x32_bf16 v[78:81], v[170:173], v[226:229], v[78:81]
	v_mfma_f32_16x16x32_bf16 v[70:73], v[178:181], v[226:229], v[70:73]
	v_mfma_f32_16x16x32_bf16 v[126:129], v[182:185], v[198:201], 0
	v_mfma_f32_16x16x32_bf16 v[114:117], v[190:193], v[198:201], 0
	v_mfma_f32_16x16x32_bf16 v[106:109], v[182:185], v[206:209], 0
	v_mfma_f32_16x16x32_bf16 v[98:101], v[190:193], v[206:209], 0
	v_mfma_f32_16x16x32_bf16 v[90:93], v[182:185], v[214:217], 0
	v_mfma_f32_16x16x32_bf16 v[82:85], v[190:193], v[214:217], 0
	v_mfma_f32_16x16x32_bf16 v[74:77], v[182:185], v[222:225], 0
	v_mfma_f32_16x16x32_bf16 v[66:69], v[190:193], v[222:225], 0
	v_mfma_f32_16x16x32_bf16 v[126:129], v[186:189], v[202:205], v[126:129]
	v_mfma_f32_16x16x32_bf16 v[114:117], v[194:197], v[202:205], v[114:117]
	v_mfma_f32_16x16x32_bf16 v[106:109], v[186:189], v[210:213], v[106:109]
	v_mfma_f32_16x16x32_bf16 v[98:101], v[194:197], v[210:213], v[98:101]
	v_mfma_f32_16x16x32_bf16 v[90:93], v[186:189], v[218:221], v[90:93]
	v_mfma_f32_16x16x32_bf16 v[82:85], v[194:197], v[218:221], v[82:85]
	v_mfma_f32_16x16x32_bf16 v[74:77], v[186:189], v[226:229], v[74:77]
	v_mfma_f32_16x16x32_bf16 v[66:69], v[194:197], v[226:229], v[66:69]
	s_barrier
	s_setprio 0
	s_add_u32 s98, s96, 0xb0000
	s_addc_u32 s99, s97, 0
	s_add_i32 s8, s69, s54
	s_mov_b32 m0, s8
	ds_read_b128 v[198:201], v163 offset:16384
	global_load_lds_dwordx4 v132, s[96:97]
	s_add_i32 m0, s8, 0x2000
	s_add_i32 s8, s72, s54
	global_load_lds_dwordx4 v136, s[96:97]
	s_mov_b32 m0, s8
	ds_read_b128 v[202:205], v238 offset:16384
	global_load_lds_dwordx4 v132, s[98:99]
	s_add_i32 m0, s8, 0x2000
	ds_read_b128 v[206:209], v163 offset:18432
	global_load_lds_dwordx4 v136, s[98:99]
	s_mov_b32 m0, s55
	ds_read_b128 v[210:213], v238 offset:18432
	global_load_lds_dwordx4 v130, s[94:95]
	s_mov_b32 m0, s56
	ds_read_b128 v[214:217], v163 offset:20480
	global_load_lds_dwordx4 v134, s[94:95]
	ds_read_b128 v[218:221], v238 offset:20480
	ds_read_b128 v[222:225], v163 offset:22528
	ds_read_b128 v[226:229], v238 offset:22528
	s_waitcnt vmcnt(8)
	s_waitcnt lgkmcnt(0)
	s_setprio 1
	s_barrier
	v_mfma_f32_16x16x32_bf16 v[62:65], v[166:169], v[198:201], 0
	v_mfma_f32_16x16x32_bf16 v[54:57], v[174:177], v[198:201], 0
	v_mfma_f32_16x16x32_bf16 v[46:49], v[166:169], v[206:209], 0
	v_mfma_f32_16x16x32_bf16 v[38:41], v[174:177], v[206:209], 0
	v_mfma_f32_16x16x32_bf16 v[30:33], v[166:169], v[214:217], 0
	v_mfma_f32_16x16x32_bf16 v[22:25], v[174:177], v[214:217], 0
	v_mfma_f32_16x16x32_bf16 v[14:17], v[166:169], v[222:225], 0
	v_mfma_f32_16x16x32_bf16 v[6:9], v[174:177], v[222:225], 0
	v_mfma_f32_16x16x32_bf16 v[62:65], v[170:173], v[202:205], v[62:65]
	v_mfma_f32_16x16x32_bf16 v[54:57], v[178:181], v[202:205], v[54:57]
	v_mfma_f32_16x16x32_bf16 v[46:49], v[170:173], v[210:213], v[46:49]
	v_mfma_f32_16x16x32_bf16 v[38:41], v[178:181], v[210:213], v[38:41]
	v_mfma_f32_16x16x32_bf16 v[30:33], v[170:173], v[218:221], v[30:33]
	v_mfma_f32_16x16x32_bf16 v[22:25], v[178:181], v[218:221], v[22:25]
	v_mfma_f32_16x16x32_bf16 v[14:17], v[170:173], v[226:229], v[14:17]
	v_mfma_f32_16x16x32_bf16 v[6:9], v[178:181], v[226:229], v[6:9]
	v_mfma_f32_16x16x32_bf16 v[58:61], v[182:185], v[198:201], 0
	v_mfma_f32_16x16x32_bf16 v[50:53], v[190:193], v[198:201], 0
	v_mfma_f32_16x16x32_bf16 v[42:45], v[182:185], v[206:209], 0
	v_mfma_f32_16x16x32_bf16 v[34:37], v[190:193], v[206:209], 0
	v_mfma_f32_16x16x32_bf16 v[26:29], v[182:185], v[214:217], 0
	v_mfma_f32_16x16x32_bf16 v[18:21], v[190:193], v[214:217], 0
	v_mfma_f32_16x16x32_bf16 v[10:13], v[182:185], v[222:225], 0
	v_mfma_f32_16x16x32_bf16 v[2:5], v[190:193], v[222:225], 0
	v_mfma_f32_16x16x32_bf16 v[58:61], v[186:189], v[202:205], v[58:61]
	v_mfma_f32_16x16x32_bf16 v[50:53], v[194:197], v[202:205], v[50:53]
	v_mfma_f32_16x16x32_bf16 v[42:45], v[186:189], v[210:213], v[42:45]
	v_mfma_f32_16x16x32_bf16 v[34:37], v[194:197], v[210:213], v[34:37]
	v_mfma_f32_16x16x32_bf16 v[26:29], v[186:189], v[218:221], v[26:29]
	v_mfma_f32_16x16x32_bf16 v[18:21], v[194:197], v[218:221], v[18:21]
	v_mfma_f32_16x16x32_bf16 v[10:13], v[186:189], v[226:229], v[10:13]
	v_mfma_f32_16x16x32_bf16 v[2:5], v[194:197], v[226:229], v[2:5]
	s_barrier
	s_setprio 0
	s_add_u32 s98, s94, 0xb0000
	s_addc_u32 s99, s95, 0
	s_add_i32 s8, 0, 0x18000
	s_add_i32 s50, 0, 0x1c000
	s_mov_b32 m0, s57
	ds_read_b128 v[166:169], v232
	global_load_lds_dwordx4 v130, s[98:99]
	s_mov_b32 m0, s58
	ds_read_b128 v[170:173], v236
	global_load_lds_dwordx4 v134, s[98:99]
	ds_read_b128 v[174:177], v232 offset:2048
	ds_read_b128 v[178:181], v236 offset:2048
	ds_read_b128 v[182:185], v233
	ds_read_b128 v[186:189], v237
	ds_read_b128 v[190:193], v233 offset:2048
	ds_read_b128 v[194:197], v237 offset:2048
	ds_read_b128 v[198:201], v163 offset:32768
	ds_read_b128 v[202:205], v238 offset:32768
	ds_read_b128 v[206:209], v163 offset:34816
	ds_read_b128 v[210:213], v238 offset:34816
	ds_read_b128 v[214:217], v163 offset:36864
	ds_read_b128 v[218:221], v238 offset:36864
	ds_read_b128 v[222:225], v163 offset:38912
	ds_read_b128 v[226:229], v238 offset:38912
	s_waitcnt vmcnt(8)
	s_waitcnt lgkmcnt(0)
	s_setprio 1
	s_barrier
	v_mfma_f32_16x16x32_bf16 v[122:125], v[166:169], v[198:201], v[122:125]
	v_mfma_f32_16x16x32_bf16 v[118:121], v[174:177], v[198:201], v[118:121]
	v_mfma_f32_16x16x32_bf16 v[110:113], v[166:169], v[206:209], v[110:113]
	v_mfma_f32_16x16x32_bf16 v[102:105], v[174:177], v[206:209], v[102:105]
	v_mfma_f32_16x16x32_bf16 v[94:97], v[166:169], v[214:217], v[94:97]
	v_mfma_f32_16x16x32_bf16 v[86:89], v[174:177], v[214:217], v[86:89]
	v_mfma_f32_16x16x32_bf16 v[78:81], v[166:169], v[222:225], v[78:81]
	v_mfma_f32_16x16x32_bf16 v[70:73], v[174:177], v[222:225], v[70:73]
	v_mfma_f32_16x16x32_bf16 v[122:125], v[170:173], v[202:205], v[122:125]
	v_mfma_f32_16x16x32_bf16 v[118:121], v[178:181], v[202:205], v[118:121]
	v_mfma_f32_16x16x32_bf16 v[110:113], v[170:173], v[210:213], v[110:113]
	v_mfma_f32_16x16x32_bf16 v[102:105], v[178:181], v[210:213], v[102:105]
	v_mfma_f32_16x16x32_bf16 v[94:97], v[170:173], v[218:221], v[94:97]
	v_mfma_f32_16x16x32_bf16 v[86:89], v[178:181], v[218:221], v[86:89]
	v_mfma_f32_16x16x32_bf16 v[78:81], v[170:173], v[226:229], v[78:81]
	v_mfma_f32_16x16x32_bf16 v[70:73], v[178:181], v[226:229], v[70:73]
	v_mfma_f32_16x16x32_bf16 v[126:129], v[182:185], v[198:201], v[126:129]
	v_mfma_f32_16x16x32_bf16 v[114:117], v[190:193], v[198:201], v[114:117]
	v_mfma_f32_16x16x32_bf16 v[106:109], v[182:185], v[206:209], v[106:109]
	v_mfma_f32_16x16x32_bf16 v[98:101], v[190:193], v[206:209], v[98:101]
	v_mfma_f32_16x16x32_bf16 v[90:93], v[182:185], v[214:217], v[90:93]
	v_mfma_f32_16x16x32_bf16 v[82:85], v[190:193], v[214:217], v[82:85]
	v_mfma_f32_16x16x32_bf16 v[74:77], v[182:185], v[222:225], v[74:77]
	v_mfma_f32_16x16x32_bf16 v[66:69], v[190:193], v[222:225], v[66:69]
	v_mfma_f32_16x16x32_bf16 v[126:129], v[186:189], v[202:205], v[126:129]
	v_mfma_f32_16x16x32_bf16 v[114:117], v[194:197], v[202:205], v[114:117]
	v_mfma_f32_16x16x32_bf16 v[106:109], v[186:189], v[210:213], v[106:109]
	v_mfma_f32_16x16x32_bf16 v[98:101], v[194:197], v[210:213], v[98:101]
	v_mfma_f32_16x16x32_bf16 v[90:93], v[186:189], v[218:221], v[90:93]
	v_mfma_f32_16x16x32_bf16 v[82:85], v[194:197], v[218:221], v[82:85]
	v_mfma_f32_16x16x32_bf16 v[74:77], v[186:189], v[226:229], v[74:77]
	v_mfma_f32_16x16x32_bf16 v[66:69], v[194:197], v[226:229], v[66:69]
	s_barrier
	s_setprio 0
	s_add_u32 s96, s96, 0x80
	s_addc_u32 s97, s97, 0
	s_add_u32 s98, s96, 0xb0000
	s_addc_u32 s99, s97, 0
	s_add_u32 s94, s94, 0x80
	s_addc_u32 s95, s95, 0
	s_add_i32 s8, s8, s54
	s_mov_b32 m0, s8
	ds_read_b128 v[198:201], v163 offset:49152
	global_load_lds_dwordx4 v132, s[96:97]
	s_add_i32 m0, s8, 0x2000
	s_add_i32 s8, s50, s54
	global_load_lds_dwordx4 v136, s[96:97]
	s_mov_b32 m0, s8
	ds_read_b128 v[202:205], v238 offset:49152
	global_load_lds_dwordx4 v132, s[98:99]
	s_add_i32 m0, s8, 0x2000
	ds_read_b128 v[206:209], v163 offset:51200
	global_load_lds_dwordx4 v136, s[98:99]
	s_mov_b32 m0, s64
	ds_read_b128 v[210:213], v238 offset:51200
	global_load_lds_dwordx4 v130, s[94:95]
	s_mov_b32 m0, s65
	ds_read_b128 v[214:217], v163 offset:53248
	global_load_lds_dwordx4 v134, s[94:95]
	ds_read_b128 v[218:221], v238 offset:53248
	ds_read_b128 v[222:225], v163 offset:55296
	ds_read_b128 v[226:229], v238 offset:55296
	s_waitcnt vmcnt(8)
	s_waitcnt lgkmcnt(0)
	s_setprio 1
	s_barrier
	v_mfma_f32_16x16x32_bf16 v[62:65], v[166:169], v[198:201], v[62:65]
	v_mfma_f32_16x16x32_bf16 v[54:57], v[174:177], v[198:201], v[54:57]
	v_mfma_f32_16x16x32_bf16 v[46:49], v[166:169], v[206:209], v[46:49]
	v_mfma_f32_16x16x32_bf16 v[38:41], v[174:177], v[206:209], v[38:41]
	v_mfma_f32_16x16x32_bf16 v[30:33], v[166:169], v[214:217], v[30:33]
	v_mfma_f32_16x16x32_bf16 v[22:25], v[174:177], v[214:217], v[22:25]
	v_mfma_f32_16x16x32_bf16 v[14:17], v[166:169], v[222:225], v[14:17]
	v_mfma_f32_16x16x32_bf16 v[6:9], v[174:177], v[222:225], v[6:9]
	v_mfma_f32_16x16x32_bf16 v[62:65], v[170:173], v[202:205], v[62:65]
	v_mfma_f32_16x16x32_bf16 v[54:57], v[178:181], v[202:205], v[54:57]
	v_mfma_f32_16x16x32_bf16 v[46:49], v[170:173], v[210:213], v[46:49]
	v_mfma_f32_16x16x32_bf16 v[38:41], v[178:181], v[210:213], v[38:41]
	v_mfma_f32_16x16x32_bf16 v[30:33], v[170:173], v[218:221], v[30:33]
	v_mfma_f32_16x16x32_bf16 v[22:25], v[178:181], v[218:221], v[22:25]
	v_mfma_f32_16x16x32_bf16 v[14:17], v[170:173], v[226:229], v[14:17]
	v_mfma_f32_16x16x32_bf16 v[6:9], v[178:181], v[226:229], v[6:9]
	v_mfma_f32_16x16x32_bf16 v[58:61], v[182:185], v[198:201], v[58:61]
	v_mfma_f32_16x16x32_bf16 v[50:53], v[190:193], v[198:201], v[50:53]
	v_mfma_f32_16x16x32_bf16 v[42:45], v[182:185], v[206:209], v[42:45]
	v_mfma_f32_16x16x32_bf16 v[34:37], v[190:193], v[206:209], v[34:37]
	v_mfma_f32_16x16x32_bf16 v[26:29], v[182:185], v[214:217], v[26:29]
	v_mfma_f32_16x16x32_bf16 v[18:21], v[190:193], v[214:217], v[18:21]
	v_mfma_f32_16x16x32_bf16 v[10:13], v[182:185], v[222:225], v[10:13]
	v_mfma_f32_16x16x32_bf16 v[2:5], v[190:193], v[222:225], v[2:5]
	v_mfma_f32_16x16x32_bf16 v[58:61], v[186:189], v[202:205], v[58:61]
	v_mfma_f32_16x16x32_bf16 v[50:53], v[194:197], v[202:205], v[50:53]
	v_mfma_f32_16x16x32_bf16 v[42:45], v[186:189], v[210:213], v[42:45]
	v_mfma_f32_16x16x32_bf16 v[34:37], v[194:197], v[210:213], v[34:37]
	v_mfma_f32_16x16x32_bf16 v[26:29], v[186:189], v[218:221], v[26:29]
	v_mfma_f32_16x16x32_bf16 v[18:21], v[194:197], v[218:221], v[18:21]
	v_mfma_f32_16x16x32_bf16 v[10:13], v[186:189], v[226:229], v[10:13]
	v_mfma_f32_16x16x32_bf16 v[2:5], v[194:197], v[226:229], v[2:5]
	s_barrier
	s_setprio 0
	s_mov_b32 s8, s9
	s_add_u32 s88, s88, 0x100
	s_addc_u32 s89, s89, 0
	s_add_u32 s86, s86, 0x100
	s_addc_u32 s87, s87, 0
	s_cmp_ge_i32 s9, s101
	s_cbranch_scc1 .Lmy_kexit_1
.LBB0_310:
	s_add_u32 s98, s86, 0x100
	s_addc_u32 s99, s87, 0
	s_cmp_eq_u32 s8, s100
	s_cselect_b64 s[94:95], s[90:91], s[98:99]
	s_cselect_b64 s[96:97], s[92:93], s[88:89]
	s_add_i32 s9, s8, 2
	s_add_i32 m0, s55, 0xc000
	ds_read_b128 v[166:169], v230
	global_load_lds_dwordx4 v144, s[86:87]
	s_add_i32 m0, s55, 0xe000
	ds_read_b128 v[170:173], v234
	global_load_lds_dwordx4 v142, s[86:87]
	ds_read_b128 v[174:177], v230 offset:2048
	ds_read_b128 v[178:181], v234 offset:2048
	ds_read_b128 v[182:185], v231
	ds_read_b128 v[186:189], v235
	ds_read_b128 v[190:193], v231 offset:2048
	ds_read_b128 v[194:197], v235 offset:2048
	ds_read_b128 v[198:201], v163
	ds_read_b128 v[202:205], v238
	ds_read_b128 v[206:209], v163 offset:2048
	ds_read_b128 v[210:213], v238 offset:2048
	ds_read_b128 v[214:217], v163 offset:4096
	ds_read_b128 v[218:221], v238 offset:4096
	ds_read_b128 v[222:225], v163 offset:6144
	ds_read_b128 v[226:229], v238 offset:6144
	s_waitcnt vmcnt(8)
	s_waitcnt lgkmcnt(0)
	s_setprio 1
	s_barrier
	v_mfma_f32_16x16x32_bf16 v[122:125], v[166:169], v[198:201], v[122:125]
	v_mfma_f32_16x16x32_bf16 v[118:121], v[174:177], v[198:201], v[118:121]
	v_mfma_f32_16x16x32_bf16 v[110:113], v[166:169], v[206:209], v[110:113]
	v_mfma_f32_16x16x32_bf16 v[102:105], v[174:177], v[206:209], v[102:105]
	v_mfma_f32_16x16x32_bf16 v[94:97], v[166:169], v[214:217], v[94:97]
	v_mfma_f32_16x16x32_bf16 v[86:89], v[174:177], v[214:217], v[86:89]
	v_mfma_f32_16x16x32_bf16 v[78:81], v[166:169], v[222:225], v[78:81]
	v_mfma_f32_16x16x32_bf16 v[70:73], v[174:177], v[222:225], v[70:73]
	v_mfma_f32_16x16x32_bf16 v[122:125], v[170:173], v[202:205], v[122:125]
	v_mfma_f32_16x16x32_bf16 v[118:121], v[178:181], v[202:205], v[118:121]
	v_mfma_f32_16x16x32_bf16 v[110:113], v[170:173], v[210:213], v[110:113]
	v_mfma_f32_16x16x32_bf16 v[102:105], v[178:181], v[210:213], v[102:105]
	v_mfma_f32_16x16x32_bf16 v[94:97], v[170:173], v[218:221], v[94:97]
	v_mfma_f32_16x16x32_bf16 v[86:89], v[178:181], v[218:221], v[86:89]
	v_mfma_f32_16x16x32_bf16 v[78:81], v[170:173], v[226:229], v[78:81]
	v_mfma_f32_16x16x32_bf16 v[70:73], v[178:181], v[226:229], v[70:73]
	v_mfma_f32_16x16x32_bf16 v[126:129], v[182:185], v[198:201], v[126:129]
	v_mfma_f32_16x16x32_bf16 v[114:117], v[190:193], v[198:201], v[114:117]
	v_mfma_f32_16x16x32_bf16 v[106:109], v[182:185], v[206:209], v[106:109]
	v_mfma_f32_16x16x32_bf16 v[98:101], v[190:193], v[206:209], v[98:101]
	v_mfma_f32_16x16x32_bf16 v[90:93], v[182:185], v[214:217], v[90:93]
	v_mfma_f32_16x16x32_bf16 v[82:85], v[190:193], v[214:217], v[82:85]
	v_mfma_f32_16x16x32_bf16 v[74:77], v[182:185], v[222:225], v[74:77]
	v_mfma_f32_16x16x32_bf16 v[66:69], v[190:193], v[222:225], v[66:69]
	v_mfma_f32_16x16x32_bf16 v[126:129], v[186:189], v[202:205], v[126:129]
	v_mfma_f32_16x16x32_bf16 v[114:117], v[194:197], v[202:205], v[114:117]
	v_mfma_f32_16x16x32_bf16 v[106:109], v[186:189], v[210:213], v[106:109]
	v_mfma_f32_16x16x32_bf16 v[98:101], v[194:197], v[210:213], v[98:101]
	v_mfma_f32_16x16x32_bf16 v[90:93], v[186:189], v[218:221], v[90:93]
	v_mfma_f32_16x16x32_bf16 v[82:85], v[194:197], v[218:221], v[82:85]
	v_mfma_f32_16x16x32_bf16 v[74:77], v[186:189], v[226:229], v[74:77]
	v_mfma_f32_16x16x32_bf16 v[66:69], v[194:197], v[226:229], v[66:69]
	s_barrier
	s_setprio 0
	s_add_u32 s98, s96, 0xb0000
	s_addc_u32 s99, s97, 0
	s_add_i32 s8, s69, s54
	s_mov_b32 m0, s8
	ds_read_b128 v[198:201], v163 offset:16384
	global_load_lds_dwordx4 v132, s[96:97]
	s_add_i32 m0, s8, 0x2000
	s_add_i32 s8, s72, s54
	global_load_lds_dwordx4 v136, s[96:97]
	s_mov_b32 m0, s8
	ds_read_b128 v[202:205], v238 offset:16384
	global_load_lds_dwordx4 v132, s[98:99]
	s_add_i32 m0, s8, 0x2000
	ds_read_b128 v[206:209], v163 offset:18432
	global_load_lds_dwordx4 v136, s[98:99]
	s_mov_b32 m0, s55
	ds_read_b128 v[210:213], v238 offset:18432
	global_load_lds_dwordx4 v130, s[94:95]
	s_mov_b32 m0, s56
	ds_read_b128 v[214:217], v163 offset:20480
	global_load_lds_dwordx4 v134, s[94:95]
	ds_read_b128 v[218:221], v238 offset:20480
	ds_read_b128 v[222:225], v163 offset:22528
	ds_read_b128 v[226:229], v238 offset:22528
	s_waitcnt vmcnt(8)
	s_waitcnt lgkmcnt(0)
	s_setprio 1
	s_barrier
	v_mfma_f32_16x16x32_bf16 v[62:65], v[166:169], v[198:201], v[62:65]
	v_mfma_f32_16x16x32_bf16 v[54:57], v[174:177], v[198:201], v[54:57]
	v_mfma_f32_16x16x32_bf16 v[46:49], v[166:169], v[206:209], v[46:49]
	v_mfma_f32_16x16x32_bf16 v[38:41], v[174:177], v[206:209], v[38:41]
	v_mfma_f32_16x16x32_bf16 v[30:33], v[166:169], v[214:217], v[30:33]
	v_mfma_f32_16x16x32_bf16 v[22:25], v[174:177], v[214:217], v[22:25]
	v_mfma_f32_16x16x32_bf16 v[14:17], v[166:169], v[222:225], v[14:17]
	v_mfma_f32_16x16x32_bf16 v[6:9], v[174:177], v[222:225], v[6:9]
	v_mfma_f32_16x16x32_bf16 v[62:65], v[170:173], v[202:205], v[62:65]
	v_mfma_f32_16x16x32_bf16 v[54:57], v[178:181], v[202:205], v[54:57]
	v_mfma_f32_16x16x32_bf16 v[46:49], v[170:173], v[210:213], v[46:49]
	v_mfma_f32_16x16x32_bf16 v[38:41], v[178:181], v[210:213], v[38:41]
	v_mfma_f32_16x16x32_bf16 v[30:33], v[170:173], v[218:221], v[30:33]
	v_mfma_f32_16x16x32_bf16 v[22:25], v[178:181], v[218:221], v[22:25]
	v_mfma_f32_16x16x32_bf16 v[14:17], v[170:173], v[226:229], v[14:17]
	v_mfma_f32_16x16x32_bf16 v[6:9], v[178:181], v[226:229], v[6:9]
	v_mfma_f32_16x16x32_bf16 v[58:61], v[182:185], v[198:201], v[58:61]
	v_mfma_f32_16x16x32_bf16 v[50:53], v[190:193], v[198:201], v[50:53]
	v_mfma_f32_16x16x32_bf16 v[42:45], v[182:185], v[206:209], v[42:45]
	v_mfma_f32_16x16x32_bf16 v[34:37], v[190:193], v[206:209], v[34:37]
	v_mfma_f32_16x16x32_bf16 v[26:29], v[182:185], v[214:217], v[26:29]
	v_mfma_f32_16x16x32_bf16 v[18:21], v[190:193], v[214:217], v[18:21]
	v_mfma_f32_16x16x32_bf16 v[10:13], v[182:185], v[222:225], v[10:13]
	v_mfma_f32_16x16x32_bf16 v[2:5], v[190:193], v[222:225], v[2:5]
	v_mfma_f32_16x16x32_bf16 v[58:61], v[186:189], v[202:205], v[58:61]
	v_mfma_f32_16x16x32_bf16 v[50:53], v[194:197], v[202:205], v[50:53]
	v_mfma_f32_16x16x32_bf16 v[42:45], v[186:189], v[210:213], v[42:45]
	v_mfma_f32_16x16x32_bf16 v[34:37], v[194:197], v[210:213], v[34:37]
	v_mfma_f32_16x16x32_bf16 v[26:29], v[186:189], v[218:221], v[26:29]
	v_mfma_f32_16x16x32_bf16 v[18:21], v[194:197], v[218:221], v[18:21]
	v_mfma_f32_16x16x32_bf16 v[10:13], v[186:189], v[226:229], v[10:13]
	v_mfma_f32_16x16x32_bf16 v[2:5], v[194:197], v[226:229], v[2:5]
	s_barrier
	s_setprio 0
	s_add_u32 s98, s94, 0xb0000
	s_addc_u32 s99, s95, 0
	s_add_i32 s8, 0, 0x18000
	s_add_i32 s50, 0, 0x1c000
	s_mov_b32 m0, s57
	ds_read_b128 v[166:169], v232
	global_load_lds_dwordx4 v130, s[98:99]
	s_mov_b32 m0, s58
	ds_read_b128 v[170:173], v236
	global_load_lds_dwordx4 v134, s[98:99]
	ds_read_b128 v[174:177], v232 offset:2048
	ds_read_b128 v[178:181], v236 offset:2048
	ds_read_b128 v[182:185], v233
	ds_read_b128 v[186:189], v237
	ds_read_b128 v[190:193], v233 offset:2048
	ds_read_b128 v[194:197], v237 offset:2048
	ds_read_b128 v[198:201], v163 offset:32768
	ds_read_b128 v[202:205], v238 offset:32768
	ds_read_b128 v[206:209], v163 offset:34816
	ds_read_b128 v[210:213], v238 offset:34816
	ds_read_b128 v[214:217], v163 offset:36864
	ds_read_b128 v[218:221], v238 offset:36864
	ds_read_b128 v[222:225], v163 offset:38912
	ds_read_b128 v[226:229], v238 offset:38912
	s_waitcnt vmcnt(8)
	s_waitcnt lgkmcnt(0)
	s_setprio 1
	s_barrier
	v_mfma_f32_16x16x32_bf16 v[122:125], v[166:169], v[198:201], v[122:125]
	v_mfma_f32_16x16x32_bf16 v[118:121], v[174:177], v[198:201], v[118:121]
	v_mfma_f32_16x16x32_bf16 v[110:113], v[166:169], v[206:209], v[110:113]
	v_mfma_f32_16x16x32_bf16 v[102:105], v[174:177], v[206:209], v[102:105]
	v_mfma_f32_16x16x32_bf16 v[94:97], v[166:169], v[214:217], v[94:97]
	v_mfma_f32_16x16x32_bf16 v[86:89], v[174:177], v[214:217], v[86:89]
	v_mfma_f32_16x16x32_bf16 v[78:81], v[166:169], v[222:225], v[78:81]
	v_mfma_f32_16x16x32_bf16 v[70:73], v[174:177], v[222:225], v[70:73]
	v_mfma_f32_16x16x32_bf16 v[122:125], v[170:173], v[202:205], v[122:125]
	v_mfma_f32_16x16x32_bf16 v[118:121], v[178:181], v[202:205], v[118:121]
	v_mfma_f32_16x16x32_bf16 v[110:113], v[170:173], v[210:213], v[110:113]
	v_mfma_f32_16x16x32_bf16 v[102:105], v[178:181], v[210:213], v[102:105]
	v_mfma_f32_16x16x32_bf16 v[94:97], v[170:173], v[218:221], v[94:97]
	v_mfma_f32_16x16x32_bf16 v[86:89], v[178:181], v[218:221], v[86:89]
	v_mfma_f32_16x16x32_bf16 v[78:81], v[170:173], v[226:229], v[78:81]
	v_mfma_f32_16x16x32_bf16 v[70:73], v[178:181], v[226:229], v[70:73]
	v_mfma_f32_16x16x32_bf16 v[126:129], v[182:185], v[198:201], v[126:129]
	v_mfma_f32_16x16x32_bf16 v[114:117], v[190:193], v[198:201], v[114:117]
	v_mfma_f32_16x16x32_bf16 v[106:109], v[182:185], v[206:209], v[106:109]
	v_mfma_f32_16x16x32_bf16 v[98:101], v[190:193], v[206:209], v[98:101]
	v_mfma_f32_16x16x32_bf16 v[90:93], v[182:185], v[214:217], v[90:93]
	v_mfma_f32_16x16x32_bf16 v[82:85], v[190:193], v[214:217], v[82:85]
	v_mfma_f32_16x16x32_bf16 v[74:77], v[182:185], v[222:225], v[74:77]
	v_mfma_f32_16x16x32_bf16 v[66:69], v[190:193], v[222:225], v[66:69]
	v_mfma_f32_16x16x32_bf16 v[126:129], v[186:189], v[202:205], v[126:129]
	v_mfma_f32_16x16x32_bf16 v[114:117], v[194:197], v[202:205], v[114:117]
	v_mfma_f32_16x16x32_bf16 v[106:109], v[186:189], v[210:213], v[106:109]
	v_mfma_f32_16x16x32_bf16 v[98:101], v[194:197], v[210:213], v[98:101]
	v_mfma_f32_16x16x32_bf16 v[90:93], v[186:189], v[218:221], v[90:93]
	v_mfma_f32_16x16x32_bf16 v[82:85], v[194:197], v[218:221], v[82:85]
	v_mfma_f32_16x16x32_bf16 v[74:77], v[186:189], v[226:229], v[74:77]
	v_mfma_f32_16x16x32_bf16 v[66:69], v[194:197], v[226:229], v[66:69]
	s_barrier
	s_setprio 0
	s_add_u32 s96, s96, 0x80
	s_addc_u32 s97, s97, 0
	s_add_u32 s98, s96, 0xb0000
	s_addc_u32 s99, s97, 0
	s_add_u32 s94, s94, 0x80
	s_addc_u32 s95, s95, 0
	s_add_i32 s8, s8, s54
	s_mov_b32 m0, s8
	ds_read_b128 v[198:201], v163 offset:49152
	global_load_lds_dwordx4 v132, s[96:97]
	s_add_i32 m0, s8, 0x2000
	s_add_i32 s8, s50, s54
	global_load_lds_dwordx4 v136, s[96:97]
	s_mov_b32 m0, s8
	ds_read_b128 v[202:205], v238 offset:49152
	global_load_lds_dwordx4 v132, s[98:99]
	s_add_i32 m0, s8, 0x2000
	ds_read_b128 v[206:209], v163 offset:51200
	global_load_lds_dwordx4 v136, s[98:99]
	s_mov_b32 m0, s64
	ds_read_b128 v[210:213], v238 offset:51200
	global_load_lds_dwordx4 v130, s[94:95]
	s_mov_b32 m0, s65
	ds_read_b128 v[214:217], v163 offset:53248
	global_load_lds_dwordx4 v134, s[94:95]
	ds_read_b128 v[218:221], v238 offset:53248
	ds_read_b128 v[222:225], v163 offset:55296
	ds_read_b128 v[226:229], v238 offset:55296
	s_waitcnt vmcnt(8)
	s_waitcnt lgkmcnt(0)
	s_setprio 1
	s_barrier
	v_mfma_f32_16x16x32_bf16 v[62:65], v[166:169], v[198:201], v[62:65]
	v_mfma_f32_16x16x32_bf16 v[54:57], v[174:177], v[198:201], v[54:57]
	v_mfma_f32_16x16x32_bf16 v[46:49], v[166:169], v[206:209], v[46:49]
	v_mfma_f32_16x16x32_bf16 v[38:41], v[174:177], v[206:209], v[38:41]
	v_mfma_f32_16x16x32_bf16 v[30:33], v[166:169], v[214:217], v[30:33]
	v_mfma_f32_16x16x32_bf16 v[22:25], v[174:177], v[214:217], v[22:25]
	v_mfma_f32_16x16x32_bf16 v[14:17], v[166:169], v[222:225], v[14:17]
	v_mfma_f32_16x16x32_bf16 v[6:9], v[174:177], v[222:225], v[6:9]
	v_mfma_f32_16x16x32_bf16 v[62:65], v[170:173], v[202:205], v[62:65]
	v_mfma_f32_16x16x32_bf16 v[54:57], v[178:181], v[202:205], v[54:57]
	v_mfma_f32_16x16x32_bf16 v[46:49], v[170:173], v[210:213], v[46:49]
	v_mfma_f32_16x16x32_bf16 v[38:41], v[178:181], v[210:213], v[38:41]
	v_mfma_f32_16x16x32_bf16 v[30:33], v[170:173], v[218:221], v[30:33]
	v_mfma_f32_16x16x32_bf16 v[22:25], v[178:181], v[218:221], v[22:25]
	v_mfma_f32_16x16x32_bf16 v[14:17], v[170:173], v[226:229], v[14:17]
	v_mfma_f32_16x16x32_bf16 v[6:9], v[178:181], v[226:229], v[6:9]
	v_mfma_f32_16x16x32_bf16 v[58:61], v[182:185], v[198:201], v[58:61]
	v_mfma_f32_16x16x32_bf16 v[50:53], v[190:193], v[198:201], v[50:53]
	v_mfma_f32_16x16x32_bf16 v[42:45], v[182:185], v[206:209], v[42:45]
	v_mfma_f32_16x16x32_bf16 v[34:37], v[190:193], v[206:209], v[34:37]
	v_mfma_f32_16x16x32_bf16 v[26:29], v[182:185], v[214:217], v[26:29]
	v_mfma_f32_16x16x32_bf16 v[18:21], v[190:193], v[214:217], v[18:21]
	v_mfma_f32_16x16x32_bf16 v[10:13], v[182:185], v[222:225], v[10:13]
	v_mfma_f32_16x16x32_bf16 v[2:5], v[190:193], v[222:225], v[2:5]
	v_mfma_f32_16x16x32_bf16 v[58:61], v[186:189], v[202:205], v[58:61]
	v_mfma_f32_16x16x32_bf16 v[50:53], v[194:197], v[202:205], v[50:53]
	v_mfma_f32_16x16x32_bf16 v[42:45], v[186:189], v[210:213], v[42:45]
	v_mfma_f32_16x16x32_bf16 v[34:37], v[194:197], v[210:213], v[34:37]
	v_mfma_f32_16x16x32_bf16 v[26:29], v[186:189], v[218:221], v[26:29]
	v_mfma_f32_16x16x32_bf16 v[18:21], v[194:197], v[218:221], v[18:21]
	v_mfma_f32_16x16x32_bf16 v[10:13], v[186:189], v[226:229], v[10:13]
	v_mfma_f32_16x16x32_bf16 v[2:5], v[194:197], v[226:229], v[2:5]
	s_barrier
	s_setprio 0
	s_mov_b32 s8, s9
	s_add_u32 s88, s88, 0x100
	s_addc_u32 s89, s89, 0
	s_add_u32 s86, s86, 0x100
	s_addc_u32 s87, s87, 0
	s_cmp_ge_i32 s9, s101
	s_cbranch_scc0 .LBB0_310

.LBB0_490:
	v_ashrrev_i32_e32 v7, 31, v14
	v_lshrrev_b32_e32 v7, 26, v7
	v_add_u32_e32 v7, v14, v7
	v_ashrrev_i32_e32 v15, 6, v7
	v_bfe_i32 v7, v14, 27, 1
	v_lshlrev_b32_e32 v6, 4, v14
	v_lshrrev_b32_e32 v7, 22, v7
	v_add_u32_e32 v7, v6, v7
	v_and_b32_e32 v7, 0xfffffc00, v7
	v_sub_u32_e32 v7, v6, v7
	v_lshrrev_b32_e32 v8, 4, v7
	v_bitop3_b32 v8, v8, v7, 32 bitop3:0x6c
	v_ashrrev_i32_e32 v7, 31, v7
	v_lshrrev_b32_e32 v7, 26, v7
	v_add_u32_e32 v7, v8, v7
	v_ashrrev_i32_e32 v16, 6, v7
	v_lshlrev_b32_e32 v9, 3, v15
	v_mul_i32_i24_e32 v10, 64, v16
	v_and_b32_e32 v9, -16, v9
	v_sub_u32_e32 v8, v8, v10
	v_mov_b32_e32 v10, 1
	v_add_u32_e32 v7, v16, v9
	v_lshlrev_b32_e32 v9, 5, v15
	v_ashrrev_i16_sdwa v8, v10, sext(v8) dst_sel:DWORD dst_unused:UNUSED_PAD src0_sel:DWORD src1_sel:BYTE_0
	v_and_b32_e32 v9, 32, v9
	v_bfe_i32 v17, v8, 0, 16
	v_and_b32_e32 v12, 3, v16
	s_mov_b32 s5, 0x1fffe0
	v_add_lshl_u32 v9, v9, v17, 1
	v_add_u32_e32 v6, 0x2000, v6
	v_lshlrev_b32_e32 v8, 1, v7
	v_lshrrev_b32_e32 v11, 2, v7
	v_and_or_b32 v12, v7, s5, v12
	v_lshl_add_u32 v130, v7, 11, v9
	v_ashrrev_i32_e32 v7, 31, v6
	v_lshrrev_b32_e32 v7, 22, v7
	v_add_u32_e32 v7, v6, v7
	v_ashrrev_i32_e32 v18, 10, v7
	v_mul_i32_i24_e32 v7, 0x400, v18
	v_sub_u32_e32 v6, v6, v7
	v_and_b32_e32 v8, 24, v8
	v_and_b32_e32 v11, 4, v11
	v_lshrrev_b32_e32 v7, 4, v6
	v_or3_b32 v8, v12, v11, v8
	v_bitop3_b32 v6, v7, v6, 32 bitop3:0x6c
	v_lshl_add_u32 v132, v8, 11, v9
	v_ashrrev_i32_e32 v8, 31, v6
	v_lshrrev_b32_e32 v8, 26, v8
	v_add_u32_e32 v8, v6, v8
	v_lshlrev_b32_e32 v7, 3, v18
	v_ashrrev_i32_e32 v19, 6, v8
	v_and_b32_e32 v8, 0xc0, v8
	v_and_b32_e32 v7, -16, v7
	v_sub_u32_e32 v6, v6, v8
	s_ashr_i32 s4, s18, 6
	v_add_u32_e32 v7, v19, v7
	v_ashrrev_i16_sdwa v6, v10, sext(v6) dst_sel:DWORD dst_unused:UNUSED_PAD src0_sel:DWORD src1_sel:BYTE_0
	v_lshlrev_b32_e32 v9, 5, v18
	v_bfe_i32 v20, v6, 0, 16
	v_lshlrev_b32_e32 v6, 1, v7
	v_lshrrev_b32_e32 v8, 2, v7
	v_and_b32_e32 v10, 3, v19
	s_lshl_b32 s25, s4, 10
	v_and_b32_e32 v9, 32, v9
	v_and_b32_e32 v6, 24, v6
	v_and_b32_e32 v8, 4, v8
	v_and_or_b32 v10, v7, s5, v10
	s_add_i32 s49, s25, 0
	v_or3_b32 v6, v10, v8, v6
	v_add_lshl_u32 v8, v9, v20, 1
	s_add_i32 m0, s49, 0x10000
	v_readfirstlane_b32 s10, v4
	v_readfirstlane_b32 s11, v5
	v_lshl_add_u32 v136, v6, 11, v8
	v_lshl_add_u32 v134, v7, 11, v8
	s_add_i32 s58, s49, 0x2000
	s_add_i32 s59, s49, 0x4000
	s_add_i32 s60, s49, 0x6000
	v_lshrrev_b32_e32 v242, 6, v1
	v_and_b32_e32 v243, 63, v1
	v_lshlrev_b32_e32 v245, 4, v243
	v_lshrrev_b32_e32 v244, 5, v243
	v_lshlrev_b32_e32 v244, 5, v244
	v_xor_b32_e32 v245, v245, v244
	v_lshrrev_b32_e32 v244, 1, v242
	v_lshlrev_b32_e32 v244, 4, v244
	v_lshrrev_b32_e32 v243, 6, v245
	v_add_u32_e32 v244, v244, v243
	v_and_b32_e32 v245, 63, v245
	v_and_b32_e32 v242, 1, v242
	v_lshl_add_u32 v245, v242, 6, v245
	v_mul_u32_u24_e32 v244, 0x800, v244
	v_add_u32_e32 v240, v244, v245
	v_lshrrev_b32_e32 v242, 6, v1
	v_and_b32_e32 v243, 63, v1
	v_lshrrev_b32_e32 v244, 3, v243
	v_lshl_add_u32 v244, v242, 3, v244
	v_lshrrev_b32_e32 v245, 4, v243
	v_and_b32_e32 v245, 3, v245
	v_lshlrev_b32_e32 v245, 1, v245
	v_and_b32_e32 v243, 7, v243
	v_xor_b32_e32 v245, v243, v245
	v_lshlrev_b32_e32 v245, 4, v245
	v_mul_u32_u24_e32 v244, 0x800, v244
	v_add_u32_e32 v241, v244, v245
	v_sub_u32_e32 v130, v130, v240
	v_add_u32_e32 v130, v130, v241
	v_lshrrev_b32_e32 v242, 6, v1
	v_and_b32_e32 v243, 63, v1
	v_lshlrev_b32_e32 v245, 4, v243
	v_lshrrev_b32_e32 v244, 5, v243
	v_lshlrev_b32_e32 v244, 5, v244
	v_xor_b32_e32 v245, v245, v244
	v_add_u32_e32 v242, 8, v242
	v_lshrrev_b32_e32 v244, 1, v242
	v_lshlrev_b32_e32 v244, 4, v244
	v_lshrrev_b32_e32 v243, 6, v245
	v_add_u32_e32 v244, v244, v243
	v_and_b32_e32 v245, 63, v245
	v_and_b32_e32 v242, 1, v242
	v_lshl_add_u32 v245, v242, 6, v245
	v_mul_u32_u24_e32 v244, 0x800, v244
	v_add_u32_e32 v240, v244, v245
	v_lshrrev_b32_e32 v242, 6, v1
	v_and_b32_e32 v243, 63, v1
	v_lshrrev_b32_e32 v244, 3, v243
	v_lshl_add_u32 v244, v242, 3, v244
	v_add_u32_e32 v244, 64, v244
	v_lshrrev_b32_e32 v245, 4, v243
	v_and_b32_e32 v245, 3, v245
	v_lshlrev_b32_e32 v245, 1, v245
	v_and_b32_e32 v243, 7, v243
	v_xor_b32_e32 v245, v243, v245
	v_lshlrev_b32_e32 v245, 4, v245
	v_mul_u32_u24_e32 v244, 0x800, v244
	v_add_u32_e32 v241, v244, v245
	v_sub_u32_e32 v134, v134, v240
	v_add_u32_e32 v134, v134, v241
	v_lshrrev_b32_e32 v242, 6, v1
	v_and_b32_e32 v243, 63, v1
	v_lshlrev_b32_e32 v245, 4, v243
	v_lshrrev_b32_e32 v244, 5, v243
	v_lshlrev_b32_e32 v244, 5, v244
	v_xor_b32_e32 v245, v245, v244
	v_lshrrev_b32_e32 v244, 1, v242
	v_lshlrev_b32_e32 v244, 4, v244
	v_lshrrev_b32_e32 v243, 6, v245
	v_add_u32_e32 v244, v244, v243
	v_and_b32_e32 v245, 63, v245
	v_and_b32_e32 v242, 1, v242
	v_lshl_add_u32 v245, v242, 6, v245
	v_and_b32_e32 v242, 31, v244
	v_sub_u32_e32 v244, v244, v242
	v_and_b32_e32 v243, 3, v242
	v_add_u32_e32 v244, v244, v243
	v_lshrrev_b32_e32 v243, 4, v242
	v_lshl_add_u32 v244, v243, 2, v244
	v_and_b32_e32 v243, 15, v242
	v_lshrrev_b32_e32 v243, 2, v243
	v_lshl_add_u32 v244, v243, 3, v244
	v_mul_u32_u24_e32 v244, 0x800, v244
	v_add_u32_e32 v240, v244, v245
	v_lshrrev_b32_e32 v242, 6, v1
	v_and_b32_e32 v243, 63, v1
	v_lshrrev_b32_e32 v244, 3, v243
	v_lshl_add_u32 v244, v242, 3, v244
	v_lshrrev_b32_e32 v245, 4, v243
	v_and_b32_e32 v245, 3, v245
	v_lshlrev_b32_e32 v245, 1, v245
	v_and_b32_e32 v243, 7, v243
	v_xor_b32_e32 v245, v243, v245
	v_lshlrev_b32_e32 v245, 4, v245
	v_and_b32_e32 v242, 31, v244
	v_sub_u32_e32 v244, v244, v242
	v_and_b32_e32 v243, 3, v242
	v_add_u32_e32 v244, v244, v243
	v_lshrrev_b32_e32 v243, 4, v242
	v_lshl_add_u32 v244, v243, 2, v244
	v_and_b32_e32 v243, 15, v242
	v_lshrrev_b32_e32 v243, 2, v243
	v_lshl_add_u32 v244, v243, 3, v244
	v_mul_u32_u24_e32 v244, 0x800, v244
	v_add_u32_e32 v241, v244, v245
	v_sub_u32_e32 v132, v132, v240
	v_add_u32_e32 v132, v132, v241
	v_lshrrev_b32_e32 v242, 6, v1
	v_and_b32_e32 v243, 63, v1
	v_lshlrev_b32_e32 v245, 4, v243
	v_lshrrev_b32_e32 v244, 5, v243
	v_lshlrev_b32_e32 v244, 5, v244
	v_xor_b32_e32 v245, v245, v244
	v_add_u32_e32 v242, 8, v242
	v_lshrrev_b32_e32 v244, 1, v242
	v_lshlrev_b32_e32 v244, 4, v244
	v_lshrrev_b32_e32 v243, 6, v245
	v_add_u32_e32 v244, v244, v243
	v_and_b32_e32 v245, 63, v245
	v_and_b32_e32 v242, 1, v242
	v_lshl_add_u32 v245, v242, 6, v245
	v_and_b32_e32 v242, 31, v244
	v_sub_u32_e32 v244, v244, v242
	v_and_b32_e32 v243, 3, v242
	v_add_u32_e32 v244, v244, v243
	v_lshrrev_b32_e32 v243, 4, v242
	v_lshl_add_u32 v244, v243, 2, v244
	v_and_b32_e32 v243, 15, v242
	v_lshrrev_b32_e32 v243, 2, v243
	v_lshl_add_u32 v244, v243, 3, v244
	v_mul_u32_u24_e32 v244, 0x800, v244
	v_add_u32_e32 v240, v244, v245
	v_lshrrev_b32_e32 v242, 6, v1
	v_and_b32_e32 v243, 63, v1
	v_lshrrev_b32_e32 v244, 3, v243
	v_lshl_add_u32 v244, v242, 3, v244
	v_add_u32_e32 v244, 64, v244
	v_lshrrev_b32_e32 v245, 4, v243
	v_and_b32_e32 v245, 3, v245
	v_lshlrev_b32_e32 v245, 1, v245
	v_and_b32_e32 v243, 7, v243
	v_xor_b32_e32 v245, v243, v245
	v_lshlrev_b32_e32 v245, 4, v245
	v_and_b32_e32 v242, 31, v244
	v_sub_u32_e32 v244, v244, v242
	v_and_b32_e32 v243, 3, v242
	v_add_u32_e32 v244, v244, v243
	v_lshrrev_b32_e32 v243, 4, v242
	v_lshl_add_u32 v244, v243, 2, v244
	v_and_b32_e32 v243, 15, v242
	v_lshrrev_b32_e32 v243, 2, v243
	v_lshl_add_u32 v244, v243, 3, v244
	v_mul_u32_u24_e32 v244, 0x800, v244
	v_add_u32_e32 v241, v244, v245
	v_sub_u32_e32 v136, v136, v240
	v_add_u32_e32 v136, v136, v241
	global_load_lds_dwordx4 v132, s[10:11]
	s_add_i32 m0, s49, 0x12000
	s_ashr_i32 s5, s18, 8
	global_load_lds_dwordx4 v136, s[10:11]
	s_mov_b64 s[10:11], 0x40000
	v_lshl_add_u64 v[6:7], v[4:5], 0, s[10:11]
	s_add_i32 m0, s49, 0x14000
	v_readfirstlane_b32 s12, v6
	v_readfirstlane_b32 s13, v7
	v_lshl_add_u64 v[6:7], v[2:3], 0, s[10:11]
	v_mov_b32_e32 v139, 0
	v_mov_b32_e32 v133, v139
	v_mov_b32_e32 v137, v139
	v_mov_b32_e32 v131, v139
	global_load_lds_dwordx4 v132, s[12:13]
	s_add_i32 m0, s49, 0x16000
	v_mov_b32_e32 v135, v139
	global_load_lds_dwordx4 v136, s[12:13]
	v_readfirstlane_b32 s12, v2
	v_readfirstlane_b32 s13, v3
	s_mov_b32 m0, s49
	s_cmp_eq_u32 s5, 1
	s_mov_b32 s61, 0
	v_lshl_add_u64 v[12:13], v[4:5], 0, v[132:133]
	v_lshl_add_u64 v[10:11], v[4:5], 0, v[136:137]
	global_load_lds_dwordx4 v130, s[12:13]
	s_mov_b32 m0, s58
	v_lshl_add_u64 v[8:9], v[2:3], 0, v[134:135]
	global_load_lds_dwordx4 v134, s[12:13]
	v_readfirstlane_b32 s12, v6
	v_readfirstlane_b32 s13, v7
	s_mov_b32 m0, s59
	v_lshl_add_u64 v[6:7], v[2:3], 0, v[130:131]
	s_nop 2
	global_load_lds_dwordx4 v130, s[12:13]
	s_mov_b32 m0, s60
	s_nop 0
	global_load_lds_dwordx4 v134, s[12:13]
	s_cselect_b64 s[12:13], -1, 0
	s_cmp_lg_u32 s5, 1
	s_cbranch_scc1 .LBB0_492
	s_barrier
.LBB0_492:
	s_and_b32 s7, s4, 3
	s_lshl_b32 s62, s5, 6
	s_lshl_b32 s5, s5, 13
	s_lshl_b32 s63, s7, 5
	s_lshl_b32 s19, s7, 12
	s_add_u32 s64, s38, 0x119c2000
	s_mov_b64 s[14:15], 0x80
	s_addc_u32 s65, s39, 0
	s_add_i32 m0, s49, 0x18000
	v_lshl_add_u64 v[12:13], v[12:13], 0, s[14:15]
	s_waitcnt vmcnt(2)
	s_barrier
	global_load_lds_dwordx4 v[12:13], off
	v_lshl_add_u64 v[10:11], v[10:11], 0, s[14:15]
	s_add_i32 m0, s49, 0x1a000
	s_add_i32 s66, s49, 0x8000
	global_load_lds_dwordx4 v[10:11], off
	v_lshl_add_u64 v[6:7], v[6:7], 0, s[14:15]
	s_mov_b32 m0, s66
	s_add_i32 s67, s49, 0xa000
	global_load_lds_dwordx4 v[6:7], off
	v_lshl_add_u64 v[6:7], v[8:9], 0, s[14:15]
	s_mov_b32 m0, s67
	s_mov_b64 s[16:17], 0x40080
	global_load_lds_dwordx4 v[6:7], off
	v_lshl_add_u64 v[6:7], v[4:5], 0, s[16:17]
	s_add_i32 m0, s49, 0x1c000
	v_lshl_add_u64 v[8:9], v[6:7], 0, v[132:133]
	global_load_lds_dwordx4 v[8:9], off
	v_lshl_add_u64 v[6:7], v[6:7], 0, v[136:137]
	s_add_i32 m0, s49, 0x1e000
	v_and_b32_e32 v140, 15, v14
	global_load_lds_dwordx4 v[6:7], off
	v_bfe_u32 v6, v14, 4, 2
	v_lshlrev_b32_e32 v7, 4, v6
	v_lshlrev_b32_e32 v9, 2, v14
	v_lshl_or_b32 v8, v140, 6, v7
	v_and_b32_e32 v9, 32, v9
	s_cmpk_lt_u32 s18, 0x100
	v_bitop3_b32 v160, v8, s19, v9 bitop3:0xde
	s_cselect_b64 s[18:19], -1, 0
	s_lshl_b32 s4, s4, 6
	v_bitop3_b32 v10, v8, s5, v9 bitop3:0xde
	v_and_or_b32 v161, s4, 64, v7
	v_cmp_eq_u32_e64 s[4:5], 0, v6
	v_lshl_or_b32 v162, v6, 3, s63
	v_lshlrev_b32_e32 v6, 14, v18
	v_and_b32_e32 v6, 0xffff8000, v6
	v_lshl_add_u32 v6, v19, 11, v6
	v_and_b32_e32 v7, 1, v18
	v_lshl_or_b32 v6, v7, 6, v6
	v_lshl_add_u32 v142, v20, 1, v6
	v_lshlrev_b32_e32 v6, 14, v15
	v_and_b32_e32 v6, 0xffff8000, v6
	v_lshl_add_u32 v6, v16, 11, v6
	v_and_b32_e32 v7, 1, v15
	s_waitcnt vmcnt(6)
	s_lshl_b32 s7, s7, 2
	v_lshl_or_b32 v6, v7, 6, v6
	s_add_u32 s68, s64, s7
	v_lshl_add_u32 v144, v17, 1, v6
	s_mov_b32 s22, 0xfffc0080
	v_mbcnt_lo_u32_b32 v6, -1, 0
	s_addc_u32 s69, s65, 0
	v_mov_b32_e32 v143, v139
	v_mov_b32_e32 v145, v139
	s_movk_i32 s72, 0xa5
	s_add_i32 s73, 0, 0x20050
	s_add_i32 s74, 0, 0x20080
	s_add_i32 s75, 0, 0x200b0
	s_add_i32 s76, 0, 0x200e0
	s_mov_b64 s[20:21], 0x100
	s_mov_b32 s23, -1
	s_add_i32 s77, 0, 0x10000
	s_add_i32 s78, 0, 0x14000
	v_add_u32_e32 v163, 0, v10
	s_movk_i32 s79, 0x7fff
	s_mov_b32 s24, 0xbfb8aa3b
	v_mbcnt_hi_u32_b32 v164, -1, v6
	v_mov_b64_e32 v[150:151], v[4:5]
	v_mov_b64_e32 v[148:149], v[2:3]
	s_barrier
	v_lshrrev_b32_e32 v242, 6, v1
	v_and_b32_e32 v243, 63, v1
	v_lshlrev_b32_e32 v245, 4, v243
	v_lshrrev_b32_e32 v244, 5, v243
	v_lshlrev_b32_e32 v244, 5, v244
	v_xor_b32_e32 v245, v245, v244
	v_lshrrev_b32_e32 v244, 1, v242
	v_lshlrev_b32_e32 v244, 4, v244
	v_lshrrev_b32_e32 v243, 6, v245
	v_add_u32_e32 v244, v244, v243
	v_and_b32_e32 v245, 63, v245
	v_and_b32_e32 v242, 1, v242
	v_lshl_add_u32 v245, v242, 6, v245
	v_mul_u32_u24_e32 v244, 0x800, v244
	v_add_u32_e32 v240, v244, v245
	v_lshrrev_b32_e32 v242, 6, v1
	v_and_b32_e32 v243, 63, v1
	v_lshrrev_b32_e32 v244, 3, v243
	v_lshl_add_u32 v244, v242, 3, v244
	v_lshrrev_b32_e32 v245, 4, v243
	v_and_b32_e32 v245, 3, v245
	v_lshlrev_b32_e32 v245, 1, v245
	v_and_b32_e32 v243, 7, v243
	v_xor_b32_e32 v245, v243, v245
	v_lshlrev_b32_e32 v245, 4, v245
	v_mul_u32_u24_e32 v244, 0x800, v244
	v_add_u32_e32 v241, v244, v245
	v_sub_u32_e32 v144, v144, v240
	v_add_u32_e32 v144, v144, v241
	v_lshrrev_b32_e32 v242, 6, v1
	v_and_b32_e32 v243, 63, v1
	v_lshlrev_b32_e32 v245, 4, v243
	v_lshrrev_b32_e32 v244, 5, v243
	v_lshlrev_b32_e32 v244, 5, v244
	v_xor_b32_e32 v245, v245, v244
	v_add_u32_e32 v242, 8, v242
	v_lshrrev_b32_e32 v244, 1, v242
	v_lshlrev_b32_e32 v244, 4, v244
	v_lshrrev_b32_e32 v243, 6, v245
	v_add_u32_e32 v244, v244, v243
	v_and_b32_e32 v245, 63, v245
	v_and_b32_e32 v242, 1, v242
	v_lshl_add_u32 v245, v242, 6, v245
	v_mul_u32_u24_e32 v244, 0x800, v244
	v_add_u32_e32 v240, v244, v245
	v_lshrrev_b32_e32 v242, 6, v1
	v_and_b32_e32 v243, 63, v1
	v_lshrrev_b32_e32 v244, 3, v243
	v_lshl_add_u32 v244, v242, 3, v244
	v_add_u32_e32 v244, 64, v244
	v_lshrrev_b32_e32 v245, 4, v243
	v_and_b32_e32 v245, 3, v245
	v_lshlrev_b32_e32 v245, 1, v245
	v_and_b32_e32 v243, 7, v243
	v_xor_b32_e32 v245, v243, v245
	v_lshlrev_b32_e32 v245, 4, v245
	v_mul_u32_u24_e32 v244, 0x800, v244
	v_add_u32_e32 v241, v244, v245
	v_sub_u32_e32 v142, v142, v240
	v_add_u32_e32 v142, v142, v241
	v_and_b32_e32 v240, 63, v1
	v_and_b32_e32 v241, 15, v240
	v_lshrrev_b32_e32 v242, 4, v240
	v_lshlrev_b32_e32 v243, 6, v241
	v_lshl_add_u32 v243, v242, 4, v243
	v_lshrrev_b32_e32 v244, 3, v241
	v_lshlrev_b32_e32 v245, 5, v244
	v_xor_b32_e32 v243, v243, v245
	v_sub_u32_e32 v163, v163, v243
	v_lshlrev_b32_e32 v244, 10, v244
	v_and_b32_e32 v245, 7, v241
	v_lshl_add_u32 v244, v245, 7, v244
	v_add_u32_e32 v163, v163, v244
	v_lshrrev_b32_e32 v245, 1, v245
	v_lshlrev_b32_e32 v245, 1, v245
	v_add_u32_e32 v244, 4, v242
	v_xor_b32_e32 v244, v244, v245
	v_lshl_add_u32 v238, v244, 4, v163
	v_xor_b32_e32 v244, v242, v245
	v_lshl_add_u32 v163, v244, 4, v163
	v_and_b32_e32 v240, 63, v1
	v_and_b32_e32 v241, 15, v240
	v_lshrrev_b32_e32 v242, 4, v240
	v_lshlrev_b32_e32 v243, 6, v241
	v_lshl_add_u32 v243, v242, 4, v243
	v_lshrrev_b32_e32 v244, 3, v241
	v_lshlrev_b32_e32 v245, 5, v244
	v_xor_b32_e32 v243, v243, v245
	v_sub_u32_e32 v160, v160, v243
	v_lshlrev_b32_e32 v244, 10, v244
	v_and_b32_e32 v245, 7, v241
	v_lshl_add_u32 v244, v245, 7, v244
	v_add_u32_e32 v160, v160, v244
	v_lshrrev_b32_e32 v245, 1, v245
	v_lshlrev_b32_e32 v245, 1, v245
	v_add_u32_e32 v244, 4, v242
	v_xor_b32_e32 v244, v244, v245
	v_lshl_add_u32 v239, v244, 4, v160
	v_xor_b32_e32 v244, v242, v245
	v_lshl_add_u32 v160, v244, 4, v160
	s_branch .LBB0_495

.Lmy_nb_2:
	s_nop 0
	v_readfirstlane_b32 s86, v154
	v_readfirstlane_b32 s87, v155
	v_readfirstlane_b32 s88, v152
	v_readfirstlane_b32 s89, v153
	v_readfirstlane_b32 s90, v148
	v_readfirstlane_b32 s91, v149
	v_readfirstlane_b32 s92, v150
	v_readfirstlane_b32 s93, v151
	v_readfirstlane_b32 s100, v138
	v_readfirstlane_b32 s101, v141
	v_add_u32_e32 v230, s77, v160
	v_add_u32_e32 v234, s77, v239
	v_add_u32_e32 v231, s78, v160
	v_add_u32_e32 v235, s78, v239
	v_add_u32_e32 v232, 0x18000, v160
	v_add_u32_e32 v236, 0x18000, v239
	v_add_u32_e32 v233, 0x1c000, v160
	v_add_u32_e32 v237, 0x1c000, v239
	s_add_u32 s98, s86, 0xfffc0080
	s_addc_u32 s99, s87, -1
	s_cmp_eq_u32 s7, s100
	s_cselect_b64 s[94:95], s[90:91], s[98:99]
	s_cselect_b64 s[96:97], s[92:93], s[88:89]
	s_add_i32 s45, s7, 2
	s_add_i32 m0, s49, 0xc000
	ds_read_b128 v[156:159], v230
	global_load_lds_dwordx4 v144, s[86:87]
	s_add_i32 m0, s49, 0xe000
	ds_read_b128 v[166:169], v234
	global_load_lds_dwordx4 v142, s[86:87]
	ds_read_b128 v[170:173], v230 offset:2048
	ds_read_b128 v[174:177], v234 offset:2048
	ds_read_b128 v[178:181], v231
	ds_read_b128 v[182:185], v235
	ds_read_b128 v[186:189], v231 offset:2048
	ds_read_b128 v[190:193], v235 offset:2048
	ds_read_b128 v[194:197], v163
	ds_read_b128 v[198:201], v238
	ds_read_b128 v[202:205], v163 offset:2048
	ds_read_b128 v[206:209], v238 offset:2048
	ds_read_b128 v[210:213], v163 offset:4096
	ds_read_b128 v[214:217], v238 offset:4096
	ds_read_b128 v[218:221], v163 offset:6144
	ds_read_b128 v[222:225], v238 offset:6144
	s_waitcnt vmcnt(8)
	s_waitcnt lgkmcnt(0)
	s_setprio 1
	s_barrier
	v_mfma_f32_16x16x32_bf16 v[122:125], v[156:159], v[194:197], 0
	v_mfma_f32_16x16x32_bf16 v[118:121], v[170:173], v[194:197], 0
	v_mfma_f32_16x16x32_bf16 v[110:113], v[156:159], v[202:205], 0
	v_mfma_f32_16x16x32_bf16 v[102:105], v[170:173], v[202:205], 0
	v_mfma_f32_16x16x32_bf16 v[94:97], v[156:159], v[210:213], 0
	v_mfma_f32_16x16x32_bf16 v[86:89], v[170:173], v[210:213], 0
	v_mfma_f32_16x16x32_bf16 v[78:81], v[156:159], v[218:221], 0
	v_mfma_f32_16x16x32_bf16 v[70:73], v[170:173], v[218:221], 0
	v_mfma_f32_16x16x32_bf16 v[122:125], v[166:169], v[198:201], v[122:125]
	v_mfma_f32_16x16x32_bf16 v[118:121], v[174:177], v[198:201], v[118:121]
	v_mfma_f32_16x16x32_bf16 v[110:113], v[166:169], v[206:209], v[110:113]
	v_mfma_f32_16x16x32_bf16 v[102:105], v[174:177], v[206:209], v[102:105]
	v_mfma_f32_16x16x32_bf16 v[94:97], v[166:169], v[214:217], v[94:97]
	v_mfma_f32_16x16x32_bf16 v[86:89], v[174:177], v[214:217], v[86:89]
	v_mfma_f32_16x16x32_bf16 v[78:81], v[166:169], v[222:225], v[78:81]
	v_mfma_f32_16x16x32_bf16 v[70:73], v[174:177], v[222:225], v[70:73]
	v_mfma_f32_16x16x32_bf16 v[126:129], v[178:181], v[194:197], 0
	v_mfma_f32_16x16x32_bf16 v[114:117], v[186:189], v[194:197], 0
	v_mfma_f32_16x16x32_bf16 v[106:109], v[178:181], v[202:205], 0
	v_mfma_f32_16x16x32_bf16 v[98:101], v[186:189], v[202:205], 0
	v_mfma_f32_16x16x32_bf16 v[90:93], v[178:181], v[210:213], 0
	v_mfma_f32_16x16x32_bf16 v[82:85], v[186:189], v[210:213], 0
	v_mfma_f32_16x16x32_bf16 v[74:77], v[178:181], v[218:221], 0
	v_mfma_f32_16x16x32_bf16 v[66:69], v[186:189], v[218:221], 0
	v_mfma_f32_16x16x32_bf16 v[126:129], v[182:185], v[198:201], v[126:129]
	v_mfma_f32_16x16x32_bf16 v[114:117], v[190:193], v[198:201], v[114:117]
	v_mfma_f32_16x16x32_bf16 v[106:109], v[182:185], v[206:209], v[106:109]
	v_mfma_f32_16x16x32_bf16 v[98:101], v[190:193], v[206:209], v[98:101]
	v_mfma_f32_16x16x32_bf16 v[90:93], v[182:185], v[214:217], v[90:93]
	v_mfma_f32_16x16x32_bf16 v[82:85], v[190:193], v[214:217], v[82:85]
	v_mfma_f32_16x16x32_bf16 v[74:77], v[182:185], v[222:225], v[74:77]
	v_mfma_f32_16x16x32_bf16 v[66:69], v[190:193], v[222:225], v[66:69]
	s_barrier
	s_setprio 0
	s_add_u32 s98, s96, 0x40000
	s_addc_u32 s99, s97, 0
	s_add_i32 s7, s77, s25
	s_mov_b32 m0, s7
	ds_read_b128 v[194:197], v163 offset:16384
	global_load_lds_dwordx4 v132, s[96:97]
	s_add_i32 m0, s7, 0x2000
	s_add_i32 s7, s78, s25
	global_load_lds_dwordx4 v136, s[96:97]
	s_mov_b32 m0, s7
	ds_read_b128 v[198:201], v238 offset:16384
	global_load_lds_dwordx4 v132, s[98:99]
	s_add_i32 m0, s7, 0x2000
	ds_read_b128 v[202:205], v163 offset:18432
	global_load_lds_dwordx4 v136, s[98:99]
	s_mov_b32 m0, s49
	ds_read_b128 v[206:209], v238 offset:18432
	global_load_lds_dwordx4 v130, s[94:95]
	s_mov_b32 m0, s58
	ds_read_b128 v[210:213], v163 offset:20480
	global_load_lds_dwordx4 v134, s[94:95]
	ds_read_b128 v[214:217], v238 offset:20480
	ds_read_b128 v[218:221], v163 offset:22528
	ds_read_b128 v[222:225], v238 offset:22528
	s_waitcnt vmcnt(8)
	s_waitcnt lgkmcnt(0)
	s_setprio 1
	s_barrier
	v_mfma_f32_16x16x32_bf16 v[62:65], v[156:159], v[194:197], 0
	v_mfma_f32_16x16x32_bf16 v[54:57], v[170:173], v[194:197], 0
	v_mfma_f32_16x16x32_bf16 v[46:49], v[156:159], v[202:205], 0
	v_mfma_f32_16x16x32_bf16 v[38:41], v[170:173], v[202:205], 0
	v_mfma_f32_16x16x32_bf16 v[30:33], v[156:159], v[210:213], 0
	v_mfma_f32_16x16x32_bf16 v[22:25], v[170:173], v[210:213], 0
	v_mfma_f32_16x16x32_bf16 v[14:17], v[156:159], v[218:221], 0
	v_mfma_f32_16x16x32_bf16 v[6:9], v[170:173], v[218:221], 0
	v_mfma_f32_16x16x32_bf16 v[62:65], v[166:169], v[198:201], v[62:65]
	v_mfma_f32_16x16x32_bf16 v[54:57], v[174:177], v[198:201], v[54:57]
	v_mfma_f32_16x16x32_bf16 v[46:49], v[166:169], v[206:209], v[46:49]
	v_mfma_f32_16x16x32_bf16 v[38:41], v[174:177], v[206:209], v[38:41]
	v_mfma_f32_16x16x32_bf16 v[30:33], v[166:169], v[214:217], v[30:33]
	v_mfma_f32_16x16x32_bf16 v[22:25], v[174:177], v[214:217], v[22:25]
	v_mfma_f32_16x16x32_bf16 v[14:17], v[166:169], v[222:225], v[14:17]
	v_mfma_f32_16x16x32_bf16 v[6:9], v[174:177], v[222:225], v[6:9]
	v_mfma_f32_16x16x32_bf16 v[58:61], v[178:181], v[194:197], 0
	v_mfma_f32_16x16x32_bf16 v[50:53], v[186:189], v[194:197], 0
	v_mfma_f32_16x16x32_bf16 v[42:45], v[178:181], v[202:205], 0
	v_mfma_f32_16x16x32_bf16 v[34:37], v[186:189], v[202:205], 0
	v_mfma_f32_16x16x32_bf16 v[26:29], v[178:181], v[210:213], 0
	v_mfma_f32_16x16x32_bf16 v[18:21], v[186:189], v[210:213], 0
	v_mfma_f32_16x16x32_bf16 v[10:13], v[178:181], v[218:221], 0
	v_mfma_f32_16x16x32_bf16 v[2:5], v[186:189], v[218:221], 0
	v_mfma_f32_16x16x32_bf16 v[58:61], v[182:185], v[198:201], v[58:61]
	v_mfma_f32_16x16x32_bf16 v[50:53], v[190:193], v[198:201], v[50:53]
	v_mfma_f32_16x16x32_bf16 v[42:45], v[182:185], v[206:209], v[42:45]
	v_mfma_f32_16x16x32_bf16 v[34:37], v[190:193], v[206:209], v[34:37]
	v_mfma_f32_16x16x32_bf16 v[26:29], v[182:185], v[214:217], v[26:29]
	v_mfma_f32_16x16x32_bf16 v[18:21], v[190:193], v[214:217], v[18:21]
	v_mfma_f32_16x16x32_bf16 v[10:13], v[182:185], v[222:225], v[10:13]
	v_mfma_f32_16x16x32_bf16 v[2:5], v[190:193], v[222:225], v[2:5]
	s_barrier
	s_setprio 0
	s_add_u32 s98, s94, 0x40000
	s_addc_u32 s99, s95, 0
	s_add_i32 s7, 0, 0x18000
	s_add_i32 s47, 0, 0x1c000
	s_mov_b32 m0, s59
	ds_read_b128 v[156:159], v232
	global_load_lds_dwordx4 v130, s[98:99]
	s_mov_b32 m0, s60
	ds_read_b128 v[166:169], v236
	global_load_lds_dwordx4 v134, s[98:99]
	ds_read_b128 v[170:173], v232 offset:2048
	ds_read_b128 v[174:177], v236 offset:2048
	ds_read_b128 v[178:181], v233
	ds_read_b128 v[182:185], v237
	ds_read_b128 v[186:189], v233 offset:2048
	ds_read_b128 v[190:193], v237 offset:2048
	ds_read_b128 v[194:197], v163 offset:32768
	ds_read_b128 v[198:201], v238 offset:32768
	ds_read_b128 v[202:205], v163 offset:34816
	ds_read_b128 v[206:209], v238 offset:34816
	ds_read_b128 v[210:213], v163 offset:36864
	ds_read_b128 v[214:217], v238 offset:36864
	ds_read_b128 v[218:221], v163 offset:38912
	ds_read_b128 v[222:225], v238 offset:38912
	s_waitcnt vmcnt(8)
	s_waitcnt lgkmcnt(0)
	s_setprio 1
	s_barrier
	v_mfma_f32_16x16x32_bf16 v[122:125], v[156:159], v[194:197], v[122:125]
	v_mfma_f32_16x16x32_bf16 v[118:121], v[170:173], v[194:197], v[118:121]
	v_mfma_f32_16x16x32_bf16 v[110:113], v[156:159], v[202:205], v[110:113]
	v_mfma_f32_16x16x32_bf16 v[102:105], v[170:173], v[202:205], v[102:105]
	v_mfma_f32_16x16x32_bf16 v[94:97], v[156:159], v[210:213], v[94:97]
	v_mfma_f32_16x16x32_bf16 v[86:89], v[170:173], v[210:213], v[86:89]
	v_mfma_f32_16x16x32_bf16 v[78:81], v[156:159], v[218:221], v[78:81]
	v_mfma_f32_16x16x32_bf16 v[70:73], v[170:173], v[218:221], v[70:73]
	v_mfma_f32_16x16x32_bf16 v[122:125], v[166:169], v[198:201], v[122:125]
	v_mfma_f32_16x16x32_bf16 v[118:121], v[174:177], v[198:201], v[118:121]
	v_mfma_f32_16x16x32_bf16 v[110:113], v[166:169], v[206:209], v[110:113]
	v_mfma_f32_16x16x32_bf16 v[102:105], v[174:177], v[206:209], v[102:105]
	v_mfma_f32_16x16x32_bf16 v[94:97], v[166:169], v[214:217], v[94:97]
	v_mfma_f32_16x16x32_bf16 v[86:89], v[174:177], v[214:217], v[86:89]
	v_mfma_f32_16x16x32_bf16 v[78:81], v[166:169], v[222:225], v[78:81]
	v_mfma_f32_16x16x32_bf16 v[70:73], v[174:177], v[222:225], v[70:73]
	v_mfma_f32_16x16x32_bf16 v[126:129], v[178:181], v[194:197], v[126:129]
	v_mfma_f32_16x16x32_bf16 v[114:117], v[186:189], v[194:197], v[114:117]
	v_mfma_f32_16x16x32_bf16 v[106:109], v[178:181], v[202:205], v[106:109]
	v_mfma_f32_16x16x32_bf16 v[98:101], v[186:189], v[202:205], v[98:101]
	v_mfma_f32_16x16x32_bf16 v[90:93], v[178:181], v[210:213], v[90:93]
	v_mfma_f32_16x16x32_bf16 v[82:85], v[186:189], v[210:213], v[82:85]
	v_mfma_f32_16x16x32_bf16 v[74:77], v[178:181], v[218:221], v[74:77]
	v_mfma_f32_16x16x32_bf16 v[66:69], v[186:189], v[218:221], v[66:69]
	v_mfma_f32_16x16x32_bf16 v[126:129], v[182:185], v[198:201], v[126:129]
	v_mfma_f32_16x16x32_bf16 v[114:117], v[190:193], v[198:201], v[114:117]
	v_mfma_f32_16x16x32_bf16 v[106:109], v[182:185], v[206:209], v[106:109]
	v_mfma_f32_16x16x32_bf16 v[98:101], v[190:193], v[206:209], v[98:101]
	v_mfma_f32_16x16x32_bf16 v[90:93], v[182:185], v[214:217], v[90:93]
	v_mfma_f32_16x16x32_bf16 v[82:85], v[190:193], v[214:217], v[82:85]
	v_mfma_f32_16x16x32_bf16 v[74:77], v[182:185], v[222:225], v[74:77]
	v_mfma_f32_16x16x32_bf16 v[66:69], v[190:193], v[222:225], v[66:69]
	s_barrier
	s_setprio 0
	s_add_u32 s96, s96, 0x80
	s_addc_u32 s97, s97, 0
	s_add_u32 s98, s96, 0x40000
	s_addc_u32 s99, s97, 0
	s_add_u32 s94, s94, 0x80
	s_addc_u32 s95, s95, 0
	s_add_i32 s7, s7, s25
	s_mov_b32 m0, s7
	ds_read_b128 v[194:197], v163 offset:49152
	global_load_lds_dwordx4 v132, s[96:97]
	s_add_i32 m0, s7, 0x2000
	s_add_i32 s7, s47, s25
	global_load_lds_dwordx4 v136, s[96:97]
	s_mov_b32 m0, s7
	ds_read_b128 v[198:201], v238 offset:49152
	global_load_lds_dwordx4 v132, s[98:99]
	s_add_i32 m0, s7, 0x2000
	ds_read_b128 v[202:205], v163 offset:51200
	global_load_lds_dwordx4 v136, s[98:99]
	s_mov_b32 m0, s66
	ds_read_b128 v[206:209], v238 offset:51200
	global_load_lds_dwordx4 v130, s[94:95]
	s_mov_b32 m0, s67
	ds_read_b128 v[210:213], v163 offset:53248
	global_load_lds_dwordx4 v134, s[94:95]
	ds_read_b128 v[214:217], v238 offset:53248
	ds_read_b128 v[218:221], v163 offset:55296
	ds_read_b128 v[222:225], v238 offset:55296
	s_waitcnt vmcnt(8)
	s_waitcnt lgkmcnt(0)
	s_setprio 1
	s_barrier
	v_mfma_f32_16x16x32_bf16 v[62:65], v[156:159], v[194:197], v[62:65]
	v_mfma_f32_16x16x32_bf16 v[54:57], v[170:173], v[194:197], v[54:57]
	v_mfma_f32_16x16x32_bf16 v[46:49], v[156:159], v[202:205], v[46:49]
	v_mfma_f32_16x16x32_bf16 v[38:41], v[170:173], v[202:205], v[38:41]
	v_mfma_f32_16x16x32_bf16 v[30:33], v[156:159], v[210:213], v[30:33]
	v_mfma_f32_16x16x32_bf16 v[22:25], v[170:173], v[210:213], v[22:25]
	v_mfma_f32_16x16x32_bf16 v[14:17], v[156:159], v[218:221], v[14:17]
	v_mfma_f32_16x16x32_bf16 v[6:9], v[170:173], v[218:221], v[6:9]
	v_mfma_f32_16x16x32_bf16 v[62:65], v[166:169], v[198:201], v[62:65]
	v_mfma_f32_16x16x32_bf16 v[54:57], v[174:177], v[198:201], v[54:57]
	v_mfma_f32_16x16x32_bf16 v[46:49], v[166:169], v[206:209], v[46:49]
	v_mfma_f32_16x16x32_bf16 v[38:41], v[174:177], v[206:209], v[38:41]
	v_mfma_f32_16x16x32_bf16 v[30:33], v[166:169], v[214:217], v[30:33]
	v_mfma_f32_16x16x32_bf16 v[22:25], v[174:177], v[214:217], v[22:25]
	v_mfma_f32_16x16x32_bf16 v[14:17], v[166:169], v[222:225], v[14:17]
	v_mfma_f32_16x16x32_bf16 v[6:9], v[174:177], v[222:225], v[6:9]
	v_mfma_f32_16x16x32_bf16 v[58:61], v[178:181], v[194:197], v[58:61]
	v_mfma_f32_16x16x32_bf16 v[50:53], v[186:189], v[194:197], v[50:53]
	v_mfma_f32_16x16x32_bf16 v[42:45], v[178:181], v[202:205], v[42:45]
	v_mfma_f32_16x16x32_bf16 v[34:37], v[186:189], v[202:205], v[34:37]
	v_mfma_f32_16x16x32_bf16 v[26:29], v[178:181], v[210:213], v[26:29]
	v_mfma_f32_16x16x32_bf16 v[18:21], v[186:189], v[210:213], v[18:21]
	v_mfma_f32_16x16x32_bf16 v[10:13], v[178:181], v[218:221], v[10:13]
	v_mfma_f32_16x16x32_bf16 v[2:5], v[186:189], v[218:221], v[2:5]
	v_mfma_f32_16x16x32_bf16 v[58:61], v[182:185], v[198:201], v[58:61]
	v_mfma_f32_16x16x32_bf16 v[50:53], v[190:193], v[198:201], v[50:53]
	v_mfma_f32_16x16x32_bf16 v[42:45], v[182:185], v[206:209], v[42:45]
	v_mfma_f32_16x16x32_bf16 v[34:37], v[190:193], v[206:209], v[34:37]
	v_mfma_f32_16x16x32_bf16 v[26:29], v[182:185], v[214:217], v[26:29]
	v_mfma_f32_16x16x32_bf16 v[18:21], v[190:193], v[214:217], v[18:21]
	v_mfma_f32_16x16x32_bf16 v[10:13], v[182:185], v[222:225], v[10:13]
	v_mfma_f32_16x16x32_bf16 v[2:5], v[190:193], v[222:225], v[2:5]
	s_barrier
	s_setprio 0
	s_mov_b32 s7, s45
	s_add_u32 s88, s88, 0x100
	s_addc_u32 s89, s89, 0
	s_add_u32 s86, s86, 0x100
	s_addc_u32 s87, s87, 0
	s_cmp_ge_i32 s45, s101
	s_cbranch_scc1 .Lmy_kexit_2
.LBB0_499:
	s_add_u32 s98, s86, 0xfffc0080
	s_addc_u32 s99, s87, -1
	s_cmp_eq_u32 s7, s100
	s_cselect_b64 s[94:95], s[90:91], s[98:99]
	s_cselect_b64 s[96:97], s[92:93], s[88:89]
	s_add_i32 s45, s7, 2
	s_add_i32 m0, s49, 0xc000
	ds_read_b128 v[156:159], v230
	global_load_lds_dwordx4 v144, s[86:87]
	s_add_i32 m0, s49, 0xe000
	ds_read_b128 v[166:169], v234
	global_load_lds_dwordx4 v142, s[86:87]
	ds_read_b128 v[170:173], v230 offset:2048
	ds_read_b128 v[174:177], v234 offset:2048
	ds_read_b128 v[178:181], v231
	ds_read_b128 v[182:185], v235
	ds_read_b128 v[186:189], v231 offset:2048
	ds_read_b128 v[190:193], v235 offset:2048
	ds_read_b128 v[194:197], v163
	ds_read_b128 v[198:201], v238
	ds_read_b128 v[202:205], v163 offset:2048
	ds_read_b128 v[206:209], v238 offset:2048
	ds_read_b128 v[210:213], v163 offset:4096
	ds_read_b128 v[214:217], v238 offset:4096
	ds_read_b128 v[218:221], v163 offset:6144
	ds_read_b128 v[222:225], v238 offset:6144
	s_waitcnt vmcnt(8)
	s_waitcnt lgkmcnt(0)
	s_setprio 1
	s_barrier
	v_mfma_f32_16x16x32_bf16 v[122:125], v[156:159], v[194:197], v[122:125]
	v_mfma_f32_16x16x32_bf16 v[118:121], v[170:173], v[194:197], v[118:121]
	v_mfma_f32_16x16x32_bf16 v[110:113], v[156:159], v[202:205], v[110:113]
	v_mfma_f32_16x16x32_bf16 v[102:105], v[170:173], v[202:205], v[102:105]
	v_mfma_f32_16x16x32_bf16 v[94:97], v[156:159], v[210:213], v[94:97]
	v_mfma_f32_16x16x32_bf16 v[86:89], v[170:173], v[210:213], v[86:89]
	v_mfma_f32_16x16x32_bf16 v[78:81], v[156:159], v[218:221], v[78:81]
	v_mfma_f32_16x16x32_bf16 v[70:73], v[170:173], v[218:221], v[70:73]
	v_mfma_f32_16x16x32_bf16 v[122:125], v[166:169], v[198:201], v[122:125]
	v_mfma_f32_16x16x32_bf16 v[118:121], v[174:177], v[198:201], v[118:121]
	v_mfma_f32_16x16x32_bf16 v[110:113], v[166:169], v[206:209], v[110:113]
	v_mfma_f32_16x16x32_bf16 v[102:105], v[174:177], v[206:209], v[102:105]
	v_mfma_f32_16x16x32_bf16 v[94:97], v[166:169], v[214:217], v[94:97]
	v_mfma_f32_16x16x32_bf16 v[86:89], v[174:177], v[214:217], v[86:89]
	v_mfma_f32_16x16x32_bf16 v[78:81], v[166:169], v[222:225], v[78:81]
	v_mfma_f32_16x16x32_bf16 v[70:73], v[174:177], v[222:225], v[70:73]
	v_mfma_f32_16x16x32_bf16 v[126:129], v[178:181], v[194:197], v[126:129]
	v_mfma_f32_16x16x32_bf16 v[114:117], v[186:189], v[194:197], v[114:117]
	v_mfma_f32_16x16x32_bf16 v[106:109], v[178:181], v[202:205], v[106:109]
	v_mfma_f32_16x16x32_bf16 v[98:101], v[186:189], v[202:205], v[98:101]
	v_mfma_f32_16x16x32_bf16 v[90:93], v[178:181], v[210:213], v[90:93]
	v_mfma_f32_16x16x32_bf16 v[82:85], v[186:189], v[210:213], v[82:85]
	v_mfma_f32_16x16x32_bf16 v[74:77], v[178:181], v[218:221], v[74:77]
	v_mfma_f32_16x16x32_bf16 v[66:69], v[186:189], v[218:221], v[66:69]
	v_mfma_f32_16x16x32_bf16 v[126:129], v[182:185], v[198:201], v[126:129]
	v_mfma_f32_16x16x32_bf16 v[114:117], v[190:193], v[198:201], v[114:117]
	v_mfma_f32_16x16x32_bf16 v[106:109], v[182:185], v[206:209], v[106:109]
	v_mfma_f32_16x16x32_bf16 v[98:101], v[190:193], v[206:209], v[98:101]
	v_mfma_f32_16x16x32_bf16 v[90:93], v[182:185], v[214:217], v[90:93]
	v_mfma_f32_16x16x32_bf16 v[82:85], v[190:193], v[214:217], v[82:85]
	v_mfma_f32_16x16x32_bf16 v[74:77], v[182:185], v[222:225], v[74:77]
	v_mfma_f32_16x16x32_bf16 v[66:69], v[190:193], v[222:225], v[66:69]
	s_barrier
	s_setprio 0
	s_add_u32 s98, s96, 0x40000
	s_addc_u32 s99, s97, 0
	s_add_i32 s7, s77, s25
	s_mov_b32 m0, s7
	ds_read_b128 v[194:197], v163 offset:16384
	global_load_lds_dwordx4 v132, s[96:97]
	s_add_i32 m0, s7, 0x2000
	s_add_i32 s7, s78, s25
	global_load_lds_dwordx4 v136, s[96:97]
	s_mov_b32 m0, s7
	ds_read_b128 v[198:201], v238 offset:16384
	global_load_lds_dwordx4 v132, s[98:99]
	s_add_i32 m0, s7, 0x2000
	ds_read_b128 v[202:205], v163 offset:18432
	global_load_lds_dwordx4 v136, s[98:99]
	s_mov_b32 m0, s49
	ds_read_b128 v[206:209], v238 offset:18432
	global_load_lds_dwordx4 v130, s[94:95]
	s_mov_b32 m0, s58
	ds_read_b128 v[210:213], v163 offset:20480
	global_load_lds_dwordx4 v134, s[94:95]
	ds_read_b128 v[214:217], v238 offset:20480
	ds_read_b128 v[218:221], v163 offset:22528
	ds_read_b128 v[222:225], v238 offset:22528
	s_waitcnt vmcnt(8)
	s_waitcnt lgkmcnt(0)
	s_setprio 1
	s_barrier
	v_mfma_f32_16x16x32_bf16 v[62:65], v[156:159], v[194:197], v[62:65]
	v_mfma_f32_16x16x32_bf16 v[54:57], v[170:173], v[194:197], v[54:57]
	v_mfma_f32_16x16x32_bf16 v[46:49], v[156:159], v[202:205], v[46:49]
	v_mfma_f32_16x16x32_bf16 v[38:41], v[170:173], v[202:205], v[38:41]
	v_mfma_f32_16x16x32_bf16 v[30:33], v[156:159], v[210:213], v[30:33]
	v_mfma_f32_16x16x32_bf16 v[22:25], v[170:173], v[210:213], v[22:25]
	v_mfma_f32_16x16x32_bf16 v[14:17], v[156:159], v[218:221], v[14:17]
	v_mfma_f32_16x16x32_bf16 v[6:9], v[170:173], v[218:221], v[6:9]
	v_mfma_f32_16x16x32_bf16 v[62:65], v[166:169], v[198:201], v[62:65]
	v_mfma_f32_16x16x32_bf16 v[54:57], v[174:177], v[198:201], v[54:57]
	v_mfma_f32_16x16x32_bf16 v[46:49], v[166:169], v[206:209], v[46:49]
	v_mfma_f32_16x16x32_bf16 v[38:41], v[174:177], v[206:209], v[38:41]
	v_mfma_f32_16x16x32_bf16 v[30:33], v[166:169], v[214:217], v[30:33]
	v_mfma_f32_16x16x32_bf16 v[22:25], v[174:177], v[214:217], v[22:25]
	v_mfma_f32_16x16x32_bf16 v[14:17], v[166:169], v[222:225], v[14:17]
	v_mfma_f32_16x16x32_bf16 v[6:9], v[174:177], v[222:225], v[6:9]
	v_mfma_f32_16x16x32_bf16 v[58:61], v[178:181], v[194:197], v[58:61]
	v_mfma_f32_16x16x32_bf16 v[50:53], v[186:189], v[194:197], v[50:53]
	v_mfma_f32_16x16x32_bf16 v[42:45], v[178:181], v[202:205], v[42:45]
	v_mfma_f32_16x16x32_bf16 v[34:37], v[186:189], v[202:205], v[34:37]
	v_mfma_f32_16x16x32_bf16 v[26:29], v[178:181], v[210:213], v[26:29]
	v_mfma_f32_16x16x32_bf16 v[18:21], v[186:189], v[210:213], v[18:21]
	v_mfma_f32_16x16x32_bf16 v[10:13], v[178:181], v[218:221], v[10:13]
	v_mfma_f32_16x16x32_bf16 v[2:5], v[186:189], v[218:221], v[2:5]
	v_mfma_f32_16x16x32_bf16 v[58:61], v[182:185], v[198:201], v[58:61]
	v_mfma_f32_16x16x32_bf16 v[50:53], v[190:193], v[198:201], v[50:53]
	v_mfma_f32_16x16x32_bf16 v[42:45], v[182:185], v[206:209], v[42:45]
	v_mfma_f32_16x16x32_bf16 v[34:37], v[190:193], v[206:209], v[34:37]
	v_mfma_f32_16x16x32_bf16 v[26:29], v[182:185], v[214:217], v[26:29]
	v_mfma_f32_16x16x32_bf16 v[18:21], v[190:193], v[214:217], v[18:21]
	v_mfma_f32_16x16x32_bf16 v[10:13], v[182:185], v[222:225], v[10:13]
	v_mfma_f32_16x16x32_bf16 v[2:5], v[190:193], v[222:225], v[2:5]
	s_barrier
	s_setprio 0
	s_add_u32 s98, s94, 0x40000
	s_addc_u32 s99, s95, 0
	s_add_i32 s7, 0, 0x18000
	s_add_i32 s47, 0, 0x1c000
	s_mov_b32 m0, s59
	ds_read_b128 v[156:159], v232
	global_load_lds_dwordx4 v130, s[98:99]
	s_mov_b32 m0, s60
	ds_read_b128 v[166:169], v236
	global_load_lds_dwordx4 v134, s[98:99]
	ds_read_b128 v[170:173], v232 offset:2048
	ds_read_b128 v[174:177], v236 offset:2048
	ds_read_b128 v[178:181], v233
	ds_read_b128 v[182:185], v237
	ds_read_b128 v[186:189], v233 offset:2048
	ds_read_b128 v[190:193], v237 offset:2048
	ds_read_b128 v[194:197], v163 offset:32768
	ds_read_b128 v[198:201], v238 offset:32768
	ds_read_b128 v[202:205], v163 offset:34816
	ds_read_b128 v[206:209], v238 offset:34816
	ds_read_b128 v[210:213], v163 offset:36864
	ds_read_b128 v[214:217], v238 offset:36864
	ds_read_b128 v[218:221], v163 offset:38912
	ds_read_b128 v[222:225], v238 offset:38912
	s_waitcnt vmcnt(8)
	s_waitcnt lgkmcnt(0)
	s_setprio 1
	s_barrier
	v_mfma_f32_16x16x32_bf16 v[122:125], v[156:159], v[194:197], v[122:125]
	v_mfma_f32_16x16x32_bf16 v[118:121], v[170:173], v[194:197], v[118:121]
	v_mfma_f32_16x16x32_bf16 v[110:113], v[156:159], v[202:205], v[110:113]
	v_mfma_f32_16x16x32_bf16 v[102:105], v[170:173], v[202:205], v[102:105]
	v_mfma_f32_16x16x32_bf16 v[94:97], v[156:159], v[210:213], v[94:97]
	v_mfma_f32_16x16x32_bf16 v[86:89], v[170:173], v[210:213], v[86:89]
	v_mfma_f32_16x16x32_bf16 v[78:81], v[156:159], v[218:221], v[78:81]
	v_mfma_f32_16x16x32_bf16 v[70:73], v[170:173], v[218:221], v[70:73]
	v_mfma_f32_16x16x32_bf16 v[122:125], v[166:169], v[198:201], v[122:125]
	v_mfma_f32_16x16x32_bf16 v[118:121], v[174:177], v[198:201], v[118:121]
	v_mfma_f32_16x16x32_bf16 v[110:113], v[166:169], v[206:209], v[110:113]
	v_mfma_f32_16x16x32_bf16 v[102:105], v[174:177], v[206:209], v[102:105]
	v_mfma_f32_16x16x32_bf16 v[94:97], v[166:169], v[214:217], v[94:97]
	v_mfma_f32_16x16x32_bf16 v[86:89], v[174:177], v[214:217], v[86:89]
	v_mfma_f32_16x16x32_bf16 v[78:81], v[166:169], v[222:225], v[78:81]
	v_mfma_f32_16x16x32_bf16 v[70:73], v[174:177], v[222:225], v[70:73]
	v_mfma_f32_16x16x32_bf16 v[126:129], v[178:181], v[194:197], v[126:129]
	v_mfma_f32_16x16x32_bf16 v[114:117], v[186:189], v[194:197], v[114:117]
	v_mfma_f32_16x16x32_bf16 v[106:109], v[178:181], v[202:205], v[106:109]
	v_mfma_f32_16x16x32_bf16 v[98:101], v[186:189], v[202:205], v[98:101]
	v_mfma_f32_16x16x32_bf16 v[90:93], v[178:181], v[210:213], v[90:93]
	v_mfma_f32_16x16x32_bf16 v[82:85], v[186:189], v[210:213], v[82:85]
	v_mfma_f32_16x16x32_bf16 v[74:77], v[178:181], v[218:221], v[74:77]
	v_mfma_f32_16x16x32_bf16 v[66:69], v[186:189], v[218:221], v[66:69]
	v_mfma_f32_16x16x32_bf16 v[126:129], v[182:185], v[198:201], v[126:129]
	v_mfma_f32_16x16x32_bf16 v[114:117], v[190:193], v[198:201], v[114:117]
	v_mfma_f32_16x16x32_bf16 v[106:109], v[182:185], v[206:209], v[106:109]
	v_mfma_f32_16x16x32_bf16 v[98:101], v[190:193], v[206:209], v[98:101]
	v_mfma_f32_16x16x32_bf16 v[90:93], v[182:185], v[214:217], v[90:93]
	v_mfma_f32_16x16x32_bf16 v[82:85], v[190:193], v[214:217], v[82:85]
	v_mfma_f32_16x16x32_bf16 v[74:77], v[182:185], v[222:225], v[74:77]
	v_mfma_f32_16x16x32_bf16 v[66:69], v[190:193], v[222:225], v[66:69]
	s_barrier
	s_setprio 0
	s_add_u32 s96, s96, 0x80
	s_addc_u32 s97, s97, 0
	s_add_u32 s98, s96, 0x40000
	s_addc_u32 s99, s97, 0
	s_add_u32 s94, s94, 0x80
	s_addc_u32 s95, s95, 0
	s_add_i32 s7, s7, s25
	s_mov_b32 m0, s7
	ds_read_b128 v[194:197], v163 offset:49152
	global_load_lds_dwordx4 v132, s[96:97]
	s_add_i32 m0, s7, 0x2000
	s_add_i32 s7, s47, s25
	global_load_lds_dwordx4 v136, s[96:97]
	s_mov_b32 m0, s7
	ds_read_b128 v[198:201], v238 offset:49152
	global_load_lds_dwordx4 v132, s[98:99]
	s_add_i32 m0, s7, 0x2000
	ds_read_b128 v[202:205], v163 offset:51200
	global_load_lds_dwordx4 v136, s[98:99]
	s_mov_b32 m0, s66
	ds_read_b128 v[206:209], v238 offset:51200
	global_load_lds_dwordx4 v130, s[94:95]
	s_mov_b32 m0, s67
	ds_read_b128 v[210:213], v163 offset:53248
	global_load_lds_dwordx4 v134, s[94:95]
	ds_read_b128 v[214:217], v238 offset:53248
	ds_read_b128 v[218:221], v163 offset:55296
	ds_read_b128 v[222:225], v238 offset:55296
	s_waitcnt vmcnt(8)
	s_waitcnt lgkmcnt(0)
	s_setprio 1
	s_barrier
	v_mfma_f32_16x16x32_bf16 v[62:65], v[156:159], v[194:197], v[62:65]
	v_mfma_f32_16x16x32_bf16 v[54:57], v[170:173], v[194:197], v[54:57]
	v_mfma_f32_16x16x32_bf16 v[46:49], v[156:159], v[202:205], v[46:49]
	v_mfma_f32_16x16x32_bf16 v[38:41], v[170:173], v[202:205], v[38:41]
	v_mfma_f32_16x16x32_bf16 v[30:33], v[156:159], v[210:213], v[30:33]
	v_mfma_f32_16x16x32_bf16 v[22:25], v[170:173], v[210:213], v[22:25]
	v_mfma_f32_16x16x32_bf16 v[14:17], v[156:159], v[218:221], v[14:17]
	v_mfma_f32_16x16x32_bf16 v[6:9], v[170:173], v[218:221], v[6:9]
	v_mfma_f32_16x16x32_bf16 v[62:65], v[166:169], v[198:201], v[62:65]
	v_mfma_f32_16x16x32_bf16 v[54:57], v[174:177], v[198:201], v[54:57]
	v_mfma_f32_16x16x32_bf16 v[46:49], v[166:169], v[206:209], v[46:49]
	v_mfma_f32_16x16x32_bf16 v[38:41], v[174:177], v[206:209], v[38:41]
	v_mfma_f32_16x16x32_bf16 v[30:33], v[166:169], v[214:217], v[30:33]
	v_mfma_f32_16x16x32_bf16 v[22:25], v[174:177], v[214:217], v[22:25]
	v_mfma_f32_16x16x32_bf16 v[14:17], v[166:169], v[222:225], v[14:17]
	v_mfma_f32_16x16x32_bf16 v[6:9], v[174:177], v[222:225], v[6:9]
	v_mfma_f32_16x16x32_bf16 v[58:61], v[178:181], v[194:197], v[58:61]
	v_mfma_f32_16x16x32_bf16 v[50:53], v[186:189], v[194:197], v[50:53]
	v_mfma_f32_16x16x32_bf16 v[42:45], v[178:181], v[202:205], v[42:45]
	v_mfma_f32_16x16x32_bf16 v[34:37], v[186:189], v[202:205], v[34:37]
	v_mfma_f32_16x16x32_bf16 v[26:29], v[178:181], v[210:213], v[26:29]
	v_mfma_f32_16x16x32_bf16 v[18:21], v[186:189], v[210:213], v[18:21]
	v_mfma_f32_16x16x32_bf16 v[10:13], v[178:181], v[218:221], v[10:13]
	v_mfma_f32_16x16x32_bf16 v[2:5], v[186:189], v[218:221], v[2:5]
	v_mfma_f32_16x16x32_bf16 v[58:61], v[182:185], v[198:201], v[58:61]
	v_mfma_f32_16x16x32_bf16 v[50:53], v[190:193], v[198:201], v[50:53]
	v_mfma_f32_16x16x32_bf16 v[42:45], v[182:185], v[206:209], v[42:45]
	v_mfma_f32_16x16x32_bf16 v[34:37], v[190:193], v[206:209], v[34:37]
	v_mfma_f32_16x16x32_bf16 v[26:29], v[182:185], v[214:217], v[26:29]
	v_mfma_f32_16x16x32_bf16 v[18:21], v[190:193], v[214:217], v[18:21]
	v_mfma_f32_16x16x32_bf16 v[10:13], v[182:185], v[222:225], v[10:13]
	v_mfma_f32_16x16x32_bf16 v[2:5], v[190:193], v[222:225], v[2:5]
	s_barrier
	s_setprio 0
	s_mov_b32 s7, s45
	s_add_u32 s88, s88, 0x100
	s_addc_u32 s89, s89, 0
	s_add_u32 s86, s86, 0x100
	s_addc_u32 s87, s87, 0
	s_cmp_ge_i32 s45, s101
	s_cbranch_scc0 .LBB0_499

.LBB0_757:
	s_and_b32 s7, s4, 3
	s_lshl_b32 s62, s5, 6
	s_lshl_b32 s5, s5, 13
	s_lshl_b32 s63, s7, 5
	s_lshl_b32 s19, s7, 12
	s_add_u32 s64, s38, 0x51a2000
	s_mov_b64 s[14:15], 0x80
	s_addc_u32 s65, s39, 0
	s_add_i32 m0, s49, 0x18000
	v_lshl_add_u64 v[12:13], v[12:13], 0, s[14:15]
	s_waitcnt vmcnt(2)
	s_barrier
	global_load_lds_dwordx4 v[12:13], off
	v_lshl_add_u64 v[10:11], v[10:11], 0, s[14:15]
	s_add_i32 m0, s49, 0x1a000
	s_add_i32 s66, s49, 0x8000
	global_load_lds_dwordx4 v[10:11], off
	v_lshl_add_u64 v[6:7], v[6:7], 0, s[14:15]
	s_mov_b32 m0, s66
	s_add_i32 s67, s49, 0xa000
	global_load_lds_dwordx4 v[6:7], off
	v_lshl_add_u64 v[6:7], v[8:9], 0, s[14:15]
	s_mov_b32 m0, s67
	s_mov_b64 s[16:17], 0x40080
	global_load_lds_dwordx4 v[6:7], off
	v_lshl_add_u64 v[6:7], v[4:5], 0, s[16:17]
	s_add_i32 m0, s49, 0x1c000
	v_lshl_add_u64 v[8:9], v[6:7], 0, v[132:133]
	global_load_lds_dwordx4 v[8:9], off
	v_lshl_add_u64 v[6:7], v[6:7], 0, v[136:137]
	s_add_i32 m0, s49, 0x1e000
	v_and_b32_e32 v140, 15, v14
	global_load_lds_dwordx4 v[6:7], off
	v_bfe_u32 v6, v14, 4, 2
	v_lshlrev_b32_e32 v7, 4, v6
	v_lshlrev_b32_e32 v9, 2, v14
	v_lshl_or_b32 v8, v140, 6, v7
	v_and_b32_e32 v9, 32, v9
	s_cmpk_lt_u32 s18, 0x100
	v_bitop3_b32 v141, v8, s19, v9 bitop3:0xde
	s_cselect_b64 s[18:19], -1, 0
	s_lshl_b32 s4, s4, 6
	v_bitop3_b32 v10, v8, s5, v9 bitop3:0xde
	v_and_or_b32 v158, s4, 64, v7
	v_cmp_eq_u32_e64 s[4:5], 0, v6
	v_lshl_or_b32 v159, v6, 3, s63
	v_lshlrev_b32_e32 v6, 14, v18
	v_and_b32_e32 v6, 0xffff8000, v6
	v_lshl_add_u32 v6, v19, 11, v6
	v_and_b32_e32 v7, 1, v18
	v_lshl_or_b32 v6, v7, 6, v6
	v_lshl_add_u32 v142, v20, 1, v6
	v_lshlrev_b32_e32 v6, 14, v15
	v_and_b32_e32 v6, 0xffff8000, v6
	v_lshl_add_u32 v6, v16, 11, v6
	v_and_b32_e32 v7, 1, v15
	s_waitcnt vmcnt(6)
	s_lshl_b32 s7, s7, 2
	v_lshl_or_b32 v6, v7, 6, v6
	s_add_u32 s68, s64, s7
	v_lshl_add_u32 v144, v17, 1, v6
	s_mov_b32 s22, 0xfffc0080
	v_mbcnt_lo_u32_b32 v6, -1, 0
	s_addc_u32 s69, s65, 0
	v_mov_b32_e32 v143, v139
	v_mov_b32_e32 v145, v139
	s_add_i32 s72, 0, 0x20020
	s_add_i32 s73, 0, 0x20018
	s_add_i32 s74, 0, 0x2002c
	s_add_i32 s75, 0, 0x20000
	s_mov_b64 s[20:21], 0x100
	s_mov_b32 s23, -1
	s_add_i32 s76, 0, 0x10000
	s_add_i32 s77, 0, 0x14000
	v_add_u32_e32 v160, 0, v10
	s_add_i32 s78, 0, 0x20010
	s_add_i32 s79, 0, 0x20024
	s_movk_i32 s80, 0x7fff
	s_mov_b32 s24, 0xbfb8aa3b
	v_mbcnt_hi_u32_b32 v161, -1, v6
	v_mov_b64_e32 v[146:147], v[2:3]
	v_mov_b64_e32 v[148:149], v[4:5]
	s_barrier
	v_lshrrev_b32_e32 v242, 6, v1
	v_and_b32_e32 v243, 63, v1
	v_lshlrev_b32_e32 v245, 4, v243
	v_lshrrev_b32_e32 v244, 5, v243
	v_lshlrev_b32_e32 v244, 5, v244
	v_xor_b32_e32 v245, v245, v244
	v_lshrrev_b32_e32 v244, 1, v242
	v_lshlrev_b32_e32 v244, 4, v244
	v_lshrrev_b32_e32 v243, 6, v245
	v_add_u32_e32 v244, v244, v243
	v_and_b32_e32 v245, 63, v245
	v_and_b32_e32 v242, 1, v242
	v_lshl_add_u32 v245, v242, 6, v245
	v_mul_u32_u24_e32 v244, 0x800, v244
	v_add_u32_e32 v240, v244, v245
	v_lshrrev_b32_e32 v242, 6, v1
	v_and_b32_e32 v243, 63, v1
	v_lshrrev_b32_e32 v244, 3, v243
	v_lshl_add_u32 v244, v242, 3, v244
	v_lshrrev_b32_e32 v245, 4, v243
	v_and_b32_e32 v245, 3, v245
	v_lshlrev_b32_e32 v245, 1, v245
	v_and_b32_e32 v243, 7, v243
	v_xor_b32_e32 v245, v243, v245
	v_lshlrev_b32_e32 v245, 4, v245
	v_mul_u32_u24_e32 v244, 0x800, v244
	v_add_u32_e32 v241, v244, v245
	v_sub_u32_e32 v144, v144, v240
	v_add_u32_e32 v144, v144, v241
	v_lshrrev_b32_e32 v242, 6, v1
	v_and_b32_e32 v243, 63, v1
	v_lshlrev_b32_e32 v245, 4, v243
	v_lshrrev_b32_e32 v244, 5, v243
	v_lshlrev_b32_e32 v244, 5, v244
	v_xor_b32_e32 v245, v245, v244
	v_add_u32_e32 v242, 8, v242
	v_lshrrev_b32_e32 v244, 1, v242
	v_lshlrev_b32_e32 v244, 4, v244
	v_lshrrev_b32_e32 v243, 6, v245
	v_add_u32_e32 v244, v244, v243
	v_and_b32_e32 v245, 63, v245
	v_and_b32_e32 v242, 1, v242
	v_lshl_add_u32 v245, v242, 6, v245
	v_mul_u32_u24_e32 v244, 0x800, v244
	v_add_u32_e32 v240, v244, v245
	v_lshrrev_b32_e32 v242, 6, v1
	v_and_b32_e32 v243, 63, v1
	v_lshrrev_b32_e32 v244, 3, v243
	v_lshl_add_u32 v244, v242, 3, v244
	v_add_u32_e32 v244, 64, v244
	v_lshrrev_b32_e32 v245, 4, v243
	v_and_b32_e32 v245, 3, v245
	v_lshlrev_b32_e32 v245, 1, v245
	v_and_b32_e32 v243, 7, v243
	v_xor_b32_e32 v245, v243, v245
	v_lshlrev_b32_e32 v245, 4, v245
	v_mul_u32_u24_e32 v244, 0x800, v244
	v_add_u32_e32 v241, v244, v245
	v_sub_u32_e32 v142, v142, v240
	v_add_u32_e32 v142, v142, v241
	v_and_b32_e32 v240, 63, v1
	v_and_b32_e32 v241, 15, v240
	v_lshrrev_b32_e32 v242, 4, v240
	v_lshlrev_b32_e32 v243, 6, v241
	v_lshl_add_u32 v243, v242, 4, v243
	v_lshrrev_b32_e32 v244, 3, v241
	v_lshlrev_b32_e32 v245, 5, v244
	v_xor_b32_e32 v243, v243, v245
	v_sub_u32_e32 v160, v160, v243
	v_lshlrev_b32_e32 v244, 10, v244
	v_and_b32_e32 v245, 7, v241
	v_lshl_add_u32 v244, v245, 7, v244
	v_add_u32_e32 v160, v160, v244
	v_lshrrev_b32_e32 v245, 1, v245
	v_lshlrev_b32_e32 v245, 1, v245
	v_add_u32_e32 v244, 4, v242
	v_xor_b32_e32 v244, v244, v245
	v_lshl_add_u32 v238, v244, 4, v160
	v_xor_b32_e32 v244, v242, v245
	v_lshl_add_u32 v160, v244, 4, v160
	v_and_b32_e32 v240, 63, v1
	v_and_b32_e32 v241, 15, v240
	v_lshrrev_b32_e32 v242, 4, v240
	v_lshlrev_b32_e32 v243, 6, v241
	v_lshl_add_u32 v243, v242, 4, v243
	v_lshrrev_b32_e32 v244, 3, v241
	v_lshlrev_b32_e32 v245, 5, v244
	v_xor_b32_e32 v243, v243, v245
	v_sub_u32_e32 v141, v141, v243
	v_lshlrev_b32_e32 v244, 10, v244
	v_and_b32_e32 v245, 7, v241
	v_lshl_add_u32 v244, v245, 7, v244
	v_add_u32_e32 v141, v141, v244
	v_lshrrev_b32_e32 v245, 1, v245
	v_lshlrev_b32_e32 v245, 1, v245
	v_add_u32_e32 v244, 4, v242
	v_xor_b32_e32 v244, v244, v245
	v_lshl_add_u32 v239, v244, 4, v141
	v_xor_b32_e32 v244, v242, v245
	v_lshl_add_u32 v141, v244, 4, v141
	s_branch .LBB0_760

.Lmy_nb_3:
	s_nop 0
	v_readfirstlane_b32 s86, v152
	v_readfirstlane_b32 s87, v153
	v_readfirstlane_b32 s88, v150
	v_readfirstlane_b32 s89, v151
	v_readfirstlane_b32 s90, v146
	v_readfirstlane_b32 s91, v147
	v_readfirstlane_b32 s92, v148
	v_readfirstlane_b32 s93, v149
	v_readfirstlane_b32 s100, v154
	v_readfirstlane_b32 s101, v138
	v_add_u32_e32 v230, s76, v141
	v_add_u32_e32 v234, s76, v239
	v_add_u32_e32 v231, s77, v141
	v_add_u32_e32 v235, s77, v239
	v_add_u32_e32 v232, 0x18000, v141
	v_add_u32_e32 v236, 0x18000, v239
	v_add_u32_e32 v233, 0x1c000, v141
	v_add_u32_e32 v237, 0x1c000, v239
	s_add_u32 s98, s86, 0xfffc0080
	s_addc_u32 s99, s87, -1
	s_cmp_eq_u32 s7, s100
	s_cselect_b64 s[94:95], s[90:91], s[98:99]
	s_cselect_b64 s[96:97], s[92:93], s[88:89]
	s_add_i32 s45, s7, 2
	s_add_i32 m0, s49, 0xc000
	ds_read_b128 v[164:167], v230
	global_load_lds_dwordx4 v144, s[86:87]
	s_add_i32 m0, s49, 0xe000
	ds_read_b128 v[168:171], v234
	global_load_lds_dwordx4 v142, s[86:87]
	ds_read_b128 v[172:175], v230 offset:2048
	ds_read_b128 v[176:179], v234 offset:2048
	ds_read_b128 v[180:183], v231
	ds_read_b128 v[184:187], v235
	ds_read_b128 v[188:191], v231 offset:2048
	ds_read_b128 v[192:195], v235 offset:2048
	ds_read_b128 v[196:199], v160
	ds_read_b128 v[200:203], v238
	ds_read_b128 v[204:207], v160 offset:2048
	ds_read_b128 v[208:211], v238 offset:2048
	ds_read_b128 v[212:215], v160 offset:4096
	ds_read_b128 v[216:219], v238 offset:4096
	ds_read_b128 v[220:223], v160 offset:6144
	ds_read_b128 v[224:227], v238 offset:6144
	s_waitcnt vmcnt(8)
	s_waitcnt lgkmcnt(0)
	s_setprio 1
	s_barrier
	v_mfma_f32_16x16x32_bf16 v[122:125], v[164:167], v[196:199], 0
	v_mfma_f32_16x16x32_bf16 v[118:121], v[172:175], v[196:199], 0
	v_mfma_f32_16x16x32_bf16 v[110:113], v[164:167], v[204:207], 0
	v_mfma_f32_16x16x32_bf16 v[102:105], v[172:175], v[204:207], 0
	v_mfma_f32_16x16x32_bf16 v[94:97], v[164:167], v[212:215], 0
	v_mfma_f32_16x16x32_bf16 v[86:89], v[172:175], v[212:215], 0
	v_mfma_f32_16x16x32_bf16 v[78:81], v[164:167], v[220:223], 0
	v_mfma_f32_16x16x32_bf16 v[70:73], v[172:175], v[220:223], 0
	v_mfma_f32_16x16x32_bf16 v[122:125], v[168:171], v[200:203], v[122:125]
	v_mfma_f32_16x16x32_bf16 v[118:121], v[176:179], v[200:203], v[118:121]
	v_mfma_f32_16x16x32_bf16 v[110:113], v[168:171], v[208:211], v[110:113]
	v_mfma_f32_16x16x32_bf16 v[102:105], v[176:179], v[208:211], v[102:105]
	v_mfma_f32_16x16x32_bf16 v[94:97], v[168:171], v[216:219], v[94:97]
	v_mfma_f32_16x16x32_bf16 v[86:89], v[176:179], v[216:219], v[86:89]
	v_mfma_f32_16x16x32_bf16 v[78:81], v[168:171], v[224:227], v[78:81]
	v_mfma_f32_16x16x32_bf16 v[70:73], v[176:179], v[224:227], v[70:73]
	v_mfma_f32_16x16x32_bf16 v[126:129], v[180:183], v[196:199], 0
	v_mfma_f32_16x16x32_bf16 v[114:117], v[188:191], v[196:199], 0
	v_mfma_f32_16x16x32_bf16 v[106:109], v[180:183], v[204:207], 0
	v_mfma_f32_16x16x32_bf16 v[98:101], v[188:191], v[204:207], 0
	v_mfma_f32_16x16x32_bf16 v[90:93], v[180:183], v[212:215], 0
	v_mfma_f32_16x16x32_bf16 v[82:85], v[188:191], v[212:215], 0
	v_mfma_f32_16x16x32_bf16 v[74:77], v[180:183], v[220:223], 0
	v_mfma_f32_16x16x32_bf16 v[66:69], v[188:191], v[220:223], 0
	v_mfma_f32_16x16x32_bf16 v[126:129], v[184:187], v[200:203], v[126:129]
	v_mfma_f32_16x16x32_bf16 v[114:117], v[192:195], v[200:203], v[114:117]
	v_mfma_f32_16x16x32_bf16 v[106:109], v[184:187], v[208:211], v[106:109]
	v_mfma_f32_16x16x32_bf16 v[98:101], v[192:195], v[208:211], v[98:101]
	v_mfma_f32_16x16x32_bf16 v[90:93], v[184:187], v[216:219], v[90:93]
	v_mfma_f32_16x16x32_bf16 v[82:85], v[192:195], v[216:219], v[82:85]
	v_mfma_f32_16x16x32_bf16 v[74:77], v[184:187], v[224:227], v[74:77]
	v_mfma_f32_16x16x32_bf16 v[66:69], v[192:195], v[224:227], v[66:69]
	s_barrier
	s_setprio 0
	s_add_u32 s98, s96, 0x40000
	s_addc_u32 s99, s97, 0
	s_add_i32 s7, s76, s25
	s_mov_b32 m0, s7
	ds_read_b128 v[196:199], v160 offset:16384
	global_load_lds_dwordx4 v132, s[96:97]
	s_add_i32 m0, s7, 0x2000
	s_add_i32 s7, s77, s25
	global_load_lds_dwordx4 v136, s[96:97]
	s_mov_b32 m0, s7
	ds_read_b128 v[200:203], v238 offset:16384
	global_load_lds_dwordx4 v132, s[98:99]
	s_add_i32 m0, s7, 0x2000
	ds_read_b128 v[204:207], v160 offset:18432
	global_load_lds_dwordx4 v136, s[98:99]
	s_mov_b32 m0, s49
	ds_read_b128 v[208:211], v238 offset:18432
	global_load_lds_dwordx4 v130, s[94:95]
	s_mov_b32 m0, s58
	ds_read_b128 v[212:215], v160 offset:20480
	global_load_lds_dwordx4 v134, s[94:95]
	ds_read_b128 v[216:219], v238 offset:20480
	ds_read_b128 v[220:223], v160 offset:22528
	ds_read_b128 v[224:227], v238 offset:22528
	s_waitcnt vmcnt(8)
	s_waitcnt lgkmcnt(0)
	s_setprio 1
	s_barrier
	v_mfma_f32_16x16x32_bf16 v[62:65], v[164:167], v[196:199], 0
	v_mfma_f32_16x16x32_bf16 v[54:57], v[172:175], v[196:199], 0
	v_mfma_f32_16x16x32_bf16 v[46:49], v[164:167], v[204:207], 0
	v_mfma_f32_16x16x32_bf16 v[38:41], v[172:175], v[204:207], 0
	v_mfma_f32_16x16x32_bf16 v[30:33], v[164:167], v[212:215], 0
	v_mfma_f32_16x16x32_bf16 v[22:25], v[172:175], v[212:215], 0
	v_mfma_f32_16x16x32_bf16 v[14:17], v[164:167], v[220:223], 0
	v_mfma_f32_16x16x32_bf16 v[6:9], v[172:175], v[220:223], 0
	v_mfma_f32_16x16x32_bf16 v[62:65], v[168:171], v[200:203], v[62:65]
	v_mfma_f32_16x16x32_bf16 v[54:57], v[176:179], v[200:203], v[54:57]
	v_mfma_f32_16x16x32_bf16 v[46:49], v[168:171], v[208:211], v[46:49]
	v_mfma_f32_16x16x32_bf16 v[38:41], v[176:179], v[208:211], v[38:41]
	v_mfma_f32_16x16x32_bf16 v[30:33], v[168:171], v[216:219], v[30:33]
	v_mfma_f32_16x16x32_bf16 v[22:25], v[176:179], v[216:219], v[22:25]
	v_mfma_f32_16x16x32_bf16 v[14:17], v[168:171], v[224:227], v[14:17]
	v_mfma_f32_16x16x32_bf16 v[6:9], v[176:179], v[224:227], v[6:9]
	v_mfma_f32_16x16x32_bf16 v[58:61], v[180:183], v[196:199], 0
	v_mfma_f32_16x16x32_bf16 v[50:53], v[188:191], v[196:199], 0
	v_mfma_f32_16x16x32_bf16 v[42:45], v[180:183], v[204:207], 0
	v_mfma_f32_16x16x32_bf16 v[34:37], v[188:191], v[204:207], 0
	v_mfma_f32_16x16x32_bf16 v[26:29], v[180:183], v[212:215], 0
	v_mfma_f32_16x16x32_bf16 v[18:21], v[188:191], v[212:215], 0
	v_mfma_f32_16x16x32_bf16 v[10:13], v[180:183], v[220:223], 0
	v_mfma_f32_16x16x32_bf16 v[2:5], v[188:191], v[220:223], 0
	v_mfma_f32_16x16x32_bf16 v[58:61], v[184:187], v[200:203], v[58:61]
	v_mfma_f32_16x16x32_bf16 v[50:53], v[192:195], v[200:203], v[50:53]
	v_mfma_f32_16x16x32_bf16 v[42:45], v[184:187], v[208:211], v[42:45]
	v_mfma_f32_16x16x32_bf16 v[34:37], v[192:195], v[208:211], v[34:37]
	v_mfma_f32_16x16x32_bf16 v[26:29], v[184:187], v[216:219], v[26:29]
	v_mfma_f32_16x16x32_bf16 v[18:21], v[192:195], v[216:219], v[18:21]
	v_mfma_f32_16x16x32_bf16 v[10:13], v[184:187], v[224:227], v[10:13]
	v_mfma_f32_16x16x32_bf16 v[2:5], v[192:195], v[224:227], v[2:5]
	s_barrier
	s_setprio 0
	s_add_u32 s98, s94, 0x40000
	s_addc_u32 s99, s95, 0
	s_add_i32 s7, 0, 0x18000
	s_add_i32 s47, 0, 0x1c000
	s_mov_b32 m0, s59
	ds_read_b128 v[164:167], v232
	global_load_lds_dwordx4 v130, s[98:99]
	s_mov_b32 m0, s60
	ds_read_b128 v[168:171], v236
	global_load_lds_dwordx4 v134, s[98:99]
	ds_read_b128 v[172:175], v232 offset:2048
	ds_read_b128 v[176:179], v236 offset:2048
	ds_read_b128 v[180:183], v233
	ds_read_b128 v[184:187], v237
	ds_read_b128 v[188:191], v233 offset:2048
	ds_read_b128 v[192:195], v237 offset:2048
	ds_read_b128 v[196:199], v160 offset:32768
	ds_read_b128 v[200:203], v238 offset:32768
	ds_read_b128 v[204:207], v160 offset:34816
	ds_read_b128 v[208:211], v238 offset:34816
	ds_read_b128 v[212:215], v160 offset:36864
	ds_read_b128 v[216:219], v238 offset:36864
	ds_read_b128 v[220:223], v160 offset:38912
	ds_read_b128 v[224:227], v238 offset:38912
	s_waitcnt vmcnt(8)
	s_waitcnt lgkmcnt(0)
	s_setprio 1
	s_barrier
	v_mfma_f32_16x16x32_bf16 v[122:125], v[164:167], v[196:199], v[122:125]
	v_mfma_f32_16x16x32_bf16 v[118:121], v[172:175], v[196:199], v[118:121]
	v_mfma_f32_16x16x32_bf16 v[110:113], v[164:167], v[204:207], v[110:113]
	v_mfma_f32_16x16x32_bf16 v[102:105], v[172:175], v[204:207], v[102:105]
	v_mfma_f32_16x16x32_bf16 v[94:97], v[164:167], v[212:215], v[94:97]
	v_mfma_f32_16x16x32_bf16 v[86:89], v[172:175], v[212:215], v[86:89]
	v_mfma_f32_16x16x32_bf16 v[78:81], v[164:167], v[220:223], v[78:81]
	v_mfma_f32_16x16x32_bf16 v[70:73], v[172:175], v[220:223], v[70:73]
	v_mfma_f32_16x16x32_bf16 v[122:125], v[168:171], v[200:203], v[122:125]
	v_mfma_f32_16x16x32_bf16 v[118:121], v[176:179], v[200:203], v[118:121]
	v_mfma_f32_16x16x32_bf16 v[110:113], v[168:171], v[208:211], v[110:113]
	v_mfma_f32_16x16x32_bf16 v[102:105], v[176:179], v[208:211], v[102:105]
	v_mfma_f32_16x16x32_bf16 v[94:97], v[168:171], v[216:219], v[94:97]
	v_mfma_f32_16x16x32_bf16 v[86:89], v[176:179], v[216:219], v[86:89]
	v_mfma_f32_16x16x32_bf16 v[78:81], v[168:171], v[224:227], v[78:81]
	v_mfma_f32_16x16x32_bf16 v[70:73], v[176:179], v[224:227], v[70:73]
	v_mfma_f32_16x16x32_bf16 v[126:129], v[180:183], v[196:199], v[126:129]
	v_mfma_f32_16x16x32_bf16 v[114:117], v[188:191], v[196:199], v[114:117]
	v_mfma_f32_16x16x32_bf16 v[106:109], v[180:183], v[204:207], v[106:109]
	v_mfma_f32_16x16x32_bf16 v[98:101], v[188:191], v[204:207], v[98:101]
	v_mfma_f32_16x16x32_bf16 v[90:93], v[180:183], v[212:215], v[90:93]
	v_mfma_f32_16x16x32_bf16 v[82:85], v[188:191], v[212:215], v[82:85]
	v_mfma_f32_16x16x32_bf16 v[74:77], v[180:183], v[220:223], v[74:77]
	v_mfma_f32_16x16x32_bf16 v[66:69], v[188:191], v[220:223], v[66:69]
	v_mfma_f32_16x16x32_bf16 v[126:129], v[184:187], v[200:203], v[126:129]
	v_mfma_f32_16x16x32_bf16 v[114:117], v[192:195], v[200:203], v[114:117]
	v_mfma_f32_16x16x32_bf16 v[106:109], v[184:187], v[208:211], v[106:109]
	v_mfma_f32_16x16x32_bf16 v[98:101], v[192:195], v[208:211], v[98:101]
	v_mfma_f32_16x16x32_bf16 v[90:93], v[184:187], v[216:219], v[90:93]
	v_mfma_f32_16x16x32_bf16 v[82:85], v[192:195], v[216:219], v[82:85]
	v_mfma_f32_16x16x32_bf16 v[74:77], v[184:187], v[224:227], v[74:77]
	v_mfma_f32_16x16x32_bf16 v[66:69], v[192:195], v[224:227], v[66:69]
	s_barrier
	s_setprio 0
	s_add_u32 s96, s96, 0x80
	s_addc_u32 s97, s97, 0
	s_add_u32 s98, s96, 0x40000
	s_addc_u32 s99, s97, 0
	s_add_u32 s94, s94, 0x80
	s_addc_u32 s95, s95, 0
	s_add_i32 s7, s7, s25
	s_mov_b32 m0, s7
	ds_read_b128 v[196:199], v160 offset:49152
	global_load_lds_dwordx4 v132, s[96:97]
	s_add_i32 m0, s7, 0x2000
	s_add_i32 s7, s47, s25
	global_load_lds_dwordx4 v136, s[96:97]
	s_mov_b32 m0, s7
	ds_read_b128 v[200:203], v238 offset:49152
	global_load_lds_dwordx4 v132, s[98:99]
	s_add_i32 m0, s7, 0x2000
	ds_read_b128 v[204:207], v160 offset:51200
	global_load_lds_dwordx4 v136, s[98:99]
	s_mov_b32 m0, s66
	ds_read_b128 v[208:211], v238 offset:51200
	global_load_lds_dwordx4 v130, s[94:95]
	s_mov_b32 m0, s67
	ds_read_b128 v[212:215], v160 offset:53248
	global_load_lds_dwordx4 v134, s[94:95]
	ds_read_b128 v[216:219], v238 offset:53248
	ds_read_b128 v[220:223], v160 offset:55296
	ds_read_b128 v[224:227], v238 offset:55296
	s_waitcnt vmcnt(8)
	s_waitcnt lgkmcnt(0)
	s_setprio 1
	s_barrier
	v_mfma_f32_16x16x32_bf16 v[62:65], v[164:167], v[196:199], v[62:65]
	v_mfma_f32_16x16x32_bf16 v[54:57], v[172:175], v[196:199], v[54:57]
	v_mfma_f32_16x16x32_bf16 v[46:49], v[164:167], v[204:207], v[46:49]
	v_mfma_f32_16x16x32_bf16 v[38:41], v[172:175], v[204:207], v[38:41]
	v_mfma_f32_16x16x32_bf16 v[30:33], v[164:167], v[212:215], v[30:33]
	v_mfma_f32_16x16x32_bf16 v[22:25], v[172:175], v[212:215], v[22:25]
	v_mfma_f32_16x16x32_bf16 v[14:17], v[164:167], v[220:223], v[14:17]
	v_mfma_f32_16x16x32_bf16 v[6:9], v[172:175], v[220:223], v[6:9]
	v_mfma_f32_16x16x32_bf16 v[62:65], v[168:171], v[200:203], v[62:65]
	v_mfma_f32_16x16x32_bf16 v[54:57], v[176:179], v[200:203], v[54:57]
	v_mfma_f32_16x16x32_bf16 v[46:49], v[168:171], v[208:211], v[46:49]
	v_mfma_f32_16x16x32_bf16 v[38:41], v[176:179], v[208:211], v[38:41]
	v_mfma_f32_16x16x32_bf16 v[30:33], v[168:171], v[216:219], v[30:33]
	v_mfma_f32_16x16x32_bf16 v[22:25], v[176:179], v[216:219], v[22:25]
	v_mfma_f32_16x16x32_bf16 v[14:17], v[168:171], v[224:227], v[14:17]
	v_mfma_f32_16x16x32_bf16 v[6:9], v[176:179], v[224:227], v[6:9]
	v_mfma_f32_16x16x32_bf16 v[58:61], v[180:183], v[196:199], v[58:61]
	v_mfma_f32_16x16x32_bf16 v[50:53], v[188:191], v[196:199], v[50:53]
	v_mfma_f32_16x16x32_bf16 v[42:45], v[180:183], v[204:207], v[42:45]
	v_mfma_f32_16x16x32_bf16 v[34:37], v[188:191], v[204:207], v[34:37]
	v_mfma_f32_16x16x32_bf16 v[26:29], v[180:183], v[212:215], v[26:29]
	v_mfma_f32_16x16x32_bf16 v[18:21], v[188:191], v[212:215], v[18:21]
	v_mfma_f32_16x16x32_bf16 v[10:13], v[180:183], v[220:223], v[10:13]
	v_mfma_f32_16x16x32_bf16 v[2:5], v[188:191], v[220:223], v[2:5]
	v_mfma_f32_16x16x32_bf16 v[58:61], v[184:187], v[200:203], v[58:61]
	v_mfma_f32_16x16x32_bf16 v[50:53], v[192:195], v[200:203], v[50:53]
	v_mfma_f32_16x16x32_bf16 v[42:45], v[184:187], v[208:211], v[42:45]
	v_mfma_f32_16x16x32_bf16 v[34:37], v[192:195], v[208:211], v[34:37]
	v_mfma_f32_16x16x32_bf16 v[26:29], v[184:187], v[216:219], v[26:29]
	v_mfma_f32_16x16x32_bf16 v[18:21], v[192:195], v[216:219], v[18:21]
	v_mfma_f32_16x16x32_bf16 v[10:13], v[184:187], v[224:227], v[10:13]
	v_mfma_f32_16x16x32_bf16 v[2:5], v[192:195], v[224:227], v[2:5]
	s_barrier
	s_setprio 0
	s_mov_b32 s7, s45
	s_add_u32 s88, s88, 0x100
	s_addc_u32 s89, s89, 0
	s_add_u32 s86, s86, 0x100
	s_addc_u32 s87, s87, 0
	s_cmp_ge_i32 s45, s101
	s_cbranch_scc1 .Lmy_kexit_3
.LBB0_768:
	s_add_u32 s98, s86, 0xfffc0080
	s_addc_u32 s99, s87, -1
	s_cmp_eq_u32 s7, s100
	s_cselect_b64 s[94:95], s[90:91], s[98:99]
	s_cselect_b64 s[96:97], s[92:93], s[88:89]
	s_add_i32 s45, s7, 2
	s_add_i32 m0, s49, 0xc000
	ds_read_b128 v[164:167], v230
	global_load_lds_dwordx4 v144, s[86:87]
	s_add_i32 m0, s49, 0xe000
	ds_read_b128 v[168:171], v234
	global_load_lds_dwordx4 v142, s[86:87]
	ds_read_b128 v[172:175], v230 offset:2048
	ds_read_b128 v[176:179], v234 offset:2048
	ds_read_b128 v[180:183], v231
	ds_read_b128 v[184:187], v235
	ds_read_b128 v[188:191], v231 offset:2048
	ds_read_b128 v[192:195], v235 offset:2048
	ds_read_b128 v[196:199], v160
	ds_read_b128 v[200:203], v238
	ds_read_b128 v[204:207], v160 offset:2048
	ds_read_b128 v[208:211], v238 offset:2048
	ds_read_b128 v[212:215], v160 offset:4096
	ds_read_b128 v[216:219], v238 offset:4096
	ds_read_b128 v[220:223], v160 offset:6144
	ds_read_b128 v[224:227], v238 offset:6144
	s_waitcnt vmcnt(8)
	s_waitcnt lgkmcnt(0)
	s_setprio 1
	s_barrier
	v_mfma_f32_16x16x32_bf16 v[122:125], v[164:167], v[196:199], v[122:125]
	v_mfma_f32_16x16x32_bf16 v[118:121], v[172:175], v[196:199], v[118:121]
	v_mfma_f32_16x16x32_bf16 v[110:113], v[164:167], v[204:207], v[110:113]
	v_mfma_f32_16x16x32_bf16 v[102:105], v[172:175], v[204:207], v[102:105]
	v_mfma_f32_16x16x32_bf16 v[94:97], v[164:167], v[212:215], v[94:97]
	v_mfma_f32_16x16x32_bf16 v[86:89], v[172:175], v[212:215], v[86:89]
	v_mfma_f32_16x16x32_bf16 v[78:81], v[164:167], v[220:223], v[78:81]
	v_mfma_f32_16x16x32_bf16 v[70:73], v[172:175], v[220:223], v[70:73]
	v_mfma_f32_16x16x32_bf16 v[122:125], v[168:171], v[200:203], v[122:125]
	v_mfma_f32_16x16x32_bf16 v[118:121], v[176:179], v[200:203], v[118:121]
	v_mfma_f32_16x16x32_bf16 v[110:113], v[168:171], v[208:211], v[110:113]
	v_mfma_f32_16x16x32_bf16 v[102:105], v[176:179], v[208:211], v[102:105]
	v_mfma_f32_16x16x32_bf16 v[94:97], v[168:171], v[216:219], v[94:97]
	v_mfma_f32_16x16x32_bf16 v[86:89], v[176:179], v[216:219], v[86:89]
	v_mfma_f32_16x16x32_bf16 v[78:81], v[168:171], v[224:227], v[78:81]
	v_mfma_f32_16x16x32_bf16 v[70:73], v[176:179], v[224:227], v[70:73]
	v_mfma_f32_16x16x32_bf16 v[126:129], v[180:183], v[196:199], v[126:129]
	v_mfma_f32_16x16x32_bf16 v[114:117], v[188:191], v[196:199], v[114:117]
	v_mfma_f32_16x16x32_bf16 v[106:109], v[180:183], v[204:207], v[106:109]
	v_mfma_f32_16x16x32_bf16 v[98:101], v[188:191], v[204:207], v[98:101]
	v_mfma_f32_16x16x32_bf16 v[90:93], v[180:183], v[212:215], v[90:93]
	v_mfma_f32_16x16x32_bf16 v[82:85], v[188:191], v[212:215], v[82:85]
	v_mfma_f32_16x16x32_bf16 v[74:77], v[180:183], v[220:223], v[74:77]
	v_mfma_f32_16x16x32_bf16 v[66:69], v[188:191], v[220:223], v[66:69]
	v_mfma_f32_16x16x32_bf16 v[126:129], v[184:187], v[200:203], v[126:129]
	v_mfma_f32_16x16x32_bf16 v[114:117], v[192:195], v[200:203], v[114:117]
	v_mfma_f32_16x16x32_bf16 v[106:109], v[184:187], v[208:211], v[106:109]
	v_mfma_f32_16x16x32_bf16 v[98:101], v[192:195], v[208:211], v[98:101]
	v_mfma_f32_16x16x32_bf16 v[90:93], v[184:187], v[216:219], v[90:93]
	v_mfma_f32_16x16x32_bf16 v[82:85], v[192:195], v[216:219], v[82:85]
	v_mfma_f32_16x16x32_bf16 v[74:77], v[184:187], v[224:227], v[74:77]
	v_mfma_f32_16x16x32_bf16 v[66:69], v[192:195], v[224:227], v[66:69]
	s_barrier
	s_setprio 0
	s_add_u32 s98, s96, 0x40000
	s_addc_u32 s99, s97, 0
	s_add_i32 s7, s76, s25
	s_mov_b32 m0, s7
	ds_read_b128 v[196:199], v160 offset:16384
	global_load_lds_dwordx4 v132, s[96:97]
	s_add_i32 m0, s7, 0x2000
	s_add_i32 s7, s77, s25
	global_load_lds_dwordx4 v136, s[96:97]
	s_mov_b32 m0, s7
	ds_read_b128 v[200:203], v238 offset:16384
	global_load_lds_dwordx4 v132, s[98:99]
	s_add_i32 m0, s7, 0x2000
	ds_read_b128 v[204:207], v160 offset:18432
	global_load_lds_dwordx4 v136, s[98:99]
	s_mov_b32 m0, s49
	ds_read_b128 v[208:211], v238 offset:18432
	global_load_lds_dwordx4 v130, s[94:95]
	s_mov_b32 m0, s58
	ds_read_b128 v[212:215], v160 offset:20480
	global_load_lds_dwordx4 v134, s[94:95]
	ds_read_b128 v[216:219], v238 offset:20480
	ds_read_b128 v[220:223], v160 offset:22528
	ds_read_b128 v[224:227], v238 offset:22528
	s_waitcnt vmcnt(8)
	s_waitcnt lgkmcnt(0)
	s_setprio 1
	s_barrier
	v_mfma_f32_16x16x32_bf16 v[62:65], v[164:167], v[196:199], v[62:65]
	v_mfma_f32_16x16x32_bf16 v[54:57], v[172:175], v[196:199], v[54:57]
	v_mfma_f32_16x16x32_bf16 v[46:49], v[164:167], v[204:207], v[46:49]
	v_mfma_f32_16x16x32_bf16 v[38:41], v[172:175], v[204:207], v[38:41]
	v_mfma_f32_16x16x32_bf16 v[30:33], v[164:167], v[212:215], v[30:33]
	v_mfma_f32_16x16x32_bf16 v[22:25], v[172:175], v[212:215], v[22:25]
	v_mfma_f32_16x16x32_bf16 v[14:17], v[164:167], v[220:223], v[14:17]
	v_mfma_f32_16x16x32_bf16 v[6:9], v[172:175], v[220:223], v[6:9]
	v_mfma_f32_16x16x32_bf16 v[62:65], v[168:171], v[200:203], v[62:65]
	v_mfma_f32_16x16x32_bf16 v[54:57], v[176:179], v[200:203], v[54:57]
	v_mfma_f32_16x16x32_bf16 v[46:49], v[168:171], v[208:211], v[46:49]
	v_mfma_f32_16x16x32_bf16 v[38:41], v[176:179], v[208:211], v[38:41]
	v_mfma_f32_16x16x32_bf16 v[30:33], v[168:171], v[216:219], v[30:33]
	v_mfma_f32_16x16x32_bf16 v[22:25], v[176:179], v[216:219], v[22:25]
	v_mfma_f32_16x16x32_bf16 v[14:17], v[168:171], v[224:227], v[14:17]
	v_mfma_f32_16x16x32_bf16 v[6:9], v[176:179], v[224:227], v[6:9]
	v_mfma_f32_16x16x32_bf16 v[58:61], v[180:183], v[196:199], v[58:61]
	v_mfma_f32_16x16x32_bf16 v[50:53], v[188:191], v[196:199], v[50:53]
	v_mfma_f32_16x16x32_bf16 v[42:45], v[180:183], v[204:207], v[42:45]
	v_mfma_f32_16x16x32_bf16 v[34:37], v[188:191], v[204:207], v[34:37]
	v_mfma_f32_16x16x32_bf16 v[26:29], v[180:183], v[212:215], v[26:29]
	v_mfma_f32_16x16x32_bf16 v[18:21], v[188:191], v[212:215], v[18:21]
	v_mfma_f32_16x16x32_bf16 v[10:13], v[180:183], v[220:223], v[10:13]
	v_mfma_f32_16x16x32_bf16 v[2:5], v[188:191], v[220:223], v[2:5]
	v_mfma_f32_16x16x32_bf16 v[58:61], v[184:187], v[200:203], v[58:61]
	v_mfma_f32_16x16x32_bf16 v[50:53], v[192:195], v[200:203], v[50:53]
	v_mfma_f32_16x16x32_bf16 v[42:45], v[184:187], v[208:211], v[42:45]
	v_mfma_f32_16x16x32_bf16 v[34:37], v[192:195], v[208:211], v[34:37]
	v_mfma_f32_16x16x32_bf16 v[26:29], v[184:187], v[216:219], v[26:29]
	v_mfma_f32_16x16x32_bf16 v[18:21], v[192:195], v[216:219], v[18:21]
	v_mfma_f32_16x16x32_bf16 v[10:13], v[184:187], v[224:227], v[10:13]
	v_mfma_f32_16x16x32_bf16 v[2:5], v[192:195], v[224:227], v[2:5]
	s_barrier
	s_setprio 0
	s_add_u32 s98, s94, 0x40000
	s_addc_u32 s99, s95, 0
	s_add_i32 s7, 0, 0x18000
	s_add_i32 s47, 0, 0x1c000
	s_mov_b32 m0, s59
	ds_read_b128 v[164:167], v232
	global_load_lds_dwordx4 v130, s[98:99]
	s_mov_b32 m0, s60
	ds_read_b128 v[168:171], v236
	global_load_lds_dwordx4 v134, s[98:99]
	ds_read_b128 v[172:175], v232 offset:2048
	ds_read_b128 v[176:179], v236 offset:2048
	ds_read_b128 v[180:183], v233
	ds_read_b128 v[184:187], v237
	ds_read_b128 v[188:191], v233 offset:2048
	ds_read_b128 v[192:195], v237 offset:2048
	ds_read_b128 v[196:199], v160 offset:32768
	ds_read_b128 v[200:203], v238 offset:32768
	ds_read_b128 v[204:207], v160 offset:34816
	ds_read_b128 v[208:211], v238 offset:34816
	ds_read_b128 v[212:215], v160 offset:36864
	ds_read_b128 v[216:219], v238 offset:36864
	ds_read_b128 v[220:223], v160 offset:38912
	ds_read_b128 v[224:227], v238 offset:38912
	s_waitcnt vmcnt(8)
	s_waitcnt lgkmcnt(0)
	s_setprio 1
	s_barrier
	v_mfma_f32_16x16x32_bf16 v[122:125], v[164:167], v[196:199], v[122:125]
	v_mfma_f32_16x16x32_bf16 v[118:121], v[172:175], v[196:199], v[118:121]
	v_mfma_f32_16x16x32_bf16 v[110:113], v[164:167], v[204:207], v[110:113]
	v_mfma_f32_16x16x32_bf16 v[102:105], v[172:175], v[204:207], v[102:105]
	v_mfma_f32_16x16x32_bf16 v[94:97], v[164:167], v[212:215], v[94:97]
	v_mfma_f32_16x16x32_bf16 v[86:89], v[172:175], v[212:215], v[86:89]
	v_mfma_f32_16x16x32_bf16 v[78:81], v[164:167], v[220:223], v[78:81]
	v_mfma_f32_16x16x32_bf16 v[70:73], v[172:175], v[220:223], v[70:73]
	v_mfma_f32_16x16x32_bf16 v[122:125], v[168:171], v[200:203], v[122:125]
	v_mfma_f32_16x16x32_bf16 v[118:121], v[176:179], v[200:203], v[118:121]
	v_mfma_f32_16x16x32_bf16 v[110:113], v[168:171], v[208:211], v[110:113]
	v_mfma_f32_16x16x32_bf16 v[102:105], v[176:179], v[208:211], v[102:105]
	v_mfma_f32_16x16x32_bf16 v[94:97], v[168:171], v[216:219], v[94:97]
	v_mfma_f32_16x16x32_bf16 v[86:89], v[176:179], v[216:219], v[86:89]
	v_mfma_f32_16x16x32_bf16 v[78:81], v[168:171], v[224:227], v[78:81]
	v_mfma_f32_16x16x32_bf16 v[70:73], v[176:179], v[224:227], v[70:73]
	v_mfma_f32_16x16x32_bf16 v[126:129], v[180:183], v[196:199], v[126:129]
	v_mfma_f32_16x16x32_bf16 v[114:117], v[188:191], v[196:199], v[114:117]
	v_mfma_f32_16x16x32_bf16 v[106:109], v[180:183], v[204:207], v[106:109]
	v_mfma_f32_16x16x32_bf16 v[98:101], v[188:191], v[204:207], v[98:101]
	v_mfma_f32_16x16x32_bf16 v[90:93], v[180:183], v[212:215], v[90:93]
	v_mfma_f32_16x16x32_bf16 v[82:85], v[188:191], v[212:215], v[82:85]
	v_mfma_f32_16x16x32_bf16 v[74:77], v[180:183], v[220:223], v[74:77]
	v_mfma_f32_16x16x32_bf16 v[66:69], v[188:191], v[220:223], v[66:69]
	v_mfma_f32_16x16x32_bf16 v[126:129], v[184:187], v[200:203], v[126:129]
	v_mfma_f32_16x16x32_bf16 v[114:117], v[192:195], v[200:203], v[114:117]
	v_mfma_f32_16x16x32_bf16 v[106:109], v[184:187], v[208:211], v[106:109]
	v_mfma_f32_16x16x32_bf16 v[98:101], v[192:195], v[208:211], v[98:101]
	v_mfma_f32_16x16x32_bf16 v[90:93], v[184:187], v[216:219], v[90:93]
	v_mfma_f32_16x16x32_bf16 v[82:85], v[192:195], v[216:219], v[82:85]
	v_mfma_f32_16x16x32_bf16 v[74:77], v[184:187], v[224:227], v[74:77]
	v_mfma_f32_16x16x32_bf16 v[66:69], v[192:195], v[224:227], v[66:69]
	s_barrier
	s_setprio 0
	s_add_u32 s96, s96, 0x80
	s_addc_u32 s97, s97, 0
	s_add_u32 s98, s96, 0x40000
	s_addc_u32 s99, s97, 0
	s_add_u32 s94, s94, 0x80
	s_addc_u32 s95, s95, 0
	s_add_i32 s7, s7, s25
	s_mov_b32 m0, s7
	ds_read_b128 v[196:199], v160 offset:49152
	global_load_lds_dwordx4 v132, s[96:97]
	s_add_i32 m0, s7, 0x2000
	s_add_i32 s7, s47, s25
	global_load_lds_dwordx4 v136, s[96:97]
	s_mov_b32 m0, s7
	ds_read_b128 v[200:203], v238 offset:49152
	global_load_lds_dwordx4 v132, s[98:99]
	s_add_i32 m0, s7, 0x2000
	ds_read_b128 v[204:207], v160 offset:51200
	global_load_lds_dwordx4 v136, s[98:99]
	s_mov_b32 m0, s66
	ds_read_b128 v[208:211], v238 offset:51200
	global_load_lds_dwordx4 v130, s[94:95]
	s_mov_b32 m0, s67
	ds_read_b128 v[212:215], v160 offset:53248
	global_load_lds_dwordx4 v134, s[94:95]
	ds_read_b128 v[216:219], v238 offset:53248
	ds_read_b128 v[220:223], v160 offset:55296
	ds_read_b128 v[224:227], v238 offset:55296
	s_waitcnt vmcnt(8)
	s_waitcnt lgkmcnt(0)
	s_setprio 1
	s_barrier
	v_mfma_f32_16x16x32_bf16 v[62:65], v[164:167], v[196:199], v[62:65]
	v_mfma_f32_16x16x32_bf16 v[54:57], v[172:175], v[196:199], v[54:57]
	v_mfma_f32_16x16x32_bf16 v[46:49], v[164:167], v[204:207], v[46:49]
	v_mfma_f32_16x16x32_bf16 v[38:41], v[172:175], v[204:207], v[38:41]
	v_mfma_f32_16x16x32_bf16 v[30:33], v[164:167], v[212:215], v[30:33]
	v_mfma_f32_16x16x32_bf16 v[22:25], v[172:175], v[212:215], v[22:25]
	v_mfma_f32_16x16x32_bf16 v[14:17], v[164:167], v[220:223], v[14:17]
	v_mfma_f32_16x16x32_bf16 v[6:9], v[172:175], v[220:223], v[6:9]
	v_mfma_f32_16x16x32_bf16 v[62:65], v[168:171], v[200:203], v[62:65]
	v_mfma_f32_16x16x32_bf16 v[54:57], v[176:179], v[200:203], v[54:57]
	v_mfma_f32_16x16x32_bf16 v[46:49], v[168:171], v[208:211], v[46:49]
	v_mfma_f32_16x16x32_bf16 v[38:41], v[176:179], v[208:211], v[38:41]
	v_mfma_f32_16x16x32_bf16 v[30:33], v[168:171], v[216:219], v[30:33]
	v_mfma_f32_16x16x32_bf16 v[22:25], v[176:179], v[216:219], v[22:25]
	v_mfma_f32_16x16x32_bf16 v[14:17], v[168:171], v[224:227], v[14:17]
	v_mfma_f32_16x16x32_bf16 v[6:9], v[176:179], v[224:227], v[6:9]
	v_mfma_f32_16x16x32_bf16 v[58:61], v[180:183], v[196:199], v[58:61]
	v_mfma_f32_16x16x32_bf16 v[50:53], v[188:191], v[196:199], v[50:53]
	v_mfma_f32_16x16x32_bf16 v[42:45], v[180:183], v[204:207], v[42:45]
	v_mfma_f32_16x16x32_bf16 v[34:37], v[188:191], v[204:207], v[34:37]
	v_mfma_f32_16x16x32_bf16 v[26:29], v[180:183], v[212:215], v[26:29]
	v_mfma_f32_16x16x32_bf16 v[18:21], v[188:191], v[212:215], v[18:21]
	v_mfma_f32_16x16x32_bf16 v[10:13], v[180:183], v[220:223], v[10:13]
	v_mfma_f32_16x16x32_bf16 v[2:5], v[188:191], v[220:223], v[2:5]
	v_mfma_f32_16x16x32_bf16 v[58:61], v[184:187], v[200:203], v[58:61]
	v_mfma_f32_16x16x32_bf16 v[50:53], v[192:195], v[200:203], v[50:53]
	v_mfma_f32_16x16x32_bf16 v[42:45], v[184:187], v[208:211], v[42:45]
	v_mfma_f32_16x16x32_bf16 v[34:37], v[192:195], v[208:211], v[34:37]
	v_mfma_f32_16x16x32_bf16 v[26:29], v[184:187], v[216:219], v[26:29]
	v_mfma_f32_16x16x32_bf16 v[18:21], v[192:195], v[216:219], v[18:21]
	v_mfma_f32_16x16x32_bf16 v[10:13], v[184:187], v[224:227], v[10:13]
	v_mfma_f32_16x16x32_bf16 v[2:5], v[192:195], v[224:227], v[2:5]
	s_barrier
	s_setprio 0
	s_mov_b32 s7, s45
	s_add_u32 s88, s88, 0x100
	s_addc_u32 s89, s89, 0
	s_add_u32 s86, s86, 0x100
	s_addc_u32 s87, s87, 0
	s_cmp_ge_i32 s45, s101
	s_cbranch_scc0 .LBB0_768

.LBB0_940:
	v_ashrrev_i32_e32 v7, 31, v14
	v_lshrrev_b32_e32 v7, 26, v7
	v_add_u32_e32 v7, v14, v7
	v_ashrrev_i32_e32 v15, 6, v7
	v_bfe_i32 v7, v14, 27, 1
	v_lshlrev_b32_e32 v6, 4, v14
	v_lshrrev_b32_e32 v7, 22, v7
	v_add_u32_e32 v7, v6, v7
	v_and_b32_e32 v7, 0xfffffc00, v7
	v_sub_u32_e32 v7, v6, v7
	v_lshrrev_b32_e32 v8, 4, v7
	v_bitop3_b32 v8, v8, v7, 32 bitop3:0x6c
	v_ashrrev_i32_e32 v7, 31, v7
	v_lshrrev_b32_e32 v7, 26, v7
	v_add_u32_e32 v7, v8, v7
	v_ashrrev_i32_e32 v16, 6, v7
	v_lshlrev_b32_e32 v9, 3, v15
	v_mul_i32_i24_e32 v10, 64, v16
	v_and_b32_e32 v9, -16, v9
	v_sub_u32_e32 v8, v8, v10
	v_mov_b32_e32 v10, 1
	v_add_u32_e32 v7, v16, v9
	v_lshlrev_b32_e32 v9, 5, v15
	v_ashrrev_i16_sdwa v8, v10, sext(v8) dst_sel:DWORD dst_unused:UNUSED_PAD src0_sel:DWORD src1_sel:BYTE_0
	v_and_b32_e32 v9, 32, v9
	v_bfe_i32 v17, v8, 0, 16
	v_and_b32_e32 v12, 3, v16
	s_mov_b32 s5, 0x1fffe0
	v_add_lshl_u32 v9, v9, v17, 1
	v_add_u32_e32 v6, 0x2000, v6
	v_lshlrev_b32_e32 v8, 1, v7
	v_lshrrev_b32_e32 v11, 2, v7
	v_and_or_b32 v12, v7, s5, v12
	v_lshl_add_u32 v130, v7, 11, v9
	v_ashrrev_i32_e32 v7, 31, v6
	v_lshrrev_b32_e32 v7, 22, v7
	v_add_u32_e32 v7, v6, v7
	v_ashrrev_i32_e32 v18, 10, v7
	v_mul_i32_i24_e32 v7, 0x400, v18
	v_sub_u32_e32 v6, v6, v7
	v_and_b32_e32 v8, 24, v8
	v_and_b32_e32 v11, 4, v11
	v_lshrrev_b32_e32 v7, 4, v6
	v_or3_b32 v8, v12, v11, v8
	v_bitop3_b32 v6, v7, v6, 32 bitop3:0x6c
	v_lshl_add_u32 v132, v8, 11, v9
	v_ashrrev_i32_e32 v8, 31, v6
	v_lshrrev_b32_e32 v8, 26, v8
	v_add_u32_e32 v8, v6, v8
	v_lshlrev_b32_e32 v7, 3, v18
	v_ashrrev_i32_e32 v19, 6, v8
	v_and_b32_e32 v8, 0xc0, v8
	v_and_b32_e32 v7, -16, v7
	v_sub_u32_e32 v6, v6, v8
	s_ashr_i32 s4, s12, 6
	v_add_u32_e32 v7, v19, v7
	v_ashrrev_i16_sdwa v6, v10, sext(v6) dst_sel:DWORD dst_unused:UNUSED_PAD src0_sel:DWORD src1_sel:BYTE_0
	v_lshlrev_b32_e32 v9, 5, v18
	v_bfe_i32 v20, v6, 0, 16
	v_lshlrev_b32_e32 v6, 1, v7
	v_lshrrev_b32_e32 v8, 2, v7
	v_and_b32_e32 v10, 3, v19
	s_lshl_b32 s29, s4, 10
	v_and_b32_e32 v9, 32, v9
	v_and_b32_e32 v6, 24, v6
	v_and_b32_e32 v8, 4, v8
	v_and_or_b32 v10, v7, s5, v10
	s_add_i32 s51, s29, 0
	v_or3_b32 v6, v10, v8, v6
	v_add_lshl_u32 v8, v9, v20, 1
	s_add_i32 m0, s51, 0x10000
	v_readfirstlane_b32 s10, v4
	v_readfirstlane_b32 s11, v5
	v_lshl_add_u32 v136, v6, 11, v8
	v_lshl_add_u32 v134, v7, 11, v8
	s_add_i32 s60, s51, 0x2000
	s_add_i32 s61, s51, 0x4000
	s_add_i32 s62, s51, 0x6000
	v_lshrrev_b32_e32 v242, 6, v1
	v_and_b32_e32 v243, 63, v1
	v_lshlrev_b32_e32 v245, 4, v243
	v_lshrrev_b32_e32 v244, 5, v243
	v_lshlrev_b32_e32 v244, 5, v244
	v_xor_b32_e32 v245, v245, v244
	v_lshrrev_b32_e32 v244, 1, v242
	v_lshlrev_b32_e32 v244, 4, v244
	v_lshrrev_b32_e32 v243, 6, v245
	v_add_u32_e32 v244, v244, v243
	v_and_b32_e32 v245, 63, v245
	v_and_b32_e32 v242, 1, v242
	v_lshl_add_u32 v245, v242, 6, v245
	v_mul_u32_u24_e32 v244, 0x800, v244
	v_add_u32_e32 v240, v244, v245
	v_lshrrev_b32_e32 v242, 6, v1
	v_and_b32_e32 v243, 63, v1
	v_lshrrev_b32_e32 v244, 3, v243
	v_lshl_add_u32 v244, v242, 3, v244
	v_lshrrev_b32_e32 v245, 4, v243
	v_and_b32_e32 v245, 3, v245
	v_lshlrev_b32_e32 v245, 1, v245
	v_and_b32_e32 v243, 7, v243
	v_xor_b32_e32 v245, v243, v245
	v_lshlrev_b32_e32 v245, 4, v245
	v_mul_u32_u24_e32 v244, 0x800, v244
	v_add_u32_e32 v241, v244, v245
	v_sub_u32_e32 v130, v130, v240
	v_add_u32_e32 v130, v130, v241
	v_lshrrev_b32_e32 v242, 6, v1
	v_and_b32_e32 v243, 63, v1
	v_lshlrev_b32_e32 v245, 4, v243
	v_lshrrev_b32_e32 v244, 5, v243
	v_lshlrev_b32_e32 v244, 5, v244
	v_xor_b32_e32 v245, v245, v244
	v_add_u32_e32 v242, 8, v242
	v_lshrrev_b32_e32 v244, 1, v242
	v_lshlrev_b32_e32 v244, 4, v244
	v_lshrrev_b32_e32 v243, 6, v245
	v_add_u32_e32 v244, v244, v243
	v_and_b32_e32 v245, 63, v245
	v_and_b32_e32 v242, 1, v242
	v_lshl_add_u32 v245, v242, 6, v245
	v_mul_u32_u24_e32 v244, 0x800, v244
	v_add_u32_e32 v240, v244, v245
	v_lshrrev_b32_e32 v242, 6, v1
	v_and_b32_e32 v243, 63, v1
	v_lshrrev_b32_e32 v244, 3, v243
	v_lshl_add_u32 v244, v242, 3, v244
	v_add_u32_e32 v244, 64, v244
	v_lshrrev_b32_e32 v245, 4, v243
	v_and_b32_e32 v245, 3, v245
	v_lshlrev_b32_e32 v245, 1, v245
	v_and_b32_e32 v243, 7, v243
	v_xor_b32_e32 v245, v243, v245
	v_lshlrev_b32_e32 v245, 4, v245
	v_mul_u32_u24_e32 v244, 0x800, v244
	v_add_u32_e32 v241, v244, v245
	v_sub_u32_e32 v134, v134, v240
	v_add_u32_e32 v134, v134, v241
	v_lshrrev_b32_e32 v242, 6, v1
	v_and_b32_e32 v243, 63, v1
	v_lshlrev_b32_e32 v245, 4, v243
	v_lshrrev_b32_e32 v244, 5, v243
	v_lshlrev_b32_e32 v244, 5, v244
	v_xor_b32_e32 v245, v245, v244
	v_lshrrev_b32_e32 v244, 1, v242
	v_lshlrev_b32_e32 v244, 4, v244
	v_lshrrev_b32_e32 v243, 6, v245
	v_add_u32_e32 v244, v244, v243
	v_and_b32_e32 v245, 63, v245
	v_and_b32_e32 v242, 1, v242
	v_lshl_add_u32 v245, v242, 6, v245
	v_and_b32_e32 v242, 31, v244
	v_sub_u32_e32 v244, v244, v242
	v_and_b32_e32 v243, 3, v242
	v_add_u32_e32 v244, v244, v243
	v_lshrrev_b32_e32 v243, 4, v242
	v_lshl_add_u32 v244, v243, 2, v244
	v_and_b32_e32 v243, 15, v242
	v_lshrrev_b32_e32 v243, 2, v243
	v_lshl_add_u32 v244, v243, 3, v244
	v_mul_u32_u24_e32 v244, 0x800, v244
	v_add_u32_e32 v240, v244, v245
	v_lshrrev_b32_e32 v242, 6, v1
	v_and_b32_e32 v243, 63, v1
	v_lshrrev_b32_e32 v244, 3, v243
	v_lshl_add_u32 v244, v242, 3, v244
	v_lshrrev_b32_e32 v245, 4, v243
	v_and_b32_e32 v245, 3, v245
	v_lshlrev_b32_e32 v245, 1, v245
	v_and_b32_e32 v243, 7, v243
	v_xor_b32_e32 v245, v243, v245
	v_lshlrev_b32_e32 v245, 4, v245
	v_and_b32_e32 v242, 31, v244
	v_sub_u32_e32 v244, v244, v242
	v_and_b32_e32 v243, 3, v242
	v_add_u32_e32 v244, v244, v243
	v_lshrrev_b32_e32 v243, 4, v242
	v_lshl_add_u32 v244, v243, 2, v244
	v_and_b32_e32 v243, 15, v242
	v_lshrrev_b32_e32 v243, 2, v243
	v_lshl_add_u32 v244, v243, 3, v244
	v_mul_u32_u24_e32 v244, 0x800, v244
	v_add_u32_e32 v241, v244, v245
	v_sub_u32_e32 v132, v132, v240
	v_add_u32_e32 v132, v132, v241
	v_lshrrev_b32_e32 v242, 6, v1
	v_and_b32_e32 v243, 63, v1
	v_lshlrev_b32_e32 v245, 4, v243
	v_lshrrev_b32_e32 v244, 5, v243
	v_lshlrev_b32_e32 v244, 5, v244
	v_xor_b32_e32 v245, v245, v244
	v_add_u32_e32 v242, 8, v242
	v_lshrrev_b32_e32 v244, 1, v242
	v_lshlrev_b32_e32 v244, 4, v244
	v_lshrrev_b32_e32 v243, 6, v245
	v_add_u32_e32 v244, v244, v243
	v_and_b32_e32 v245, 63, v245
	v_and_b32_e32 v242, 1, v242
	v_lshl_add_u32 v245, v242, 6, v245
	v_and_b32_e32 v242, 31, v244
	v_sub_u32_e32 v244, v244, v242
	v_and_b32_e32 v243, 3, v242
	v_add_u32_e32 v244, v244, v243
	v_lshrrev_b32_e32 v243, 4, v242
	v_lshl_add_u32 v244, v243, 2, v244
	v_and_b32_e32 v243, 15, v242
	v_lshrrev_b32_e32 v243, 2, v243
	v_lshl_add_u32 v244, v243, 3, v244
	v_mul_u32_u24_e32 v244, 0x800, v244
	v_add_u32_e32 v240, v244, v245
	v_lshrrev_b32_e32 v242, 6, v1
	v_and_b32_e32 v243, 63, v1
	v_lshrrev_b32_e32 v244, 3, v243
	v_lshl_add_u32 v244, v242, 3, v244
	v_add_u32_e32 v244, 64, v244
	v_lshrrev_b32_e32 v245, 4, v243
	v_and_b32_e32 v245, 3, v245
	v_lshlrev_b32_e32 v245, 1, v245
	v_and_b32_e32 v243, 7, v243
	v_xor_b32_e32 v245, v243, v245
	v_lshlrev_b32_e32 v245, 4, v245
	v_and_b32_e32 v242, 31, v244
	v_sub_u32_e32 v244, v244, v242
	v_and_b32_e32 v243, 3, v242
	v_add_u32_e32 v244, v244, v243
	v_lshrrev_b32_e32 v243, 4, v242
	v_lshl_add_u32 v244, v243, 2, v244
	v_and_b32_e32 v243, 15, v242
	v_lshrrev_b32_e32 v243, 2, v243
	v_lshl_add_u32 v244, v243, 3, v244
	v_mul_u32_u24_e32 v244, 0x800, v244
	v_add_u32_e32 v241, v244, v245
	v_sub_u32_e32 v136, v136, v240
	v_add_u32_e32 v136, v136, v241
	global_load_lds_dwordx4 v132, s[10:11]
	s_add_i32 m0, s51, 0x12000
	s_ashr_i32 s5, s12, 8
	global_load_lds_dwordx4 v136, s[10:11]
	s_mov_b64 s[10:11], 0x40000
	v_lshl_add_u64 v[6:7], v[4:5], 0, s[10:11]
	s_add_i32 m0, s51, 0x14000
	v_readfirstlane_b32 s14, v6
	v_readfirstlane_b32 s15, v7
	v_lshl_add_u64 v[6:7], v[2:3], 0, s[10:11]
	v_mov_b32_e32 v139, 0
	v_mov_b32_e32 v133, v139
	v_mov_b32_e32 v137, v139
	v_mov_b32_e32 v131, v139
	global_load_lds_dwordx4 v132, s[14:15]
	s_add_i32 m0, s51, 0x16000
	v_mov_b32_e32 v135, v139
	global_load_lds_dwordx4 v136, s[14:15]
	v_readfirstlane_b32 s14, v2
	v_readfirstlane_b32 s15, v3
	s_mov_b32 m0, s51
	s_cmp_eq_u32 s5, 1
	s_mov_b32 s13, 0
	v_lshl_add_u64 v[12:13], v[4:5], 0, v[132:133]
	v_lshl_add_u64 v[10:11], v[4:5], 0, v[136:137]
	global_load_lds_dwordx4 v130, s[14:15]
	s_mov_b32 m0, s60
	v_lshl_add_u64 v[8:9], v[2:3], 0, v[134:135]
	global_load_lds_dwordx4 v134, s[14:15]
	v_readfirstlane_b32 s14, v6
	v_readfirstlane_b32 s15, v7
	s_mov_b32 m0, s61
	v_lshl_add_u64 v[6:7], v[2:3], 0, v[130:131]
	s_nop 2
	global_load_lds_dwordx4 v130, s[14:15]
	s_mov_b32 m0, s62
	s_nop 0
	global_load_lds_dwordx4 v134, s[14:15]
	s_cselect_b64 s[14:15], -1, 0
	s_cmp_lg_u32 s5, 1
	s_cbranch_scc1 .LBB0_942
	s_barrier
.LBB0_942:
	s_mov_b64 s[16:17], 0x80
	s_add_i32 m0, s51, 0x18000
	v_lshl_add_u64 v[12:13], v[12:13], 0, s[16:17]
	s_waitcnt vmcnt(2)
	s_barrier
	global_load_lds_dwordx4 v[12:13], off
	v_lshl_add_u64 v[10:11], v[10:11], 0, s[16:17]
	s_add_i32 m0, s51, 0x1a000
	s_add_i32 s63, s51, 0x8000
	global_load_lds_dwordx4 v[10:11], off
	v_lshl_add_u64 v[6:7], v[6:7], 0, s[16:17]
	s_mov_b32 m0, s63
	s_add_i32 s64, s51, 0xa000
	global_load_lds_dwordx4 v[6:7], off
	v_lshl_add_u64 v[6:7], v[8:9], 0, s[16:17]
	s_mov_b32 m0, s64
	s_mov_b64 s[18:19], 0x40080
	global_load_lds_dwordx4 v[6:7], off
	v_lshl_add_u64 v[6:7], v[4:5], 0, s[18:19]
	s_add_i32 m0, s51, 0x1c000
	v_lshl_add_u64 v[8:9], v[6:7], 0, v[132:133]
	global_load_lds_dwordx4 v[8:9], off
	v_lshl_add_u64 v[6:7], v[6:7], 0, v[136:137]
	s_add_i32 m0, s51, 0x1e000
	v_and_b32_e32 v140, 15, v14
	global_load_lds_dwordx4 v[6:7], off
	v_bfe_u32 v6, v14, 4, 2
	v_lshlrev_b32_e32 v7, 4, v6
	v_lshlrev_b32_e32 v9, 2, v14
	s_and_b32 s7, s4, 3
	s_lshl_b32 s65, s5, 6
	v_lshl_or_b32 v8, v140, 6, v7
	s_lshl_b32 s5, s5, 13
	v_and_b32_e32 v9, 32, v9
	v_bitop3_b32 v10, v8, s5, v9 bitop3:0xde
	s_lshl_b32 s66, s7, 5
	s_lshl_b32 s5, s7, 12
	s_cmpk_lt_u32 s12, 0x100
	s_cselect_b64 s[20:21], -1, 0
	s_lshl_b32 s4, s4, 6
	v_bitop3_b32 v141, v8, s5, v9 bitop3:0xde
	v_and_or_b32 v158, s4, 64, v7
	v_cmp_eq_u32_e64 s[4:5], 0, v6
	v_lshl_or_b32 v159, v6, 3, s66
	v_lshlrev_b32_e32 v6, 14, v18
	v_and_b32_e32 v6, 0xffff8000, v6
	v_lshl_add_u32 v6, v19, 11, v6
	v_and_b32_e32 v7, 1, v18
	v_lshl_or_b32 v6, v7, 6, v6
	v_lshl_add_u32 v142, v20, 1, v6
	v_lshlrev_b32_e32 v6, 14, v15
	v_and_b32_e32 v6, 0xffff8000, v6
	v_lshl_add_u32 v6, v16, 11, v6
	v_and_b32_e32 v7, 1, v15
	s_waitcnt vmcnt(6)
	v_lshl_or_b32 v6, v7, 6, v6
	s_add_i32 s74, 0, 0x10000
	v_lshl_add_u32 v144, v17, 1, v6
	s_mov_b32 s24, 0xfffc0080
	s_add_i32 s78, s74, s29
	v_mbcnt_lo_u32_b32 v6, -1, 0
	s_lshl_b32 s12, s7, 2
	v_mov_b32_e32 v143, v139
	v_mov_b32_e32 v145, v139
	s_movk_i32 s67, 0x161
	s_add_i32 s68, 0, 0x20020
	s_add_i32 s69, 0, 0x20018
	s_add_i32 s72, 0, 0x2002c
	s_add_i32 s73, 0, 0x20000
	s_mov_b64 s[22:23], 0x100
	s_mov_b32 s25, -1
	s_add_i32 s75, 0, 0x14000
	v_add_u32_e32 v160, 0, v10
	s_add_i32 s76, s51, 0xc000
	s_add_i32 s77, s51, 0xe000
	s_add_i32 s79, s78, 0x2000
	s_add_i32 s80, 0, 0x20010
	s_add_i32 s81, 0, 0x20024
	s_movk_i32 s82, 0x7fff
	s_mov_b32 s28, 0xbfb8aa3b
	v_mbcnt_hi_u32_b32 v161, -1, v6
	s_mov_b32 s83, s13
	v_mov_b64_e32 v[148:149], v[4:5]
	v_mov_b64_e32 v[146:147], v[2:3]
	s_barrier
	v_lshrrev_b32_e32 v242, 6, v1
	v_and_b32_e32 v243, 63, v1
	v_lshlrev_b32_e32 v245, 4, v243
	v_lshrrev_b32_e32 v244, 5, v243
	v_lshlrev_b32_e32 v244, 5, v244
	v_xor_b32_e32 v245, v245, v244
	v_lshrrev_b32_e32 v244, 1, v242
	v_lshlrev_b32_e32 v244, 4, v244
	v_lshrrev_b32_e32 v243, 6, v245
	v_add_u32_e32 v244, v244, v243
	v_and_b32_e32 v245, 63, v245
	v_and_b32_e32 v242, 1, v242
	v_lshl_add_u32 v245, v242, 6, v245
	v_mul_u32_u24_e32 v244, 0x800, v244
	v_add_u32_e32 v240, v244, v245
	v_lshrrev_b32_e32 v242, 6, v1
	v_and_b32_e32 v243, 63, v1
	v_lshrrev_b32_e32 v244, 3, v243
	v_lshl_add_u32 v244, v242, 3, v244
	v_lshrrev_b32_e32 v245, 4, v243
	v_and_b32_e32 v245, 3, v245
	v_lshlrev_b32_e32 v245, 1, v245
	v_and_b32_e32 v243, 7, v243
	v_xor_b32_e32 v245, v243, v245
	v_lshlrev_b32_e32 v245, 4, v245
	v_mul_u32_u24_e32 v244, 0x800, v244
	v_add_u32_e32 v241, v244, v245
	v_sub_u32_e32 v144, v144, v240
	v_add_u32_e32 v144, v144, v241
	v_lshrrev_b32_e32 v242, 6, v1
	v_and_b32_e32 v243, 63, v1
	v_lshlrev_b32_e32 v245, 4, v243
	v_lshrrev_b32_e32 v244, 5, v243
	v_lshlrev_b32_e32 v244, 5, v244
	v_xor_b32_e32 v245, v245, v244
	v_add_u32_e32 v242, 8, v242
	v_lshrrev_b32_e32 v244, 1, v242
	v_lshlrev_b32_e32 v244, 4, v244
	v_lshrrev_b32_e32 v243, 6, v245
	v_add_u32_e32 v244, v244, v243
	v_and_b32_e32 v245, 63, v245
	v_and_b32_e32 v242, 1, v242
	v_lshl_add_u32 v245, v242, 6, v245
	v_mul_u32_u24_e32 v244, 0x800, v244
	v_add_u32_e32 v240, v244, v245
	v_lshrrev_b32_e32 v242, 6, v1
	v_and_b32_e32 v243, 63, v1
	v_lshrrev_b32_e32 v244, 3, v243
	v_lshl_add_u32 v244, v242, 3, v244
	v_add_u32_e32 v244, 64, v244
	v_lshrrev_b32_e32 v245, 4, v243
	v_and_b32_e32 v245, 3, v245
	v_lshlrev_b32_e32 v245, 1, v245
	v_and_b32_e32 v243, 7, v243
	v_xor_b32_e32 v245, v243, v245
	v_lshlrev_b32_e32 v245, 4, v245
	v_mul_u32_u24_e32 v244, 0x800, v244
	v_add_u32_e32 v241, v244, v245
	v_sub_u32_e32 v142, v142, v240
	v_add_u32_e32 v142, v142, v241
	v_and_b32_e32 v240, 63, v1
	v_and_b32_e32 v241, 15, v240
	v_lshrrev_b32_e32 v242, 4, v240
	v_lshlrev_b32_e32 v243, 6, v241
	v_lshl_add_u32 v243, v242, 4, v243
	v_lshrrev_b32_e32 v244, 3, v241
	v_lshlrev_b32_e32 v245, 5, v244
	v_xor_b32_e32 v243, v243, v245
	v_sub_u32_e32 v160, v160, v243
	v_lshlrev_b32_e32 v244, 10, v244
	v_and_b32_e32 v245, 7, v241
	v_lshl_add_u32 v244, v245, 7, v244
	v_add_u32_e32 v160, v160, v244
	v_lshrrev_b32_e32 v245, 1, v245
	v_lshlrev_b32_e32 v245, 1, v245
	v_add_u32_e32 v244, 4, v242
	v_xor_b32_e32 v244, v244, v245
	v_lshl_add_u32 v238, v244, 4, v160
	v_xor_b32_e32 v244, v242, v245
	v_lshl_add_u32 v160, v244, 4, v160
	v_and_b32_e32 v240, 63, v1
	v_and_b32_e32 v241, 15, v240
	v_lshrrev_b32_e32 v242, 4, v240
	v_lshlrev_b32_e32 v243, 6, v241
	v_lshl_add_u32 v243, v242, 4, v243
	v_lshrrev_b32_e32 v244, 3, v241
	v_lshlrev_b32_e32 v245, 5, v244
	v_xor_b32_e32 v243, v243, v245
	v_sub_u32_e32 v141, v141, v243
	v_lshlrev_b32_e32 v244, 10, v244
	v_and_b32_e32 v245, 7, v241
	v_lshl_add_u32 v244, v245, 7, v244
	v_add_u32_e32 v141, v141, v244
	v_lshrrev_b32_e32 v245, 1, v245
	v_lshlrev_b32_e32 v245, 1, v245
	v_add_u32_e32 v244, 4, v242
	v_xor_b32_e32 v244, v244, v245
	v_lshl_add_u32 v239, v244, 4, v141
	v_xor_b32_e32 v244, v242, v245
	v_lshl_add_u32 v141, v244, 4, v141
	s_branch .LBB0_945

.Lmy_nb_4:
	s_nop 0
	v_readfirstlane_b32 s86, v152
	v_readfirstlane_b32 s87, v153
	v_readfirstlane_b32 s88, v150
	v_readfirstlane_b32 s89, v151
	v_readfirstlane_b32 s90, v146
	v_readfirstlane_b32 s91, v147
	v_readfirstlane_b32 s92, v148
	v_readfirstlane_b32 s93, v149
	v_readfirstlane_b32 s100, v154
	v_readfirstlane_b32 s101, v138
	v_add_u32_e32 v230, s74, v141
	v_add_u32_e32 v234, s74, v239
	v_add_u32_e32 v231, s75, v141
	v_add_u32_e32 v235, s75, v239
	v_add_u32_e32 v232, 0x18000, v141
	v_add_u32_e32 v236, 0x18000, v239
	v_add_u32_e32 v233, 0x1c000, v141
	v_add_u32_e32 v237, 0x1c000, v239
	s_add_u32 s98, s86, 0xfffc0080
	s_addc_u32 s99, s87, -1
	s_cmp_eq_u32 s7, s100
	s_cselect_b64 s[94:95], s[90:91], s[98:99]
	s_cselect_b64 s[96:97], s[92:93], s[88:89]
	s_add_i32 s47, s7, 2
	s_mov_b32 m0, s76
	ds_read_b128 v[164:167], v230
	global_load_lds_dwordx4 v144, s[86:87]
	s_mov_b32 m0, s77
	ds_read_b128 v[168:171], v234
	global_load_lds_dwordx4 v142, s[86:87]
	ds_read_b128 v[172:175], v230 offset:2048
	ds_read_b128 v[176:179], v234 offset:2048
	ds_read_b128 v[180:183], v231
	ds_read_b128 v[184:187], v235
	ds_read_b128 v[188:191], v231 offset:2048
	ds_read_b128 v[192:195], v235 offset:2048
	ds_read_b128 v[196:199], v160
	ds_read_b128 v[200:203], v238
	ds_read_b128 v[204:207], v160 offset:2048
	ds_read_b128 v[208:211], v238 offset:2048
	ds_read_b128 v[212:215], v160 offset:4096
	ds_read_b128 v[216:219], v238 offset:4096
	ds_read_b128 v[220:223], v160 offset:6144
	ds_read_b128 v[224:227], v238 offset:6144
	s_waitcnt vmcnt(8)
	s_waitcnt lgkmcnt(0)
	s_setprio 1
	s_barrier
	v_mfma_f32_16x16x32_bf16 v[122:125], v[164:167], v[196:199], 0
	v_mfma_f32_16x16x32_bf16 v[118:121], v[172:175], v[196:199], 0
	v_mfma_f32_16x16x32_bf16 v[110:113], v[164:167], v[204:207], 0
	v_mfma_f32_16x16x32_bf16 v[102:105], v[172:175], v[204:207], 0
	v_mfma_f32_16x16x32_bf16 v[94:97], v[164:167], v[212:215], 0
	v_mfma_f32_16x16x32_bf16 v[86:89], v[172:175], v[212:215], 0
	v_mfma_f32_16x16x32_bf16 v[78:81], v[164:167], v[220:223], 0
	v_mfma_f32_16x16x32_bf16 v[70:73], v[172:175], v[220:223], 0
	v_mfma_f32_16x16x32_bf16 v[122:125], v[168:171], v[200:203], v[122:125]
	v_mfma_f32_16x16x32_bf16 v[118:121], v[176:179], v[200:203], v[118:121]
	v_mfma_f32_16x16x32_bf16 v[110:113], v[168:171], v[208:211], v[110:113]
	v_mfma_f32_16x16x32_bf16 v[102:105], v[176:179], v[208:211], v[102:105]
	v_mfma_f32_16x16x32_bf16 v[94:97], v[168:171], v[216:219], v[94:97]
	v_mfma_f32_16x16x32_bf16 v[86:89], v[176:179], v[216:219], v[86:89]
	v_mfma_f32_16x16x32_bf16 v[78:81], v[168:171], v[224:227], v[78:81]
	v_mfma_f32_16x16x32_bf16 v[70:73], v[176:179], v[224:227], v[70:73]
	v_mfma_f32_16x16x32_bf16 v[126:129], v[180:183], v[196:199], 0
	v_mfma_f32_16x16x32_bf16 v[114:117], v[188:191], v[196:199], 0
	v_mfma_f32_16x16x32_bf16 v[106:109], v[180:183], v[204:207], 0
	v_mfma_f32_16x16x32_bf16 v[98:101], v[188:191], v[204:207], 0
	v_mfma_f32_16x16x32_bf16 v[90:93], v[180:183], v[212:215], 0
	v_mfma_f32_16x16x32_bf16 v[82:85], v[188:191], v[212:215], 0
	v_mfma_f32_16x16x32_bf16 v[74:77], v[180:183], v[220:223], 0
	v_mfma_f32_16x16x32_bf16 v[66:69], v[188:191], v[220:223], 0
	v_mfma_f32_16x16x32_bf16 v[126:129], v[184:187], v[200:203], v[126:129]
	v_mfma_f32_16x16x32_bf16 v[114:117], v[192:195], v[200:203], v[114:117]
	v_mfma_f32_16x16x32_bf16 v[106:109], v[184:187], v[208:211], v[106:109]
	v_mfma_f32_16x16x32_bf16 v[98:101], v[192:195], v[208:211], v[98:101]
	v_mfma_f32_16x16x32_bf16 v[90:93], v[184:187], v[216:219], v[90:93]
	v_mfma_f32_16x16x32_bf16 v[82:85], v[192:195], v[216:219], v[82:85]
	v_mfma_f32_16x16x32_bf16 v[74:77], v[184:187], v[224:227], v[74:77]
	v_mfma_f32_16x16x32_bf16 v[66:69], v[192:195], v[224:227], v[66:69]
	s_barrier
	s_setprio 0
	s_add_u32 s98, s96, 0x40000
	s_addc_u32 s99, s97, 0
	s_mov_b32 m0, s78
	ds_read_b128 v[196:199], v160 offset:16384
	global_load_lds_dwordx4 v132, s[96:97]
	s_mov_b32 m0, s79
	s_add_i32 s7, s75, s29
	global_load_lds_dwordx4 v136, s[96:97]
	s_mov_b32 m0, s7
	ds_read_b128 v[200:203], v238 offset:16384
	global_load_lds_dwordx4 v132, s[98:99]
	s_add_i32 m0, s7, 0x2000
	ds_read_b128 v[204:207], v160 offset:18432
	global_load_lds_dwordx4 v136, s[98:99]
	s_mov_b32 m0, s51
	ds_read_b128 v[208:211], v238 offset:18432
	global_load_lds_dwordx4 v130, s[94:95]
	s_mov_b32 m0, s60
	ds_read_b128 v[212:215], v160 offset:20480
	global_load_lds_dwordx4 v134, s[94:95]
	ds_read_b128 v[216:219], v238 offset:20480
	ds_read_b128 v[220:223], v160 offset:22528
	ds_read_b128 v[224:227], v238 offset:22528
	s_waitcnt vmcnt(8)
	s_waitcnt lgkmcnt(0)
	s_setprio 1
	s_barrier
	v_mfma_f32_16x16x32_bf16 v[62:65], v[164:167], v[196:199], 0
	v_mfma_f32_16x16x32_bf16 v[54:57], v[172:175], v[196:199], 0
	v_mfma_f32_16x16x32_bf16 v[46:49], v[164:167], v[204:207], 0
	v_mfma_f32_16x16x32_bf16 v[38:41], v[172:175], v[204:207], 0
	v_mfma_f32_16x16x32_bf16 v[30:33], v[164:167], v[212:215], 0
	v_mfma_f32_16x16x32_bf16 v[22:25], v[172:175], v[212:215], 0
	v_mfma_f32_16x16x32_bf16 v[14:17], v[164:167], v[220:223], 0
	v_mfma_f32_16x16x32_bf16 v[6:9], v[172:175], v[220:223], 0
	v_mfma_f32_16x16x32_bf16 v[62:65], v[168:171], v[200:203], v[62:65]
	v_mfma_f32_16x16x32_bf16 v[54:57], v[176:179], v[200:203], v[54:57]
	v_mfma_f32_16x16x32_bf16 v[46:49], v[168:171], v[208:211], v[46:49]
	v_mfma_f32_16x16x32_bf16 v[38:41], v[176:179], v[208:211], v[38:41]
	v_mfma_f32_16x16x32_bf16 v[30:33], v[168:171], v[216:219], v[30:33]
	v_mfma_f32_16x16x32_bf16 v[22:25], v[176:179], v[216:219], v[22:25]
	v_mfma_f32_16x16x32_bf16 v[14:17], v[168:171], v[224:227], v[14:17]
	v_mfma_f32_16x16x32_bf16 v[6:9], v[176:179], v[224:227], v[6:9]
	v_mfma_f32_16x16x32_bf16 v[58:61], v[180:183], v[196:199], 0
	v_mfma_f32_16x16x32_bf16 v[50:53], v[188:191], v[196:199], 0
	v_mfma_f32_16x16x32_bf16 v[42:45], v[180:183], v[204:207], 0
	v_mfma_f32_16x16x32_bf16 v[34:37], v[188:191], v[204:207], 0
	v_mfma_f32_16x16x32_bf16 v[26:29], v[180:183], v[212:215], 0
	v_mfma_f32_16x16x32_bf16 v[18:21], v[188:191], v[212:215], 0
	v_mfma_f32_16x16x32_bf16 v[10:13], v[180:183], v[220:223], 0
	v_mfma_f32_16x16x32_bf16 v[2:5], v[188:191], v[220:223], 0
	v_mfma_f32_16x16x32_bf16 v[58:61], v[184:187], v[200:203], v[58:61]
	v_mfma_f32_16x16x32_bf16 v[50:53], v[192:195], v[200:203], v[50:53]
	v_mfma_f32_16x16x32_bf16 v[42:45], v[184:187], v[208:211], v[42:45]
	v_mfma_f32_16x16x32_bf16 v[34:37], v[192:195], v[208:211], v[34:37]
	v_mfma_f32_16x16x32_bf16 v[26:29], v[184:187], v[216:219], v[26:29]
	v_mfma_f32_16x16x32_bf16 v[18:21], v[192:195], v[216:219], v[18:21]
	v_mfma_f32_16x16x32_bf16 v[10:13], v[184:187], v[224:227], v[10:13]
	v_mfma_f32_16x16x32_bf16 v[2:5], v[192:195], v[224:227], v[2:5]
	s_barrier
	s_setprio 0
	s_add_u32 s98, s94, 0x40000
	s_addc_u32 s99, s95, 0
	s_add_i32 s7, 0, 0x18000
	s_add_i32 s49, 0, 0x1c000
	s_mov_b32 m0, s61
	ds_read_b128 v[164:167], v232
	global_load_lds_dwordx4 v130, s[98:99]
	s_mov_b32 m0, s62
	ds_read_b128 v[168:171], v236
	global_load_lds_dwordx4 v134, s[98:99]
	ds_read_b128 v[172:175], v232 offset:2048
	ds_read_b128 v[176:179], v236 offset:2048
	ds_read_b128 v[180:183], v233
	ds_read_b128 v[184:187], v237
	ds_read_b128 v[188:191], v233 offset:2048
	ds_read_b128 v[192:195], v237 offset:2048
	ds_read_b128 v[196:199], v160 offset:32768
	ds_read_b128 v[200:203], v238 offset:32768
	ds_read_b128 v[204:207], v160 offset:34816
	ds_read_b128 v[208:211], v238 offset:34816
	ds_read_b128 v[212:215], v160 offset:36864
	ds_read_b128 v[216:219], v238 offset:36864
	ds_read_b128 v[220:223], v160 offset:38912
	ds_read_b128 v[224:227], v238 offset:38912
	s_waitcnt vmcnt(8)
	s_waitcnt lgkmcnt(0)
	s_setprio 1
	s_barrier
	v_mfma_f32_16x16x32_bf16 v[122:125], v[164:167], v[196:199], v[122:125]
	v_mfma_f32_16x16x32_bf16 v[118:121], v[172:175], v[196:199], v[118:121]
	v_mfma_f32_16x16x32_bf16 v[110:113], v[164:167], v[204:207], v[110:113]
	v_mfma_f32_16x16x32_bf16 v[102:105], v[172:175], v[204:207], v[102:105]
	v_mfma_f32_16x16x32_bf16 v[94:97], v[164:167], v[212:215], v[94:97]
	v_mfma_f32_16x16x32_bf16 v[86:89], v[172:175], v[212:215], v[86:89]
	v_mfma_f32_16x16x32_bf16 v[78:81], v[164:167], v[220:223], v[78:81]
	v_mfma_f32_16x16x32_bf16 v[70:73], v[172:175], v[220:223], v[70:73]
	v_mfma_f32_16x16x32_bf16 v[122:125], v[168:171], v[200:203], v[122:125]
	v_mfma_f32_16x16x32_bf16 v[118:121], v[176:179], v[200:203], v[118:121]
	v_mfma_f32_16x16x32_bf16 v[110:113], v[168:171], v[208:211], v[110:113]
	v_mfma_f32_16x16x32_bf16 v[102:105], v[176:179], v[208:211], v[102:105]
	v_mfma_f32_16x16x32_bf16 v[94:97], v[168:171], v[216:219], v[94:97]
	v_mfma_f32_16x16x32_bf16 v[86:89], v[176:179], v[216:219], v[86:89]
	v_mfma_f32_16x16x32_bf16 v[78:81], v[168:171], v[224:227], v[78:81]
	v_mfma_f32_16x16x32_bf16 v[70:73], v[176:179], v[224:227], v[70:73]
	v_mfma_f32_16x16x32_bf16 v[126:129], v[180:183], v[196:199], v[126:129]
	v_mfma_f32_16x16x32_bf16 v[114:117], v[188:191], v[196:199], v[114:117]
	v_mfma_f32_16x16x32_bf16 v[106:109], v[180:183], v[204:207], v[106:109]
	v_mfma_f32_16x16x32_bf16 v[98:101], v[188:191], v[204:207], v[98:101]
	v_mfma_f32_16x16x32_bf16 v[90:93], v[180:183], v[212:215], v[90:93]
	v_mfma_f32_16x16x32_bf16 v[82:85], v[188:191], v[212:215], v[82:85]
	v_mfma_f32_16x16x32_bf16 v[74:77], v[180:183], v[220:223], v[74:77]
	v_mfma_f32_16x16x32_bf16 v[66:69], v[188:191], v[220:223], v[66:69]
	v_mfma_f32_16x16x32_bf16 v[126:129], v[184:187], v[200:203], v[126:129]
	v_mfma_f32_16x16x32_bf16 v[114:117], v[192:195], v[200:203], v[114:117]
	v_mfma_f32_16x16x32_bf16 v[106:109], v[184:187], v[208:211], v[106:109]
	v_mfma_f32_16x16x32_bf16 v[98:101], v[192:195], v[208:211], v[98:101]
	v_mfma_f32_16x16x32_bf16 v[90:93], v[184:187], v[216:219], v[90:93]
	v_mfma_f32_16x16x32_bf16 v[82:85], v[192:195], v[216:219], v[82:85]
	v_mfma_f32_16x16x32_bf16 v[74:77], v[184:187], v[224:227], v[74:77]
	v_mfma_f32_16x16x32_bf16 v[66:69], v[192:195], v[224:227], v[66:69]
	s_barrier
	s_setprio 0
	s_add_u32 s96, s96, 0x80
	s_addc_u32 s97, s97, 0
	s_add_u32 s98, s96, 0x40000
	s_addc_u32 s99, s97, 0
	s_add_u32 s94, s94, 0x80
	s_addc_u32 s95, s95, 0
	s_add_i32 s7, s7, s29
	s_mov_b32 m0, s7
	ds_read_b128 v[196:199], v160 offset:49152
	global_load_lds_dwordx4 v132, s[96:97]
	s_add_i32 m0, s7, 0x2000
	s_add_i32 s7, s49, s29
	global_load_lds_dwordx4 v136, s[96:97]
	s_mov_b32 m0, s7
	ds_read_b128 v[200:203], v238 offset:49152
	global_load_lds_dwordx4 v132, s[98:99]
	s_add_i32 m0, s7, 0x2000
	ds_read_b128 v[204:207], v160 offset:51200
	global_load_lds_dwordx4 v136, s[98:99]
	s_mov_b32 m0, s63
	ds_read_b128 v[208:211], v238 offset:51200
	global_load_lds_dwordx4 v130, s[94:95]
	s_mov_b32 m0, s64
	ds_read_b128 v[212:215], v160 offset:53248
	global_load_lds_dwordx4 v134, s[94:95]
	ds_read_b128 v[216:219], v238 offset:53248
	ds_read_b128 v[220:223], v160 offset:55296
	ds_read_b128 v[224:227], v238 offset:55296
	s_waitcnt vmcnt(8)
	s_waitcnt lgkmcnt(0)
	s_setprio 1
	s_barrier
	v_mfma_f32_16x16x32_bf16 v[62:65], v[164:167], v[196:199], v[62:65]
	v_mfma_f32_16x16x32_bf16 v[54:57], v[172:175], v[196:199], v[54:57]
	v_mfma_f32_16x16x32_bf16 v[46:49], v[164:167], v[204:207], v[46:49]
	v_mfma_f32_16x16x32_bf16 v[38:41], v[172:175], v[204:207], v[38:41]
	v_mfma_f32_16x16x32_bf16 v[30:33], v[164:167], v[212:215], v[30:33]
	v_mfma_f32_16x16x32_bf16 v[22:25], v[172:175], v[212:215], v[22:25]
	v_mfma_f32_16x16x32_bf16 v[14:17], v[164:167], v[220:223], v[14:17]
	v_mfma_f32_16x16x32_bf16 v[6:9], v[172:175], v[220:223], v[6:9]
	v_mfma_f32_16x16x32_bf16 v[62:65], v[168:171], v[200:203], v[62:65]
	v_mfma_f32_16x16x32_bf16 v[54:57], v[176:179], v[200:203], v[54:57]
	v_mfma_f32_16x16x32_bf16 v[46:49], v[168:171], v[208:211], v[46:49]
	v_mfma_f32_16x16x32_bf16 v[38:41], v[176:179], v[208:211], v[38:41]
	v_mfma_f32_16x16x32_bf16 v[30:33], v[168:171], v[216:219], v[30:33]
	v_mfma_f32_16x16x32_bf16 v[22:25], v[176:179], v[216:219], v[22:25]
	v_mfma_f32_16x16x32_bf16 v[14:17], v[168:171], v[224:227], v[14:17]
	v_mfma_f32_16x16x32_bf16 v[6:9], v[176:179], v[224:227], v[6:9]
	v_mfma_f32_16x16x32_bf16 v[58:61], v[180:183], v[196:199], v[58:61]
	v_mfma_f32_16x16x32_bf16 v[50:53], v[188:191], v[196:199], v[50:53]
	v_mfma_f32_16x16x32_bf16 v[42:45], v[180:183], v[204:207], v[42:45]
	v_mfma_f32_16x16x32_bf16 v[34:37], v[188:191], v[204:207], v[34:37]
	v_mfma_f32_16x16x32_bf16 v[26:29], v[180:183], v[212:215], v[26:29]
	v_mfma_f32_16x16x32_bf16 v[18:21], v[188:191], v[212:215], v[18:21]
	v_mfma_f32_16x16x32_bf16 v[10:13], v[180:183], v[220:223], v[10:13]
	v_mfma_f32_16x16x32_bf16 v[2:5], v[188:191], v[220:223], v[2:5]
	v_mfma_f32_16x16x32_bf16 v[58:61], v[184:187], v[200:203], v[58:61]
	v_mfma_f32_16x16x32_bf16 v[50:53], v[192:195], v[200:203], v[50:53]
	v_mfma_f32_16x16x32_bf16 v[42:45], v[184:187], v[208:211], v[42:45]
	v_mfma_f32_16x16x32_bf16 v[34:37], v[192:195], v[208:211], v[34:37]
	v_mfma_f32_16x16x32_bf16 v[26:29], v[184:187], v[216:219], v[26:29]
	v_mfma_f32_16x16x32_bf16 v[18:21], v[192:195], v[216:219], v[18:21]
	v_mfma_f32_16x16x32_bf16 v[10:13], v[184:187], v[224:227], v[10:13]
	v_mfma_f32_16x16x32_bf16 v[2:5], v[192:195], v[224:227], v[2:5]
	s_barrier
	s_setprio 0
	s_mov_b32 s7, s47
	s_add_u32 s88, s88, 0x100
	s_addc_u32 s89, s89, 0
	s_add_u32 s86, s86, 0x100
	s_addc_u32 s87, s87, 0
	s_cmp_ge_i32 s47, s101
	s_cbranch_scc1 .Lmy_kexit_4
.LBB0_949:
	s_add_u32 s98, s86, 0xfffc0080
	s_addc_u32 s99, s87, -1
	s_cmp_eq_u32 s7, s100
	s_cselect_b64 s[94:95], s[90:91], s[98:99]
	s_cselect_b64 s[96:97], s[92:93], s[88:89]
	s_add_i32 s47, s7, 2
	s_mov_b32 m0, s76
	ds_read_b128 v[164:167], v230
	global_load_lds_dwordx4 v144, s[86:87]
	s_mov_b32 m0, s77
	ds_read_b128 v[168:171], v234
	global_load_lds_dwordx4 v142, s[86:87]
	ds_read_b128 v[172:175], v230 offset:2048
	ds_read_b128 v[176:179], v234 offset:2048
	ds_read_b128 v[180:183], v231
	ds_read_b128 v[184:187], v235
	ds_read_b128 v[188:191], v231 offset:2048
	ds_read_b128 v[192:195], v235 offset:2048
	ds_read_b128 v[196:199], v160
	ds_read_b128 v[200:203], v238
	ds_read_b128 v[204:207], v160 offset:2048
	ds_read_b128 v[208:211], v238 offset:2048
	ds_read_b128 v[212:215], v160 offset:4096
	ds_read_b128 v[216:219], v238 offset:4096
	ds_read_b128 v[220:223], v160 offset:6144
	ds_read_b128 v[224:227], v238 offset:6144
	s_waitcnt vmcnt(8)
	s_waitcnt lgkmcnt(0)
	s_setprio 1
	s_barrier
	v_mfma_f32_16x16x32_bf16 v[122:125], v[164:167], v[196:199], v[122:125]
	v_mfma_f32_16x16x32_bf16 v[118:121], v[172:175], v[196:199], v[118:121]
	v_mfma_f32_16x16x32_bf16 v[110:113], v[164:167], v[204:207], v[110:113]
	v_mfma_f32_16x16x32_bf16 v[102:105], v[172:175], v[204:207], v[102:105]
	v_mfma_f32_16x16x32_bf16 v[94:97], v[164:167], v[212:215], v[94:97]
	v_mfma_f32_16x16x32_bf16 v[86:89], v[172:175], v[212:215], v[86:89]
	v_mfma_f32_16x16x32_bf16 v[78:81], v[164:167], v[220:223], v[78:81]
	v_mfma_f32_16x16x32_bf16 v[70:73], v[172:175], v[220:223], v[70:73]
	v_mfma_f32_16x16x32_bf16 v[122:125], v[168:171], v[200:203], v[122:125]
	v_mfma_f32_16x16x32_bf16 v[118:121], v[176:179], v[200:203], v[118:121]
	v_mfma_f32_16x16x32_bf16 v[110:113], v[168:171], v[208:211], v[110:113]
	v_mfma_f32_16x16x32_bf16 v[102:105], v[176:179], v[208:211], v[102:105]
	v_mfma_f32_16x16x32_bf16 v[94:97], v[168:171], v[216:219], v[94:97]
	v_mfma_f32_16x16x32_bf16 v[86:89], v[176:179], v[216:219], v[86:89]
	v_mfma_f32_16x16x32_bf16 v[78:81], v[168:171], v[224:227], v[78:81]
	v_mfma_f32_16x16x32_bf16 v[70:73], v[176:179], v[224:227], v[70:73]
	v_mfma_f32_16x16x32_bf16 v[126:129], v[180:183], v[196:199], v[126:129]
	v_mfma_f32_16x16x32_bf16 v[114:117], v[188:191], v[196:199], v[114:117]
	v_mfma_f32_16x16x32_bf16 v[106:109], v[180:183], v[204:207], v[106:109]
	v_mfma_f32_16x16x32_bf16 v[98:101], v[188:191], v[204:207], v[98:101]
	v_mfma_f32_16x16x32_bf16 v[90:93], v[180:183], v[212:215], v[90:93]
	v_mfma_f32_16x16x32_bf16 v[82:85], v[188:191], v[212:215], v[82:85]
	v_mfma_f32_16x16x32_bf16 v[74:77], v[180:183], v[220:223], v[74:77]
	v_mfma_f32_16x16x32_bf16 v[66:69], v[188:191], v[220:223], v[66:69]
	v_mfma_f32_16x16x32_bf16 v[126:129], v[184:187], v[200:203], v[126:129]
	v_mfma_f32_16x16x32_bf16 v[114:117], v[192:195], v[200:203], v[114:117]
	v_mfma_f32_16x16x32_bf16 v[106:109], v[184:187], v[208:211], v[106:109]
	v_mfma_f32_16x16x32_bf16 v[98:101], v[192:195], v[208:211], v[98:101]
	v_mfma_f32_16x16x32_bf16 v[90:93], v[184:187], v[216:219], v[90:93]
	v_mfma_f32_16x16x32_bf16 v[82:85], v[192:195], v[216:219], v[82:85]
	v_mfma_f32_16x16x32_bf16 v[74:77], v[184:187], v[224:227], v[74:77]
	v_mfma_f32_16x16x32_bf16 v[66:69], v[192:195], v[224:227], v[66:69]
	s_barrier
	s_setprio 0
	s_add_u32 s98, s96, 0x40000
	s_addc_u32 s99, s97, 0
	s_mov_b32 m0, s78
	ds_read_b128 v[196:199], v160 offset:16384
	global_load_lds_dwordx4 v132, s[96:97]
	s_mov_b32 m0, s79
	s_add_i32 s7, s75, s29
	global_load_lds_dwordx4 v136, s[96:97]
	s_mov_b32 m0, s7
	ds_read_b128 v[200:203], v238 offset:16384
	global_load_lds_dwordx4 v132, s[98:99]
	s_add_i32 m0, s7, 0x2000
	ds_read_b128 v[204:207], v160 offset:18432
	global_load_lds_dwordx4 v136, s[98:99]
	s_mov_b32 m0, s51
	ds_read_b128 v[208:211], v238 offset:18432
	global_load_lds_dwordx4 v130, s[94:95]
	s_mov_b32 m0, s60
	ds_read_b128 v[212:215], v160 offset:20480
	global_load_lds_dwordx4 v134, s[94:95]
	ds_read_b128 v[216:219], v238 offset:20480
	ds_read_b128 v[220:223], v160 offset:22528
	ds_read_b128 v[224:227], v238 offset:22528
	s_waitcnt vmcnt(8)
	s_waitcnt lgkmcnt(0)
	s_setprio 1
	s_barrier
	v_mfma_f32_16x16x32_bf16 v[62:65], v[164:167], v[196:199], v[62:65]
	v_mfma_f32_16x16x32_bf16 v[54:57], v[172:175], v[196:199], v[54:57]
	v_mfma_f32_16x16x32_bf16 v[46:49], v[164:167], v[204:207], v[46:49]
	v_mfma_f32_16x16x32_bf16 v[38:41], v[172:175], v[204:207], v[38:41]
	v_mfma_f32_16x16x32_bf16 v[30:33], v[164:167], v[212:215], v[30:33]
	v_mfma_f32_16x16x32_bf16 v[22:25], v[172:175], v[212:215], v[22:25]
	v_mfma_f32_16x16x32_bf16 v[14:17], v[164:167], v[220:223], v[14:17]
	v_mfma_f32_16x16x32_bf16 v[6:9], v[172:175], v[220:223], v[6:9]
	v_mfma_f32_16x16x32_bf16 v[62:65], v[168:171], v[200:203], v[62:65]
	v_mfma_f32_16x16x32_bf16 v[54:57], v[176:179], v[200:203], v[54:57]
	v_mfma_f32_16x16x32_bf16 v[46:49], v[168:171], v[208:211], v[46:49]
	v_mfma_f32_16x16x32_bf16 v[38:41], v[176:179], v[208:211], v[38:41]
	v_mfma_f32_16x16x32_bf16 v[30:33], v[168:171], v[216:219], v[30:33]
	v_mfma_f32_16x16x32_bf16 v[22:25], v[176:179], v[216:219], v[22:25]
	v_mfma_f32_16x16x32_bf16 v[14:17], v[168:171], v[224:227], v[14:17]
	v_mfma_f32_16x16x32_bf16 v[6:9], v[176:179], v[224:227], v[6:9]
	v_mfma_f32_16x16x32_bf16 v[58:61], v[180:183], v[196:199], v[58:61]
	v_mfma_f32_16x16x32_bf16 v[50:53], v[188:191], v[196:199], v[50:53]
	v_mfma_f32_16x16x32_bf16 v[42:45], v[180:183], v[204:207], v[42:45]
	v_mfma_f32_16x16x32_bf16 v[34:37], v[188:191], v[204:207], v[34:37]
	v_mfma_f32_16x16x32_bf16 v[26:29], v[180:183], v[212:215], v[26:29]
	v_mfma_f32_16x16x32_bf16 v[18:21], v[188:191], v[212:215], v[18:21]
	v_mfma_f32_16x16x32_bf16 v[10:13], v[180:183], v[220:223], v[10:13]
	v_mfma_f32_16x16x32_bf16 v[2:5], v[188:191], v[220:223], v[2:5]
	v_mfma_f32_16x16x32_bf16 v[58:61], v[184:187], v[200:203], v[58:61]
	v_mfma_f32_16x16x32_bf16 v[50:53], v[192:195], v[200:203], v[50:53]
	v_mfma_f32_16x16x32_bf16 v[42:45], v[184:187], v[208:211], v[42:45]
	v_mfma_f32_16x16x32_bf16 v[34:37], v[192:195], v[208:211], v[34:37]
	v_mfma_f32_16x16x32_bf16 v[26:29], v[184:187], v[216:219], v[26:29]
	v_mfma_f32_16x16x32_bf16 v[18:21], v[192:195], v[216:219], v[18:21]
	v_mfma_f32_16x16x32_bf16 v[10:13], v[184:187], v[224:227], v[10:13]
	v_mfma_f32_16x16x32_bf16 v[2:5], v[192:195], v[224:227], v[2:5]
	s_barrier
	s_setprio 0
	s_add_u32 s98, s94, 0x40000
	s_addc_u32 s99, s95, 0
	s_add_i32 s7, 0, 0x18000
	s_add_i32 s49, 0, 0x1c000
	s_mov_b32 m0, s61
	ds_read_b128 v[164:167], v232
	global_load_lds_dwordx4 v130, s[98:99]
	s_mov_b32 m0, s62
	ds_read_b128 v[168:171], v236
	global_load_lds_dwordx4 v134, s[98:99]
	ds_read_b128 v[172:175], v232 offset:2048
	ds_read_b128 v[176:179], v236 offset:2048
	ds_read_b128 v[180:183], v233
	ds_read_b128 v[184:187], v237
	ds_read_b128 v[188:191], v233 offset:2048
	ds_read_b128 v[192:195], v237 offset:2048
	ds_read_b128 v[196:199], v160 offset:32768
	ds_read_b128 v[200:203], v238 offset:32768
	ds_read_b128 v[204:207], v160 offset:34816
	ds_read_b128 v[208:211], v238 offset:34816
	ds_read_b128 v[212:215], v160 offset:36864
	ds_read_b128 v[216:219], v238 offset:36864
	ds_read_b128 v[220:223], v160 offset:38912
	ds_read_b128 v[224:227], v238 offset:38912
	s_waitcnt vmcnt(8)
	s_waitcnt lgkmcnt(0)
	s_setprio 1
	s_barrier
	v_mfma_f32_16x16x32_bf16 v[122:125], v[164:167], v[196:199], v[122:125]
	v_mfma_f32_16x16x32_bf16 v[118:121], v[172:175], v[196:199], v[118:121]
	v_mfma_f32_16x16x32_bf16 v[110:113], v[164:167], v[204:207], v[110:113]
	v_mfma_f32_16x16x32_bf16 v[102:105], v[172:175], v[204:207], v[102:105]
	v_mfma_f32_16x16x32_bf16 v[94:97], v[164:167], v[212:215], v[94:97]
	v_mfma_f32_16x16x32_bf16 v[86:89], v[172:175], v[212:215], v[86:89]
	v_mfma_f32_16x16x32_bf16 v[78:81], v[164:167], v[220:223], v[78:81]
	v_mfma_f32_16x16x32_bf16 v[70:73], v[172:175], v[220:223], v[70:73]
	v_mfma_f32_16x16x32_bf16 v[122:125], v[168:171], v[200:203], v[122:125]
	v_mfma_f32_16x16x32_bf16 v[118:121], v[176:179], v[200:203], v[118:121]
	v_mfma_f32_16x16x32_bf16 v[110:113], v[168:171], v[208:211], v[110:113]
	v_mfma_f32_16x16x32_bf16 v[102:105], v[176:179], v[208:211], v[102:105]
	v_mfma_f32_16x16x32_bf16 v[94:97], v[168:171], v[216:219], v[94:97]
	v_mfma_f32_16x16x32_bf16 v[86:89], v[176:179], v[216:219], v[86:89]
	v_mfma_f32_16x16x32_bf16 v[78:81], v[168:171], v[224:227], v[78:81]
	v_mfma_f32_16x16x32_bf16 v[70:73], v[176:179], v[224:227], v[70:73]
	v_mfma_f32_16x16x32_bf16 v[126:129], v[180:183], v[196:199], v[126:129]
	v_mfma_f32_16x16x32_bf16 v[114:117], v[188:191], v[196:199], v[114:117]
	v_mfma_f32_16x16x32_bf16 v[106:109], v[180:183], v[204:207], v[106:109]
	v_mfma_f32_16x16x32_bf16 v[98:101], v[188:191], v[204:207], v[98:101]
	v_mfma_f32_16x16x32_bf16 v[90:93], v[180:183], v[212:215], v[90:93]
	v_mfma_f32_16x16x32_bf16 v[82:85], v[188:191], v[212:215], v[82:85]
	v_mfma_f32_16x16x32_bf16 v[74:77], v[180:183], v[220:223], v[74:77]
	v_mfma_f32_16x16x32_bf16 v[66:69], v[188:191], v[220:223], v[66:69]
	v_mfma_f32_16x16x32_bf16 v[126:129], v[184:187], v[200:203], v[126:129]
	v_mfma_f32_16x16x32_bf16 v[114:117], v[192:195], v[200:203], v[114:117]
	v_mfma_f32_16x16x32_bf16 v[106:109], v[184:187], v[208:211], v[106:109]
	v_mfma_f32_16x16x32_bf16 v[98:101], v[192:195], v[208:211], v[98:101]
	v_mfma_f32_16x16x32_bf16 v[90:93], v[184:187], v[216:219], v[90:93]
	v_mfma_f32_16x16x32_bf16 v[82:85], v[192:195], v[216:219], v[82:85]
	v_mfma_f32_16x16x32_bf16 v[74:77], v[184:187], v[224:227], v[74:77]
	v_mfma_f32_16x16x32_bf16 v[66:69], v[192:195], v[224:227], v[66:69]
	s_barrier
	s_setprio 0
	s_add_u32 s96, s96, 0x80
	s_addc_u32 s97, s97, 0
	s_add_u32 s98, s96, 0x40000
	s_addc_u32 s99, s97, 0
	s_add_u32 s94, s94, 0x80
	s_addc_u32 s95, s95, 0
	s_add_i32 s7, s7, s29
	s_mov_b32 m0, s7
	ds_read_b128 v[196:199], v160 offset:49152
	global_load_lds_dwordx4 v132, s[96:97]
	s_add_i32 m0, s7, 0x2000
	s_add_i32 s7, s49, s29
	global_load_lds_dwordx4 v136, s[96:97]
	s_mov_b32 m0, s7
	ds_read_b128 v[200:203], v238 offset:49152
	global_load_lds_dwordx4 v132, s[98:99]
	s_add_i32 m0, s7, 0x2000
	ds_read_b128 v[204:207], v160 offset:51200
	global_load_lds_dwordx4 v136, s[98:99]
	s_mov_b32 m0, s63
	ds_read_b128 v[208:211], v238 offset:51200
	global_load_lds_dwordx4 v130, s[94:95]
	s_mov_b32 m0, s64
	ds_read_b128 v[212:215], v160 offset:53248
	global_load_lds_dwordx4 v134, s[94:95]
	ds_read_b128 v[216:219], v238 offset:53248
	ds_read_b128 v[220:223], v160 offset:55296
	ds_read_b128 v[224:227], v238 offset:55296
	s_waitcnt vmcnt(8)
	s_waitcnt lgkmcnt(0)
	s_setprio 1
	s_barrier
	v_mfma_f32_16x16x32_bf16 v[62:65], v[164:167], v[196:199], v[62:65]
	v_mfma_f32_16x16x32_bf16 v[54:57], v[172:175], v[196:199], v[54:57]
	v_mfma_f32_16x16x32_bf16 v[46:49], v[164:167], v[204:207], v[46:49]
	v_mfma_f32_16x16x32_bf16 v[38:41], v[172:175], v[204:207], v[38:41]
	v_mfma_f32_16x16x32_bf16 v[30:33], v[164:167], v[212:215], v[30:33]
	v_mfma_f32_16x16x32_bf16 v[22:25], v[172:175], v[212:215], v[22:25]
	v_mfma_f32_16x16x32_bf16 v[14:17], v[164:167], v[220:223], v[14:17]
	v_mfma_f32_16x16x32_bf16 v[6:9], v[172:175], v[220:223], v[6:9]
	v_mfma_f32_16x16x32_bf16 v[62:65], v[168:171], v[200:203], v[62:65]
	v_mfma_f32_16x16x32_bf16 v[54:57], v[176:179], v[200:203], v[54:57]
	v_mfma_f32_16x16x32_bf16 v[46:49], v[168:171], v[208:211], v[46:49]
	v_mfma_f32_16x16x32_bf16 v[38:41], v[176:179], v[208:211], v[38:41]
	v_mfma_f32_16x16x32_bf16 v[30:33], v[168:171], v[216:219], v[30:33]
	v_mfma_f32_16x16x32_bf16 v[22:25], v[176:179], v[216:219], v[22:25]
	v_mfma_f32_16x16x32_bf16 v[14:17], v[168:171], v[224:227], v[14:17]
	v_mfma_f32_16x16x32_bf16 v[6:9], v[176:179], v[224:227], v[6:9]
	v_mfma_f32_16x16x32_bf16 v[58:61], v[180:183], v[196:199], v[58:61]
	v_mfma_f32_16x16x32_bf16 v[50:53], v[188:191], v[196:199], v[50:53]
	v_mfma_f32_16x16x32_bf16 v[42:45], v[180:183], v[204:207], v[42:45]
	v_mfma_f32_16x16x32_bf16 v[34:37], v[188:191], v[204:207], v[34:37]
	v_mfma_f32_16x16x32_bf16 v[26:29], v[180:183], v[212:215], v[26:29]
	v_mfma_f32_16x16x32_bf16 v[18:21], v[188:191], v[212:215], v[18:21]
	v_mfma_f32_16x16x32_bf16 v[10:13], v[180:183], v[220:223], v[10:13]
	v_mfma_f32_16x16x32_bf16 v[2:5], v[188:191], v[220:223], v[2:5]
	v_mfma_f32_16x16x32_bf16 v[58:61], v[184:187], v[200:203], v[58:61]
	v_mfma_f32_16x16x32_bf16 v[50:53], v[192:195], v[200:203], v[50:53]
	v_mfma_f32_16x16x32_bf16 v[42:45], v[184:187], v[208:211], v[42:45]
	v_mfma_f32_16x16x32_bf16 v[34:37], v[192:195], v[208:211], v[34:37]
	v_mfma_f32_16x16x32_bf16 v[26:29], v[184:187], v[216:219], v[26:29]
	v_mfma_f32_16x16x32_bf16 v[18:21], v[192:195], v[216:219], v[18:21]
	v_mfma_f32_16x16x32_bf16 v[10:13], v[184:187], v[224:227], v[10:13]
	v_mfma_f32_16x16x32_bf16 v[2:5], v[192:195], v[224:227], v[2:5]
	s_barrier
	s_setprio 0
	s_mov_b32 s7, s47
	s_add_u32 s88, s88, 0x100
	s_addc_u32 s89, s89, 0
	s_add_u32 s86, s86, 0x100
	s_addc_u32 s87, s87, 0
	s_cmp_ge_i32 s47, s101
	s_cbranch_scc0 .LBB0_949

.LBB0_1067:
	v_ashrrev_i32_e32 v5, 31, v12
	v_lshrrev_b32_e32 v5, 26, v5
	v_add_u32_e32 v5, v12, v5
	v_ashrrev_i32_e32 v13, 6, v5
	v_bfe_i32 v5, v12, 27, 1
	v_lshlrev_b32_e32 v4, 4, v12
	v_lshrrev_b32_e32 v5, 22, v5
	v_add_u32_e32 v5, v4, v5
	v_and_b32_e32 v5, 0xfffffc00, v5
	v_sub_u32_e32 v5, v4, v5
	v_lshrrev_b32_e32 v6, 4, v5
	v_bitop3_b32 v6, v6, v5, 32 bitop3:0x6c
	v_ashrrev_i32_e32 v5, 31, v5
	v_lshrrev_b32_e32 v5, 26, v5
	v_lshlrev_b32_e32 v7, 3, v13
	v_add_u32_e32 v5, v6, v5
	v_and_b32_e32 v7, -16, v7
	v_ashrrev_i32_e32 v14, 6, v5
	v_add_u32_e32 v5, v14, v7
	v_lshlrev_b32_e32 v7, 5, v13
	v_and_b32_e32 v15, 32, v7
	v_mul_i32_i24_e32 v7, 64, v14
	v_sub_u32_e32 v6, v6, v7
	v_mov_b32_e32 v7, 1
	v_ashrrev_i16_sdwa v6, v7, sext(v6) dst_sel:DWORD dst_unused:UNUSED_PAD src0_sel:DWORD src1_sel:BYTE_0
	v_lshlrev_b32_e32 v8, 1, v5
	v_lshrrev_b32_e32 v9, 2, v5
	v_and_b32_e32 v10, 3, v14
	s_mov_b32 s5, 0xffffe0
	v_bfe_i32 v16, v6, 0, 16
	v_and_b32_e32 v8, 24, v8
	v_and_b32_e32 v9, 4, v9
	v_and_or_b32 v10, v5, s5, v10
	s_movk_i32 s7, 0xb00
	v_add_u32_e32 v6, v15, v16
	v_or3_b32 v8, v10, v9, v8
	v_mul_lo_u32 v5, v5, s7
	v_add_lshl_u32 v130, v6, v5, 1
	v_mul_u32_u24_e32 v5, 0xb00, v8
	v_add_u32_e32 v4, 0x2000, v4
	v_add_lshl_u32 v132, v5, v6, 1
	v_ashrrev_i32_e32 v5, 31, v4
	v_lshrrev_b32_e32 v5, 22, v5
	v_add_u32_e32 v5, v4, v5
	v_ashrrev_i32_e32 v17, 10, v5
	v_mul_i32_i24_e32 v5, 0x400, v17
	v_sub_u32_e32 v4, v4, v5
	v_lshrrev_b32_e32 v5, 4, v4
	v_bitop3_b32 v4, v5, v4, 32 bitop3:0x6c
	v_ashrrev_i32_e32 v6, 31, v4
	v_lshrrev_b32_e32 v6, 26, v6
	v_lshlrev_b32_e32 v5, 3, v17
	v_add_u32_e32 v6, v4, v6
	v_and_b32_e32 v5, -16, v5
	v_ashrrev_i32_e32 v19, 6, v6
	v_and_b32_e32 v6, 0xc0, v6
	v_add_u32_e32 v5, v19, v5
	v_lshlrev_b32_e32 v8, 5, v17
	v_sub_u32_e32 v4, v4, v6
	s_ashr_i32 s4, s6, 6
	v_and_b32_e32 v18, 32, v8
	v_ashrrev_i16_sdwa v4, v7, sext(v4) dst_sel:DWORD dst_unused:UNUSED_PAD src0_sel:DWORD src1_sel:BYTE_0
	v_lshlrev_b32_e32 v6, 1, v5
	v_lshrrev_b32_e32 v7, 2, v5
	v_and_b32_e32 v8, 3, v19
	v_bfe_i32 v20, v4, 0, 16
	v_and_b32_e32 v6, 24, v6
	v_and_b32_e32 v7, 4, v7
	v_and_or_b32 v8, v5, s5, v8
	s_lshl_b32 s23, s4, 10
	v_add_u32_e32 v4, v18, v20
	v_or3_b32 v6, v8, v7, v6
	v_mul_lo_u32 v5, v5, s7
	s_add_i32 s46, s23, 0
	v_add_lshl_u32 v134, v4, v5, 1
	v_mul_u32_u24_e32 v5, 0xb00, v6
	s_add_i32 m0, s46, 0x10000
	v_readfirstlane_b32 s10, v2
	v_readfirstlane_b32 s11, v3
	v_add_lshl_u32 v136, v5, v4, 1
	s_add_i32 s47, s46, 0x2000
	s_add_i32 s48, s46, 0x4000
	s_add_i32 s49, s46, 0x6000
	s_ashr_i32 s5, s6, 8
	v_lshrrev_b32_e32 v242, 6, v1
	v_and_b32_e32 v243, 63, v1
	v_lshlrev_b32_e32 v245, 4, v243
	v_lshrrev_b32_e32 v244, 5, v243
	v_lshlrev_b32_e32 v244, 5, v244
	v_xor_b32_e32 v245, v245, v244
	v_lshrrev_b32_e32 v244, 1, v242
	v_lshlrev_b32_e32 v244, 4, v244
	v_lshrrev_b32_e32 v243, 6, v245
	v_add_u32_e32 v244, v244, v243
	v_and_b32_e32 v245, 63, v245
	v_and_b32_e32 v242, 1, v242
	v_lshl_add_u32 v245, v242, 6, v245
	v_mul_u32_u24_e32 v244, 0x1600, v244
	v_add_u32_e32 v240, v244, v245
	v_lshrrev_b32_e32 v242, 6, v1
	v_and_b32_e32 v243, 63, v1
	v_lshrrev_b32_e32 v244, 3, v243
	v_lshl_add_u32 v244, v242, 3, v244
	v_lshrrev_b32_e32 v245, 4, v243
	v_and_b32_e32 v245, 3, v245
	v_lshlrev_b32_e32 v245, 1, v245
	v_and_b32_e32 v243, 7, v243
	v_xor_b32_e32 v245, v243, v245
	v_lshlrev_b32_e32 v245, 4, v245
	v_mul_u32_u24_e32 v244, 0x1600, v244
	v_add_u32_e32 v241, v244, v245
	v_sub_u32_e32 v130, v130, v240
	v_add_u32_e32 v130, v130, v241
	v_lshrrev_b32_e32 v242, 6, v1
	v_and_b32_e32 v243, 63, v1
	v_lshlrev_b32_e32 v245, 4, v243
	v_lshrrev_b32_e32 v244, 5, v243
	v_lshlrev_b32_e32 v244, 5, v244
	v_xor_b32_e32 v245, v245, v244
	v_add_u32_e32 v242, 8, v242
	v_lshrrev_b32_e32 v244, 1, v242
	v_lshlrev_b32_e32 v244, 4, v244
	v_lshrrev_b32_e32 v243, 6, v245
	v_add_u32_e32 v244, v244, v243
	v_and_b32_e32 v245, 63, v245
	v_and_b32_e32 v242, 1, v242
	v_lshl_add_u32 v245, v242, 6, v245
	v_mul_u32_u24_e32 v244, 0x1600, v244
	v_add_u32_e32 v240, v244, v245
	v_lshrrev_b32_e32 v242, 6, v1
	v_and_b32_e32 v243, 63, v1
	v_lshrrev_b32_e32 v244, 3, v243
	v_lshl_add_u32 v244, v242, 3, v244
	v_add_u32_e32 v244, 64, v244
	v_lshrrev_b32_e32 v245, 4, v243
	v_and_b32_e32 v245, 3, v245
	v_lshlrev_b32_e32 v245, 1, v245
	v_and_b32_e32 v243, 7, v243
	v_xor_b32_e32 v245, v243, v245
	v_lshlrev_b32_e32 v245, 4, v245
	v_mul_u32_u24_e32 v244, 0x1600, v244
	v_add_u32_e32 v241, v244, v245
	v_sub_u32_e32 v134, v134, v240
	v_add_u32_e32 v134, v134, v241
	v_lshrrev_b32_e32 v242, 6, v1
	v_and_b32_e32 v243, 63, v1
	v_lshlrev_b32_e32 v245, 4, v243
	v_lshrrev_b32_e32 v244, 5, v243
	v_lshlrev_b32_e32 v244, 5, v244
	v_xor_b32_e32 v245, v245, v244
	v_lshrrev_b32_e32 v244, 1, v242
	v_lshlrev_b32_e32 v244, 4, v244
	v_lshrrev_b32_e32 v243, 6, v245
	v_add_u32_e32 v244, v244, v243
	v_and_b32_e32 v245, 63, v245
	v_and_b32_e32 v242, 1, v242
	v_lshl_add_u32 v245, v242, 6, v245
	v_and_b32_e32 v242, 31, v244
	v_sub_u32_e32 v244, v244, v242
	v_and_b32_e32 v243, 3, v242
	v_add_u32_e32 v244, v244, v243
	v_lshrrev_b32_e32 v243, 4, v242
	v_lshl_add_u32 v244, v243, 2, v244
	v_and_b32_e32 v243, 15, v242
	v_lshrrev_b32_e32 v243, 2, v243
	v_lshl_add_u32 v244, v243, 3, v244
	v_mul_u32_u24_e32 v244, 0x1600, v244
	v_add_u32_e32 v240, v244, v245
	v_lshrrev_b32_e32 v242, 6, v1
	v_and_b32_e32 v243, 63, v1
	v_lshrrev_b32_e32 v244, 3, v243
	v_lshl_add_u32 v244, v242, 3, v244
	v_lshrrev_b32_e32 v245, 4, v243
	v_and_b32_e32 v245, 3, v245
	v_lshlrev_b32_e32 v245, 1, v245
	v_and_b32_e32 v243, 7, v243
	v_xor_b32_e32 v245, v243, v245
	v_lshlrev_b32_e32 v245, 4, v245
	v_and_b32_e32 v242, 31, v244
	v_sub_u32_e32 v244, v244, v242
	v_and_b32_e32 v243, 3, v242
	v_add_u32_e32 v244, v244, v243
	v_lshrrev_b32_e32 v243, 4, v242
	v_lshl_add_u32 v244, v243, 2, v244
	v_and_b32_e32 v243, 15, v242
	v_lshrrev_b32_e32 v243, 2, v243
	v_lshl_add_u32 v244, v243, 3, v244
	v_mul_u32_u24_e32 v244, 0x1600, v244
	v_add_u32_e32 v241, v244, v245
	v_sub_u32_e32 v132, v132, v240
	v_add_u32_e32 v132, v132, v241
	v_lshrrev_b32_e32 v242, 6, v1
	v_and_b32_e32 v243, 63, v1
	v_lshlrev_b32_e32 v245, 4, v243
	v_lshrrev_b32_e32 v244, 5, v243
	v_lshlrev_b32_e32 v244, 5, v244
	v_xor_b32_e32 v245, v245, v244
	v_add_u32_e32 v242, 8, v242
	v_lshrrev_b32_e32 v244, 1, v242
	v_lshlrev_b32_e32 v244, 4, v244
	v_lshrrev_b32_e32 v243, 6, v245
	v_add_u32_e32 v244, v244, v243
	v_and_b32_e32 v245, 63, v245
	v_and_b32_e32 v242, 1, v242
	v_lshl_add_u32 v245, v242, 6, v245
	v_and_b32_e32 v242, 31, v244
	v_sub_u32_e32 v244, v244, v242
	v_and_b32_e32 v243, 3, v242
	v_add_u32_e32 v244, v244, v243
	v_lshrrev_b32_e32 v243, 4, v242
	v_lshl_add_u32 v244, v243, 2, v244
	v_and_b32_e32 v243, 15, v242
	v_lshrrev_b32_e32 v243, 2, v243
	v_lshl_add_u32 v244, v243, 3, v244
	v_mul_u32_u24_e32 v244, 0x1600, v244
	v_add_u32_e32 v240, v244, v245
	v_lshrrev_b32_e32 v242, 6, v1
	v_and_b32_e32 v243, 63, v1
	v_lshrrev_b32_e32 v244, 3, v243
	v_lshl_add_u32 v244, v242, 3, v244
	v_add_u32_e32 v244, 64, v244
	v_lshrrev_b32_e32 v245, 4, v243
	v_and_b32_e32 v245, 3, v245
	v_lshlrev_b32_e32 v245, 1, v245
	v_and_b32_e32 v243, 7, v243
	v_xor_b32_e32 v245, v243, v245
	v_lshlrev_b32_e32 v245, 4, v245
	v_and_b32_e32 v242, 31, v244
	v_sub_u32_e32 v244, v244, v242
	v_and_b32_e32 v243, 3, v242
	v_add_u32_e32 v244, v244, v243
	v_lshrrev_b32_e32 v243, 4, v242
	v_lshl_add_u32 v244, v243, 2, v244
	v_and_b32_e32 v243, 15, v242
	v_lshrrev_b32_e32 v243, 2, v243
	v_lshl_add_u32 v244, v243, 3, v244
	v_mul_u32_u24_e32 v244, 0x1600, v244
	v_add_u32_e32 v241, v244, v245
	v_sub_u32_e32 v136, v136, v240
	v_add_u32_e32 v136, v136, v241
	global_load_lds_dwordx4 v132, s[10:11]
	s_add_i32 m0, s46, 0x12000
	v_mov_b32_e32 v139, 0
	global_load_lds_dwordx4 v136, s[10:11]
	s_mov_b64 s[10:11], 0xb0000
	v_lshl_add_u64 v[4:5], v[2:3], 0, s[10:11]
	s_add_i32 m0, s46, 0x14000
	v_readfirstlane_b32 s12, v4
	v_readfirstlane_b32 s13, v5
	v_lshl_add_u64 v[4:5], v[150:151], 0, s[10:11]
	v_mov_b32_e32 v133, v139
	v_mov_b32_e32 v137, v139
	v_mov_b32_e32 v131, v139
	v_mov_b32_e32 v135, v139
	global_load_lds_dwordx4 v132, s[12:13]
	s_add_i32 m0, s46, 0x16000
	s_cmp_eq_u32 s5, 1
	global_load_lds_dwordx4 v136, s[12:13]
	v_readfirstlane_b32 s12, v150
	v_readfirstlane_b32 s13, v151
	s_mov_b32 m0, s46
	s_mov_b32 s50, 0
	v_lshl_add_u64 v[10:11], v[2:3], 0, v[132:133]
	v_lshl_add_u64 v[8:9], v[2:3], 0, v[136:137]
	v_lshl_add_u64 v[6:7], v[150:151], 0, v[134:135]
	global_load_lds_dwordx4 v130, s[12:13]
	s_mov_b32 m0, s47
	s_nop 0
	global_load_lds_dwordx4 v134, s[12:13]
	v_readfirstlane_b32 s12, v4
	v_readfirstlane_b32 s13, v5
	s_mov_b32 m0, s48
	v_lshl_add_u64 v[4:5], v[150:151], 0, v[130:131]
	s_nop 2
	global_load_lds_dwordx4 v130, s[12:13]
	s_mov_b32 m0, s49
	s_nop 0
	global_load_lds_dwordx4 v134, s[12:13]
	s_cselect_b64 s[12:13], -1, 0
	s_cmp_lg_u32 s5, 1
	s_cbranch_scc1 .LBB0_1069
	s_barrier
.LBB0_1069:
	s_and_b32 s20, s4, 3
	s_lshl_b32 s51, s5, 6
	s_lshl_b32 s5, s5, 13
	s_lshl_b32 s56, s20, 5
	s_lshl_b32 s18, s20, 12
	s_add_u32 s57, s38, 0x51a2000
	s_mov_b64 s[14:15], 0x80
	s_addc_u32 s58, s39, 0
	s_add_i32 m0, s46, 0x18000
	v_lshl_add_u64 v[10:11], v[10:11], 0, s[14:15]
	s_waitcnt vmcnt(2)
	s_barrier
	global_load_lds_dwordx4 v[10:11], off
	v_lshl_add_u64 v[8:9], v[8:9], 0, s[14:15]
	s_add_i32 m0, s46, 0x1a000
	s_add_i32 s59, s46, 0x8000
	global_load_lds_dwordx4 v[8:9], off
	v_lshl_add_u64 v[4:5], v[4:5], 0, s[14:15]
	s_mov_b32 m0, s59
	s_add_i32 s60, s46, 0xa000
	global_load_lds_dwordx4 v[4:5], off
	v_lshl_add_u64 v[4:5], v[6:7], 0, s[14:15]
	s_mov_b32 m0, s60
	s_mov_b64 s[16:17], 0xb0080
	global_load_lds_dwordx4 v[4:5], off
	v_lshl_add_u64 v[4:5], v[2:3], 0, s[16:17]
	s_add_i32 m0, s46, 0x1c000
	v_lshl_add_u64 v[6:7], v[4:5], 0, v[132:133]
	global_load_lds_dwordx4 v[6:7], off
	v_lshl_add_u64 v[4:5], v[4:5], 0, v[136:137]
	s_add_i32 m0, s46, 0x1e000
	v_and_b32_e32 v140, 15, v12
	global_load_lds_dwordx4 v[4:5], off
	v_bfe_u32 v4, v12, 4, 2
	v_lshlrev_b32_e32 v5, 4, v4
	v_lshlrev_b32_e32 v7, 2, v12
	v_lshl_or_b32 v6, v140, 6, v5
	v_and_b32_e32 v7, 32, v7
	s_cmpk_lt_u32 s6, 0x100
	v_bitop3_b32 v141, v6, s18, v7 bitop3:0xde
	s_cselect_b64 s[18:19], -1, 0
	s_lshl_b32 s4, s4, 6
	s_lshl_b32 s6, s20, 2
	v_bitop3_b32 v8, v6, s5, v7 bitop3:0xde
	v_and_or_b32 v158, s4, 64, v5
	v_cmp_eq_u32_e64 s[4:5], 0, v4
	s_add_u32 s61, s57, s6
	v_lshl_or_b32 v159, v4, 3, s56
	v_lshrrev_b32_e32 v5, 1, v17
	v_mul_lo_u32 v4, v19, s7
	s_mov_b32 s6, 0xb000
	v_mad_u64_u32 v[4:5], s[20:21], v5, s6, v[4:5]
	v_or_b32_e32 v4, v4, v18
	v_add_lshl_u32 v138, v4, v20, 1
	v_lshrrev_b32_e32 v5, 1, v13
	v_mul_lo_u32 v4, v14, s7
	v_mad_u64_u32 v[4:5], s[6:7], v5, s6, v[4:5]
	s_waitcnt vmcnt(6)
	v_or_b32_e32 v4, v4, v15
	v_lshl_add_u64 v[142:143], v[138:139], 0, s[16:17]
	v_add_lshl_u32 v138, v4, v16, 1
	v_mbcnt_lo_u32_b32 v4, -1, 0
	s_addc_u32 s62, s58, 0
	v_lshl_add_u64 v[144:145], v[138:139], 0, s[16:17]
	s_add_i32 s63, 0, 0x20020
	s_add_i32 s64, 0, 0x20018
	s_add_i32 s65, 0, 0x2002c
	s_add_i32 s66, 0, 0x20000
	s_mov_b64 s[20:21], 0x100
	s_add_i32 s67, 0, 0x10000
	s_add_i32 s68, 0, 0x14000
	v_add_u32_e32 v160, 0, v8
	s_add_i32 s69, 0, 0x20010
	s_add_i32 s72, 0, 0x20024
	s_movk_i32 s73, 0x7fff
	s_mov_b32 s22, 0xbfb8aa3b
	v_mbcnt_hi_u32_b32 v161, -1, v4
	v_mov_b64_e32 v[146:147], v[150:151]
	v_mov_b64_e32 v[148:149], v[2:3]
	s_barrier
	v_lshrrev_b32_e32 v242, 6, v1
	v_and_b32_e32 v243, 63, v1
	v_lshlrev_b32_e32 v245, 4, v243
	v_lshrrev_b32_e32 v244, 5, v243
	v_lshlrev_b32_e32 v244, 5, v244
	v_xor_b32_e32 v245, v245, v244
	v_lshrrev_b32_e32 v244, 1, v242
	v_lshlrev_b32_e32 v244, 4, v244
	v_lshrrev_b32_e32 v243, 6, v245
	v_add_u32_e32 v244, v244, v243
	v_and_b32_e32 v245, 63, v245
	v_and_b32_e32 v242, 1, v242
	v_lshl_add_u32 v245, v242, 6, v245
	v_mul_u32_u24_e32 v244, 0x1600, v244
	v_add_u32_e32 v240, v244, v245
	v_lshrrev_b32_e32 v242, 6, v1
	v_and_b32_e32 v243, 63, v1
	v_lshrrev_b32_e32 v244, 3, v243
	v_lshl_add_u32 v244, v242, 3, v244
	v_lshrrev_b32_e32 v245, 4, v243
	v_and_b32_e32 v245, 3, v245
	v_lshlrev_b32_e32 v245, 1, v245
	v_and_b32_e32 v243, 7, v243
	v_xor_b32_e32 v245, v243, v245
	v_lshlrev_b32_e32 v245, 4, v245
	v_mul_u32_u24_e32 v244, 0x1600, v244
	v_add_u32_e32 v241, v244, v245
	v_sub_u32_e32 v144, v144, v240
	v_add_u32_e32 v144, v144, v241
	v_lshrrev_b32_e32 v242, 6, v1
	v_and_b32_e32 v243, 63, v1
	v_lshlrev_b32_e32 v245, 4, v243
	v_lshrrev_b32_e32 v244, 5, v243
	v_lshlrev_b32_e32 v244, 5, v244
	v_xor_b32_e32 v245, v245, v244
	v_add_u32_e32 v242, 8, v242
	v_lshrrev_b32_e32 v244, 1, v242
	v_lshlrev_b32_e32 v244, 4, v244
	v_lshrrev_b32_e32 v243, 6, v245
	v_add_u32_e32 v244, v244, v243
	v_and_b32_e32 v245, 63, v245
	v_and_b32_e32 v242, 1, v242
	v_lshl_add_u32 v245, v242, 6, v245
	v_mul_u32_u24_e32 v244, 0x1600, v244
	v_add_u32_e32 v240, v244, v245
	v_lshrrev_b32_e32 v242, 6, v1
	v_and_b32_e32 v243, 63, v1
	v_lshrrev_b32_e32 v244, 3, v243
	v_lshl_add_u32 v244, v242, 3, v244
	v_add_u32_e32 v244, 64, v244
	v_lshrrev_b32_e32 v245, 4, v243
	v_and_b32_e32 v245, 3, v245
	v_lshlrev_b32_e32 v245, 1, v245
	v_and_b32_e32 v243, 7, v243
	v_xor_b32_e32 v245, v243, v245
	v_lshlrev_b32_e32 v245, 4, v245
	v_mul_u32_u24_e32 v244, 0x1600, v244
	v_add_u32_e32 v241, v244, v245
	v_sub_u32_e32 v142, v142, v240
	v_add_u32_e32 v142, v142, v241
	v_and_b32_e32 v240, 63, v1
	v_and_b32_e32 v241, 15, v240
	v_lshrrev_b32_e32 v242, 4, v240
	v_lshlrev_b32_e32 v243, 6, v241
	v_lshl_add_u32 v243, v242, 4, v243
	v_lshrrev_b32_e32 v244, 3, v241
	v_lshlrev_b32_e32 v245, 5, v244
	v_xor_b32_e32 v243, v243, v245
	v_sub_u32_e32 v160, v160, v243
	v_lshlrev_b32_e32 v244, 10, v244
	v_and_b32_e32 v245, 7, v241
	v_lshl_add_u32 v244, v245, 7, v244
	v_add_u32_e32 v160, v160, v244
	v_lshrrev_b32_e32 v245, 1, v245
	v_lshlrev_b32_e32 v245, 1, v245
	v_add_u32_e32 v244, 4, v242
	v_xor_b32_e32 v244, v244, v245
	v_lshl_add_u32 v238, v244, 4, v160
	v_xor_b32_e32 v244, v242, v245
	v_lshl_add_u32 v160, v244, 4, v160
	v_and_b32_e32 v240, 63, v1
	v_and_b32_e32 v241, 15, v240
	v_lshrrev_b32_e32 v242, 4, v240
	v_lshlrev_b32_e32 v243, 6, v241
	v_lshl_add_u32 v243, v242, 4, v243
	v_lshrrev_b32_e32 v244, 3, v241
	v_lshlrev_b32_e32 v245, 5, v244
	v_xor_b32_e32 v243, v243, v245
	v_sub_u32_e32 v141, v141, v243
	v_lshlrev_b32_e32 v244, 10, v244
	v_and_b32_e32 v245, 7, v241
	v_lshl_add_u32 v244, v245, 7, v244
	v_add_u32_e32 v141, v141, v244
	v_lshrrev_b32_e32 v245, 1, v245
	v_lshlrev_b32_e32 v245, 1, v245
	v_add_u32_e32 v244, 4, v242
	v_xor_b32_e32 v244, v244, v245
	v_lshl_add_u32 v239, v244, 4, v141
	v_xor_b32_e32 v244, v242, v245
	v_lshl_add_u32 v141, v244, 4, v141
	s_branch .LBB0_1072

.Lmy_nb_5:
	s_nop 0
	v_readfirstlane_b32 s86, v150
	v_readfirstlane_b32 s87, v151
	v_readfirstlane_b32 s88, v152
	v_readfirstlane_b32 s89, v153
	v_readfirstlane_b32 s90, v146
	v_readfirstlane_b32 s91, v147
	v_readfirstlane_b32 s92, v148
	v_readfirstlane_b32 s93, v149
	v_readfirstlane_b32 s100, v138
	v_readfirstlane_b32 s101, v156
	v_add_u32_e32 v230, s67, v141
	v_add_u32_e32 v234, s67, v239
	v_add_u32_e32 v231, s68, v141
	v_add_u32_e32 v235, s68, v239
	v_add_u32_e32 v232, 0x18000, v141
	v_add_u32_e32 v236, 0x18000, v239
	v_add_u32_e32 v233, 0x1c000, v141
	v_add_u32_e32 v237, 0x1c000, v239
	s_add_u32 s98, s86, 0x100
	s_addc_u32 s99, s87, 0
	s_cmp_eq_u32 s6, s100
	s_cselect_b64 s[94:95], s[90:91], s[98:99]
	s_cselect_b64 s[96:97], s[92:93], s[88:89]
	s_add_i32 s7, s6, 2
	s_add_i32 m0, s46, 0xc000
	ds_read_b128 v[164:167], v230
	global_load_lds_dwordx4 v144, s[86:87]
	s_add_i32 m0, s46, 0xe000
	ds_read_b128 v[168:171], v234
	global_load_lds_dwordx4 v142, s[86:87]
	ds_read_b128 v[172:175], v230 offset:2048
	ds_read_b128 v[176:179], v234 offset:2048
	ds_read_b128 v[180:183], v231
	ds_read_b128 v[184:187], v235
	ds_read_b128 v[188:191], v231 offset:2048
	ds_read_b128 v[192:195], v235 offset:2048
	ds_read_b128 v[196:199], v160
	ds_read_b128 v[200:203], v238
	ds_read_b128 v[204:207], v160 offset:2048
	ds_read_b128 v[208:211], v238 offset:2048
	ds_read_b128 v[212:215], v160 offset:4096
	ds_read_b128 v[216:219], v238 offset:4096
	ds_read_b128 v[220:223], v160 offset:6144
	ds_read_b128 v[224:227], v238 offset:6144
	s_waitcnt vmcnt(8)
	s_waitcnt lgkmcnt(0)
	s_setprio 1
	s_barrier
	v_mfma_f32_16x16x32_bf16 v[122:125], v[164:167], v[196:199], 0
	v_mfma_f32_16x16x32_bf16 v[118:121], v[172:175], v[196:199], 0
	v_mfma_f32_16x16x32_bf16 v[110:113], v[164:167], v[204:207], 0
	v_mfma_f32_16x16x32_bf16 v[102:105], v[172:175], v[204:207], 0
	v_mfma_f32_16x16x32_bf16 v[94:97], v[164:167], v[212:215], 0
	v_mfma_f32_16x16x32_bf16 v[86:89], v[172:175], v[212:215], 0
	v_mfma_f32_16x16x32_bf16 v[78:81], v[164:167], v[220:223], 0
	v_mfma_f32_16x16x32_bf16 v[70:73], v[172:175], v[220:223], 0
	v_mfma_f32_16x16x32_bf16 v[122:125], v[168:171], v[200:203], v[122:125]
	v_mfma_f32_16x16x32_bf16 v[118:121], v[176:179], v[200:203], v[118:121]
	v_mfma_f32_16x16x32_bf16 v[110:113], v[168:171], v[208:211], v[110:113]
	v_mfma_f32_16x16x32_bf16 v[102:105], v[176:179], v[208:211], v[102:105]
	v_mfma_f32_16x16x32_bf16 v[94:97], v[168:171], v[216:219], v[94:97]
	v_mfma_f32_16x16x32_bf16 v[86:89], v[176:179], v[216:219], v[86:89]
	v_mfma_f32_16x16x32_bf16 v[78:81], v[168:171], v[224:227], v[78:81]
	v_mfma_f32_16x16x32_bf16 v[70:73], v[176:179], v[224:227], v[70:73]
	v_mfma_f32_16x16x32_bf16 v[126:129], v[180:183], v[196:199], 0
	v_mfma_f32_16x16x32_bf16 v[114:117], v[188:191], v[196:199], 0
	v_mfma_f32_16x16x32_bf16 v[106:109], v[180:183], v[204:207], 0
	v_mfma_f32_16x16x32_bf16 v[98:101], v[188:191], v[204:207], 0
	v_mfma_f32_16x16x32_bf16 v[90:93], v[180:183], v[212:215], 0
	v_mfma_f32_16x16x32_bf16 v[82:85], v[188:191], v[212:215], 0
	v_mfma_f32_16x16x32_bf16 v[74:77], v[180:183], v[220:223], 0
	v_mfma_f32_16x16x32_bf16 v[66:69], v[188:191], v[220:223], 0
	v_mfma_f32_16x16x32_bf16 v[126:129], v[184:187], v[200:203], v[126:129]
	v_mfma_f32_16x16x32_bf16 v[114:117], v[192:195], v[200:203], v[114:117]
	v_mfma_f32_16x16x32_bf16 v[106:109], v[184:187], v[208:211], v[106:109]
	v_mfma_f32_16x16x32_bf16 v[98:101], v[192:195], v[208:211], v[98:101]
	v_mfma_f32_16x16x32_bf16 v[90:93], v[184:187], v[216:219], v[90:93]
	v_mfma_f32_16x16x32_bf16 v[82:85], v[192:195], v[216:219], v[82:85]
	v_mfma_f32_16x16x32_bf16 v[74:77], v[184:187], v[224:227], v[74:77]
	v_mfma_f32_16x16x32_bf16 v[66:69], v[192:195], v[224:227], v[66:69]
	s_barrier
	s_setprio 0
	s_add_u32 s98, s96, 0xb0000
	s_addc_u32 s99, s97, 0
	s_add_i32 s6, s67, s23
	s_mov_b32 m0, s6
	ds_read_b128 v[196:199], v160 offset:16384
	global_load_lds_dwordx4 v132, s[96:97]
	s_add_i32 m0, s6, 0x2000
	s_add_i32 s6, s68, s23
	global_load_lds_dwordx4 v136, s[96:97]
	s_mov_b32 m0, s6
	ds_read_b128 v[200:203], v238 offset:16384
	global_load_lds_dwordx4 v132, s[98:99]
	s_add_i32 m0, s6, 0x2000
	ds_read_b128 v[204:207], v160 offset:18432
	global_load_lds_dwordx4 v136, s[98:99]
	s_mov_b32 m0, s46
	ds_read_b128 v[208:211], v238 offset:18432
	global_load_lds_dwordx4 v130, s[94:95]
	s_mov_b32 m0, s47
	ds_read_b128 v[212:215], v160 offset:20480
	global_load_lds_dwordx4 v134, s[94:95]
	ds_read_b128 v[216:219], v238 offset:20480
	ds_read_b128 v[220:223], v160 offset:22528
	ds_read_b128 v[224:227], v238 offset:22528
	s_waitcnt vmcnt(8)
	s_waitcnt lgkmcnt(0)
	s_setprio 1
	s_barrier
	v_mfma_f32_16x16x32_bf16 v[62:65], v[164:167], v[196:199], 0
	v_mfma_f32_16x16x32_bf16 v[54:57], v[172:175], v[196:199], 0
	v_mfma_f32_16x16x32_bf16 v[46:49], v[164:167], v[204:207], 0
	v_mfma_f32_16x16x32_bf16 v[38:41], v[172:175], v[204:207], 0
	v_mfma_f32_16x16x32_bf16 v[30:33], v[164:167], v[212:215], 0
	v_mfma_f32_16x16x32_bf16 v[22:25], v[172:175], v[212:215], 0
	v_mfma_f32_16x16x32_bf16 v[14:17], v[164:167], v[220:223], 0
	v_mfma_f32_16x16x32_bf16 v[6:9], v[172:175], v[220:223], 0
	v_mfma_f32_16x16x32_bf16 v[62:65], v[168:171], v[200:203], v[62:65]
	v_mfma_f32_16x16x32_bf16 v[54:57], v[176:179], v[200:203], v[54:57]
	v_mfma_f32_16x16x32_bf16 v[46:49], v[168:171], v[208:211], v[46:49]
	v_mfma_f32_16x16x32_bf16 v[38:41], v[176:179], v[208:211], v[38:41]
	v_mfma_f32_16x16x32_bf16 v[30:33], v[168:171], v[216:219], v[30:33]
	v_mfma_f32_16x16x32_bf16 v[22:25], v[176:179], v[216:219], v[22:25]
	v_mfma_f32_16x16x32_bf16 v[14:17], v[168:171], v[224:227], v[14:17]
	v_mfma_f32_16x16x32_bf16 v[6:9], v[176:179], v[224:227], v[6:9]
	v_mfma_f32_16x16x32_bf16 v[58:61], v[180:183], v[196:199], 0
	v_mfma_f32_16x16x32_bf16 v[50:53], v[188:191], v[196:199], 0
	v_mfma_f32_16x16x32_bf16 v[42:45], v[180:183], v[204:207], 0
	v_mfma_f32_16x16x32_bf16 v[34:37], v[188:191], v[204:207], 0
	v_mfma_f32_16x16x32_bf16 v[26:29], v[180:183], v[212:215], 0
	v_mfma_f32_16x16x32_bf16 v[18:21], v[188:191], v[212:215], 0
	v_mfma_f32_16x16x32_bf16 v[10:13], v[180:183], v[220:223], 0
	v_mfma_f32_16x16x32_bf16 v[2:5], v[188:191], v[220:223], 0
	v_mfma_f32_16x16x32_bf16 v[58:61], v[184:187], v[200:203], v[58:61]
	v_mfma_f32_16x16x32_bf16 v[50:53], v[192:195], v[200:203], v[50:53]
	v_mfma_f32_16x16x32_bf16 v[42:45], v[184:187], v[208:211], v[42:45]
	v_mfma_f32_16x16x32_bf16 v[34:37], v[192:195], v[208:211], v[34:37]
	v_mfma_f32_16x16x32_bf16 v[26:29], v[184:187], v[216:219], v[26:29]
	v_mfma_f32_16x16x32_bf16 v[18:21], v[192:195], v[216:219], v[18:21]
	v_mfma_f32_16x16x32_bf16 v[10:13], v[184:187], v[224:227], v[10:13]
	v_mfma_f32_16x16x32_bf16 v[2:5], v[192:195], v[224:227], v[2:5]
	s_barrier
	s_setprio 0
	s_add_u32 s98, s94, 0xb0000
	s_addc_u32 s99, s95, 0
	s_add_i32 s6, 0, 0x18000
	s_add_i32 s29, 0, 0x1c000
	s_mov_b32 m0, s48
	ds_read_b128 v[164:167], v232
	global_load_lds_dwordx4 v130, s[98:99]
	s_mov_b32 m0, s49
	ds_read_b128 v[168:171], v236
	global_load_lds_dwordx4 v134, s[98:99]
	ds_read_b128 v[172:175], v232 offset:2048
	ds_read_b128 v[176:179], v236 offset:2048
	ds_read_b128 v[180:183], v233
	ds_read_b128 v[184:187], v237
	ds_read_b128 v[188:191], v233 offset:2048
	ds_read_b128 v[192:195], v237 offset:2048
	ds_read_b128 v[196:199], v160 offset:32768
	ds_read_b128 v[200:203], v238 offset:32768
	ds_read_b128 v[204:207], v160 offset:34816
	ds_read_b128 v[208:211], v238 offset:34816
	ds_read_b128 v[212:215], v160 offset:36864
	ds_read_b128 v[216:219], v238 offset:36864
	ds_read_b128 v[220:223], v160 offset:38912
	ds_read_b128 v[224:227], v238 offset:38912
	s_waitcnt vmcnt(8)
	s_waitcnt lgkmcnt(0)
	s_setprio 1
	s_barrier
	v_mfma_f32_16x16x32_bf16 v[122:125], v[164:167], v[196:199], v[122:125]
	v_mfma_f32_16x16x32_bf16 v[118:121], v[172:175], v[196:199], v[118:121]
	v_mfma_f32_16x16x32_bf16 v[110:113], v[164:167], v[204:207], v[110:113]
	v_mfma_f32_16x16x32_bf16 v[102:105], v[172:175], v[204:207], v[102:105]
	v_mfma_f32_16x16x32_bf16 v[94:97], v[164:167], v[212:215], v[94:97]
	v_mfma_f32_16x16x32_bf16 v[86:89], v[172:175], v[212:215], v[86:89]
	v_mfma_f32_16x16x32_bf16 v[78:81], v[164:167], v[220:223], v[78:81]
	v_mfma_f32_16x16x32_bf16 v[70:73], v[172:175], v[220:223], v[70:73]
	v_mfma_f32_16x16x32_bf16 v[122:125], v[168:171], v[200:203], v[122:125]
	v_mfma_f32_16x16x32_bf16 v[118:121], v[176:179], v[200:203], v[118:121]
	v_mfma_f32_16x16x32_bf16 v[110:113], v[168:171], v[208:211], v[110:113]
	v_mfma_f32_16x16x32_bf16 v[102:105], v[176:179], v[208:211], v[102:105]
	v_mfma_f32_16x16x32_bf16 v[94:97], v[168:171], v[216:219], v[94:97]
	v_mfma_f32_16x16x32_bf16 v[86:89], v[176:179], v[216:219], v[86:89]
	v_mfma_f32_16x16x32_bf16 v[78:81], v[168:171], v[224:227], v[78:81]
	v_mfma_f32_16x16x32_bf16 v[70:73], v[176:179], v[224:227], v[70:73]
	v_mfma_f32_16x16x32_bf16 v[126:129], v[180:183], v[196:199], v[126:129]
	v_mfma_f32_16x16x32_bf16 v[114:117], v[188:191], v[196:199], v[114:117]
	v_mfma_f32_16x16x32_bf16 v[106:109], v[180:183], v[204:207], v[106:109]
	v_mfma_f32_16x16x32_bf16 v[98:101], v[188:191], v[204:207], v[98:101]
	v_mfma_f32_16x16x32_bf16 v[90:93], v[180:183], v[212:215], v[90:93]
	v_mfma_f32_16x16x32_bf16 v[82:85], v[188:191], v[212:215], v[82:85]
	v_mfma_f32_16x16x32_bf16 v[74:77], v[180:183], v[220:223], v[74:77]
	v_mfma_f32_16x16x32_bf16 v[66:69], v[188:191], v[220:223], v[66:69]
	v_mfma_f32_16x16x32_bf16 v[126:129], v[184:187], v[200:203], v[126:129]
	v_mfma_f32_16x16x32_bf16 v[114:117], v[192:195], v[200:203], v[114:117]
	v_mfma_f32_16x16x32_bf16 v[106:109], v[184:187], v[208:211], v[106:109]
	v_mfma_f32_16x16x32_bf16 v[98:101], v[192:195], v[208:211], v[98:101]
	v_mfma_f32_16x16x32_bf16 v[90:93], v[184:187], v[216:219], v[90:93]
	v_mfma_f32_16x16x32_bf16 v[82:85], v[192:195], v[216:219], v[82:85]
	v_mfma_f32_16x16x32_bf16 v[74:77], v[184:187], v[224:227], v[74:77]
	v_mfma_f32_16x16x32_bf16 v[66:69], v[192:195], v[224:227], v[66:69]
	s_barrier
	s_setprio 0
	s_add_u32 s96, s96, 0x80
	s_addc_u32 s97, s97, 0
	s_add_u32 s98, s96, 0xb0000
	s_addc_u32 s99, s97, 0
	s_add_u32 s94, s94, 0x80
	s_addc_u32 s95, s95, 0
	s_add_i32 s6, s6, s23
	s_mov_b32 m0, s6
	ds_read_b128 v[196:199], v160 offset:49152
	global_load_lds_dwordx4 v132, s[96:97]
	s_add_i32 m0, s6, 0x2000
	s_add_i32 s6, s29, s23
	global_load_lds_dwordx4 v136, s[96:97]
	s_mov_b32 m0, s6
	ds_read_b128 v[200:203], v238 offset:49152
	global_load_lds_dwordx4 v132, s[98:99]
	s_add_i32 m0, s6, 0x2000
	ds_read_b128 v[204:207], v160 offset:51200
	global_load_lds_dwordx4 v136, s[98:99]
	s_mov_b32 m0, s59
	ds_read_b128 v[208:211], v238 offset:51200
	global_load_lds_dwordx4 v130, s[94:95]
	s_mov_b32 m0, s60
	ds_read_b128 v[212:215], v160 offset:53248
	global_load_lds_dwordx4 v134, s[94:95]
	ds_read_b128 v[216:219], v238 offset:53248
	ds_read_b128 v[220:223], v160 offset:55296
	ds_read_b128 v[224:227], v238 offset:55296
	s_waitcnt vmcnt(8)
	s_waitcnt lgkmcnt(0)
	s_setprio 1
	s_barrier
	v_mfma_f32_16x16x32_bf16 v[62:65], v[164:167], v[196:199], v[62:65]
	v_mfma_f32_16x16x32_bf16 v[54:57], v[172:175], v[196:199], v[54:57]
	v_mfma_f32_16x16x32_bf16 v[46:49], v[164:167], v[204:207], v[46:49]
	v_mfma_f32_16x16x32_bf16 v[38:41], v[172:175], v[204:207], v[38:41]
	v_mfma_f32_16x16x32_bf16 v[30:33], v[164:167], v[212:215], v[30:33]
	v_mfma_f32_16x16x32_bf16 v[22:25], v[172:175], v[212:215], v[22:25]
	v_mfma_f32_16x16x32_bf16 v[14:17], v[164:167], v[220:223], v[14:17]
	v_mfma_f32_16x16x32_bf16 v[6:9], v[172:175], v[220:223], v[6:9]
	v_mfma_f32_16x16x32_bf16 v[62:65], v[168:171], v[200:203], v[62:65]
	v_mfma_f32_16x16x32_bf16 v[54:57], v[176:179], v[200:203], v[54:57]
	v_mfma_f32_16x16x32_bf16 v[46:49], v[168:171], v[208:211], v[46:49]
	v_mfma_f32_16x16x32_bf16 v[38:41], v[176:179], v[208:211], v[38:41]
	v_mfma_f32_16x16x32_bf16 v[30:33], v[168:171], v[216:219], v[30:33]
	v_mfma_f32_16x16x32_bf16 v[22:25], v[176:179], v[216:219], v[22:25]
	v_mfma_f32_16x16x32_bf16 v[14:17], v[168:171], v[224:227], v[14:17]
	v_mfma_f32_16x16x32_bf16 v[6:9], v[176:179], v[224:227], v[6:9]
	v_mfma_f32_16x16x32_bf16 v[58:61], v[180:183], v[196:199], v[58:61]
	v_mfma_f32_16x16x32_bf16 v[50:53], v[188:191], v[196:199], v[50:53]
	v_mfma_f32_16x16x32_bf16 v[42:45], v[180:183], v[204:207], v[42:45]
	v_mfma_f32_16x16x32_bf16 v[34:37], v[188:191], v[204:207], v[34:37]
	v_mfma_f32_16x16x32_bf16 v[26:29], v[180:183], v[212:215], v[26:29]
	v_mfma_f32_16x16x32_bf16 v[18:21], v[188:191], v[212:215], v[18:21]
	v_mfma_f32_16x16x32_bf16 v[10:13], v[180:183], v[220:223], v[10:13]
	v_mfma_f32_16x16x32_bf16 v[2:5], v[188:191], v[220:223], v[2:5]
	v_mfma_f32_16x16x32_bf16 v[58:61], v[184:187], v[200:203], v[58:61]
	v_mfma_f32_16x16x32_bf16 v[50:53], v[192:195], v[200:203], v[50:53]
	v_mfma_f32_16x16x32_bf16 v[42:45], v[184:187], v[208:211], v[42:45]
	v_mfma_f32_16x16x32_bf16 v[34:37], v[192:195], v[208:211], v[34:37]
	v_mfma_f32_16x16x32_bf16 v[26:29], v[184:187], v[216:219], v[26:29]
	v_mfma_f32_16x16x32_bf16 v[18:21], v[192:195], v[216:219], v[18:21]
	v_mfma_f32_16x16x32_bf16 v[10:13], v[184:187], v[224:227], v[10:13]
	v_mfma_f32_16x16x32_bf16 v[2:5], v[192:195], v[224:227], v[2:5]
	s_barrier
	s_setprio 0
	s_mov_b32 s6, s7
	s_add_u32 s88, s88, 0x100
	s_addc_u32 s89, s89, 0
	s_add_u32 s86, s86, 0x100
	s_addc_u32 s87, s87, 0
	s_cmp_ge_i32 s7, s101
	s_cbranch_scc1 .Lmy_kexit_5
.LBB0_1080:
	s_add_u32 s98, s86, 0x100
	s_addc_u32 s99, s87, 0
	s_cmp_eq_u32 s6, s100
	s_cselect_b64 s[94:95], s[90:91], s[98:99]
	s_cselect_b64 s[96:97], s[92:93], s[88:89]
	s_add_i32 s7, s6, 2
	s_add_i32 m0, s46, 0xc000
	ds_read_b128 v[164:167], v230
	global_load_lds_dwordx4 v144, s[86:87]
	s_add_i32 m0, s46, 0xe000
	ds_read_b128 v[168:171], v234
	global_load_lds_dwordx4 v142, s[86:87]
	ds_read_b128 v[172:175], v230 offset:2048
	ds_read_b128 v[176:179], v234 offset:2048
	ds_read_b128 v[180:183], v231
	ds_read_b128 v[184:187], v235
	ds_read_b128 v[188:191], v231 offset:2048
	ds_read_b128 v[192:195], v235 offset:2048
	ds_read_b128 v[196:199], v160
	ds_read_b128 v[200:203], v238
	ds_read_b128 v[204:207], v160 offset:2048
	ds_read_b128 v[208:211], v238 offset:2048
	ds_read_b128 v[212:215], v160 offset:4096
	ds_read_b128 v[216:219], v238 offset:4096
	ds_read_b128 v[220:223], v160 offset:6144
	ds_read_b128 v[224:227], v238 offset:6144
	s_waitcnt vmcnt(8)
	s_waitcnt lgkmcnt(0)
	s_setprio 1
	s_barrier
	v_mfma_f32_16x16x32_bf16 v[122:125], v[164:167], v[196:199], v[122:125]
	v_mfma_f32_16x16x32_bf16 v[118:121], v[172:175], v[196:199], v[118:121]
	v_mfma_f32_16x16x32_bf16 v[110:113], v[164:167], v[204:207], v[110:113]
	v_mfma_f32_16x16x32_bf16 v[102:105], v[172:175], v[204:207], v[102:105]
	v_mfma_f32_16x16x32_bf16 v[94:97], v[164:167], v[212:215], v[94:97]
	v_mfma_f32_16x16x32_bf16 v[86:89], v[172:175], v[212:215], v[86:89]
	v_mfma_f32_16x16x32_bf16 v[78:81], v[164:167], v[220:223], v[78:81]
	v_mfma_f32_16x16x32_bf16 v[70:73], v[172:175], v[220:223], v[70:73]
	v_mfma_f32_16x16x32_bf16 v[122:125], v[168:171], v[200:203], v[122:125]
	v_mfma_f32_16x16x32_bf16 v[118:121], v[176:179], v[200:203], v[118:121]
	v_mfma_f32_16x16x32_bf16 v[110:113], v[168:171], v[208:211], v[110:113]
	v_mfma_f32_16x16x32_bf16 v[102:105], v[176:179], v[208:211], v[102:105]
	v_mfma_f32_16x16x32_bf16 v[94:97], v[168:171], v[216:219], v[94:97]
	v_mfma_f32_16x16x32_bf16 v[86:89], v[176:179], v[216:219], v[86:89]
	v_mfma_f32_16x16x32_bf16 v[78:81], v[168:171], v[224:227], v[78:81]
	v_mfma_f32_16x16x32_bf16 v[70:73], v[176:179], v[224:227], v[70:73]
	v_mfma_f32_16x16x32_bf16 v[126:129], v[180:183], v[196:199], v[126:129]
	v_mfma_f32_16x16x32_bf16 v[114:117], v[188:191], v[196:199], v[114:117]
	v_mfma_f32_16x16x32_bf16 v[106:109], v[180:183], v[204:207], v[106:109]
	v_mfma_f32_16x16x32_bf16 v[98:101], v[188:191], v[204:207], v[98:101]
	v_mfma_f32_16x16x32_bf16 v[90:93], v[180:183], v[212:215], v[90:93]
	v_mfma_f32_16x16x32_bf16 v[82:85], v[188:191], v[212:215], v[82:85]
	v_mfma_f32_16x16x32_bf16 v[74:77], v[180:183], v[220:223], v[74:77]
	v_mfma_f32_16x16x32_bf16 v[66:69], v[188:191], v[220:223], v[66:69]
	v_mfma_f32_16x16x32_bf16 v[126:129], v[184:187], v[200:203], v[126:129]
	v_mfma_f32_16x16x32_bf16 v[114:117], v[192:195], v[200:203], v[114:117]
	v_mfma_f32_16x16x32_bf16 v[106:109], v[184:187], v[208:211], v[106:109]
	v_mfma_f32_16x16x32_bf16 v[98:101], v[192:195], v[208:211], v[98:101]
	v_mfma_f32_16x16x32_bf16 v[90:93], v[184:187], v[216:219], v[90:93]
	v_mfma_f32_16x16x32_bf16 v[82:85], v[192:195], v[216:219], v[82:85]
	v_mfma_f32_16x16x32_bf16 v[74:77], v[184:187], v[224:227], v[74:77]
	v_mfma_f32_16x16x32_bf16 v[66:69], v[192:195], v[224:227], v[66:69]
	s_barrier
	s_setprio 0
	s_add_u32 s98, s96, 0xb0000
	s_addc_u32 s99, s97, 0
	s_add_i32 s6, s67, s23
	s_mov_b32 m0, s6
	ds_read_b128 v[196:199], v160 offset:16384
	global_load_lds_dwordx4 v132, s[96:97]
	s_add_i32 m0, s6, 0x2000
	s_add_i32 s6, s68, s23
	global_load_lds_dwordx4 v136, s[96:97]
	s_mov_b32 m0, s6
	ds_read_b128 v[200:203], v238 offset:16384
	global_load_lds_dwordx4 v132, s[98:99]
	s_add_i32 m0, s6, 0x2000
	ds_read_b128 v[204:207], v160 offset:18432
	global_load_lds_dwordx4 v136, s[98:99]
	s_mov_b32 m0, s46
	ds_read_b128 v[208:211], v238 offset:18432
	global_load_lds_dwordx4 v130, s[94:95]
	s_mov_b32 m0, s47
	ds_read_b128 v[212:215], v160 offset:20480
	global_load_lds_dwordx4 v134, s[94:95]
	ds_read_b128 v[216:219], v238 offset:20480
	ds_read_b128 v[220:223], v160 offset:22528
	ds_read_b128 v[224:227], v238 offset:22528
	s_waitcnt vmcnt(8)
	s_waitcnt lgkmcnt(0)
	s_setprio 1
	s_barrier
	v_mfma_f32_16x16x32_bf16 v[62:65], v[164:167], v[196:199], v[62:65]
	v_mfma_f32_16x16x32_bf16 v[54:57], v[172:175], v[196:199], v[54:57]
	v_mfma_f32_16x16x32_bf16 v[46:49], v[164:167], v[204:207], v[46:49]
	v_mfma_f32_16x16x32_bf16 v[38:41], v[172:175], v[204:207], v[38:41]
	v_mfma_f32_16x16x32_bf16 v[30:33], v[164:167], v[212:215], v[30:33]
	v_mfma_f32_16x16x32_bf16 v[22:25], v[172:175], v[212:215], v[22:25]
	v_mfma_f32_16x16x32_bf16 v[14:17], v[164:167], v[220:223], v[14:17]
	v_mfma_f32_16x16x32_bf16 v[6:9], v[172:175], v[220:223], v[6:9]
	v_mfma_f32_16x16x32_bf16 v[62:65], v[168:171], v[200:203], v[62:65]
	v_mfma_f32_16x16x32_bf16 v[54:57], v[176:179], v[200:203], v[54:57]
	v_mfma_f32_16x16x32_bf16 v[46:49], v[168:171], v[208:211], v[46:49]
	v_mfma_f32_16x16x32_bf16 v[38:41], v[176:179], v[208:211], v[38:41]
	v_mfma_f32_16x16x32_bf16 v[30:33], v[168:171], v[216:219], v[30:33]
	v_mfma_f32_16x16x32_bf16 v[22:25], v[176:179], v[216:219], v[22:25]
	v_mfma_f32_16x16x32_bf16 v[14:17], v[168:171], v[224:227], v[14:17]
	v_mfma_f32_16x16x32_bf16 v[6:9], v[176:179], v[224:227], v[6:9]
	v_mfma_f32_16x16x32_bf16 v[58:61], v[180:183], v[196:199], v[58:61]
	v_mfma_f32_16x16x32_bf16 v[50:53], v[188:191], v[196:199], v[50:53]
	v_mfma_f32_16x16x32_bf16 v[42:45], v[180:183], v[204:207], v[42:45]
	v_mfma_f32_16x16x32_bf16 v[34:37], v[188:191], v[204:207], v[34:37]
	v_mfma_f32_16x16x32_bf16 v[26:29], v[180:183], v[212:215], v[26:29]
	v_mfma_f32_16x16x32_bf16 v[18:21], v[188:191], v[212:215], v[18:21]
	v_mfma_f32_16x16x32_bf16 v[10:13], v[180:183], v[220:223], v[10:13]
	v_mfma_f32_16x16x32_bf16 v[2:5], v[188:191], v[220:223], v[2:5]
	v_mfma_f32_16x16x32_bf16 v[58:61], v[184:187], v[200:203], v[58:61]
	v_mfma_f32_16x16x32_bf16 v[50:53], v[192:195], v[200:203], v[50:53]
	v_mfma_f32_16x16x32_bf16 v[42:45], v[184:187], v[208:211], v[42:45]
	v_mfma_f32_16x16x32_bf16 v[34:37], v[192:195], v[208:211], v[34:37]
	v_mfma_f32_16x16x32_bf16 v[26:29], v[184:187], v[216:219], v[26:29]
	v_mfma_f32_16x16x32_bf16 v[18:21], v[192:195], v[216:219], v[18:21]
	v_mfma_f32_16x16x32_bf16 v[10:13], v[184:187], v[224:227], v[10:13]
	v_mfma_f32_16x16x32_bf16 v[2:5], v[192:195], v[224:227], v[2:5]
	s_barrier
	s_setprio 0
	s_add_u32 s98, s94, 0xb0000
	s_addc_u32 s99, s95, 0
	s_add_i32 s6, 0, 0x18000
	s_add_i32 s29, 0, 0x1c000
	s_mov_b32 m0, s48
	ds_read_b128 v[164:167], v232
	global_load_lds_dwordx4 v130, s[98:99]
	s_mov_b32 m0, s49
	ds_read_b128 v[168:171], v236
	global_load_lds_dwordx4 v134, s[98:99]
	ds_read_b128 v[172:175], v232 offset:2048
	ds_read_b128 v[176:179], v236 offset:2048
	ds_read_b128 v[180:183], v233
	ds_read_b128 v[184:187], v237
	ds_read_b128 v[188:191], v233 offset:2048
	ds_read_b128 v[192:195], v237 offset:2048
	ds_read_b128 v[196:199], v160 offset:32768
	ds_read_b128 v[200:203], v238 offset:32768
	ds_read_b128 v[204:207], v160 offset:34816
	ds_read_b128 v[208:211], v238 offset:34816
	ds_read_b128 v[212:215], v160 offset:36864
	ds_read_b128 v[216:219], v238 offset:36864
	ds_read_b128 v[220:223], v160 offset:38912
	ds_read_b128 v[224:227], v238 offset:38912
	s_waitcnt vmcnt(8)
	s_waitcnt lgkmcnt(0)
	s_setprio 1
	s_barrier
	v_mfma_f32_16x16x32_bf16 v[122:125], v[164:167], v[196:199], v[122:125]
	v_mfma_f32_16x16x32_bf16 v[118:121], v[172:175], v[196:199], v[118:121]
	v_mfma_f32_16x16x32_bf16 v[110:113], v[164:167], v[204:207], v[110:113]
	v_mfma_f32_16x16x32_bf16 v[102:105], v[172:175], v[204:207], v[102:105]
	v_mfma_f32_16x16x32_bf16 v[94:97], v[164:167], v[212:215], v[94:97]
	v_mfma_f32_16x16x32_bf16 v[86:89], v[172:175], v[212:215], v[86:89]
	v_mfma_f32_16x16x32_bf16 v[78:81], v[164:167], v[220:223], v[78:81]
	v_mfma_f32_16x16x32_bf16 v[70:73], v[172:175], v[220:223], v[70:73]
	v_mfma_f32_16x16x32_bf16 v[122:125], v[168:171], v[200:203], v[122:125]
	v_mfma_f32_16x16x32_bf16 v[118:121], v[176:179], v[200:203], v[118:121]
	v_mfma_f32_16x16x32_bf16 v[110:113], v[168:171], v[208:211], v[110:113]
	v_mfma_f32_16x16x32_bf16 v[102:105], v[176:179], v[208:211], v[102:105]
	v_mfma_f32_16x16x32_bf16 v[94:97], v[168:171], v[216:219], v[94:97]
	v_mfma_f32_16x16x32_bf16 v[86:89], v[176:179], v[216:219], v[86:89]
	v_mfma_f32_16x16x32_bf16 v[78:81], v[168:171], v[224:227], v[78:81]
	v_mfma_f32_16x16x32_bf16 v[70:73], v[176:179], v[224:227], v[70:73]
	v_mfma_f32_16x16x32_bf16 v[126:129], v[180:183], v[196:199], v[126:129]
	v_mfma_f32_16x16x32_bf16 v[114:117], v[188:191], v[196:199], v[114:117]
	v_mfma_f32_16x16x32_bf16 v[106:109], v[180:183], v[204:207], v[106:109]
	v_mfma_f32_16x16x32_bf16 v[98:101], v[188:191], v[204:207], v[98:101]
	v_mfma_f32_16x16x32_bf16 v[90:93], v[180:183], v[212:215], v[90:93]
	v_mfma_f32_16x16x32_bf16 v[82:85], v[188:191], v[212:215], v[82:85]
	v_mfma_f32_16x16x32_bf16 v[74:77], v[180:183], v[220:223], v[74:77]
	v_mfma_f32_16x16x32_bf16 v[66:69], v[188:191], v[220:223], v[66:69]
	v_mfma_f32_16x16x32_bf16 v[126:129], v[184:187], v[200:203], v[126:129]
	v_mfma_f32_16x16x32_bf16 v[114:117], v[192:195], v[200:203], v[114:117]
	v_mfma_f32_16x16x32_bf16 v[106:109], v[184:187], v[208:211], v[106:109]
	v_mfma_f32_16x16x32_bf16 v[98:101], v[192:195], v[208:211], v[98:101]
	v_mfma_f32_16x16x32_bf16 v[90:93], v[184:187], v[216:219], v[90:93]
	v_mfma_f32_16x16x32_bf16 v[82:85], v[192:195], v[216:219], v[82:85]
	v_mfma_f32_16x16x32_bf16 v[74:77], v[184:187], v[224:227], v[74:77]
	v_mfma_f32_16x16x32_bf16 v[66:69], v[192:195], v[224:227], v[66:69]
	s_barrier
	s_setprio 0
	s_add_u32 s96, s96, 0x80
	s_addc_u32 s97, s97, 0
	s_add_u32 s98, s96, 0xb0000
	s_addc_u32 s99, s97, 0
	s_add_u32 s94, s94, 0x80
	s_addc_u32 s95, s95, 0
	s_add_i32 s6, s6, s23
	s_mov_b32 m0, s6
	ds_read_b128 v[196:199], v160 offset:49152
	global_load_lds_dwordx4 v132, s[96:97]
	s_add_i32 m0, s6, 0x2000
	s_add_i32 s6, s29, s23
	global_load_lds_dwordx4 v136, s[96:97]
	s_mov_b32 m0, s6
	ds_read_b128 v[200:203], v238 offset:49152
	global_load_lds_dwordx4 v132, s[98:99]
	s_add_i32 m0, s6, 0x2000
	ds_read_b128 v[204:207], v160 offset:51200
	global_load_lds_dwordx4 v136, s[98:99]
	s_mov_b32 m0, s59
	ds_read_b128 v[208:211], v238 offset:51200
	global_load_lds_dwordx4 v130, s[94:95]
	s_mov_b32 m0, s60
	ds_read_b128 v[212:215], v160 offset:53248
	global_load_lds_dwordx4 v134, s[94:95]
	ds_read_b128 v[216:219], v238 offset:53248
	ds_read_b128 v[220:223], v160 offset:55296
	ds_read_b128 v[224:227], v238 offset:55296
	s_waitcnt vmcnt(8)
	s_waitcnt lgkmcnt(0)
	s_setprio 1
	s_barrier
	v_mfma_f32_16x16x32_bf16 v[62:65], v[164:167], v[196:199], v[62:65]
	v_mfma_f32_16x16x32_bf16 v[54:57], v[172:175], v[196:199], v[54:57]
	v_mfma_f32_16x16x32_bf16 v[46:49], v[164:167], v[204:207], v[46:49]
	v_mfma_f32_16x16x32_bf16 v[38:41], v[172:175], v[204:207], v[38:41]
	v_mfma_f32_16x16x32_bf16 v[30:33], v[164:167], v[212:215], v[30:33]
	v_mfma_f32_16x16x32_bf16 v[22:25], v[172:175], v[212:215], v[22:25]
	v_mfma_f32_16x16x32_bf16 v[14:17], v[164:167], v[220:223], v[14:17]
	v_mfma_f32_16x16x32_bf16 v[6:9], v[172:175], v[220:223], v[6:9]
	v_mfma_f32_16x16x32_bf16 v[62:65], v[168:171], v[200:203], v[62:65]
	v_mfma_f32_16x16x32_bf16 v[54:57], v[176:179], v[200:203], v[54:57]
	v_mfma_f32_16x16x32_bf16 v[46:49], v[168:171], v[208:211], v[46:49]
	v_mfma_f32_16x16x32_bf16 v[38:41], v[176:179], v[208:211], v[38:41]
	v_mfma_f32_16x16x32_bf16 v[30:33], v[168:171], v[216:219], v[30:33]
	v_mfma_f32_16x16x32_bf16 v[22:25], v[176:179], v[216:219], v[22:25]
	v_mfma_f32_16x16x32_bf16 v[14:17], v[168:171], v[224:227], v[14:17]
	v_mfma_f32_16x16x32_bf16 v[6:9], v[176:179], v[224:227], v[6:9]
	v_mfma_f32_16x16x32_bf16 v[58:61], v[180:183], v[196:199], v[58:61]
	v_mfma_f32_16x16x32_bf16 v[50:53], v[188:191], v[196:199], v[50:53]
	v_mfma_f32_16x16x32_bf16 v[42:45], v[180:183], v[204:207], v[42:45]
	v_mfma_f32_16x16x32_bf16 v[34:37], v[188:191], v[204:207], v[34:37]
	v_mfma_f32_16x16x32_bf16 v[26:29], v[180:183], v[212:215], v[26:29]
	v_mfma_f32_16x16x32_bf16 v[18:21], v[188:191], v[212:215], v[18:21]
	v_mfma_f32_16x16x32_bf16 v[10:13], v[180:183], v[220:223], v[10:13]
	v_mfma_f32_16x16x32_bf16 v[2:5], v[188:191], v[220:223], v[2:5]
	v_mfma_f32_16x16x32_bf16 v[58:61], v[184:187], v[200:203], v[58:61]
	v_mfma_f32_16x16x32_bf16 v[50:53], v[192:195], v[200:203], v[50:53]
	v_mfma_f32_16x16x32_bf16 v[42:45], v[184:187], v[208:211], v[42:45]
	v_mfma_f32_16x16x32_bf16 v[34:37], v[192:195], v[208:211], v[34:37]
	v_mfma_f32_16x16x32_bf16 v[26:29], v[184:187], v[216:219], v[26:29]
	v_mfma_f32_16x16x32_bf16 v[18:21], v[192:195], v[216:219], v[18:21]
	v_mfma_f32_16x16x32_bf16 v[10:13], v[184:187], v[224:227], v[10:13]
	v_mfma_f32_16x16x32_bf16 v[2:5], v[192:195], v[224:227], v[2:5]
	s_barrier
	s_setprio 0
	s_mov_b32 s6, s7
	s_add_u32 s88, s88, 0x100
	s_addc_u32 s89, s89, 0
	s_add_u32 s86, s86, 0x100
	s_addc_u32 s87, s87, 0
	s_cmp_ge_i32 s7, s101
	s_cbranch_scc0 .LBB0_1080

.LBB0_1254:
	s_mov_b64 s[16:17], 0x80
	s_add_i32 m0, s51, 0x18000
	v_lshl_add_u64 v[12:13], v[12:13], 0, s[16:17]
	s_waitcnt vmcnt(2)
	s_barrier
	global_load_lds_dwordx4 v[12:13], off
	v_lshl_add_u64 v[10:11], v[10:11], 0, s[16:17]
	s_add_i32 m0, s51, 0x1a000
	s_add_i32 s63, s51, 0x8000
	global_load_lds_dwordx4 v[10:11], off
	v_lshl_add_u64 v[6:7], v[6:7], 0, s[16:17]
	s_mov_b32 m0, s63
	s_add_i32 s64, s51, 0xa000
	global_load_lds_dwordx4 v[6:7], off
	v_lshl_add_u64 v[6:7], v[8:9], 0, s[16:17]
	s_mov_b32 m0, s64
	s_mov_b64 s[18:19], 0x40080
	global_load_lds_dwordx4 v[6:7], off
	v_lshl_add_u64 v[6:7], v[4:5], 0, s[18:19]
	s_add_i32 m0, s51, 0x1c000
	v_lshl_add_u64 v[8:9], v[6:7], 0, v[132:133]
	global_load_lds_dwordx4 v[8:9], off
	v_lshl_add_u64 v[6:7], v[6:7], 0, v[136:137]
	s_add_i32 m0, s51, 0x1e000
	v_and_b32_e32 v140, 15, v14
	global_load_lds_dwordx4 v[6:7], off
	v_bfe_u32 v6, v14, 4, 2
	v_lshlrev_b32_e32 v7, 4, v6
	v_lshlrev_b32_e32 v9, 2, v14
	s_and_b32 s7, s4, 3
	s_lshl_b32 s65, s5, 6
	v_lshl_or_b32 v8, v140, 6, v7
	s_lshl_b32 s5, s5, 13
	v_and_b32_e32 v9, 32, v9
	v_bitop3_b32 v10, v8, s5, v9 bitop3:0xde
	s_lshl_b32 s66, s7, 5
	s_lshl_b32 s5, s7, 12
	s_cmpk_lt_u32 s12, 0x100
	s_cselect_b64 s[20:21], -1, 0
	s_lshl_b32 s4, s4, 6
	v_bitop3_b32 v141, v8, s5, v9 bitop3:0xde
	v_and_or_b32 v158, s4, 64, v7
	v_cmp_eq_u32_e64 s[4:5], 0, v6
	v_lshl_or_b32 v159, v6, 3, s66
	v_lshlrev_b32_e32 v6, 14, v18
	v_and_b32_e32 v6, 0xffff8000, v6
	v_lshl_add_u32 v6, v19, 11, v6
	v_and_b32_e32 v7, 1, v18
	v_lshl_or_b32 v6, v7, 6, v6
	v_lshl_add_u32 v142, v20, 1, v6
	v_lshlrev_b32_e32 v6, 14, v15
	v_and_b32_e32 v6, 0xffff8000, v6
	v_lshl_add_u32 v6, v16, 11, v6
	v_and_b32_e32 v7, 1, v15
	s_waitcnt vmcnt(6)
	v_lshl_or_b32 v6, v7, 6, v6
	s_add_i32 s74, 0, 0x10000
	v_lshl_add_u32 v144, v17, 1, v6
	s_mov_b32 s24, 0xfffc0080
	s_add_i32 s78, s74, s29
	v_mbcnt_lo_u32_b32 v6, -1, 0
	s_lshl_b32 s12, s7, 2
	v_mov_b32_e32 v143, v139
	v_mov_b32_e32 v145, v139
	s_movk_i32 s67, 0x161
	s_add_i32 s70, 0, 0x20020
	s_add_i32 s71, 0, 0x20018
	s_add_i32 s72, 0, 0x2002c
	s_add_i32 s73, 0, 0x20000
	s_mov_b64 s[22:23], 0x100
	s_mov_b32 s25, -1
	s_add_i32 s75, 0, 0x14000
	v_add_u32_e32 v160, 0, v10
	s_add_i32 s76, s51, 0xc000
	s_add_i32 s77, s51, 0xe000
	s_add_i32 s79, s78, 0x2000
	s_add_i32 s80, 0, 0x20010
	s_add_i32 s81, 0, 0x20024
	s_movk_i32 s82, 0x7fff
	s_mov_b32 s28, 0xbfb8aa3b
	v_mbcnt_hi_u32_b32 v161, -1, v6
	s_mov_b32 s83, s13
	v_mov_b64_e32 v[148:149], v[4:5]
	v_mov_b64_e32 v[146:147], v[2:3]
	s_barrier
	v_lshrrev_b32_e32 v242, 6, v1
	v_and_b32_e32 v243, 63, v1
	v_lshlrev_b32_e32 v245, 4, v243
	v_lshrrev_b32_e32 v244, 5, v243
	v_lshlrev_b32_e32 v244, 5, v244
	v_xor_b32_e32 v245, v245, v244
	v_lshrrev_b32_e32 v244, 1, v242
	v_lshlrev_b32_e32 v244, 4, v244
	v_lshrrev_b32_e32 v243, 6, v245
	v_add_u32_e32 v244, v244, v243
	v_and_b32_e32 v245, 63, v245
	v_and_b32_e32 v242, 1, v242
	v_lshl_add_u32 v245, v242, 6, v245
	v_mul_u32_u24_e32 v244, 0x800, v244
	v_add_u32_e32 v240, v244, v245
	v_lshrrev_b32_e32 v242, 6, v1
	v_and_b32_e32 v243, 63, v1
	v_lshrrev_b32_e32 v244, 3, v243
	v_lshl_add_u32 v244, v242, 3, v244
	v_lshrrev_b32_e32 v245, 4, v243
	v_and_b32_e32 v245, 3, v245
	v_lshlrev_b32_e32 v245, 1, v245
	v_and_b32_e32 v243, 7, v243
	v_xor_b32_e32 v245, v243, v245
	v_lshlrev_b32_e32 v245, 4, v245
	v_mul_u32_u24_e32 v244, 0x800, v244
	v_add_u32_e32 v241, v244, v245
	v_sub_u32_e32 v144, v144, v240
	v_add_u32_e32 v144, v144, v241
	v_lshrrev_b32_e32 v242, 6, v1
	v_and_b32_e32 v243, 63, v1
	v_lshlrev_b32_e32 v245, 4, v243
	v_lshrrev_b32_e32 v244, 5, v243
	v_lshlrev_b32_e32 v244, 5, v244
	v_xor_b32_e32 v245, v245, v244
	v_add_u32_e32 v242, 8, v242
	v_lshrrev_b32_e32 v244, 1, v242
	v_lshlrev_b32_e32 v244, 4, v244
	v_lshrrev_b32_e32 v243, 6, v245
	v_add_u32_e32 v244, v244, v243
	v_and_b32_e32 v245, 63, v245
	v_and_b32_e32 v242, 1, v242
	v_lshl_add_u32 v245, v242, 6, v245
	v_mul_u32_u24_e32 v244, 0x800, v244
	v_add_u32_e32 v240, v244, v245
	v_lshrrev_b32_e32 v242, 6, v1
	v_and_b32_e32 v243, 63, v1
	v_lshrrev_b32_e32 v244, 3, v243
	v_lshl_add_u32 v244, v242, 3, v244
	v_add_u32_e32 v244, 64, v244
	v_lshrrev_b32_e32 v245, 4, v243
	v_and_b32_e32 v245, 3, v245
	v_lshlrev_b32_e32 v245, 1, v245
	v_and_b32_e32 v243, 7, v243
	v_xor_b32_e32 v245, v243, v245
	v_lshlrev_b32_e32 v245, 4, v245
	v_mul_u32_u24_e32 v244, 0x800, v244
	v_add_u32_e32 v241, v244, v245
	v_sub_u32_e32 v142, v142, v240
	v_add_u32_e32 v142, v142, v241
	v_and_b32_e32 v240, 63, v1
	v_and_b32_e32 v241, 15, v240
	v_lshrrev_b32_e32 v242, 4, v240
	v_lshlrev_b32_e32 v243, 6, v241
	v_lshl_add_u32 v243, v242, 4, v243
	v_lshrrev_b32_e32 v244, 3, v241
	v_lshlrev_b32_e32 v245, 5, v244
	v_xor_b32_e32 v243, v243, v245
	v_sub_u32_e32 v160, v160, v243
	v_lshlrev_b32_e32 v244, 10, v244
	v_and_b32_e32 v245, 7, v241
	v_lshl_add_u32 v244, v245, 7, v244
	v_add_u32_e32 v160, v160, v244
	v_lshrrev_b32_e32 v245, 1, v245
	v_lshlrev_b32_e32 v245, 1, v245
	v_add_u32_e32 v244, 4, v242
	v_xor_b32_e32 v244, v244, v245
	v_lshl_add_u32 v238, v244, 4, v160
	v_xor_b32_e32 v244, v242, v245
	v_lshl_add_u32 v160, v244, 4, v160
	v_and_b32_e32 v240, 63, v1
	v_and_b32_e32 v241, 15, v240
	v_lshrrev_b32_e32 v242, 4, v240
	v_lshlrev_b32_e32 v243, 6, v241
	v_lshl_add_u32 v243, v242, 4, v243
	v_lshrrev_b32_e32 v244, 3, v241
	v_lshlrev_b32_e32 v245, 5, v244
	v_xor_b32_e32 v243, v243, v245
	v_sub_u32_e32 v141, v141, v243
	v_lshlrev_b32_e32 v244, 10, v244
	v_and_b32_e32 v245, 7, v241
	v_lshl_add_u32 v244, v245, 7, v244
	v_add_u32_e32 v141, v141, v244
	v_lshrrev_b32_e32 v245, 1, v245
	v_lshlrev_b32_e32 v245, 1, v245
	v_add_u32_e32 v244, 4, v242
	v_xor_b32_e32 v244, v244, v245
	v_lshl_add_u32 v239, v244, 4, v141
	v_xor_b32_e32 v244, v242, v245
	v_lshl_add_u32 v141, v244, 4, v141
	s_branch .LBB0_1257

.LBB0_1381:
	s_and_b32 s20, s4, 3
	s_lshl_b32 s51, s5, 6
	s_lshl_b32 s5, s5, 13
	s_lshl_b32 s56, s20, 5
	s_lshl_b32 s18, s20, 12
	s_add_u32 s57, s38, 0x51a2000
	s_mov_b64 s[14:15], 0x80
	s_addc_u32 s58, s39, 0
	s_add_i32 m0, s46, 0x18000
	v_lshl_add_u64 v[10:11], v[10:11], 0, s[14:15]
	s_waitcnt vmcnt(2)
	s_barrier
	global_load_lds_dwordx4 v[10:11], off
	v_lshl_add_u64 v[8:9], v[8:9], 0, s[14:15]
	s_add_i32 m0, s46, 0x1a000
	s_add_i32 s59, s46, 0x8000
	global_load_lds_dwordx4 v[8:9], off
	v_lshl_add_u64 v[4:5], v[4:5], 0, s[14:15]
	s_mov_b32 m0, s59
	s_add_i32 s60, s46, 0xa000
	global_load_lds_dwordx4 v[4:5], off
	v_lshl_add_u64 v[4:5], v[6:7], 0, s[14:15]
	s_mov_b32 m0, s60
	s_mov_b64 s[16:17], 0xb0080
	global_load_lds_dwordx4 v[4:5], off
	v_lshl_add_u64 v[4:5], v[2:3], 0, s[16:17]
	s_add_i32 m0, s46, 0x1c000
	v_lshl_add_u64 v[6:7], v[4:5], 0, v[132:133]
	global_load_lds_dwordx4 v[6:7], off
	v_lshl_add_u64 v[4:5], v[4:5], 0, v[136:137]
	s_add_i32 m0, s46, 0x1e000
	v_and_b32_e32 v140, 15, v12
	global_load_lds_dwordx4 v[4:5], off
	v_bfe_u32 v4, v12, 4, 2
	v_lshlrev_b32_e32 v5, 4, v4
	v_lshlrev_b32_e32 v7, 2, v12
	v_lshl_or_b32 v6, v140, 6, v5
	v_and_b32_e32 v7, 32, v7
	s_cmpk_lt_u32 s6, 0x100
	v_bitop3_b32 v141, v6, s18, v7 bitop3:0xde
	s_cselect_b64 s[18:19], -1, 0
	s_lshl_b32 s4, s4, 6
	s_lshl_b32 s6, s20, 2
	v_bitop3_b32 v8, v6, s5, v7 bitop3:0xde
	v_and_or_b32 v158, s4, 64, v5
	v_cmp_eq_u32_e64 s[4:5], 0, v4
	s_add_u32 s61, s57, s6
	v_lshl_or_b32 v159, v4, 3, s56
	v_lshrrev_b32_e32 v5, 1, v17
	v_mul_lo_u32 v4, v19, s7
	s_mov_b32 s6, 0xb000
	v_mad_u64_u32 v[4:5], s[20:21], v5, s6, v[4:5]
	v_or_b32_e32 v4, v4, v18
	v_add_lshl_u32 v138, v4, v20, 1
	v_lshrrev_b32_e32 v5, 1, v13
	v_mul_lo_u32 v4, v14, s7
	v_mad_u64_u32 v[4:5], s[6:7], v5, s6, v[4:5]
	s_waitcnt vmcnt(6)
	v_or_b32_e32 v4, v4, v15
	v_lshl_add_u64 v[142:143], v[138:139], 0, s[16:17]
	v_add_lshl_u32 v138, v4, v16, 1
	v_mbcnt_lo_u32_b32 v4, -1, 0
	s_addc_u32 s62, s58, 0
	v_lshl_add_u64 v[144:145], v[138:139], 0, s[16:17]
	s_add_i32 s63, 0, 0x20020
	s_add_i32 s64, 0, 0x20018
	s_add_i32 s65, 0, 0x2002c
	s_add_i32 s66, 0, 0x20000
	s_mov_b64 s[20:21], 0x100
	s_add_i32 s67, 0, 0x10000
	s_add_i32 s70, 0, 0x14000
	v_add_u32_e32 v160, 0, v8
	s_add_i32 s71, 0, 0x20010
	s_add_i32 s72, 0, 0x20024
	s_movk_i32 s73, 0x7fff
	s_mov_b32 s22, 0xbfb8aa3b
	v_mbcnt_hi_u32_b32 v161, -1, v4
	v_mov_b64_e32 v[146:147], v[150:151]
	v_mov_b64_e32 v[148:149], v[2:3]
	s_barrier
	v_lshrrev_b32_e32 v242, 6, v1
	v_and_b32_e32 v243, 63, v1
	v_lshlrev_b32_e32 v245, 4, v243
	v_lshrrev_b32_e32 v244, 5, v243
	v_lshlrev_b32_e32 v244, 5, v244
	v_xor_b32_e32 v245, v245, v244
	v_lshrrev_b32_e32 v244, 1, v242
	v_lshlrev_b32_e32 v244, 4, v244
	v_lshrrev_b32_e32 v243, 6, v245
	v_add_u32_e32 v244, v244, v243
	v_and_b32_e32 v245, 63, v245
	v_and_b32_e32 v242, 1, v242
	v_lshl_add_u32 v245, v242, 6, v245
	v_mul_u32_u24_e32 v244, 0x1600, v244
	v_add_u32_e32 v240, v244, v245
	v_lshrrev_b32_e32 v242, 6, v1
	v_and_b32_e32 v243, 63, v1
	v_lshrrev_b32_e32 v244, 3, v243
	v_lshl_add_u32 v244, v242, 3, v244
	v_lshrrev_b32_e32 v245, 4, v243
	v_and_b32_e32 v245, 3, v245
	v_lshlrev_b32_e32 v245, 1, v245
	v_and_b32_e32 v243, 7, v243
	v_xor_b32_e32 v245, v243, v245
	v_lshlrev_b32_e32 v245, 4, v245
	v_mul_u32_u24_e32 v244, 0x1600, v244
	v_add_u32_e32 v241, v244, v245
	v_sub_u32_e32 v144, v144, v240
	v_add_u32_e32 v144, v144, v241
	v_lshrrev_b32_e32 v242, 6, v1
	v_and_b32_e32 v243, 63, v1
	v_lshlrev_b32_e32 v245, 4, v243
	v_lshrrev_b32_e32 v244, 5, v243
	v_lshlrev_b32_e32 v244, 5, v244
	v_xor_b32_e32 v245, v245, v244
	v_add_u32_e32 v242, 8, v242
	v_lshrrev_b32_e32 v244, 1, v242
	v_lshlrev_b32_e32 v244, 4, v244
	v_lshrrev_b32_e32 v243, 6, v245
	v_add_u32_e32 v244, v244, v243
	v_and_b32_e32 v245, 63, v245
	v_and_b32_e32 v242, 1, v242
	v_lshl_add_u32 v245, v242, 6, v245
	v_mul_u32_u24_e32 v244, 0x1600, v244
	v_add_u32_e32 v240, v244, v245
	v_lshrrev_b32_e32 v242, 6, v1
	v_and_b32_e32 v243, 63, v1
	v_lshrrev_b32_e32 v244, 3, v243
	v_lshl_add_u32 v244, v242, 3, v244
	v_add_u32_e32 v244, 64, v244
	v_lshrrev_b32_e32 v245, 4, v243
	v_and_b32_e32 v245, 3, v245
	v_lshlrev_b32_e32 v245, 1, v245
	v_and_b32_e32 v243, 7, v243
	v_xor_b32_e32 v245, v243, v245
	v_lshlrev_b32_e32 v245, 4, v245
	v_mul_u32_u24_e32 v244, 0x1600, v244
	v_add_u32_e32 v241, v244, v245
	v_sub_u32_e32 v142, v142, v240
	v_add_u32_e32 v142, v142, v241
	v_and_b32_e32 v240, 63, v1
	v_and_b32_e32 v241, 15, v240
	v_lshrrev_b32_e32 v242, 4, v240
	v_lshlrev_b32_e32 v243, 6, v241
	v_lshl_add_u32 v243, v242, 4, v243
	v_lshrrev_b32_e32 v244, 3, v241
	v_lshlrev_b32_e32 v245, 5, v244
	v_xor_b32_e32 v243, v243, v245
	v_sub_u32_e32 v160, v160, v243
	v_lshlrev_b32_e32 v244, 10, v244
	v_and_b32_e32 v245, 7, v241
	v_lshl_add_u32 v244, v245, 7, v244
	v_add_u32_e32 v160, v160, v244
	v_lshrrev_b32_e32 v245, 1, v245
	v_lshlrev_b32_e32 v245, 1, v245
	v_add_u32_e32 v244, 4, v242
	v_xor_b32_e32 v244, v244, v245
	v_lshl_add_u32 v238, v244, 4, v160
	v_xor_b32_e32 v244, v242, v245
	v_lshl_add_u32 v160, v244, 4, v160
	v_and_b32_e32 v240, 63, v1
	v_and_b32_e32 v241, 15, v240
	v_lshrrev_b32_e32 v242, 4, v240
	v_lshlrev_b32_e32 v243, 6, v241
	v_lshl_add_u32 v243, v242, 4, v243
	v_lshrrev_b32_e32 v244, 3, v241
	v_lshlrev_b32_e32 v245, 5, v244
	v_xor_b32_e32 v243, v243, v245
	v_sub_u32_e32 v141, v141, v243
	v_lshlrev_b32_e32 v244, 10, v244
	v_and_b32_e32 v245, 7, v241
	v_lshl_add_u32 v244, v245, 7, v244
	v_add_u32_e32 v141, v141, v244
	v_lshrrev_b32_e32 v245, 1, v245
	v_lshlrev_b32_e32 v245, 1, v245
	v_add_u32_e32 v244, 4, v242
	v_xor_b32_e32 v244, v244, v245
	v_lshl_add_u32 v239, v244, 4, v141
	v_xor_b32_e32 v244, v242, v245
	v_lshl_add_u32 v141, v244, 4, v141
	s_branch .LBB0_1384

.Lmy_nb_7:
	s_nop 0
	v_readfirstlane_b32 s86, v150
	v_readfirstlane_b32 s87, v151
	v_readfirstlane_b32 s88, v152
	v_readfirstlane_b32 s89, v153
	v_readfirstlane_b32 s90, v146
	v_readfirstlane_b32 s91, v147
	v_readfirstlane_b32 s92, v148
	v_readfirstlane_b32 s93, v149
	v_readfirstlane_b32 s100, v138
	v_readfirstlane_b32 s101, v156
	v_add_u32_e32 v230, s67, v141
	v_add_u32_e32 v234, s67, v239
	v_add_u32_e32 v231, s70, v141
	v_add_u32_e32 v235, s70, v239
	v_add_u32_e32 v232, 0x18000, v141
	v_add_u32_e32 v236, 0x18000, v239
	v_add_u32_e32 v233, 0x1c000, v141
	v_add_u32_e32 v237, 0x1c000, v239
	s_add_u32 s98, s86, 0x100
	s_addc_u32 s99, s87, 0
	s_cmp_eq_u32 s6, s100
	s_cselect_b64 s[94:95], s[90:91], s[98:99]
	s_cselect_b64 s[96:97], s[92:93], s[88:89]
	s_add_i32 s7, s6, 2
	s_add_i32 m0, s46, 0xc000
	ds_read_b128 v[164:167], v230
	global_load_lds_dwordx4 v144, s[86:87]
	s_add_i32 m0, s46, 0xe000
	ds_read_b128 v[168:171], v234
	global_load_lds_dwordx4 v142, s[86:87]
	ds_read_b128 v[172:175], v230 offset:2048
	ds_read_b128 v[176:179], v234 offset:2048
	ds_read_b128 v[180:183], v231
	ds_read_b128 v[184:187], v235
	ds_read_b128 v[188:191], v231 offset:2048
	ds_read_b128 v[192:195], v235 offset:2048
	ds_read_b128 v[196:199], v160
	ds_read_b128 v[200:203], v238
	ds_read_b128 v[204:207], v160 offset:2048
	ds_read_b128 v[208:211], v238 offset:2048
	ds_read_b128 v[212:215], v160 offset:4096
	ds_read_b128 v[216:219], v238 offset:4096
	ds_read_b128 v[220:223], v160 offset:6144
	ds_read_b128 v[224:227], v238 offset:6144
	s_waitcnt vmcnt(8)
	s_waitcnt lgkmcnt(0)
	s_setprio 1
	s_barrier
	v_mfma_f32_16x16x32_bf16 v[122:125], v[164:167], v[196:199], 0
	v_mfma_f32_16x16x32_bf16 v[118:121], v[172:175], v[196:199], 0
	v_mfma_f32_16x16x32_bf16 v[110:113], v[164:167], v[204:207], 0
	v_mfma_f32_16x16x32_bf16 v[102:105], v[172:175], v[204:207], 0
	v_mfma_f32_16x16x32_bf16 v[94:97], v[164:167], v[212:215], 0
	v_mfma_f32_16x16x32_bf16 v[86:89], v[172:175], v[212:215], 0
	v_mfma_f32_16x16x32_bf16 v[78:81], v[164:167], v[220:223], 0
	v_mfma_f32_16x16x32_bf16 v[70:73], v[172:175], v[220:223], 0
	v_mfma_f32_16x16x32_bf16 v[122:125], v[168:171], v[200:203], v[122:125]
	v_mfma_f32_16x16x32_bf16 v[118:121], v[176:179], v[200:203], v[118:121]
	v_mfma_f32_16x16x32_bf16 v[110:113], v[168:171], v[208:211], v[110:113]
	v_mfma_f32_16x16x32_bf16 v[102:105], v[176:179], v[208:211], v[102:105]
	v_mfma_f32_16x16x32_bf16 v[94:97], v[168:171], v[216:219], v[94:97]
	v_mfma_f32_16x16x32_bf16 v[86:89], v[176:179], v[216:219], v[86:89]
	v_mfma_f32_16x16x32_bf16 v[78:81], v[168:171], v[224:227], v[78:81]
	v_mfma_f32_16x16x32_bf16 v[70:73], v[176:179], v[224:227], v[70:73]
	v_mfma_f32_16x16x32_bf16 v[126:129], v[180:183], v[196:199], 0
	v_mfma_f32_16x16x32_bf16 v[114:117], v[188:191], v[196:199], 0
	v_mfma_f32_16x16x32_bf16 v[106:109], v[180:183], v[204:207], 0
	v_mfma_f32_16x16x32_bf16 v[98:101], v[188:191], v[204:207], 0
	v_mfma_f32_16x16x32_bf16 v[90:93], v[180:183], v[212:215], 0
	v_mfma_f32_16x16x32_bf16 v[82:85], v[188:191], v[212:215], 0
	v_mfma_f32_16x16x32_bf16 v[74:77], v[180:183], v[220:223], 0
	v_mfma_f32_16x16x32_bf16 v[66:69], v[188:191], v[220:223], 0
	v_mfma_f32_16x16x32_bf16 v[126:129], v[184:187], v[200:203], v[126:129]
	v_mfma_f32_16x16x32_bf16 v[114:117], v[192:195], v[200:203], v[114:117]
	v_mfma_f32_16x16x32_bf16 v[106:109], v[184:187], v[208:211], v[106:109]
	v_mfma_f32_16x16x32_bf16 v[98:101], v[192:195], v[208:211], v[98:101]
	v_mfma_f32_16x16x32_bf16 v[90:93], v[184:187], v[216:219], v[90:93]
	v_mfma_f32_16x16x32_bf16 v[82:85], v[192:195], v[216:219], v[82:85]
	v_mfma_f32_16x16x32_bf16 v[74:77], v[184:187], v[224:227], v[74:77]
	v_mfma_f32_16x16x32_bf16 v[66:69], v[192:195], v[224:227], v[66:69]
	s_barrier
	s_setprio 0
	s_add_u32 s98, s96, 0xb0000
	s_addc_u32 s99, s97, 0
	s_add_i32 s6, s67, s23
	s_mov_b32 m0, s6
	ds_read_b128 v[196:199], v160 offset:16384
	global_load_lds_dwordx4 v132, s[96:97]
	s_add_i32 m0, s6, 0x2000
	s_add_i32 s6, s70, s23
	global_load_lds_dwordx4 v136, s[96:97]
	s_mov_b32 m0, s6
	ds_read_b128 v[200:203], v238 offset:16384
	global_load_lds_dwordx4 v132, s[98:99]
	s_add_i32 m0, s6, 0x2000
	ds_read_b128 v[204:207], v160 offset:18432
	global_load_lds_dwordx4 v136, s[98:99]
	s_mov_b32 m0, s46
	ds_read_b128 v[208:211], v238 offset:18432
	global_load_lds_dwordx4 v130, s[94:95]
	s_mov_b32 m0, s47
	ds_read_b128 v[212:215], v160 offset:20480
	global_load_lds_dwordx4 v134, s[94:95]
	ds_read_b128 v[216:219], v238 offset:20480
	ds_read_b128 v[220:223], v160 offset:22528
	ds_read_b128 v[224:227], v238 offset:22528
	s_waitcnt vmcnt(8)
	s_waitcnt lgkmcnt(0)
	s_setprio 1
	s_barrier
	v_mfma_f32_16x16x32_bf16 v[62:65], v[164:167], v[196:199], 0
	v_mfma_f32_16x16x32_bf16 v[54:57], v[172:175], v[196:199], 0
	v_mfma_f32_16x16x32_bf16 v[46:49], v[164:167], v[204:207], 0
	v_mfma_f32_16x16x32_bf16 v[38:41], v[172:175], v[204:207], 0
	v_mfma_f32_16x16x32_bf16 v[30:33], v[164:167], v[212:215], 0
	v_mfma_f32_16x16x32_bf16 v[22:25], v[172:175], v[212:215], 0
	v_mfma_f32_16x16x32_bf16 v[14:17], v[164:167], v[220:223], 0
	v_mfma_f32_16x16x32_bf16 v[6:9], v[172:175], v[220:223], 0
	v_mfma_f32_16x16x32_bf16 v[62:65], v[168:171], v[200:203], v[62:65]
	v_mfma_f32_16x16x32_bf16 v[54:57], v[176:179], v[200:203], v[54:57]
	v_mfma_f32_16x16x32_bf16 v[46:49], v[168:171], v[208:211], v[46:49]
	v_mfma_f32_16x16x32_bf16 v[38:41], v[176:179], v[208:211], v[38:41]
	v_mfma_f32_16x16x32_bf16 v[30:33], v[168:171], v[216:219], v[30:33]
	v_mfma_f32_16x16x32_bf16 v[22:25], v[176:179], v[216:219], v[22:25]
	v_mfma_f32_16x16x32_bf16 v[14:17], v[168:171], v[224:227], v[14:17]
	v_mfma_f32_16x16x32_bf16 v[6:9], v[176:179], v[224:227], v[6:9]
	v_mfma_f32_16x16x32_bf16 v[58:61], v[180:183], v[196:199], 0
	v_mfma_f32_16x16x32_bf16 v[50:53], v[188:191], v[196:199], 0
	v_mfma_f32_16x16x32_bf16 v[42:45], v[180:183], v[204:207], 0
	v_mfma_f32_16x16x32_bf16 v[34:37], v[188:191], v[204:207], 0
	v_mfma_f32_16x16x32_bf16 v[26:29], v[180:183], v[212:215], 0
	v_mfma_f32_16x16x32_bf16 v[18:21], v[188:191], v[212:215], 0
	v_mfma_f32_16x16x32_bf16 v[10:13], v[180:183], v[220:223], 0
	v_mfma_f32_16x16x32_bf16 v[2:5], v[188:191], v[220:223], 0
	v_mfma_f32_16x16x32_bf16 v[58:61], v[184:187], v[200:203], v[58:61]
	v_mfma_f32_16x16x32_bf16 v[50:53], v[192:195], v[200:203], v[50:53]
	v_mfma_f32_16x16x32_bf16 v[42:45], v[184:187], v[208:211], v[42:45]
	v_mfma_f32_16x16x32_bf16 v[34:37], v[192:195], v[208:211], v[34:37]
	v_mfma_f32_16x16x32_bf16 v[26:29], v[184:187], v[216:219], v[26:29]
	v_mfma_f32_16x16x32_bf16 v[18:21], v[192:195], v[216:219], v[18:21]
	v_mfma_f32_16x16x32_bf16 v[10:13], v[184:187], v[224:227], v[10:13]
	v_mfma_f32_16x16x32_bf16 v[2:5], v[192:195], v[224:227], v[2:5]
	s_barrier
	s_setprio 0
	s_add_u32 s98, s94, 0xb0000
	s_addc_u32 s99, s95, 0
	s_add_i32 s6, 0, 0x18000
	s_add_i32 s29, 0, 0x1c000
	s_mov_b32 m0, s48
	ds_read_b128 v[164:167], v232
	global_load_lds_dwordx4 v130, s[98:99]
	s_mov_b32 m0, s49
	ds_read_b128 v[168:171], v236
	global_load_lds_dwordx4 v134, s[98:99]
	ds_read_b128 v[172:175], v232 offset:2048
	ds_read_b128 v[176:179], v236 offset:2048
	ds_read_b128 v[180:183], v233
	ds_read_b128 v[184:187], v237
	ds_read_b128 v[188:191], v233 offset:2048
	ds_read_b128 v[192:195], v237 offset:2048
	ds_read_b128 v[196:199], v160 offset:32768
	ds_read_b128 v[200:203], v238 offset:32768
	ds_read_b128 v[204:207], v160 offset:34816
	ds_read_b128 v[208:211], v238 offset:34816
	ds_read_b128 v[212:215], v160 offset:36864
	ds_read_b128 v[216:219], v238 offset:36864
	ds_read_b128 v[220:223], v160 offset:38912
	ds_read_b128 v[224:227], v238 offset:38912
	s_waitcnt vmcnt(8)
	s_waitcnt lgkmcnt(0)
	s_setprio 1
	s_barrier
	v_mfma_f32_16x16x32_bf16 v[122:125], v[164:167], v[196:199], v[122:125]
	v_mfma_f32_16x16x32_bf16 v[118:121], v[172:175], v[196:199], v[118:121]
	v_mfma_f32_16x16x32_bf16 v[110:113], v[164:167], v[204:207], v[110:113]
	v_mfma_f32_16x16x32_bf16 v[102:105], v[172:175], v[204:207], v[102:105]
	v_mfma_f32_16x16x32_bf16 v[94:97], v[164:167], v[212:215], v[94:97]
	v_mfma_f32_16x16x32_bf16 v[86:89], v[172:175], v[212:215], v[86:89]
	v_mfma_f32_16x16x32_bf16 v[78:81], v[164:167], v[220:223], v[78:81]
	v_mfma_f32_16x16x32_bf16 v[70:73], v[172:175], v[220:223], v[70:73]
	v_mfma_f32_16x16x32_bf16 v[122:125], v[168:171], v[200:203], v[122:125]
	v_mfma_f32_16x16x32_bf16 v[118:121], v[176:179], v[200:203], v[118:121]
	v_mfma_f32_16x16x32_bf16 v[110:113], v[168:171], v[208:211], v[110:113]
	v_mfma_f32_16x16x32_bf16 v[102:105], v[176:179], v[208:211], v[102:105]
	v_mfma_f32_16x16x32_bf16 v[94:97], v[168:171], v[216:219], v[94:97]
	v_mfma_f32_16x16x32_bf16 v[86:89], v[176:179], v[216:219], v[86:89]
	v_mfma_f32_16x16x32_bf16 v[78:81], v[168:171], v[224:227], v[78:81]
	v_mfma_f32_16x16x32_bf16 v[70:73], v[176:179], v[224:227], v[70:73]
	v_mfma_f32_16x16x32_bf16 v[126:129], v[180:183], v[196:199], v[126:129]
	v_mfma_f32_16x16x32_bf16 v[114:117], v[188:191], v[196:199], v[114:117]
	v_mfma_f32_16x16x32_bf16 v[106:109], v[180:183], v[204:207], v[106:109]
	v_mfma_f32_16x16x32_bf16 v[98:101], v[188:191], v[204:207], v[98:101]
	v_mfma_f32_16x16x32_bf16 v[90:93], v[180:183], v[212:215], v[90:93]
	v_mfma_f32_16x16x32_bf16 v[82:85], v[188:191], v[212:215], v[82:85]
	v_mfma_f32_16x16x32_bf16 v[74:77], v[180:183], v[220:223], v[74:77]
	v_mfma_f32_16x16x32_bf16 v[66:69], v[188:191], v[220:223], v[66:69]
	v_mfma_f32_16x16x32_bf16 v[126:129], v[184:187], v[200:203], v[126:129]
	v_mfma_f32_16x16x32_bf16 v[114:117], v[192:195], v[200:203], v[114:117]
	v_mfma_f32_16x16x32_bf16 v[106:109], v[184:187], v[208:211], v[106:109]
	v_mfma_f32_16x16x32_bf16 v[98:101], v[192:195], v[208:211], v[98:101]
	v_mfma_f32_16x16x32_bf16 v[90:93], v[184:187], v[216:219], v[90:93]
	v_mfma_f32_16x16x32_bf16 v[82:85], v[192:195], v[216:219], v[82:85]
	v_mfma_f32_16x16x32_bf16 v[74:77], v[184:187], v[224:227], v[74:77]
	v_mfma_f32_16x16x32_bf16 v[66:69], v[192:195], v[224:227], v[66:69]
	s_barrier
	s_setprio 0
	s_add_u32 s96, s96, 0x80
	s_addc_u32 s97, s97, 0
	s_add_u32 s98, s96, 0xb0000
	s_addc_u32 s99, s97, 0
	s_add_u32 s94, s94, 0x80
	s_addc_u32 s95, s95, 0
	s_add_i32 s6, s6, s23
	s_mov_b32 m0, s6
	ds_read_b128 v[196:199], v160 offset:49152
	global_load_lds_dwordx4 v132, s[96:97]
	s_add_i32 m0, s6, 0x2000
	s_add_i32 s6, s29, s23
	global_load_lds_dwordx4 v136, s[96:97]
	s_mov_b32 m0, s6
	ds_read_b128 v[200:203], v238 offset:49152
	global_load_lds_dwordx4 v132, s[98:99]
	s_add_i32 m0, s6, 0x2000
	ds_read_b128 v[204:207], v160 offset:51200
	global_load_lds_dwordx4 v136, s[98:99]
	s_mov_b32 m0, s59
	ds_read_b128 v[208:211], v238 offset:51200
	global_load_lds_dwordx4 v130, s[94:95]
	s_mov_b32 m0, s60
	ds_read_b128 v[212:215], v160 offset:53248
	global_load_lds_dwordx4 v134, s[94:95]
	ds_read_b128 v[216:219], v238 offset:53248
	ds_read_b128 v[220:223], v160 offset:55296
	ds_read_b128 v[224:227], v238 offset:55296
	s_waitcnt vmcnt(8)
	s_waitcnt lgkmcnt(0)
	s_setprio 1
	s_barrier
	v_mfma_f32_16x16x32_bf16 v[62:65], v[164:167], v[196:199], v[62:65]
	v_mfma_f32_16x16x32_bf16 v[54:57], v[172:175], v[196:199], v[54:57]
	v_mfma_f32_16x16x32_bf16 v[46:49], v[164:167], v[204:207], v[46:49]
	v_mfma_f32_16x16x32_bf16 v[38:41], v[172:175], v[204:207], v[38:41]
	v_mfma_f32_16x16x32_bf16 v[30:33], v[164:167], v[212:215], v[30:33]
	v_mfma_f32_16x16x32_bf16 v[22:25], v[172:175], v[212:215], v[22:25]
	v_mfma_f32_16x16x32_bf16 v[14:17], v[164:167], v[220:223], v[14:17]
	v_mfma_f32_16x16x32_bf16 v[6:9], v[172:175], v[220:223], v[6:9]
	v_mfma_f32_16x16x32_bf16 v[62:65], v[168:171], v[200:203], v[62:65]
	v_mfma_f32_16x16x32_bf16 v[54:57], v[176:179], v[200:203], v[54:57]
	v_mfma_f32_16x16x32_bf16 v[46:49], v[168:171], v[208:211], v[46:49]
	v_mfma_f32_16x16x32_bf16 v[38:41], v[176:179], v[208:211], v[38:41]
	v_mfma_f32_16x16x32_bf16 v[30:33], v[168:171], v[216:219], v[30:33]
	v_mfma_f32_16x16x32_bf16 v[22:25], v[176:179], v[216:219], v[22:25]
	v_mfma_f32_16x16x32_bf16 v[14:17], v[168:171], v[224:227], v[14:17]
	v_mfma_f32_16x16x32_bf16 v[6:9], v[176:179], v[224:227], v[6:9]
	v_mfma_f32_16x16x32_bf16 v[58:61], v[180:183], v[196:199], v[58:61]
	v_mfma_f32_16x16x32_bf16 v[50:53], v[188:191], v[196:199], v[50:53]
	v_mfma_f32_16x16x32_bf16 v[42:45], v[180:183], v[204:207], v[42:45]
	v_mfma_f32_16x16x32_bf16 v[34:37], v[188:191], v[204:207], v[34:37]
	v_mfma_f32_16x16x32_bf16 v[26:29], v[180:183], v[212:215], v[26:29]
	v_mfma_f32_16x16x32_bf16 v[18:21], v[188:191], v[212:215], v[18:21]
	v_mfma_f32_16x16x32_bf16 v[10:13], v[180:183], v[220:223], v[10:13]
	v_mfma_f32_16x16x32_bf16 v[2:5], v[188:191], v[220:223], v[2:5]
	v_mfma_f32_16x16x32_bf16 v[58:61], v[184:187], v[200:203], v[58:61]
	v_mfma_f32_16x16x32_bf16 v[50:53], v[192:195], v[200:203], v[50:53]
	v_mfma_f32_16x16x32_bf16 v[42:45], v[184:187], v[208:211], v[42:45]
	v_mfma_f32_16x16x32_bf16 v[34:37], v[192:195], v[208:211], v[34:37]
	v_mfma_f32_16x16x32_bf16 v[26:29], v[184:187], v[216:219], v[26:29]
	v_mfma_f32_16x16x32_bf16 v[18:21], v[192:195], v[216:219], v[18:21]
	v_mfma_f32_16x16x32_bf16 v[10:13], v[184:187], v[224:227], v[10:13]
	v_mfma_f32_16x16x32_bf16 v[2:5], v[192:195], v[224:227], v[2:5]
	s_barrier
	s_setprio 0
	s_mov_b32 s6, s7
	s_add_u32 s88, s88, 0x100
	s_addc_u32 s89, s89, 0
	s_add_u32 s86, s86, 0x100
	s_addc_u32 s87, s87, 0
	s_cmp_ge_i32 s7, s101
	s_cbranch_scc1 .Lmy_kexit_7
.LBB0_1392:
	s_add_u32 s98, s86, 0x100
	s_addc_u32 s99, s87, 0
	s_cmp_eq_u32 s6, s100
	s_cselect_b64 s[94:95], s[90:91], s[98:99]
	s_cselect_b64 s[96:97], s[92:93], s[88:89]
	s_add_i32 s7, s6, 2
	s_add_i32 m0, s46, 0xc000
	ds_read_b128 v[164:167], v230
	global_load_lds_dwordx4 v144, s[86:87]
	s_add_i32 m0, s46, 0xe000
	ds_read_b128 v[168:171], v234
	global_load_lds_dwordx4 v142, s[86:87]
	ds_read_b128 v[172:175], v230 offset:2048
	ds_read_b128 v[176:179], v234 offset:2048
	ds_read_b128 v[180:183], v231
	ds_read_b128 v[184:187], v235
	ds_read_b128 v[188:191], v231 offset:2048
	ds_read_b128 v[192:195], v235 offset:2048
	ds_read_b128 v[196:199], v160
	ds_read_b128 v[200:203], v238
	ds_read_b128 v[204:207], v160 offset:2048
	ds_read_b128 v[208:211], v238 offset:2048
	ds_read_b128 v[212:215], v160 offset:4096
	ds_read_b128 v[216:219], v238 offset:4096
	ds_read_b128 v[220:223], v160 offset:6144
	ds_read_b128 v[224:227], v238 offset:6144
	s_waitcnt vmcnt(8)
	s_waitcnt lgkmcnt(0)
	s_setprio 1
	s_barrier
	v_mfma_f32_16x16x32_bf16 v[122:125], v[164:167], v[196:199], v[122:125]
	v_mfma_f32_16x16x32_bf16 v[118:121], v[172:175], v[196:199], v[118:121]
	v_mfma_f32_16x16x32_bf16 v[110:113], v[164:167], v[204:207], v[110:113]
	v_mfma_f32_16x16x32_bf16 v[102:105], v[172:175], v[204:207], v[102:105]
	v_mfma_f32_16x16x32_bf16 v[94:97], v[164:167], v[212:215], v[94:97]
	v_mfma_f32_16x16x32_bf16 v[86:89], v[172:175], v[212:215], v[86:89]
	v_mfma_f32_16x16x32_bf16 v[78:81], v[164:167], v[220:223], v[78:81]
	v_mfma_f32_16x16x32_bf16 v[70:73], v[172:175], v[220:223], v[70:73]
	v_mfma_f32_16x16x32_bf16 v[122:125], v[168:171], v[200:203], v[122:125]
	v_mfma_f32_16x16x32_bf16 v[118:121], v[176:179], v[200:203], v[118:121]
	v_mfma_f32_16x16x32_bf16 v[110:113], v[168:171], v[208:211], v[110:113]
	v_mfma_f32_16x16x32_bf16 v[102:105], v[176:179], v[208:211], v[102:105]
	v_mfma_f32_16x16x32_bf16 v[94:97], v[168:171], v[216:219], v[94:97]
	v_mfma_f32_16x16x32_bf16 v[86:89], v[176:179], v[216:219], v[86:89]
	v_mfma_f32_16x16x32_bf16 v[78:81], v[168:171], v[224:227], v[78:81]
	v_mfma_f32_16x16x32_bf16 v[70:73], v[176:179], v[224:227], v[70:73]
	v_mfma_f32_16x16x32_bf16 v[126:129], v[180:183], v[196:199], v[126:129]
	v_mfma_f32_16x16x32_bf16 v[114:117], v[188:191], v[196:199], v[114:117]
	v_mfma_f32_16x16x32_bf16 v[106:109], v[180:183], v[204:207], v[106:109]
	v_mfma_f32_16x16x32_bf16 v[98:101], v[188:191], v[204:207], v[98:101]
	v_mfma_f32_16x16x32_bf16 v[90:93], v[180:183], v[212:215], v[90:93]
	v_mfma_f32_16x16x32_bf16 v[82:85], v[188:191], v[212:215], v[82:85]
	v_mfma_f32_16x16x32_bf16 v[74:77], v[180:183], v[220:223], v[74:77]
	v_mfma_f32_16x16x32_bf16 v[66:69], v[188:191], v[220:223], v[66:69]
	v_mfma_f32_16x16x32_bf16 v[126:129], v[184:187], v[200:203], v[126:129]
	v_mfma_f32_16x16x32_bf16 v[114:117], v[192:195], v[200:203], v[114:117]
	v_mfma_f32_16x16x32_bf16 v[106:109], v[184:187], v[208:211], v[106:109]
	v_mfma_f32_16x16x32_bf16 v[98:101], v[192:195], v[208:211], v[98:101]
	v_mfma_f32_16x16x32_bf16 v[90:93], v[184:187], v[216:219], v[90:93]
	v_mfma_f32_16x16x32_bf16 v[82:85], v[192:195], v[216:219], v[82:85]
	v_mfma_f32_16x16x32_bf16 v[74:77], v[184:187], v[224:227], v[74:77]
	v_mfma_f32_16x16x32_bf16 v[66:69], v[192:195], v[224:227], v[66:69]
	s_barrier
	s_setprio 0
	s_add_u32 s98, s96, 0xb0000
	s_addc_u32 s99, s97, 0
	s_add_i32 s6, s67, s23
	s_mov_b32 m0, s6
	ds_read_b128 v[196:199], v160 offset:16384
	global_load_lds_dwordx4 v132, s[96:97]
	s_add_i32 m0, s6, 0x2000
	s_add_i32 s6, s70, s23
	global_load_lds_dwordx4 v136, s[96:97]
	s_mov_b32 m0, s6
	ds_read_b128 v[200:203], v238 offset:16384
	global_load_lds_dwordx4 v132, s[98:99]
	s_add_i32 m0, s6, 0x2000
	ds_read_b128 v[204:207], v160 offset:18432
	global_load_lds_dwordx4 v136, s[98:99]
	s_mov_b32 m0, s46
	ds_read_b128 v[208:211], v238 offset:18432
	global_load_lds_dwordx4 v130, s[94:95]
	s_mov_b32 m0, s47
	ds_read_b128 v[212:215], v160 offset:20480
	global_load_lds_dwordx4 v134, s[94:95]
	ds_read_b128 v[216:219], v238 offset:20480
	ds_read_b128 v[220:223], v160 offset:22528
	ds_read_b128 v[224:227], v238 offset:22528
	s_waitcnt vmcnt(8)
	s_waitcnt lgkmcnt(0)
	s_setprio 1
	s_barrier
	v_mfma_f32_16x16x32_bf16 v[62:65], v[164:167], v[196:199], v[62:65]
	v_mfma_f32_16x16x32_bf16 v[54:57], v[172:175], v[196:199], v[54:57]
	v_mfma_f32_16x16x32_bf16 v[46:49], v[164:167], v[204:207], v[46:49]
	v_mfma_f32_16x16x32_bf16 v[38:41], v[172:175], v[204:207], v[38:41]
	v_mfma_f32_16x16x32_bf16 v[30:33], v[164:167], v[212:215], v[30:33]
	v_mfma_f32_16x16x32_bf16 v[22:25], v[172:175], v[212:215], v[22:25]
	v_mfma_f32_16x16x32_bf16 v[14:17], v[164:167], v[220:223], v[14:17]
	v_mfma_f32_16x16x32_bf16 v[6:9], v[172:175], v[220:223], v[6:9]
	v_mfma_f32_16x16x32_bf16 v[62:65], v[168:171], v[200:203], v[62:65]
	v_mfma_f32_16x16x32_bf16 v[54:57], v[176:179], v[200:203], v[54:57]
	v_mfma_f32_16x16x32_bf16 v[46:49], v[168:171], v[208:211], v[46:49]
	v_mfma_f32_16x16x32_bf16 v[38:41], v[176:179], v[208:211], v[38:41]
	v_mfma_f32_16x16x32_bf16 v[30:33], v[168:171], v[216:219], v[30:33]
	v_mfma_f32_16x16x32_bf16 v[22:25], v[176:179], v[216:219], v[22:25]
	v_mfma_f32_16x16x32_bf16 v[14:17], v[168:171], v[224:227], v[14:17]
	v_mfma_f32_16x16x32_bf16 v[6:9], v[176:179], v[224:227], v[6:9]
	v_mfma_f32_16x16x32_bf16 v[58:61], v[180:183], v[196:199], v[58:61]
	v_mfma_f32_16x16x32_bf16 v[50:53], v[188:191], v[196:199], v[50:53]
	v_mfma_f32_16x16x32_bf16 v[42:45], v[180:183], v[204:207], v[42:45]
	v_mfma_f32_16x16x32_bf16 v[34:37], v[188:191], v[204:207], v[34:37]
	v_mfma_f32_16x16x32_bf16 v[26:29], v[180:183], v[212:215], v[26:29]
	v_mfma_f32_16x16x32_bf16 v[18:21], v[188:191], v[212:215], v[18:21]
	v_mfma_f32_16x16x32_bf16 v[10:13], v[180:183], v[220:223], v[10:13]
	v_mfma_f32_16x16x32_bf16 v[2:5], v[188:191], v[220:223], v[2:5]
	v_mfma_f32_16x16x32_bf16 v[58:61], v[184:187], v[200:203], v[58:61]
	v_mfma_f32_16x16x32_bf16 v[50:53], v[192:195], v[200:203], v[50:53]
	v_mfma_f32_16x16x32_bf16 v[42:45], v[184:187], v[208:211], v[42:45]
	v_mfma_f32_16x16x32_bf16 v[34:37], v[192:195], v[208:211], v[34:37]
	v_mfma_f32_16x16x32_bf16 v[26:29], v[184:187], v[216:219], v[26:29]
	v_mfma_f32_16x16x32_bf16 v[18:21], v[192:195], v[216:219], v[18:21]
	v_mfma_f32_16x16x32_bf16 v[10:13], v[184:187], v[224:227], v[10:13]
	v_mfma_f32_16x16x32_bf16 v[2:5], v[192:195], v[224:227], v[2:5]
	s_barrier
	s_setprio 0
	s_add_u32 s98, s94, 0xb0000
	s_addc_u32 s99, s95, 0
	s_add_i32 s6, 0, 0x18000
	s_add_i32 s29, 0, 0x1c000
	s_mov_b32 m0, s48
	ds_read_b128 v[164:167], v232
	global_load_lds_dwordx4 v130, s[98:99]
	s_mov_b32 m0, s49
	ds_read_b128 v[168:171], v236
	global_load_lds_dwordx4 v134, s[98:99]
	ds_read_b128 v[172:175], v232 offset:2048
	ds_read_b128 v[176:179], v236 offset:2048
	ds_read_b128 v[180:183], v233
	ds_read_b128 v[184:187], v237
	ds_read_b128 v[188:191], v233 offset:2048
	ds_read_b128 v[192:195], v237 offset:2048
	ds_read_b128 v[196:199], v160 offset:32768
	ds_read_b128 v[200:203], v238 offset:32768
	ds_read_b128 v[204:207], v160 offset:34816
	ds_read_b128 v[208:211], v238 offset:34816
	ds_read_b128 v[212:215], v160 offset:36864
	ds_read_b128 v[216:219], v238 offset:36864
	ds_read_b128 v[220:223], v160 offset:38912
	ds_read_b128 v[224:227], v238 offset:38912
	s_waitcnt vmcnt(8)
	s_waitcnt lgkmcnt(0)
	s_setprio 1
	s_barrier
	v_mfma_f32_16x16x32_bf16 v[122:125], v[164:167], v[196:199], v[122:125]
	v_mfma_f32_16x16x32_bf16 v[118:121], v[172:175], v[196:199], v[118:121]
	v_mfma_f32_16x16x32_bf16 v[110:113], v[164:167], v[204:207], v[110:113]
	v_mfma_f32_16x16x32_bf16 v[102:105], v[172:175], v[204:207], v[102:105]
	v_mfma_f32_16x16x32_bf16 v[94:97], v[164:167], v[212:215], v[94:97]
	v_mfma_f32_16x16x32_bf16 v[86:89], v[172:175], v[212:215], v[86:89]
	v_mfma_f32_16x16x32_bf16 v[78:81], v[164:167], v[220:223], v[78:81]
	v_mfma_f32_16x16x32_bf16 v[70:73], v[172:175], v[220:223], v[70:73]
	v_mfma_f32_16x16x32_bf16 v[122:125], v[168:171], v[200:203], v[122:125]
	v_mfma_f32_16x16x32_bf16 v[118:121], v[176:179], v[200:203], v[118:121]
	v_mfma_f32_16x16x32_bf16 v[110:113], v[168:171], v[208:211], v[110:113]
	v_mfma_f32_16x16x32_bf16 v[102:105], v[176:179], v[208:211], v[102:105]
	v_mfma_f32_16x16x32_bf16 v[94:97], v[168:171], v[216:219], v[94:97]
	v_mfma_f32_16x16x32_bf16 v[86:89], v[176:179], v[216:219], v[86:89]
	v_mfma_f32_16x16x32_bf16 v[78:81], v[168:171], v[224:227], v[78:81]
	v_mfma_f32_16x16x32_bf16 v[70:73], v[176:179], v[224:227], v[70:73]
	v_mfma_f32_16x16x32_bf16 v[126:129], v[180:183], v[196:199], v[126:129]
	v_mfma_f32_16x16x32_bf16 v[114:117], v[188:191], v[196:199], v[114:117]
	v_mfma_f32_16x16x32_bf16 v[106:109], v[180:183], v[204:207], v[106:109]
	v_mfma_f32_16x16x32_bf16 v[98:101], v[188:191], v[204:207], v[98:101]
	v_mfma_f32_16x16x32_bf16 v[90:93], v[180:183], v[212:215], v[90:93]
	v_mfma_f32_16x16x32_bf16 v[82:85], v[188:191], v[212:215], v[82:85]
	v_mfma_f32_16x16x32_bf16 v[74:77], v[180:183], v[220:223], v[74:77]
	v_mfma_f32_16x16x32_bf16 v[66:69], v[188:191], v[220:223], v[66:69]
	v_mfma_f32_16x16x32_bf16 v[126:129], v[184:187], v[200:203], v[126:129]
	v_mfma_f32_16x16x32_bf16 v[114:117], v[192:195], v[200:203], v[114:117]
	v_mfma_f32_16x16x32_bf16 v[106:109], v[184:187], v[208:211], v[106:109]
	v_mfma_f32_16x16x32_bf16 v[98:101], v[192:195], v[208:211], v[98:101]
	v_mfma_f32_16x16x32_bf16 v[90:93], v[184:187], v[216:219], v[90:93]
	v_mfma_f32_16x16x32_bf16 v[82:85], v[192:195], v[216:219], v[82:85]
	v_mfma_f32_16x16x32_bf16 v[74:77], v[184:187], v[224:227], v[74:77]
	v_mfma_f32_16x16x32_bf16 v[66:69], v[192:195], v[224:227], v[66:69]
	s_barrier
	s_setprio 0
	s_add_u32 s96, s96, 0x80
	s_addc_u32 s97, s97, 0
	s_add_u32 s98, s96, 0xb0000
	s_addc_u32 s99, s97, 0
	s_add_u32 s94, s94, 0x80
	s_addc_u32 s95, s95, 0
	s_add_i32 s6, s6, s23
	s_mov_b32 m0, s6
	ds_read_b128 v[196:199], v160 offset:49152
	global_load_lds_dwordx4 v132, s[96:97]
	s_add_i32 m0, s6, 0x2000
	s_add_i32 s6, s29, s23
	global_load_lds_dwordx4 v136, s[96:97]
	s_mov_b32 m0, s6
	ds_read_b128 v[200:203], v238 offset:49152
	global_load_lds_dwordx4 v132, s[98:99]
	s_add_i32 m0, s6, 0x2000
	ds_read_b128 v[204:207], v160 offset:51200
	global_load_lds_dwordx4 v136, s[98:99]
	s_mov_b32 m0, s59
	ds_read_b128 v[208:211], v238 offset:51200
	global_load_lds_dwordx4 v130, s[94:95]
	s_mov_b32 m0, s60
	ds_read_b128 v[212:215], v160 offset:53248
	global_load_lds_dwordx4 v134, s[94:95]
	ds_read_b128 v[216:219], v238 offset:53248
	ds_read_b128 v[220:223], v160 offset:55296
	ds_read_b128 v[224:227], v238 offset:55296
	s_waitcnt vmcnt(8)
	s_waitcnt lgkmcnt(0)
	s_setprio 1
	s_barrier
	v_mfma_f32_16x16x32_bf16 v[62:65], v[164:167], v[196:199], v[62:65]
	v_mfma_f32_16x16x32_bf16 v[54:57], v[172:175], v[196:199], v[54:57]
	v_mfma_f32_16x16x32_bf16 v[46:49], v[164:167], v[204:207], v[46:49]
	v_mfma_f32_16x16x32_bf16 v[38:41], v[172:175], v[204:207], v[38:41]
	v_mfma_f32_16x16x32_bf16 v[30:33], v[164:167], v[212:215], v[30:33]
	v_mfma_f32_16x16x32_bf16 v[22:25], v[172:175], v[212:215], v[22:25]
	v_mfma_f32_16x16x32_bf16 v[14:17], v[164:167], v[220:223], v[14:17]
	v_mfma_f32_16x16x32_bf16 v[6:9], v[172:175], v[220:223], v[6:9]
	v_mfma_f32_16x16x32_bf16 v[62:65], v[168:171], v[200:203], v[62:65]
	v_mfma_f32_16x16x32_bf16 v[54:57], v[176:179], v[200:203], v[54:57]
	v_mfma_f32_16x16x32_bf16 v[46:49], v[168:171], v[208:211], v[46:49]
	v_mfma_f32_16x16x32_bf16 v[38:41], v[176:179], v[208:211], v[38:41]
	v_mfma_f32_16x16x32_bf16 v[30:33], v[168:171], v[216:219], v[30:33]
	v_mfma_f32_16x16x32_bf16 v[22:25], v[176:179], v[216:219], v[22:25]
	v_mfma_f32_16x16x32_bf16 v[14:17], v[168:171], v[224:227], v[14:17]
	v_mfma_f32_16x16x32_bf16 v[6:9], v[176:179], v[224:227], v[6:9]
	v_mfma_f32_16x16x32_bf16 v[58:61], v[180:183], v[196:199], v[58:61]
	v_mfma_f32_16x16x32_bf16 v[50:53], v[188:191], v[196:199], v[50:53]
	v_mfma_f32_16x16x32_bf16 v[42:45], v[180:183], v[204:207], v[42:45]
	v_mfma_f32_16x16x32_bf16 v[34:37], v[188:191], v[204:207], v[34:37]
	v_mfma_f32_16x16x32_bf16 v[26:29], v[180:183], v[212:215], v[26:29]
	v_mfma_f32_16x16x32_bf16 v[18:21], v[188:191], v[212:215], v[18:21]
	v_mfma_f32_16x16x32_bf16 v[10:13], v[180:183], v[220:223], v[10:13]
	v_mfma_f32_16x16x32_bf16 v[2:5], v[188:191], v[220:223], v[2:5]
	v_mfma_f32_16x16x32_bf16 v[58:61], v[184:187], v[200:203], v[58:61]
	v_mfma_f32_16x16x32_bf16 v[50:53], v[192:195], v[200:203], v[50:53]
	v_mfma_f32_16x16x32_bf16 v[42:45], v[184:187], v[208:211], v[42:45]
	v_mfma_f32_16x16x32_bf16 v[34:37], v[192:195], v[208:211], v[34:37]
	v_mfma_f32_16x16x32_bf16 v[26:29], v[184:187], v[216:219], v[26:29]
	v_mfma_f32_16x16x32_bf16 v[18:21], v[192:195], v[216:219], v[18:21]
	v_mfma_f32_16x16x32_bf16 v[10:13], v[184:187], v[224:227], v[10:13]
	v_mfma_f32_16x16x32_bf16 v[2:5], v[192:195], v[224:227], v[2:5]
	s_barrier
	s_setprio 0
	s_mov_b32 s6, s7
	s_add_u32 s88, s88, 0x100
	s_addc_u32 s89, s89, 0
	s_add_u32 s86, s86, 0x100
	s_addc_u32 s87, s87, 0
	s_cmp_ge_i32 s7, s101
	s_cbranch_scc0 .LBB0_1392

.LBB0_1566:
	s_mov_b64 s[16:17], 0x80
	s_add_i32 m0, s51, 0x18000
	v_lshl_add_u64 v[12:13], v[12:13], 0, s[16:17]
	s_waitcnt vmcnt(2)
	s_barrier
	global_load_lds_dwordx4 v[12:13], off
	v_lshl_add_u64 v[10:11], v[10:11], 0, s[16:17]
	s_add_i32 m0, s51, 0x1a000
	s_add_i32 s63, s51, 0x8000
	global_load_lds_dwordx4 v[10:11], off
	v_lshl_add_u64 v[6:7], v[6:7], 0, s[16:17]
	s_mov_b32 m0, s63
	s_add_i32 s64, s51, 0xa000
	global_load_lds_dwordx4 v[6:7], off
	v_lshl_add_u64 v[6:7], v[8:9], 0, s[16:17]
	s_mov_b32 m0, s64
	s_mov_b64 s[18:19], 0x40080
	global_load_lds_dwordx4 v[6:7], off
	v_lshl_add_u64 v[6:7], v[4:5], 0, s[18:19]
	s_add_i32 m0, s51, 0x1c000
	v_lshl_add_u64 v[8:9], v[6:7], 0, v[132:133]
	global_load_lds_dwordx4 v[8:9], off
	v_lshl_add_u64 v[6:7], v[6:7], 0, v[136:137]
	s_add_i32 m0, s51, 0x1e000
	v_and_b32_e32 v140, 15, v14
	global_load_lds_dwordx4 v[6:7], off
	v_bfe_u32 v6, v14, 4, 2
	v_lshlrev_b32_e32 v7, 4, v6
	v_lshlrev_b32_e32 v9, 2, v14
	s_and_b32 s7, s4, 3
	s_lshl_b32 s65, s5, 6
	v_lshl_or_b32 v8, v140, 6, v7
	s_lshl_b32 s5, s5, 13
	v_and_b32_e32 v9, 32, v9
	v_bitop3_b32 v10, v8, s5, v9 bitop3:0xde
	s_lshl_b32 s66, s7, 5
	s_lshl_b32 s5, s7, 12
	s_cmpk_lt_u32 s12, 0x100
	s_cselect_b64 s[20:21], -1, 0
	s_lshl_b32 s4, s4, 6
	v_bitop3_b32 v160, v8, s5, v9 bitop3:0xde
	v_and_or_b32 v161, s4, 64, v7
	v_cmp_eq_u32_e64 s[4:5], 0, v6
	v_lshl_or_b32 v162, v6, 3, s66
	v_lshlrev_b32_e32 v6, 14, v18
	v_and_b32_e32 v6, 0xffff8000, v6
	v_lshl_add_u32 v6, v19, 11, v6
	v_and_b32_e32 v7, 1, v18
	v_lshl_or_b32 v6, v7, 6, v6
	v_lshl_add_u32 v142, v20, 1, v6
	v_lshlrev_b32_e32 v6, 14, v15
	v_and_b32_e32 v6, 0xffff8000, v6
	v_lshl_add_u32 v6, v16, 11, v6
	v_and_b32_e32 v7, 1, v15
	s_waitcnt vmcnt(6)
	v_lshl_or_b32 v6, v7, 6, v6
	v_lshl_add_u32 v144, v17, 1, v6
	s_mov_b32 s24, 0xfffc0080
	v_mbcnt_lo_u32_b32 v6, -1, 0
	s_lshl_b32 s12, s7, 2
	v_mov_b32_e32 v143, v139
	v_mov_b32_e32 v145, v139
	s_movk_i32 s67, 0xc1
	s_add_i32 s70, 0, 0x20050
	s_mov_b64 s[22:23], 0x100
	s_mov_b32 s25, -1
	s_add_i32 s71, 0, 0x10000
	s_add_i32 s72, 0, 0x14000
	v_add_u32_e32 v163, 0, v10
	s_movk_i32 s73, 0x7fff
	s_mov_b32 s28, 0xbfb8aa3b
	s_add_i32 s74, s51, 0xc000
	s_add_i32 s75, s51, 0xe000
	v_mbcnt_hi_u32_b32 v164, -1, v6
	s_mov_b32 s76, s13
	v_mov_b64_e32 v[150:151], v[4:5]
	v_mov_b64_e32 v[148:149], v[2:3]
	s_barrier
	v_lshrrev_b32_e32 v242, 6, v1
	v_and_b32_e32 v243, 63, v1
	v_lshlrev_b32_e32 v245, 4, v243
	v_lshrrev_b32_e32 v244, 5, v243
	v_lshlrev_b32_e32 v244, 5, v244
	v_xor_b32_e32 v245, v245, v244
	v_lshrrev_b32_e32 v244, 1, v242
	v_lshlrev_b32_e32 v244, 4, v244
	v_lshrrev_b32_e32 v243, 6, v245
	v_add_u32_e32 v244, v244, v243
	v_and_b32_e32 v245, 63, v245
	v_and_b32_e32 v242, 1, v242
	v_lshl_add_u32 v245, v242, 6, v245
	v_mul_u32_u24_e32 v244, 0x800, v244
	v_add_u32_e32 v240, v244, v245
	v_lshrrev_b32_e32 v242, 6, v1
	v_and_b32_e32 v243, 63, v1
	v_lshrrev_b32_e32 v244, 3, v243
	v_lshl_add_u32 v244, v242, 3, v244
	v_lshrrev_b32_e32 v245, 4, v243
	v_and_b32_e32 v245, 3, v245
	v_lshlrev_b32_e32 v245, 1, v245
	v_and_b32_e32 v243, 7, v243
	v_xor_b32_e32 v245, v243, v245
	v_lshlrev_b32_e32 v245, 4, v245
	v_mul_u32_u24_e32 v244, 0x800, v244
	v_add_u32_e32 v241, v244, v245
	v_sub_u32_e32 v144, v144, v240
	v_add_u32_e32 v144, v144, v241
	v_lshrrev_b32_e32 v242, 6, v1
	v_and_b32_e32 v243, 63, v1
	v_lshlrev_b32_e32 v245, 4, v243
	v_lshrrev_b32_e32 v244, 5, v243
	v_lshlrev_b32_e32 v244, 5, v244
	v_xor_b32_e32 v245, v245, v244
	v_add_u32_e32 v242, 8, v242
	v_lshrrev_b32_e32 v244, 1, v242
	v_lshlrev_b32_e32 v244, 4, v244
	v_lshrrev_b32_e32 v243, 6, v245
	v_add_u32_e32 v244, v244, v243
	v_and_b32_e32 v245, 63, v245
	v_and_b32_e32 v242, 1, v242
	v_lshl_add_u32 v245, v242, 6, v245
	v_mul_u32_u24_e32 v244, 0x800, v244
	v_add_u32_e32 v240, v244, v245
	v_lshrrev_b32_e32 v242, 6, v1
	v_and_b32_e32 v243, 63, v1
	v_lshrrev_b32_e32 v244, 3, v243
	v_lshl_add_u32 v244, v242, 3, v244
	v_add_u32_e32 v244, 64, v244
	v_lshrrev_b32_e32 v245, 4, v243
	v_and_b32_e32 v245, 3, v245
	v_lshlrev_b32_e32 v245, 1, v245
	v_and_b32_e32 v243, 7, v243
	v_xor_b32_e32 v245, v243, v245
	v_lshlrev_b32_e32 v245, 4, v245
	v_mul_u32_u24_e32 v244, 0x800, v244
	v_add_u32_e32 v241, v244, v245
	v_sub_u32_e32 v142, v142, v240
	v_add_u32_e32 v142, v142, v241
	v_and_b32_e32 v240, 63, v1
	v_and_b32_e32 v241, 15, v240
	v_lshrrev_b32_e32 v242, 4, v240
	v_lshlrev_b32_e32 v243, 6, v241
	v_lshl_add_u32 v243, v242, 4, v243
	v_lshrrev_b32_e32 v244, 3, v241
	v_lshlrev_b32_e32 v245, 5, v244
	v_xor_b32_e32 v243, v243, v245
	v_sub_u32_e32 v163, v163, v243
	v_lshlrev_b32_e32 v244, 10, v244
	v_and_b32_e32 v245, 7, v241
	v_lshl_add_u32 v244, v245, 7, v244
	v_add_u32_e32 v163, v163, v244
	v_lshrrev_b32_e32 v245, 1, v245
	v_lshlrev_b32_e32 v245, 1, v245
	v_add_u32_e32 v244, 4, v242
	v_xor_b32_e32 v244, v244, v245
	v_lshl_add_u32 v238, v244, 4, v163
	v_xor_b32_e32 v244, v242, v245
	v_lshl_add_u32 v163, v244, 4, v163
	v_and_b32_e32 v240, 63, v1
	v_and_b32_e32 v241, 15, v240
	v_lshrrev_b32_e32 v242, 4, v240
	v_lshlrev_b32_e32 v243, 6, v241
	v_lshl_add_u32 v243, v242, 4, v243
	v_lshrrev_b32_e32 v244, 3, v241
	v_lshlrev_b32_e32 v245, 5, v244
	v_xor_b32_e32 v243, v243, v245
	v_sub_u32_e32 v160, v160, v243
	v_lshlrev_b32_e32 v244, 10, v244
	v_and_b32_e32 v245, 7, v241
	v_lshl_add_u32 v244, v245, 7, v244
	v_add_u32_e32 v160, v160, v244
	v_lshrrev_b32_e32 v245, 1, v245
	v_lshlrev_b32_e32 v245, 1, v245
	v_add_u32_e32 v244, 4, v242
	v_xor_b32_e32 v244, v244, v245
	v_lshl_add_u32 v239, v244, 4, v160
	v_xor_b32_e32 v244, v242, v245
	v_lshl_add_u32 v160, v244, 4, v160
	s_branch .LBB0_1569

.Lmy_nb_8:
	s_nop 0
	v_readfirstlane_b32 s86, v154
	v_readfirstlane_b32 s87, v155
	v_readfirstlane_b32 s88, v152
	v_readfirstlane_b32 s89, v153
	v_readfirstlane_b32 s90, v148
	v_readfirstlane_b32 s91, v149
	v_readfirstlane_b32 s92, v150
	v_readfirstlane_b32 s93, v151
	v_readfirstlane_b32 s100, v138
	v_readfirstlane_b32 s101, v141
	v_add_u32_e32 v230, s71, v160
	v_add_u32_e32 v234, s71, v239
	v_add_u32_e32 v231, s72, v160
	v_add_u32_e32 v235, s72, v239
	v_add_u32_e32 v232, 0x18000, v160
	v_add_u32_e32 v236, 0x18000, v239
	v_add_u32_e32 v233, 0x1c000, v160
	v_add_u32_e32 v237, 0x1c000, v239
	s_add_u32 s98, s86, 0xfffc0080
	s_addc_u32 s99, s87, -1
	s_cmp_eq_u32 s7, s100
	s_cselect_b64 s[94:95], s[90:91], s[98:99]
	s_cselect_b64 s[96:97], s[92:93], s[88:89]
	s_add_i32 s47, s7, 2
	s_mov_b32 m0, s74
	ds_read_b128 v[156:159], v230
	global_load_lds_dwordx4 v144, s[86:87]
	s_mov_b32 m0, s75
	ds_read_b128 v[166:169], v234
	global_load_lds_dwordx4 v142, s[86:87]
	ds_read_b128 v[170:173], v230 offset:2048
	ds_read_b128 v[174:177], v234 offset:2048
	ds_read_b128 v[178:181], v231
	ds_read_b128 v[182:185], v235
	ds_read_b128 v[186:189], v231 offset:2048
	ds_read_b128 v[190:193], v235 offset:2048
	ds_read_b128 v[194:197], v163
	ds_read_b128 v[198:201], v238
	ds_read_b128 v[202:205], v163 offset:2048
	ds_read_b128 v[206:209], v238 offset:2048
	ds_read_b128 v[210:213], v163 offset:4096
	ds_read_b128 v[214:217], v238 offset:4096
	ds_read_b128 v[218:221], v163 offset:6144
	ds_read_b128 v[222:225], v238 offset:6144
	s_waitcnt vmcnt(8)
	s_waitcnt lgkmcnt(0)
	s_setprio 1
	s_barrier
	v_mfma_f32_16x16x32_bf16 v[122:125], v[156:159], v[194:197], 0
	v_mfma_f32_16x16x32_bf16 v[118:121], v[170:173], v[194:197], 0
	v_mfma_f32_16x16x32_bf16 v[110:113], v[156:159], v[202:205], 0
	v_mfma_f32_16x16x32_bf16 v[102:105], v[170:173], v[202:205], 0
	v_mfma_f32_16x16x32_bf16 v[94:97], v[156:159], v[210:213], 0
	v_mfma_f32_16x16x32_bf16 v[86:89], v[170:173], v[210:213], 0
	v_mfma_f32_16x16x32_bf16 v[78:81], v[156:159], v[218:221], 0
	v_mfma_f32_16x16x32_bf16 v[70:73], v[170:173], v[218:221], 0
	v_mfma_f32_16x16x32_bf16 v[122:125], v[166:169], v[198:201], v[122:125]
	v_mfma_f32_16x16x32_bf16 v[118:121], v[174:177], v[198:201], v[118:121]
	v_mfma_f32_16x16x32_bf16 v[110:113], v[166:169], v[206:209], v[110:113]
	v_mfma_f32_16x16x32_bf16 v[102:105], v[174:177], v[206:209], v[102:105]
	v_mfma_f32_16x16x32_bf16 v[94:97], v[166:169], v[214:217], v[94:97]
	v_mfma_f32_16x16x32_bf16 v[86:89], v[174:177], v[214:217], v[86:89]
	v_mfma_f32_16x16x32_bf16 v[78:81], v[166:169], v[222:225], v[78:81]
	v_mfma_f32_16x16x32_bf16 v[70:73], v[174:177], v[222:225], v[70:73]
	v_mfma_f32_16x16x32_bf16 v[126:129], v[178:181], v[194:197], 0
	v_mfma_f32_16x16x32_bf16 v[114:117], v[186:189], v[194:197], 0
	v_mfma_f32_16x16x32_bf16 v[106:109], v[178:181], v[202:205], 0
	v_mfma_f32_16x16x32_bf16 v[98:101], v[186:189], v[202:205], 0
	v_mfma_f32_16x16x32_bf16 v[90:93], v[178:181], v[210:213], 0
	v_mfma_f32_16x16x32_bf16 v[82:85], v[186:189], v[210:213], 0
	v_mfma_f32_16x16x32_bf16 v[74:77], v[178:181], v[218:221], 0
	v_mfma_f32_16x16x32_bf16 v[66:69], v[186:189], v[218:221], 0
	v_mfma_f32_16x16x32_bf16 v[126:129], v[182:185], v[198:201], v[126:129]
	v_mfma_f32_16x16x32_bf16 v[114:117], v[190:193], v[198:201], v[114:117]
	v_mfma_f32_16x16x32_bf16 v[106:109], v[182:185], v[206:209], v[106:109]
	v_mfma_f32_16x16x32_bf16 v[98:101], v[190:193], v[206:209], v[98:101]
	v_mfma_f32_16x16x32_bf16 v[90:93], v[182:185], v[214:217], v[90:93]
	v_mfma_f32_16x16x32_bf16 v[82:85], v[190:193], v[214:217], v[82:85]
	v_mfma_f32_16x16x32_bf16 v[74:77], v[182:185], v[222:225], v[74:77]
	v_mfma_f32_16x16x32_bf16 v[66:69], v[190:193], v[222:225], v[66:69]
	s_barrier
	s_setprio 0
	s_add_u32 s98, s96, 0x40000
	s_addc_u32 s99, s97, 0
	s_add_i32 s7, s71, s29
	s_mov_b32 m0, s7
	ds_read_b128 v[194:197], v163 offset:16384
	global_load_lds_dwordx4 v132, s[96:97]
	s_add_i32 m0, s7, 0x2000
	s_add_i32 s7, s72, s29
	global_load_lds_dwordx4 v136, s[96:97]
	s_mov_b32 m0, s7
	ds_read_b128 v[198:201], v238 offset:16384
	global_load_lds_dwordx4 v132, s[98:99]
	s_add_i32 m0, s7, 0x2000
	ds_read_b128 v[202:205], v163 offset:18432
	global_load_lds_dwordx4 v136, s[98:99]
	s_mov_b32 m0, s51
	ds_read_b128 v[206:209], v238 offset:18432
	global_load_lds_dwordx4 v130, s[94:95]
	s_mov_b32 m0, s60
	ds_read_b128 v[210:213], v163 offset:20480
	global_load_lds_dwordx4 v134, s[94:95]
	ds_read_b128 v[214:217], v238 offset:20480
	ds_read_b128 v[218:221], v163 offset:22528
	ds_read_b128 v[222:225], v238 offset:22528
	s_waitcnt vmcnt(8)
	s_waitcnt lgkmcnt(0)
	s_setprio 1
	s_barrier
	v_mfma_f32_16x16x32_bf16 v[62:65], v[156:159], v[194:197], 0
	v_mfma_f32_16x16x32_bf16 v[54:57], v[170:173], v[194:197], 0
	v_mfma_f32_16x16x32_bf16 v[46:49], v[156:159], v[202:205], 0
	v_mfma_f32_16x16x32_bf16 v[38:41], v[170:173], v[202:205], 0
	v_mfma_f32_16x16x32_bf16 v[30:33], v[156:159], v[210:213], 0
	v_mfma_f32_16x16x32_bf16 v[22:25], v[170:173], v[210:213], 0
	v_mfma_f32_16x16x32_bf16 v[14:17], v[156:159], v[218:221], 0
	v_mfma_f32_16x16x32_bf16 v[6:9], v[170:173], v[218:221], 0
	v_mfma_f32_16x16x32_bf16 v[62:65], v[166:169], v[198:201], v[62:65]
	v_mfma_f32_16x16x32_bf16 v[54:57], v[174:177], v[198:201], v[54:57]
	v_mfma_f32_16x16x32_bf16 v[46:49], v[166:169], v[206:209], v[46:49]
	v_mfma_f32_16x16x32_bf16 v[38:41], v[174:177], v[206:209], v[38:41]
	v_mfma_f32_16x16x32_bf16 v[30:33], v[166:169], v[214:217], v[30:33]
	v_mfma_f32_16x16x32_bf16 v[22:25], v[174:177], v[214:217], v[22:25]
	v_mfma_f32_16x16x32_bf16 v[14:17], v[166:169], v[222:225], v[14:17]
	v_mfma_f32_16x16x32_bf16 v[6:9], v[174:177], v[222:225], v[6:9]
	v_mfma_f32_16x16x32_bf16 v[58:61], v[178:181], v[194:197], 0
	v_mfma_f32_16x16x32_bf16 v[50:53], v[186:189], v[194:197], 0
	v_mfma_f32_16x16x32_bf16 v[42:45], v[178:181], v[202:205], 0
	v_mfma_f32_16x16x32_bf16 v[34:37], v[186:189], v[202:205], 0
	v_mfma_f32_16x16x32_bf16 v[26:29], v[178:181], v[210:213], 0
	v_mfma_f32_16x16x32_bf16 v[18:21], v[186:189], v[210:213], 0
	v_mfma_f32_16x16x32_bf16 v[10:13], v[178:181], v[218:221], 0
	v_mfma_f32_16x16x32_bf16 v[2:5], v[186:189], v[218:221], 0
	v_mfma_f32_16x16x32_bf16 v[58:61], v[182:185], v[198:201], v[58:61]
	v_mfma_f32_16x16x32_bf16 v[50:53], v[190:193], v[198:201], v[50:53]
	v_mfma_f32_16x16x32_bf16 v[42:45], v[182:185], v[206:209], v[42:45]
	v_mfma_f32_16x16x32_bf16 v[34:37], v[190:193], v[206:209], v[34:37]
	v_mfma_f32_16x16x32_bf16 v[26:29], v[182:185], v[214:217], v[26:29]
	v_mfma_f32_16x16x32_bf16 v[18:21], v[190:193], v[214:217], v[18:21]
	v_mfma_f32_16x16x32_bf16 v[10:13], v[182:185], v[222:225], v[10:13]
	v_mfma_f32_16x16x32_bf16 v[2:5], v[190:193], v[222:225], v[2:5]
	s_barrier
	s_setprio 0
	s_add_u32 s98, s94, 0x40000
	s_addc_u32 s99, s95, 0
	s_add_i32 s7, 0, 0x18000
	s_add_i32 s49, 0, 0x1c000
	s_mov_b32 m0, s61
	ds_read_b128 v[156:159], v232
	global_load_lds_dwordx4 v130, s[98:99]
	s_mov_b32 m0, s62
	ds_read_b128 v[166:169], v236
	global_load_lds_dwordx4 v134, s[98:99]
	ds_read_b128 v[170:173], v232 offset:2048
	ds_read_b128 v[174:177], v236 offset:2048
	ds_read_b128 v[178:181], v233
	ds_read_b128 v[182:185], v237
	ds_read_b128 v[186:189], v233 offset:2048
	ds_read_b128 v[190:193], v237 offset:2048
	ds_read_b128 v[194:197], v163 offset:32768
	ds_read_b128 v[198:201], v238 offset:32768
	ds_read_b128 v[202:205], v163 offset:34816
	ds_read_b128 v[206:209], v238 offset:34816
	ds_read_b128 v[210:213], v163 offset:36864
	ds_read_b128 v[214:217], v238 offset:36864
	ds_read_b128 v[218:221], v163 offset:38912
	ds_read_b128 v[222:225], v238 offset:38912
	s_waitcnt vmcnt(8)
	s_waitcnt lgkmcnt(0)
	s_setprio 1
	s_barrier
	v_mfma_f32_16x16x32_bf16 v[122:125], v[156:159], v[194:197], v[122:125]
	v_mfma_f32_16x16x32_bf16 v[118:121], v[170:173], v[194:197], v[118:121]
	v_mfma_f32_16x16x32_bf16 v[110:113], v[156:159], v[202:205], v[110:113]
	v_mfma_f32_16x16x32_bf16 v[102:105], v[170:173], v[202:205], v[102:105]
	v_mfma_f32_16x16x32_bf16 v[94:97], v[156:159], v[210:213], v[94:97]
	v_mfma_f32_16x16x32_bf16 v[86:89], v[170:173], v[210:213], v[86:89]
	v_mfma_f32_16x16x32_bf16 v[78:81], v[156:159], v[218:221], v[78:81]
	v_mfma_f32_16x16x32_bf16 v[70:73], v[170:173], v[218:221], v[70:73]
	v_mfma_f32_16x16x32_bf16 v[122:125], v[166:169], v[198:201], v[122:125]
	v_mfma_f32_16x16x32_bf16 v[118:121], v[174:177], v[198:201], v[118:121]
	v_mfma_f32_16x16x32_bf16 v[110:113], v[166:169], v[206:209], v[110:113]
	v_mfma_f32_16x16x32_bf16 v[102:105], v[174:177], v[206:209], v[102:105]
	v_mfma_f32_16x16x32_bf16 v[94:97], v[166:169], v[214:217], v[94:97]
	v_mfma_f32_16x16x32_bf16 v[86:89], v[174:177], v[214:217], v[86:89]
	v_mfma_f32_16x16x32_bf16 v[78:81], v[166:169], v[222:225], v[78:81]
	v_mfma_f32_16x16x32_bf16 v[70:73], v[174:177], v[222:225], v[70:73]
	v_mfma_f32_16x16x32_bf16 v[126:129], v[178:181], v[194:197], v[126:129]
	v_mfma_f32_16x16x32_bf16 v[114:117], v[186:189], v[194:197], v[114:117]
	v_mfma_f32_16x16x32_bf16 v[106:109], v[178:181], v[202:205], v[106:109]
	v_mfma_f32_16x16x32_bf16 v[98:101], v[186:189], v[202:205], v[98:101]
	v_mfma_f32_16x16x32_bf16 v[90:93], v[178:181], v[210:213], v[90:93]
	v_mfma_f32_16x16x32_bf16 v[82:85], v[186:189], v[210:213], v[82:85]
	v_mfma_f32_16x16x32_bf16 v[74:77], v[178:181], v[218:221], v[74:77]
	v_mfma_f32_16x16x32_bf16 v[66:69], v[186:189], v[218:221], v[66:69]
	v_mfma_f32_16x16x32_bf16 v[126:129], v[182:185], v[198:201], v[126:129]
	v_mfma_f32_16x16x32_bf16 v[114:117], v[190:193], v[198:201], v[114:117]
	v_mfma_f32_16x16x32_bf16 v[106:109], v[182:185], v[206:209], v[106:109]
	v_mfma_f32_16x16x32_bf16 v[98:101], v[190:193], v[206:209], v[98:101]
	v_mfma_f32_16x16x32_bf16 v[90:93], v[182:185], v[214:217], v[90:93]
	v_mfma_f32_16x16x32_bf16 v[82:85], v[190:193], v[214:217], v[82:85]
	v_mfma_f32_16x16x32_bf16 v[74:77], v[182:185], v[222:225], v[74:77]
	v_mfma_f32_16x16x32_bf16 v[66:69], v[190:193], v[222:225], v[66:69]
	s_barrier
	s_setprio 0
	s_add_u32 s96, s96, 0x80
	s_addc_u32 s97, s97, 0
	s_add_u32 s98, s96, 0x40000
	s_addc_u32 s99, s97, 0
	s_add_u32 s94, s94, 0x80
	s_addc_u32 s95, s95, 0
	s_add_i32 s7, s7, s29
	s_mov_b32 m0, s7
	ds_read_b128 v[194:197], v163 offset:49152
	global_load_lds_dwordx4 v132, s[96:97]
	s_add_i32 m0, s7, 0x2000
	s_add_i32 s7, s49, s29
	global_load_lds_dwordx4 v136, s[96:97]
	s_mov_b32 m0, s7
	ds_read_b128 v[198:201], v238 offset:49152
	global_load_lds_dwordx4 v132, s[98:99]
	s_add_i32 m0, s7, 0x2000
	ds_read_b128 v[202:205], v163 offset:51200
	global_load_lds_dwordx4 v136, s[98:99]
	s_mov_b32 m0, s63
	ds_read_b128 v[206:209], v238 offset:51200
	global_load_lds_dwordx4 v130, s[94:95]
	s_mov_b32 m0, s64
	ds_read_b128 v[210:213], v163 offset:53248
	global_load_lds_dwordx4 v134, s[94:95]
	ds_read_b128 v[214:217], v238 offset:53248
	ds_read_b128 v[218:221], v163 offset:55296
	ds_read_b128 v[222:225], v238 offset:55296
	s_waitcnt vmcnt(8)
	s_waitcnt lgkmcnt(0)
	s_setprio 1
	s_barrier
	v_mfma_f32_16x16x32_bf16 v[62:65], v[156:159], v[194:197], v[62:65]
	v_mfma_f32_16x16x32_bf16 v[54:57], v[170:173], v[194:197], v[54:57]
	v_mfma_f32_16x16x32_bf16 v[46:49], v[156:159], v[202:205], v[46:49]
	v_mfma_f32_16x16x32_bf16 v[38:41], v[170:173], v[202:205], v[38:41]
	v_mfma_f32_16x16x32_bf16 v[30:33], v[156:159], v[210:213], v[30:33]
	v_mfma_f32_16x16x32_bf16 v[22:25], v[170:173], v[210:213], v[22:25]
	v_mfma_f32_16x16x32_bf16 v[14:17], v[156:159], v[218:221], v[14:17]
	v_mfma_f32_16x16x32_bf16 v[6:9], v[170:173], v[218:221], v[6:9]
	v_mfma_f32_16x16x32_bf16 v[62:65], v[166:169], v[198:201], v[62:65]
	v_mfma_f32_16x16x32_bf16 v[54:57], v[174:177], v[198:201], v[54:57]
	v_mfma_f32_16x16x32_bf16 v[46:49], v[166:169], v[206:209], v[46:49]
	v_mfma_f32_16x16x32_bf16 v[38:41], v[174:177], v[206:209], v[38:41]
	v_mfma_f32_16x16x32_bf16 v[30:33], v[166:169], v[214:217], v[30:33]
	v_mfma_f32_16x16x32_bf16 v[22:25], v[174:177], v[214:217], v[22:25]
	v_mfma_f32_16x16x32_bf16 v[14:17], v[166:169], v[222:225], v[14:17]
	v_mfma_f32_16x16x32_bf16 v[6:9], v[174:177], v[222:225], v[6:9]
	v_mfma_f32_16x16x32_bf16 v[58:61], v[178:181], v[194:197], v[58:61]
	v_mfma_f32_16x16x32_bf16 v[50:53], v[186:189], v[194:197], v[50:53]
	v_mfma_f32_16x16x32_bf16 v[42:45], v[178:181], v[202:205], v[42:45]
	v_mfma_f32_16x16x32_bf16 v[34:37], v[186:189], v[202:205], v[34:37]
	v_mfma_f32_16x16x32_bf16 v[26:29], v[178:181], v[210:213], v[26:29]
	v_mfma_f32_16x16x32_bf16 v[18:21], v[186:189], v[210:213], v[18:21]
	v_mfma_f32_16x16x32_bf16 v[10:13], v[178:181], v[218:221], v[10:13]
	v_mfma_f32_16x16x32_bf16 v[2:5], v[186:189], v[218:221], v[2:5]
	v_mfma_f32_16x16x32_bf16 v[58:61], v[182:185], v[198:201], v[58:61]
	v_mfma_f32_16x16x32_bf16 v[50:53], v[190:193], v[198:201], v[50:53]
	v_mfma_f32_16x16x32_bf16 v[42:45], v[182:185], v[206:209], v[42:45]
	v_mfma_f32_16x16x32_bf16 v[34:37], v[190:193], v[206:209], v[34:37]
	v_mfma_f32_16x16x32_bf16 v[26:29], v[182:185], v[214:217], v[26:29]
	v_mfma_f32_16x16x32_bf16 v[18:21], v[190:193], v[214:217], v[18:21]
	v_mfma_f32_16x16x32_bf16 v[10:13], v[182:185], v[222:225], v[10:13]
	v_mfma_f32_16x16x32_bf16 v[2:5], v[190:193], v[222:225], v[2:5]
	s_barrier
	s_setprio 0
	s_mov_b32 s7, s47
	s_add_u32 s88, s88, 0x100
	s_addc_u32 s89, s89, 0
	s_add_u32 s86, s86, 0x100
	s_addc_u32 s87, s87, 0
	s_cmp_ge_i32 s47, s101
	s_cbranch_scc1 .Lmy_kexit_8
.LBB0_1573:
	s_add_u32 s98, s86, 0xfffc0080
	s_addc_u32 s99, s87, -1
	s_cmp_eq_u32 s7, s100
	s_cselect_b64 s[94:95], s[90:91], s[98:99]
	s_cselect_b64 s[96:97], s[92:93], s[88:89]
	s_add_i32 s47, s7, 2
	s_mov_b32 m0, s74
	ds_read_b128 v[156:159], v230
	global_load_lds_dwordx4 v144, s[86:87]
	s_mov_b32 m0, s75
	ds_read_b128 v[166:169], v234
	global_load_lds_dwordx4 v142, s[86:87]
	ds_read_b128 v[170:173], v230 offset:2048
	ds_read_b128 v[174:177], v234 offset:2048
	ds_read_b128 v[178:181], v231
	ds_read_b128 v[182:185], v235
	ds_read_b128 v[186:189], v231 offset:2048
	ds_read_b128 v[190:193], v235 offset:2048
	ds_read_b128 v[194:197], v163
	ds_read_b128 v[198:201], v238
	ds_read_b128 v[202:205], v163 offset:2048
	ds_read_b128 v[206:209], v238 offset:2048
	ds_read_b128 v[210:213], v163 offset:4096
	ds_read_b128 v[214:217], v238 offset:4096
	ds_read_b128 v[218:221], v163 offset:6144
	ds_read_b128 v[222:225], v238 offset:6144
	s_waitcnt vmcnt(8)
	s_waitcnt lgkmcnt(0)
	s_setprio 1
	s_barrier
	v_mfma_f32_16x16x32_bf16 v[122:125], v[156:159], v[194:197], v[122:125]
	v_mfma_f32_16x16x32_bf16 v[118:121], v[170:173], v[194:197], v[118:121]
	v_mfma_f32_16x16x32_bf16 v[110:113], v[156:159], v[202:205], v[110:113]
	v_mfma_f32_16x16x32_bf16 v[102:105], v[170:173], v[202:205], v[102:105]
	v_mfma_f32_16x16x32_bf16 v[94:97], v[156:159], v[210:213], v[94:97]
	v_mfma_f32_16x16x32_bf16 v[86:89], v[170:173], v[210:213], v[86:89]
	v_mfma_f32_16x16x32_bf16 v[78:81], v[156:159], v[218:221], v[78:81]
	v_mfma_f32_16x16x32_bf16 v[70:73], v[170:173], v[218:221], v[70:73]
	v_mfma_f32_16x16x32_bf16 v[122:125], v[166:169], v[198:201], v[122:125]
	v_mfma_f32_16x16x32_bf16 v[118:121], v[174:177], v[198:201], v[118:121]
	v_mfma_f32_16x16x32_bf16 v[110:113], v[166:169], v[206:209], v[110:113]
	v_mfma_f32_16x16x32_bf16 v[102:105], v[174:177], v[206:209], v[102:105]
	v_mfma_f32_16x16x32_bf16 v[94:97], v[166:169], v[214:217], v[94:97]
	v_mfma_f32_16x16x32_bf16 v[86:89], v[174:177], v[214:217], v[86:89]
	v_mfma_f32_16x16x32_bf16 v[78:81], v[166:169], v[222:225], v[78:81]
	v_mfma_f32_16x16x32_bf16 v[70:73], v[174:177], v[222:225], v[70:73]
	v_mfma_f32_16x16x32_bf16 v[126:129], v[178:181], v[194:197], v[126:129]
	v_mfma_f32_16x16x32_bf16 v[114:117], v[186:189], v[194:197], v[114:117]
	v_mfma_f32_16x16x32_bf16 v[106:109], v[178:181], v[202:205], v[106:109]
	v_mfma_f32_16x16x32_bf16 v[98:101], v[186:189], v[202:205], v[98:101]
	v_mfma_f32_16x16x32_bf16 v[90:93], v[178:181], v[210:213], v[90:93]
	v_mfma_f32_16x16x32_bf16 v[82:85], v[186:189], v[210:213], v[82:85]
	v_mfma_f32_16x16x32_bf16 v[74:77], v[178:181], v[218:221], v[74:77]
	v_mfma_f32_16x16x32_bf16 v[66:69], v[186:189], v[218:221], v[66:69]
	v_mfma_f32_16x16x32_bf16 v[126:129], v[182:185], v[198:201], v[126:129]
	v_mfma_f32_16x16x32_bf16 v[114:117], v[190:193], v[198:201], v[114:117]
	v_mfma_f32_16x16x32_bf16 v[106:109], v[182:185], v[206:209], v[106:109]
	v_mfma_f32_16x16x32_bf16 v[98:101], v[190:193], v[206:209], v[98:101]
	v_mfma_f32_16x16x32_bf16 v[90:93], v[182:185], v[214:217], v[90:93]
	v_mfma_f32_16x16x32_bf16 v[82:85], v[190:193], v[214:217], v[82:85]
	v_mfma_f32_16x16x32_bf16 v[74:77], v[182:185], v[222:225], v[74:77]
	v_mfma_f32_16x16x32_bf16 v[66:69], v[190:193], v[222:225], v[66:69]
	s_barrier
	s_setprio 0
	s_add_u32 s98, s96, 0x40000
	s_addc_u32 s99, s97, 0
	s_add_i32 s7, s71, s29
	s_mov_b32 m0, s7
	ds_read_b128 v[194:197], v163 offset:16384
	global_load_lds_dwordx4 v132, s[96:97]
	s_add_i32 m0, s7, 0x2000
	s_add_i32 s7, s72, s29
	global_load_lds_dwordx4 v136, s[96:97]
	s_mov_b32 m0, s7
	ds_read_b128 v[198:201], v238 offset:16384
	global_load_lds_dwordx4 v132, s[98:99]
	s_add_i32 m0, s7, 0x2000
	ds_read_b128 v[202:205], v163 offset:18432
	global_load_lds_dwordx4 v136, s[98:99]
	s_mov_b32 m0, s51
	ds_read_b128 v[206:209], v238 offset:18432
	global_load_lds_dwordx4 v130, s[94:95]
	s_mov_b32 m0, s60
	ds_read_b128 v[210:213], v163 offset:20480
	global_load_lds_dwordx4 v134, s[94:95]
	ds_read_b128 v[214:217], v238 offset:20480
	ds_read_b128 v[218:221], v163 offset:22528
	ds_read_b128 v[222:225], v238 offset:22528
	s_waitcnt vmcnt(8)
	s_waitcnt lgkmcnt(0)
	s_setprio 1
	s_barrier
	v_mfma_f32_16x16x32_bf16 v[62:65], v[156:159], v[194:197], v[62:65]
	v_mfma_f32_16x16x32_bf16 v[54:57], v[170:173], v[194:197], v[54:57]
	v_mfma_f32_16x16x32_bf16 v[46:49], v[156:159], v[202:205], v[46:49]
	v_mfma_f32_16x16x32_bf16 v[38:41], v[170:173], v[202:205], v[38:41]
	v_mfma_f32_16x16x32_bf16 v[30:33], v[156:159], v[210:213], v[30:33]
	v_mfma_f32_16x16x32_bf16 v[22:25], v[170:173], v[210:213], v[22:25]
	v_mfma_f32_16x16x32_bf16 v[14:17], v[156:159], v[218:221], v[14:17]
	v_mfma_f32_16x16x32_bf16 v[6:9], v[170:173], v[218:221], v[6:9]
	v_mfma_f32_16x16x32_bf16 v[62:65], v[166:169], v[198:201], v[62:65]
	v_mfma_f32_16x16x32_bf16 v[54:57], v[174:177], v[198:201], v[54:57]
	v_mfma_f32_16x16x32_bf16 v[46:49], v[166:169], v[206:209], v[46:49]
	v_mfma_f32_16x16x32_bf16 v[38:41], v[174:177], v[206:209], v[38:41]
	v_mfma_f32_16x16x32_bf16 v[30:33], v[166:169], v[214:217], v[30:33]
	v_mfma_f32_16x16x32_bf16 v[22:25], v[174:177], v[214:217], v[22:25]
	v_mfma_f32_16x16x32_bf16 v[14:17], v[166:169], v[222:225], v[14:17]
	v_mfma_f32_16x16x32_bf16 v[6:9], v[174:177], v[222:225], v[6:9]
	v_mfma_f32_16x16x32_bf16 v[58:61], v[178:181], v[194:197], v[58:61]
	v_mfma_f32_16x16x32_bf16 v[50:53], v[186:189], v[194:197], v[50:53]
	v_mfma_f32_16x16x32_bf16 v[42:45], v[178:181], v[202:205], v[42:45]
	v_mfma_f32_16x16x32_bf16 v[34:37], v[186:189], v[202:205], v[34:37]
	v_mfma_f32_16x16x32_bf16 v[26:29], v[178:181], v[210:213], v[26:29]
	v_mfma_f32_16x16x32_bf16 v[18:21], v[186:189], v[210:213], v[18:21]
	v_mfma_f32_16x16x32_bf16 v[10:13], v[178:181], v[218:221], v[10:13]
	v_mfma_f32_16x16x32_bf16 v[2:5], v[186:189], v[218:221], v[2:5]
	v_mfma_f32_16x16x32_bf16 v[58:61], v[182:185], v[198:201], v[58:61]
	v_mfma_f32_16x16x32_bf16 v[50:53], v[190:193], v[198:201], v[50:53]
	v_mfma_f32_16x16x32_bf16 v[42:45], v[182:185], v[206:209], v[42:45]
	v_mfma_f32_16x16x32_bf16 v[34:37], v[190:193], v[206:209], v[34:37]
	v_mfma_f32_16x16x32_bf16 v[26:29], v[182:185], v[214:217], v[26:29]
	v_mfma_f32_16x16x32_bf16 v[18:21], v[190:193], v[214:217], v[18:21]
	v_mfma_f32_16x16x32_bf16 v[10:13], v[182:185], v[222:225], v[10:13]
	v_mfma_f32_16x16x32_bf16 v[2:5], v[190:193], v[222:225], v[2:5]
	s_barrier
	s_setprio 0
	s_add_u32 s98, s94, 0x40000
	s_addc_u32 s99, s95, 0
	s_add_i32 s7, 0, 0x18000
	s_add_i32 s49, 0, 0x1c000
	s_mov_b32 m0, s61
	ds_read_b128 v[156:159], v232
	global_load_lds_dwordx4 v130, s[98:99]
	s_mov_b32 m0, s62
	ds_read_b128 v[166:169], v236
	global_load_lds_dwordx4 v134, s[98:99]
	ds_read_b128 v[170:173], v232 offset:2048
	ds_read_b128 v[174:177], v236 offset:2048
	ds_read_b128 v[178:181], v233
	ds_read_b128 v[182:185], v237
	ds_read_b128 v[186:189], v233 offset:2048
	ds_read_b128 v[190:193], v237 offset:2048
	ds_read_b128 v[194:197], v163 offset:32768
	ds_read_b128 v[198:201], v238 offset:32768
	ds_read_b128 v[202:205], v163 offset:34816
	ds_read_b128 v[206:209], v238 offset:34816
	ds_read_b128 v[210:213], v163 offset:36864
	ds_read_b128 v[214:217], v238 offset:36864
	ds_read_b128 v[218:221], v163 offset:38912
	ds_read_b128 v[222:225], v238 offset:38912
	s_waitcnt vmcnt(8)
	s_waitcnt lgkmcnt(0)
	s_setprio 1
	s_barrier
	v_mfma_f32_16x16x32_bf16 v[122:125], v[156:159], v[194:197], v[122:125]
	v_mfma_f32_16x16x32_bf16 v[118:121], v[170:173], v[194:197], v[118:121]
	v_mfma_f32_16x16x32_bf16 v[110:113], v[156:159], v[202:205], v[110:113]
	v_mfma_f32_16x16x32_bf16 v[102:105], v[170:173], v[202:205], v[102:105]
	v_mfma_f32_16x16x32_bf16 v[94:97], v[156:159], v[210:213], v[94:97]
	v_mfma_f32_16x16x32_bf16 v[86:89], v[170:173], v[210:213], v[86:89]
	v_mfma_f32_16x16x32_bf16 v[78:81], v[156:159], v[218:221], v[78:81]
	v_mfma_f32_16x16x32_bf16 v[70:73], v[170:173], v[218:221], v[70:73]
	v_mfma_f32_16x16x32_bf16 v[122:125], v[166:169], v[198:201], v[122:125]
	v_mfma_f32_16x16x32_bf16 v[118:121], v[174:177], v[198:201], v[118:121]
	v_mfma_f32_16x16x32_bf16 v[110:113], v[166:169], v[206:209], v[110:113]
	v_mfma_f32_16x16x32_bf16 v[102:105], v[174:177], v[206:209], v[102:105]
	v_mfma_f32_16x16x32_bf16 v[94:97], v[166:169], v[214:217], v[94:97]
	v_mfma_f32_16x16x32_bf16 v[86:89], v[174:177], v[214:217], v[86:89]
	v_mfma_f32_16x16x32_bf16 v[78:81], v[166:169], v[222:225], v[78:81]
	v_mfma_f32_16x16x32_bf16 v[70:73], v[174:177], v[222:225], v[70:73]
	v_mfma_f32_16x16x32_bf16 v[126:129], v[178:181], v[194:197], v[126:129]
	v_mfma_f32_16x16x32_bf16 v[114:117], v[186:189], v[194:197], v[114:117]
	v_mfma_f32_16x16x32_bf16 v[106:109], v[178:181], v[202:205], v[106:109]
	v_mfma_f32_16x16x32_bf16 v[98:101], v[186:189], v[202:205], v[98:101]
	v_mfma_f32_16x16x32_bf16 v[90:93], v[178:181], v[210:213], v[90:93]
	v_mfma_f32_16x16x32_bf16 v[82:85], v[186:189], v[210:213], v[82:85]
	v_mfma_f32_16x16x32_bf16 v[74:77], v[178:181], v[218:221], v[74:77]
	v_mfma_f32_16x16x32_bf16 v[66:69], v[186:189], v[218:221], v[66:69]
	v_mfma_f32_16x16x32_bf16 v[126:129], v[182:185], v[198:201], v[126:129]
	v_mfma_f32_16x16x32_bf16 v[114:117], v[190:193], v[198:201], v[114:117]
	v_mfma_f32_16x16x32_bf16 v[106:109], v[182:185], v[206:209], v[106:109]
	v_mfma_f32_16x16x32_bf16 v[98:101], v[190:193], v[206:209], v[98:101]
	v_mfma_f32_16x16x32_bf16 v[90:93], v[182:185], v[214:217], v[90:93]
	v_mfma_f32_16x16x32_bf16 v[82:85], v[190:193], v[214:217], v[82:85]
	v_mfma_f32_16x16x32_bf16 v[74:77], v[182:185], v[222:225], v[74:77]
	v_mfma_f32_16x16x32_bf16 v[66:69], v[190:193], v[222:225], v[66:69]
	s_barrier
	s_setprio 0
	s_add_u32 s96, s96, 0x80
	s_addc_u32 s97, s97, 0
	s_add_u32 s98, s96, 0x40000
	s_addc_u32 s99, s97, 0
	s_add_u32 s94, s94, 0x80
	s_addc_u32 s95, s95, 0
	s_add_i32 s7, s7, s29
	s_mov_b32 m0, s7
	ds_read_b128 v[194:197], v163 offset:49152
	global_load_lds_dwordx4 v132, s[96:97]
	s_add_i32 m0, s7, 0x2000
	s_add_i32 s7, s49, s29
	global_load_lds_dwordx4 v136, s[96:97]
	s_mov_b32 m0, s7
	ds_read_b128 v[198:201], v238 offset:49152
	global_load_lds_dwordx4 v132, s[98:99]
	s_add_i32 m0, s7, 0x2000
	ds_read_b128 v[202:205], v163 offset:51200
	global_load_lds_dwordx4 v136, s[98:99]
	s_mov_b32 m0, s63
	ds_read_b128 v[206:209], v238 offset:51200
	global_load_lds_dwordx4 v130, s[94:95]
	s_mov_b32 m0, s64
	ds_read_b128 v[210:213], v163 offset:53248
	global_load_lds_dwordx4 v134, s[94:95]
	ds_read_b128 v[214:217], v238 offset:53248
	ds_read_b128 v[218:221], v163 offset:55296
	ds_read_b128 v[222:225], v238 offset:55296
	s_waitcnt vmcnt(8)
	s_waitcnt lgkmcnt(0)
	s_setprio 1
	s_barrier
	v_mfma_f32_16x16x32_bf16 v[62:65], v[156:159], v[194:197], v[62:65]
	v_mfma_f32_16x16x32_bf16 v[54:57], v[170:173], v[194:197], v[54:57]
	v_mfma_f32_16x16x32_bf16 v[46:49], v[156:159], v[202:205], v[46:49]
	v_mfma_f32_16x16x32_bf16 v[38:41], v[170:173], v[202:205], v[38:41]
	v_mfma_f32_16x16x32_bf16 v[30:33], v[156:159], v[210:213], v[30:33]
	v_mfma_f32_16x16x32_bf16 v[22:25], v[170:173], v[210:213], v[22:25]
	v_mfma_f32_16x16x32_bf16 v[14:17], v[156:159], v[218:221], v[14:17]
	v_mfma_f32_16x16x32_bf16 v[6:9], v[170:173], v[218:221], v[6:9]
	v_mfma_f32_16x16x32_bf16 v[62:65], v[166:169], v[198:201], v[62:65]
	v_mfma_f32_16x16x32_bf16 v[54:57], v[174:177], v[198:201], v[54:57]
	v_mfma_f32_16x16x32_bf16 v[46:49], v[166:169], v[206:209], v[46:49]
	v_mfma_f32_16x16x32_bf16 v[38:41], v[174:177], v[206:209], v[38:41]
	v_mfma_f32_16x16x32_bf16 v[30:33], v[166:169], v[214:217], v[30:33]
	v_mfma_f32_16x16x32_bf16 v[22:25], v[174:177], v[214:217], v[22:25]
	v_mfma_f32_16x16x32_bf16 v[14:17], v[166:169], v[222:225], v[14:17]
	v_mfma_f32_16x16x32_bf16 v[6:9], v[174:177], v[222:225], v[6:9]
	v_mfma_f32_16x16x32_bf16 v[58:61], v[178:181], v[194:197], v[58:61]
	v_mfma_f32_16x16x32_bf16 v[50:53], v[186:189], v[194:197], v[50:53]
	v_mfma_f32_16x16x32_bf16 v[42:45], v[178:181], v[202:205], v[42:45]
	v_mfma_f32_16x16x32_bf16 v[34:37], v[186:189], v[202:205], v[34:37]
	v_mfma_f32_16x16x32_bf16 v[26:29], v[178:181], v[210:213], v[26:29]
	v_mfma_f32_16x16x32_bf16 v[18:21], v[186:189], v[210:213], v[18:21]
	v_mfma_f32_16x16x32_bf16 v[10:13], v[178:181], v[218:221], v[10:13]
	v_mfma_f32_16x16x32_bf16 v[2:5], v[186:189], v[218:221], v[2:5]
	v_mfma_f32_16x16x32_bf16 v[58:61], v[182:185], v[198:201], v[58:61]
	v_mfma_f32_16x16x32_bf16 v[50:53], v[190:193], v[198:201], v[50:53]
	v_mfma_f32_16x16x32_bf16 v[42:45], v[182:185], v[206:209], v[42:45]
	v_mfma_f32_16x16x32_bf16 v[34:37], v[190:193], v[206:209], v[34:37]
	v_mfma_f32_16x16x32_bf16 v[26:29], v[182:185], v[214:217], v[26:29]
	v_mfma_f32_16x16x32_bf16 v[18:21], v[190:193], v[214:217], v[18:21]
	v_mfma_f32_16x16x32_bf16 v[10:13], v[182:185], v[222:225], v[10:13]
	v_mfma_f32_16x16x32_bf16 v[2:5], v[190:193], v[222:225], v[2:5]
	s_barrier
	s_setprio 0
	s_mov_b32 s7, s47
	s_add_u32 s88, s88, 0x100
	s_addc_u32 s89, s89, 0
	s_add_u32 s86, s86, 0x100
	s_addc_u32 s87, s87, 0
	s_cmp_ge_i32 s47, s101
	s_cbranch_scc0 .LBB0_1573

.LBB0_1750:
	v_ashrrev_i32_e32 v7, 31, v14
	v_lshrrev_b32_e32 v7, 26, v7
	v_add_u32_e32 v7, v14, v7
	v_ashrrev_i32_e32 v15, 6, v7
	v_bfe_i32 v7, v14, 27, 1
	v_lshlrev_b32_e32 v6, 4, v14
	v_lshrrev_b32_e32 v7, 22, v7
	v_add_u32_e32 v7, v6, v7
	v_and_b32_e32 v7, 0xfffffc00, v7
	v_sub_u32_e32 v7, v6, v7
	v_lshrrev_b32_e32 v8, 4, v7
	v_bitop3_b32 v8, v8, v7, 32 bitop3:0x6c
	v_ashrrev_i32_e32 v7, 31, v7
	v_lshrrev_b32_e32 v7, 26, v7
	v_add_u32_e32 v7, v8, v7
	v_ashrrev_i32_e32 v16, 6, v7
	v_lshlrev_b32_e32 v9, 3, v15
	v_mul_i32_i24_e32 v10, 64, v16
	v_and_b32_e32 v9, -16, v9
	v_sub_u32_e32 v8, v8, v10
	v_mov_b32_e32 v10, 1
	v_add_u32_e32 v7, v16, v9
	v_lshlrev_b32_e32 v9, 5, v15
	v_ashrrev_i16_sdwa v8, v10, sext(v8) dst_sel:DWORD dst_unused:UNUSED_PAD src0_sel:DWORD src1_sel:BYTE_0
	v_and_b32_e32 v9, 32, v9
	v_bfe_i32 v17, v8, 0, 16
	v_and_b32_e32 v12, 3, v16
	s_mov_b32 s1, 0x1fffe0
	v_add_lshl_u32 v9, v9, v17, 1
	v_add_u32_e32 v6, 0x2000, v6
	v_lshlrev_b32_e32 v8, 1, v7
	v_lshrrev_b32_e32 v11, 2, v7
	v_and_or_b32 v12, v7, s1, v12
	v_lshl_add_u32 v130, v7, 11, v9
	v_ashrrev_i32_e32 v7, 31, v6
	v_lshrrev_b32_e32 v7, 22, v7
	v_add_u32_e32 v7, v6, v7
	v_ashrrev_i32_e32 v18, 10, v7
	v_mul_i32_i24_e32 v7, 0x400, v18
	v_sub_u32_e32 v6, v6, v7
	v_and_b32_e32 v8, 24, v8
	v_and_b32_e32 v11, 4, v11
	v_lshrrev_b32_e32 v7, 4, v6
	v_or3_b32 v8, v12, v11, v8
	v_bitop3_b32 v6, v7, v6, 32 bitop3:0x6c
	v_lshl_add_u32 v132, v8, 11, v9
	v_ashrrev_i32_e32 v8, 31, v6
	v_lshrrev_b32_e32 v8, 26, v8
	v_add_u32_e32 v8, v6, v8
	v_lshlrev_b32_e32 v7, 3, v18
	v_ashrrev_i32_e32 v19, 6, v8
	v_and_b32_e32 v8, 0xc0, v8
	v_and_b32_e32 v7, -16, v7
	v_sub_u32_e32 v6, v6, v8
	s_ashr_i32 s0, s16, 6
	v_add_u32_e32 v7, v19, v7
	v_ashrrev_i16_sdwa v6, v10, sext(v6) dst_sel:DWORD dst_unused:UNUSED_PAD src0_sel:DWORD src1_sel:BYTE_0
	v_lshlrev_b32_e32 v9, 5, v18
	v_bfe_i32 v20, v6, 0, 16
	v_lshlrev_b32_e32 v6, 1, v7
	v_lshrrev_b32_e32 v8, 2, v7
	v_and_b32_e32 v10, 3, v19
	s_lshl_b32 s23, s0, 10
	v_and_b32_e32 v9, 32, v9
	v_and_b32_e32 v6, 24, v6
	v_and_b32_e32 v8, 4, v8
	v_and_or_b32 v10, v7, s1, v10
	s_add_i32 s47, s23, 0
	v_or3_b32 v6, v10, v8, v6
	v_add_lshl_u32 v8, v9, v20, 1
	s_add_i32 m0, s47, 0x10000
	v_readfirstlane_b32 s8, v4
	v_readfirstlane_b32 s9, v5
	v_lshl_add_u32 v136, v6, 11, v8
	v_lshl_add_u32 v134, v7, 11, v8
	s_add_i32 s56, s47, 0x2000
	s_add_i32 s57, s47, 0x4000
	s_add_i32 s58, s47, 0x6000
	v_lshrrev_b32_e32 v242, 6, v1
	v_and_b32_e32 v243, 63, v1
	v_lshlrev_b32_e32 v245, 4, v243
	v_lshrrev_b32_e32 v244, 5, v243
	v_lshlrev_b32_e32 v244, 5, v244
	v_xor_b32_e32 v245, v245, v244
	v_lshrrev_b32_e32 v244, 1, v242
	v_lshlrev_b32_e32 v244, 4, v244
	v_lshrrev_b32_e32 v243, 6, v245
	v_add_u32_e32 v244, v244, v243
	v_and_b32_e32 v245, 63, v245
	v_and_b32_e32 v242, 1, v242
	v_lshl_add_u32 v245, v242, 6, v245
	v_mul_u32_u24_e32 v244, 0x800, v244
	v_add_u32_e32 v240, v244, v245
	v_lshrrev_b32_e32 v242, 6, v1
	v_and_b32_e32 v243, 63, v1
	v_lshrrev_b32_e32 v244, 3, v243
	v_lshl_add_u32 v244, v242, 3, v244
	v_lshrrev_b32_e32 v245, 4, v243
	v_and_b32_e32 v245, 3, v245
	v_lshlrev_b32_e32 v245, 1, v245
	v_and_b32_e32 v243, 7, v243
	v_xor_b32_e32 v245, v243, v245
	v_lshlrev_b32_e32 v245, 4, v245
	v_mul_u32_u24_e32 v244, 0x800, v244
	v_add_u32_e32 v241, v244, v245
	v_sub_u32_e32 v130, v130, v240
	v_add_u32_e32 v130, v130, v241
	v_lshrrev_b32_e32 v242, 6, v1
	v_and_b32_e32 v243, 63, v1
	v_lshlrev_b32_e32 v245, 4, v243
	v_lshrrev_b32_e32 v244, 5, v243
	v_lshlrev_b32_e32 v244, 5, v244
	v_xor_b32_e32 v245, v245, v244
	v_add_u32_e32 v242, 8, v242
	v_lshrrev_b32_e32 v244, 1, v242
	v_lshlrev_b32_e32 v244, 4, v244
	v_lshrrev_b32_e32 v243, 6, v245
	v_add_u32_e32 v244, v244, v243
	v_and_b32_e32 v245, 63, v245
	v_and_b32_e32 v242, 1, v242
	v_lshl_add_u32 v245, v242, 6, v245
	v_mul_u32_u24_e32 v244, 0x800, v244
	v_add_u32_e32 v240, v244, v245
	v_lshrrev_b32_e32 v242, 6, v1
	v_and_b32_e32 v243, 63, v1
	v_lshrrev_b32_e32 v244, 3, v243
	v_lshl_add_u32 v244, v242, 3, v244
	v_add_u32_e32 v244, 64, v244
	v_lshrrev_b32_e32 v245, 4, v243
	v_and_b32_e32 v245, 3, v245
	v_lshlrev_b32_e32 v245, 1, v245
	v_and_b32_e32 v243, 7, v243
	v_xor_b32_e32 v245, v243, v245
	v_lshlrev_b32_e32 v245, 4, v245
	v_mul_u32_u24_e32 v244, 0x800, v244
	v_add_u32_e32 v241, v244, v245
	v_sub_u32_e32 v134, v134, v240
	v_add_u32_e32 v134, v134, v241
	v_lshrrev_b32_e32 v242, 6, v1
	v_and_b32_e32 v243, 63, v1
	v_lshlrev_b32_e32 v245, 4, v243
	v_lshrrev_b32_e32 v244, 5, v243
	v_lshlrev_b32_e32 v244, 5, v244
	v_xor_b32_e32 v245, v245, v244
	v_lshrrev_b32_e32 v244, 1, v242
	v_lshlrev_b32_e32 v244, 4, v244
	v_lshrrev_b32_e32 v243, 6, v245
	v_add_u32_e32 v244, v244, v243
	v_and_b32_e32 v245, 63, v245
	v_and_b32_e32 v242, 1, v242
	v_lshl_add_u32 v245, v242, 6, v245
	v_and_b32_e32 v242, 31, v244
	v_sub_u32_e32 v244, v244, v242
	v_and_b32_e32 v243, 3, v242
	v_add_u32_e32 v244, v244, v243
	v_lshrrev_b32_e32 v243, 4, v242
	v_lshl_add_u32 v244, v243, 2, v244
	v_and_b32_e32 v243, 15, v242
	v_lshrrev_b32_e32 v243, 2, v243
	v_lshl_add_u32 v244, v243, 3, v244
	v_mul_u32_u24_e32 v244, 0x800, v244
	v_add_u32_e32 v240, v244, v245
	v_lshrrev_b32_e32 v242, 6, v1
	v_and_b32_e32 v243, 63, v1
	v_lshrrev_b32_e32 v244, 3, v243
	v_lshl_add_u32 v244, v242, 3, v244
	v_lshrrev_b32_e32 v245, 4, v243
	v_and_b32_e32 v245, 3, v245
	v_lshlrev_b32_e32 v245, 1, v245
	v_and_b32_e32 v243, 7, v243
	v_xor_b32_e32 v245, v243, v245
	v_lshlrev_b32_e32 v245, 4, v245
	v_and_b32_e32 v242, 31, v244
	v_sub_u32_e32 v244, v244, v242
	v_and_b32_e32 v243, 3, v242
	v_add_u32_e32 v244, v244, v243
	v_lshrrev_b32_e32 v243, 4, v242
	v_lshl_add_u32 v244, v243, 2, v244
	v_and_b32_e32 v243, 15, v242
	v_lshrrev_b32_e32 v243, 2, v243
	v_lshl_add_u32 v244, v243, 3, v244
	v_mul_u32_u24_e32 v244, 0x800, v244
	v_add_u32_e32 v241, v244, v245
	v_sub_u32_e32 v132, v132, v240
	v_add_u32_e32 v132, v132, v241
	v_lshrrev_b32_e32 v242, 6, v1
	v_and_b32_e32 v243, 63, v1
	v_lshlrev_b32_e32 v245, 4, v243
	v_lshrrev_b32_e32 v244, 5, v243
	v_lshlrev_b32_e32 v244, 5, v244
	v_xor_b32_e32 v245, v245, v244
	v_add_u32_e32 v242, 8, v242
	v_lshrrev_b32_e32 v244, 1, v242
	v_lshlrev_b32_e32 v244, 4, v244
	v_lshrrev_b32_e32 v243, 6, v245
	v_add_u32_e32 v244, v244, v243
	v_and_b32_e32 v245, 63, v245
	v_and_b32_e32 v242, 1, v242
	v_lshl_add_u32 v245, v242, 6, v245
	v_and_b32_e32 v242, 31, v244
	v_sub_u32_e32 v244, v244, v242
	v_and_b32_e32 v243, 3, v242
	v_add_u32_e32 v244, v244, v243
	v_lshrrev_b32_e32 v243, 4, v242
	v_lshl_add_u32 v244, v243, 2, v244
	v_and_b32_e32 v243, 15, v242
	v_lshrrev_b32_e32 v243, 2, v243
	v_lshl_add_u32 v244, v243, 3, v244
	v_mul_u32_u24_e32 v244, 0x800, v244
	v_add_u32_e32 v240, v244, v245
	v_lshrrev_b32_e32 v242, 6, v1
	v_and_b32_e32 v243, 63, v1
	v_lshrrev_b32_e32 v244, 3, v243
	v_lshl_add_u32 v244, v242, 3, v244
	v_add_u32_e32 v244, 64, v244
	v_lshrrev_b32_e32 v245, 4, v243
	v_and_b32_e32 v245, 3, v245
	v_lshlrev_b32_e32 v245, 1, v245
	v_and_b32_e32 v243, 7, v243
	v_xor_b32_e32 v245, v243, v245
	v_lshlrev_b32_e32 v245, 4, v245
	v_and_b32_e32 v242, 31, v244
	v_sub_u32_e32 v244, v244, v242
	v_and_b32_e32 v243, 3, v242
	v_add_u32_e32 v244, v244, v243
	v_lshrrev_b32_e32 v243, 4, v242
	v_lshl_add_u32 v244, v243, 2, v244
	v_and_b32_e32 v243, 15, v242
	v_lshrrev_b32_e32 v243, 2, v243
	v_lshl_add_u32 v244, v243, 3, v244
	v_mul_u32_u24_e32 v244, 0x800, v244
	v_add_u32_e32 v241, v244, v245
	v_sub_u32_e32 v136, v136, v240
	v_add_u32_e32 v136, v136, v241
	global_load_lds_dwordx4 v132, s[8:9]
	s_add_i32 m0, s47, 0x12000
	s_ashr_i32 s1, s16, 8
	global_load_lds_dwordx4 v136, s[8:9]
	s_mov_b64 s[8:9], 0x40000
	v_lshl_add_u64 v[6:7], v[4:5], 0, s[8:9]
	s_add_i32 m0, s47, 0x14000
	v_readfirstlane_b32 s10, v6
	v_readfirstlane_b32 s11, v7
	v_lshl_add_u64 v[6:7], v[2:3], 0, s[8:9]
	v_mov_b32_e32 v139, 0
	v_mov_b32_e32 v133, v139
	v_mov_b32_e32 v137, v139
	v_mov_b32_e32 v131, v139
	global_load_lds_dwordx4 v132, s[10:11]
	s_add_i32 m0, s47, 0x16000
	v_mov_b32_e32 v135, v139
	global_load_lds_dwordx4 v136, s[10:11]
	v_readfirstlane_b32 s10, v2
	v_readfirstlane_b32 s11, v3
	s_mov_b32 m0, s47
	s_cmp_eq_u32 s1, 1
	s_mov_b32 s59, 0
	v_lshl_add_u64 v[12:13], v[4:5], 0, v[132:133]
	v_lshl_add_u64 v[10:11], v[4:5], 0, v[136:137]
	global_load_lds_dwordx4 v130, s[10:11]
	s_mov_b32 m0, s56
	v_lshl_add_u64 v[8:9], v[2:3], 0, v[134:135]
	global_load_lds_dwordx4 v134, s[10:11]
	v_readfirstlane_b32 s10, v6
	v_readfirstlane_b32 s11, v7
	s_mov_b32 m0, s57
	v_lshl_add_u64 v[6:7], v[2:3], 0, v[130:131]
	s_nop 2
	global_load_lds_dwordx4 v130, s[10:11]
	s_mov_b32 m0, s58
	s_nop 0
	global_load_lds_dwordx4 v134, s[10:11]
	s_cselect_b64 s[10:11], -1, 0
	s_cmp_lg_u32 s1, 1
	s_cbranch_scc1 .LBB0_1752
	s_barrier
.LBB0_1752:
	s_and_b32 s5, s0, 3
	s_lshl_b32 s60, s1, 6
	s_lshl_b32 s1, s1, 13
	s_lshl_b32 s61, s5, 5
	s_lshl_b32 s17, s5, 12
	s_add_u32 s62, s38, 0x51a2000
	s_mov_b64 s[12:13], 0x80
	s_addc_u32 s63, s39, 0
	s_add_i32 m0, s47, 0x18000
	v_lshl_add_u64 v[12:13], v[12:13], 0, s[12:13]
	s_waitcnt vmcnt(2)
	s_barrier
	global_load_lds_dwordx4 v[12:13], off
	v_lshl_add_u64 v[10:11], v[10:11], 0, s[12:13]
	s_add_i32 m0, s47, 0x1a000
	s_add_i32 s64, s47, 0x8000
	global_load_lds_dwordx4 v[10:11], off
	v_lshl_add_u64 v[6:7], v[6:7], 0, s[12:13]
	s_mov_b32 m0, s64
	s_add_i32 s65, s47, 0xa000
	global_load_lds_dwordx4 v[6:7], off
	v_lshl_add_u64 v[6:7], v[8:9], 0, s[12:13]
	s_mov_b32 m0, s65
	s_mov_b64 s[14:15], 0x40080
	global_load_lds_dwordx4 v[6:7], off
	v_lshl_add_u64 v[6:7], v[4:5], 0, s[14:15]
	s_add_i32 m0, s47, 0x1c000
	v_lshl_add_u64 v[8:9], v[6:7], 0, v[132:133]
	global_load_lds_dwordx4 v[8:9], off
	v_lshl_add_u64 v[6:7], v[6:7], 0, v[136:137]
	s_add_i32 m0, s47, 0x1e000
	v_and_b32_e32 v140, 15, v14
	global_load_lds_dwordx4 v[6:7], off
	v_bfe_u32 v6, v14, 4, 2
	v_lshlrev_b32_e32 v7, 4, v6
	v_lshlrev_b32_e32 v9, 2, v14
	v_lshl_or_b32 v8, v140, 6, v7
	v_and_b32_e32 v9, 32, v9
	s_cmpk_lt_u32 s16, 0x100
	v_bitop3_b32 v141, v8, s17, v9 bitop3:0xde
	s_cselect_b64 s[16:17], -1, 0
	s_lshl_b32 s0, s0, 6
	v_bitop3_b32 v10, v8, s1, v9 bitop3:0xde
	v_and_or_b32 v158, s0, 64, v7
	v_cmp_eq_u32_e64 s[0:1], 0, v6
	v_lshl_or_b32 v159, v6, 3, s61
	v_lshlrev_b32_e32 v6, 14, v18
	v_and_b32_e32 v6, 0xffff8000, v6
	v_lshl_add_u32 v6, v19, 11, v6
	v_and_b32_e32 v7, 1, v18
	v_lshl_or_b32 v6, v7, 6, v6
	v_lshl_add_u32 v142, v20, 1, v6
	v_lshlrev_b32_e32 v6, 14, v15
	v_and_b32_e32 v6, 0xffff8000, v6
	v_lshl_add_u32 v6, v16, 11, v6
	v_and_b32_e32 v7, 1, v15
	s_waitcnt vmcnt(6)
	s_lshl_b32 s5, s5, 2
	v_lshl_or_b32 v6, v7, 6, v6
	s_add_u32 s66, s62, s5
	v_lshl_add_u32 v144, v17, 1, v6
	s_mov_b32 s20, 0xfffc0080
	v_mbcnt_lo_u32_b32 v6, -1, 0
	s_addc_u32 s67, s63, 0
	v_mov_b32_e32 v143, v139
	v_mov_b32_e32 v145, v139
	s_add_i32 s70, 0, 0x20020
	s_add_i32 s71, 0, 0x20018
	s_add_i32 s72, 0, 0x2002c
	s_add_i32 s73, 0, 0x20000
	s_mov_b64 s[18:19], 0x100
	s_mov_b32 s21, -1
	s_add_i32 s74, 0, 0x10000
	s_add_i32 s75, 0, 0x14000
	v_add_u32_e32 v160, 0, v10
	s_add_i32 s76, 0, 0x20010
	s_add_i32 s77, 0, 0x20024
	s_movk_i32 s78, 0x7fff
	s_mov_b32 s22, 0xbfb8aa3b
	v_mbcnt_hi_u32_b32 v161, -1, v6
	v_mov_b64_e32 v[146:147], v[2:3]
	v_mov_b64_e32 v[148:149], v[4:5]
	s_barrier
	v_lshrrev_b32_e32 v242, 6, v1
	v_and_b32_e32 v243, 63, v1
	v_lshlrev_b32_e32 v245, 4, v243
	v_lshrrev_b32_e32 v244, 5, v243
	v_lshlrev_b32_e32 v244, 5, v244
	v_xor_b32_e32 v245, v245, v244
	v_lshrrev_b32_e32 v244, 1, v242
	v_lshlrev_b32_e32 v244, 4, v244
	v_lshrrev_b32_e32 v243, 6, v245
	v_add_u32_e32 v244, v244, v243
	v_and_b32_e32 v245, 63, v245
	v_and_b32_e32 v242, 1, v242
	v_lshl_add_u32 v245, v242, 6, v245
	v_mul_u32_u24_e32 v244, 0x800, v244
	v_add_u32_e32 v240, v244, v245
	v_lshrrev_b32_e32 v242, 6, v1
	v_and_b32_e32 v243, 63, v1
	v_lshrrev_b32_e32 v244, 3, v243
	v_lshl_add_u32 v244, v242, 3, v244
	v_lshrrev_b32_e32 v245, 4, v243
	v_and_b32_e32 v245, 3, v245
	v_lshlrev_b32_e32 v245, 1, v245
	v_and_b32_e32 v243, 7, v243
	v_xor_b32_e32 v245, v243, v245
	v_lshlrev_b32_e32 v245, 4, v245
	v_mul_u32_u24_e32 v244, 0x800, v244
	v_add_u32_e32 v241, v244, v245
	v_sub_u32_e32 v144, v144, v240
	v_add_u32_e32 v144, v144, v241
	v_lshrrev_b32_e32 v242, 6, v1
	v_and_b32_e32 v243, 63, v1
	v_lshlrev_b32_e32 v245, 4, v243
	v_lshrrev_b32_e32 v244, 5, v243
	v_lshlrev_b32_e32 v244, 5, v244
	v_xor_b32_e32 v245, v245, v244
	v_add_u32_e32 v242, 8, v242
	v_lshrrev_b32_e32 v244, 1, v242
	v_lshlrev_b32_e32 v244, 4, v244
	v_lshrrev_b32_e32 v243, 6, v245
	v_add_u32_e32 v244, v244, v243
	v_and_b32_e32 v245, 63, v245
	v_and_b32_e32 v242, 1, v242
	v_lshl_add_u32 v245, v242, 6, v245
	v_mul_u32_u24_e32 v244, 0x800, v244
	v_add_u32_e32 v240, v244, v245
	v_lshrrev_b32_e32 v242, 6, v1
	v_and_b32_e32 v243, 63, v1
	v_lshrrev_b32_e32 v244, 3, v243
	v_lshl_add_u32 v244, v242, 3, v244
	v_add_u32_e32 v244, 64, v244
	v_lshrrev_b32_e32 v245, 4, v243
	v_and_b32_e32 v245, 3, v245
	v_lshlrev_b32_e32 v245, 1, v245
	v_and_b32_e32 v243, 7, v243
	v_xor_b32_e32 v245, v243, v245
	v_lshlrev_b32_e32 v245, 4, v245
	v_mul_u32_u24_e32 v244, 0x800, v244
	v_add_u32_e32 v241, v244, v245
	v_sub_u32_e32 v142, v142, v240
	v_add_u32_e32 v142, v142, v241
	v_and_b32_e32 v240, 63, v1
	v_and_b32_e32 v241, 15, v240
	v_lshrrev_b32_e32 v242, 4, v240
	v_lshlrev_b32_e32 v243, 6, v241
	v_lshl_add_u32 v243, v242, 4, v243
	v_lshrrev_b32_e32 v244, 3, v241
	v_lshlrev_b32_e32 v245, 5, v244
	v_xor_b32_e32 v243, v243, v245
	v_sub_u32_e32 v160, v160, v243
	v_lshlrev_b32_e32 v244, 10, v244
	v_and_b32_e32 v245, 7, v241
	v_lshl_add_u32 v244, v245, 7, v244
	v_add_u32_e32 v160, v160, v244
	v_lshrrev_b32_e32 v245, 1, v245
	v_lshlrev_b32_e32 v245, 1, v245
	v_add_u32_e32 v244, 4, v242
	v_xor_b32_e32 v244, v244, v245
	v_lshl_add_u32 v238, v244, 4, v160
	v_xor_b32_e32 v244, v242, v245
	v_lshl_add_u32 v160, v244, 4, v160
	v_and_b32_e32 v240, 63, v1
	v_and_b32_e32 v241, 15, v240
	v_lshrrev_b32_e32 v242, 4, v240
	v_lshlrev_b32_e32 v243, 6, v241
	v_lshl_add_u32 v243, v242, 4, v243
	v_lshrrev_b32_e32 v244, 3, v241
	v_lshlrev_b32_e32 v245, 5, v244
	v_xor_b32_e32 v243, v243, v245
	v_sub_u32_e32 v141, v141, v243
	v_lshlrev_b32_e32 v244, 10, v244
	v_and_b32_e32 v245, 7, v241
	v_lshl_add_u32 v244, v245, 7, v244
	v_add_u32_e32 v141, v141, v244
	v_lshrrev_b32_e32 v245, 1, v245
	v_lshlrev_b32_e32 v245, 1, v245
	v_add_u32_e32 v244, 4, v242
	v_xor_b32_e32 v244, v244, v245
	v_lshl_add_u32 v239, v244, 4, v141
	v_xor_b32_e32 v244, v242, v245
	v_lshl_add_u32 v141, v244, 4, v141
	s_branch .LBB0_1755

.Lmy_nb_9:
	s_nop 0
	v_readfirstlane_b32 s86, v152
	v_readfirstlane_b32 s87, v153
	v_readfirstlane_b32 s88, v150
	v_readfirstlane_b32 s89, v151
	v_readfirstlane_b32 s90, v146
	v_readfirstlane_b32 s91, v147
	v_readfirstlane_b32 s92, v148
	v_readfirstlane_b32 s93, v149
	v_readfirstlane_b32 s100, v154
	v_readfirstlane_b32 s101, v138
	v_add_u32_e32 v230, s74, v141
	v_add_u32_e32 v234, s74, v239
	v_add_u32_e32 v231, s75, v141
	v_add_u32_e32 v235, s75, v239
	v_add_u32_e32 v232, 0x18000, v141
	v_add_u32_e32 v236, 0x18000, v239
	v_add_u32_e32 v233, 0x1c000, v141
	v_add_u32_e32 v237, 0x1c000, v239
	s_add_u32 s98, s86, 0xfffc0080
	s_addc_u32 s99, s87, -1
	s_cmp_eq_u32 s5, s100
	s_cselect_b64 s[94:95], s[90:91], s[98:99]
	s_cselect_b64 s[96:97], s[92:93], s[88:89]
	s_add_i32 s29, s5, 2
	s_add_i32 m0, s47, 0xc000
	ds_read_b128 v[164:167], v230
	global_load_lds_dwordx4 v144, s[86:87]
	s_add_i32 m0, s47, 0xe000
	ds_read_b128 v[168:171], v234
	global_load_lds_dwordx4 v142, s[86:87]
	ds_read_b128 v[172:175], v230 offset:2048
	ds_read_b128 v[176:179], v234 offset:2048
	ds_read_b128 v[180:183], v231
	ds_read_b128 v[184:187], v235
	ds_read_b128 v[188:191], v231 offset:2048
	ds_read_b128 v[192:195], v235 offset:2048
	ds_read_b128 v[196:199], v160
	ds_read_b128 v[200:203], v238
	ds_read_b128 v[204:207], v160 offset:2048
	ds_read_b128 v[208:211], v238 offset:2048
	ds_read_b128 v[212:215], v160 offset:4096
	ds_read_b128 v[216:219], v238 offset:4096
	ds_read_b128 v[220:223], v160 offset:6144
	ds_read_b128 v[224:227], v238 offset:6144
	s_waitcnt vmcnt(8)
	s_waitcnt lgkmcnt(0)
	s_setprio 1
	s_barrier
	v_mfma_f32_16x16x32_bf16 v[122:125], v[164:167], v[196:199], 0
	v_mfma_f32_16x16x32_bf16 v[118:121], v[172:175], v[196:199], 0
	v_mfma_f32_16x16x32_bf16 v[110:113], v[164:167], v[204:207], 0
	v_mfma_f32_16x16x32_bf16 v[102:105], v[172:175], v[204:207], 0
	v_mfma_f32_16x16x32_bf16 v[94:97], v[164:167], v[212:215], 0
	v_mfma_f32_16x16x32_bf16 v[86:89], v[172:175], v[212:215], 0
	v_mfma_f32_16x16x32_bf16 v[78:81], v[164:167], v[220:223], 0
	v_mfma_f32_16x16x32_bf16 v[70:73], v[172:175], v[220:223], 0
	v_mfma_f32_16x16x32_bf16 v[122:125], v[168:171], v[200:203], v[122:125]
	v_mfma_f32_16x16x32_bf16 v[118:121], v[176:179], v[200:203], v[118:121]
	v_mfma_f32_16x16x32_bf16 v[110:113], v[168:171], v[208:211], v[110:113]
	v_mfma_f32_16x16x32_bf16 v[102:105], v[176:179], v[208:211], v[102:105]
	v_mfma_f32_16x16x32_bf16 v[94:97], v[168:171], v[216:219], v[94:97]
	v_mfma_f32_16x16x32_bf16 v[86:89], v[176:179], v[216:219], v[86:89]
	v_mfma_f32_16x16x32_bf16 v[78:81], v[168:171], v[224:227], v[78:81]
	v_mfma_f32_16x16x32_bf16 v[70:73], v[176:179], v[224:227], v[70:73]
	v_mfma_f32_16x16x32_bf16 v[126:129], v[180:183], v[196:199], 0
	v_mfma_f32_16x16x32_bf16 v[114:117], v[188:191], v[196:199], 0
	v_mfma_f32_16x16x32_bf16 v[106:109], v[180:183], v[204:207], 0
	v_mfma_f32_16x16x32_bf16 v[98:101], v[188:191], v[204:207], 0
	v_mfma_f32_16x16x32_bf16 v[90:93], v[180:183], v[212:215], 0
	v_mfma_f32_16x16x32_bf16 v[82:85], v[188:191], v[212:215], 0
	v_mfma_f32_16x16x32_bf16 v[74:77], v[180:183], v[220:223], 0
	v_mfma_f32_16x16x32_bf16 v[66:69], v[188:191], v[220:223], 0
	v_mfma_f32_16x16x32_bf16 v[126:129], v[184:187], v[200:203], v[126:129]
	v_mfma_f32_16x16x32_bf16 v[114:117], v[192:195], v[200:203], v[114:117]
	v_mfma_f32_16x16x32_bf16 v[106:109], v[184:187], v[208:211], v[106:109]
	v_mfma_f32_16x16x32_bf16 v[98:101], v[192:195], v[208:211], v[98:101]
	v_mfma_f32_16x16x32_bf16 v[90:93], v[184:187], v[216:219], v[90:93]
	v_mfma_f32_16x16x32_bf16 v[82:85], v[192:195], v[216:219], v[82:85]
	v_mfma_f32_16x16x32_bf16 v[74:77], v[184:187], v[224:227], v[74:77]
	v_mfma_f32_16x16x32_bf16 v[66:69], v[192:195], v[224:227], v[66:69]
	s_barrier
	s_setprio 0
	s_add_u32 s98, s96, 0x40000
	s_addc_u32 s99, s97, 0
	s_add_i32 s5, s74, s23
	s_mov_b32 m0, s5
	ds_read_b128 v[196:199], v160 offset:16384
	global_load_lds_dwordx4 v132, s[96:97]
	s_add_i32 m0, s5, 0x2000
	s_add_i32 s5, s75, s23
	global_load_lds_dwordx4 v136, s[96:97]
	s_mov_b32 m0, s5
	ds_read_b128 v[200:203], v238 offset:16384
	global_load_lds_dwordx4 v132, s[98:99]
	s_add_i32 m0, s5, 0x2000
	ds_read_b128 v[204:207], v160 offset:18432
	global_load_lds_dwordx4 v136, s[98:99]
	s_mov_b32 m0, s47
	ds_read_b128 v[208:211], v238 offset:18432
	global_load_lds_dwordx4 v130, s[94:95]
	s_mov_b32 m0, s56
	ds_read_b128 v[212:215], v160 offset:20480
	global_load_lds_dwordx4 v134, s[94:95]
	ds_read_b128 v[216:219], v238 offset:20480
	ds_read_b128 v[220:223], v160 offset:22528
	ds_read_b128 v[224:227], v238 offset:22528
	s_waitcnt vmcnt(8)
	s_waitcnt lgkmcnt(0)
	s_setprio 1
	s_barrier
	v_mfma_f32_16x16x32_bf16 v[62:65], v[164:167], v[196:199], 0
	v_mfma_f32_16x16x32_bf16 v[54:57], v[172:175], v[196:199], 0
	v_mfma_f32_16x16x32_bf16 v[46:49], v[164:167], v[204:207], 0
	v_mfma_f32_16x16x32_bf16 v[38:41], v[172:175], v[204:207], 0
	v_mfma_f32_16x16x32_bf16 v[30:33], v[164:167], v[212:215], 0
	v_mfma_f32_16x16x32_bf16 v[22:25], v[172:175], v[212:215], 0
	v_mfma_f32_16x16x32_bf16 v[14:17], v[164:167], v[220:223], 0
	v_mfma_f32_16x16x32_bf16 v[6:9], v[172:175], v[220:223], 0
	v_mfma_f32_16x16x32_bf16 v[62:65], v[168:171], v[200:203], v[62:65]
	v_mfma_f32_16x16x32_bf16 v[54:57], v[176:179], v[200:203], v[54:57]
	v_mfma_f32_16x16x32_bf16 v[46:49], v[168:171], v[208:211], v[46:49]
	v_mfma_f32_16x16x32_bf16 v[38:41], v[176:179], v[208:211], v[38:41]
	v_mfma_f32_16x16x32_bf16 v[30:33], v[168:171], v[216:219], v[30:33]
	v_mfma_f32_16x16x32_bf16 v[22:25], v[176:179], v[216:219], v[22:25]
	v_mfma_f32_16x16x32_bf16 v[14:17], v[168:171], v[224:227], v[14:17]
	v_mfma_f32_16x16x32_bf16 v[6:9], v[176:179], v[224:227], v[6:9]
	v_mfma_f32_16x16x32_bf16 v[58:61], v[180:183], v[196:199], 0
	v_mfma_f32_16x16x32_bf16 v[50:53], v[188:191], v[196:199], 0
	v_mfma_f32_16x16x32_bf16 v[42:45], v[180:183], v[204:207], 0
	v_mfma_f32_16x16x32_bf16 v[34:37], v[188:191], v[204:207], 0
	v_mfma_f32_16x16x32_bf16 v[26:29], v[180:183], v[212:215], 0
	v_mfma_f32_16x16x32_bf16 v[18:21], v[188:191], v[212:215], 0
	v_mfma_f32_16x16x32_bf16 v[10:13], v[180:183], v[220:223], 0
	v_mfma_f32_16x16x32_bf16 v[2:5], v[188:191], v[220:223], 0
	v_mfma_f32_16x16x32_bf16 v[58:61], v[184:187], v[200:203], v[58:61]
	v_mfma_f32_16x16x32_bf16 v[50:53], v[192:195], v[200:203], v[50:53]
	v_mfma_f32_16x16x32_bf16 v[42:45], v[184:187], v[208:211], v[42:45]
	v_mfma_f32_16x16x32_bf16 v[34:37], v[192:195], v[208:211], v[34:37]
	v_mfma_f32_16x16x32_bf16 v[26:29], v[184:187], v[216:219], v[26:29]
	v_mfma_f32_16x16x32_bf16 v[18:21], v[192:195], v[216:219], v[18:21]
	v_mfma_f32_16x16x32_bf16 v[10:13], v[184:187], v[224:227], v[10:13]
	v_mfma_f32_16x16x32_bf16 v[2:5], v[192:195], v[224:227], v[2:5]
	s_barrier
	s_setprio 0
	s_add_u32 s98, s94, 0x40000
	s_addc_u32 s99, s95, 0
	s_add_i32 s5, 0, 0x18000
	s_add_i32 s45, 0, 0x1c000
	s_mov_b32 m0, s57
	ds_read_b128 v[164:167], v232
	global_load_lds_dwordx4 v130, s[98:99]
	s_mov_b32 m0, s58
	ds_read_b128 v[168:171], v236
	global_load_lds_dwordx4 v134, s[98:99]
	ds_read_b128 v[172:175], v232 offset:2048
	ds_read_b128 v[176:179], v236 offset:2048
	ds_read_b128 v[180:183], v233
	ds_read_b128 v[184:187], v237
	ds_read_b128 v[188:191], v233 offset:2048
	ds_read_b128 v[192:195], v237 offset:2048
	ds_read_b128 v[196:199], v160 offset:32768
	ds_read_b128 v[200:203], v238 offset:32768
	ds_read_b128 v[204:207], v160 offset:34816
	ds_read_b128 v[208:211], v238 offset:34816
	ds_read_b128 v[212:215], v160 offset:36864
	ds_read_b128 v[216:219], v238 offset:36864
	ds_read_b128 v[220:223], v160 offset:38912
	ds_read_b128 v[224:227], v238 offset:38912
	s_waitcnt vmcnt(8)
	s_waitcnt lgkmcnt(0)
	s_setprio 1
	s_barrier
	v_mfma_f32_16x16x32_bf16 v[122:125], v[164:167], v[196:199], v[122:125]
	v_mfma_f32_16x16x32_bf16 v[118:121], v[172:175], v[196:199], v[118:121]
	v_mfma_f32_16x16x32_bf16 v[110:113], v[164:167], v[204:207], v[110:113]
	v_mfma_f32_16x16x32_bf16 v[102:105], v[172:175], v[204:207], v[102:105]
	v_mfma_f32_16x16x32_bf16 v[94:97], v[164:167], v[212:215], v[94:97]
	v_mfma_f32_16x16x32_bf16 v[86:89], v[172:175], v[212:215], v[86:89]
	v_mfma_f32_16x16x32_bf16 v[78:81], v[164:167], v[220:223], v[78:81]
	v_mfma_f32_16x16x32_bf16 v[70:73], v[172:175], v[220:223], v[70:73]
	v_mfma_f32_16x16x32_bf16 v[122:125], v[168:171], v[200:203], v[122:125]
	v_mfma_f32_16x16x32_bf16 v[118:121], v[176:179], v[200:203], v[118:121]
	v_mfma_f32_16x16x32_bf16 v[110:113], v[168:171], v[208:211], v[110:113]
	v_mfma_f32_16x16x32_bf16 v[102:105], v[176:179], v[208:211], v[102:105]
	v_mfma_f32_16x16x32_bf16 v[94:97], v[168:171], v[216:219], v[94:97]
	v_mfma_f32_16x16x32_bf16 v[86:89], v[176:179], v[216:219], v[86:89]
	v_mfma_f32_16x16x32_bf16 v[78:81], v[168:171], v[224:227], v[78:81]
	v_mfma_f32_16x16x32_bf16 v[70:73], v[176:179], v[224:227], v[70:73]
	v_mfma_f32_16x16x32_bf16 v[126:129], v[180:183], v[196:199], v[126:129]
	v_mfma_f32_16x16x32_bf16 v[114:117], v[188:191], v[196:199], v[114:117]
	v_mfma_f32_16x16x32_bf16 v[106:109], v[180:183], v[204:207], v[106:109]
	v_mfma_f32_16x16x32_bf16 v[98:101], v[188:191], v[204:207], v[98:101]
	v_mfma_f32_16x16x32_bf16 v[90:93], v[180:183], v[212:215], v[90:93]
	v_mfma_f32_16x16x32_bf16 v[82:85], v[188:191], v[212:215], v[82:85]
	v_mfma_f32_16x16x32_bf16 v[74:77], v[180:183], v[220:223], v[74:77]
	v_mfma_f32_16x16x32_bf16 v[66:69], v[188:191], v[220:223], v[66:69]
	v_mfma_f32_16x16x32_bf16 v[126:129], v[184:187], v[200:203], v[126:129]
	v_mfma_f32_16x16x32_bf16 v[114:117], v[192:195], v[200:203], v[114:117]
	v_mfma_f32_16x16x32_bf16 v[106:109], v[184:187], v[208:211], v[106:109]
	v_mfma_f32_16x16x32_bf16 v[98:101], v[192:195], v[208:211], v[98:101]
	v_mfma_f32_16x16x32_bf16 v[90:93], v[184:187], v[216:219], v[90:93]
	v_mfma_f32_16x16x32_bf16 v[82:85], v[192:195], v[216:219], v[82:85]
	v_mfma_f32_16x16x32_bf16 v[74:77], v[184:187], v[224:227], v[74:77]
	v_mfma_f32_16x16x32_bf16 v[66:69], v[192:195], v[224:227], v[66:69]
	s_barrier
	s_setprio 0
	s_add_u32 s96, s96, 0x80
	s_addc_u32 s97, s97, 0
	s_add_u32 s98, s96, 0x40000
	s_addc_u32 s99, s97, 0
	s_add_u32 s94, s94, 0x80
	s_addc_u32 s95, s95, 0
	s_add_i32 s5, s5, s23
	s_mov_b32 m0, s5
	ds_read_b128 v[196:199], v160 offset:49152
	global_load_lds_dwordx4 v132, s[96:97]
	s_add_i32 m0, s5, 0x2000
	s_add_i32 s5, s45, s23
	global_load_lds_dwordx4 v136, s[96:97]
	s_mov_b32 m0, s5
	ds_read_b128 v[200:203], v238 offset:49152
	global_load_lds_dwordx4 v132, s[98:99]
	s_add_i32 m0, s5, 0x2000
	ds_read_b128 v[204:207], v160 offset:51200
	global_load_lds_dwordx4 v136, s[98:99]
	s_mov_b32 m0, s64
	ds_read_b128 v[208:211], v238 offset:51200
	global_load_lds_dwordx4 v130, s[94:95]
	s_mov_b32 m0, s65
	ds_read_b128 v[212:215], v160 offset:53248
	global_load_lds_dwordx4 v134, s[94:95]
	ds_read_b128 v[216:219], v238 offset:53248
	ds_read_b128 v[220:223], v160 offset:55296
	ds_read_b128 v[224:227], v238 offset:55296
	s_waitcnt vmcnt(8)
	s_waitcnt lgkmcnt(0)
	s_setprio 1
	s_barrier
	v_mfma_f32_16x16x32_bf16 v[62:65], v[164:167], v[196:199], v[62:65]
	v_mfma_f32_16x16x32_bf16 v[54:57], v[172:175], v[196:199], v[54:57]
	v_mfma_f32_16x16x32_bf16 v[46:49], v[164:167], v[204:207], v[46:49]
	v_mfma_f32_16x16x32_bf16 v[38:41], v[172:175], v[204:207], v[38:41]
	v_mfma_f32_16x16x32_bf16 v[30:33], v[164:167], v[212:215], v[30:33]
	v_mfma_f32_16x16x32_bf16 v[22:25], v[172:175], v[212:215], v[22:25]
	v_mfma_f32_16x16x32_bf16 v[14:17], v[164:167], v[220:223], v[14:17]
	v_mfma_f32_16x16x32_bf16 v[6:9], v[172:175], v[220:223], v[6:9]
	v_mfma_f32_16x16x32_bf16 v[62:65], v[168:171], v[200:203], v[62:65]
	v_mfma_f32_16x16x32_bf16 v[54:57], v[176:179], v[200:203], v[54:57]
	v_mfma_f32_16x16x32_bf16 v[46:49], v[168:171], v[208:211], v[46:49]
	v_mfma_f32_16x16x32_bf16 v[38:41], v[176:179], v[208:211], v[38:41]
	v_mfma_f32_16x16x32_bf16 v[30:33], v[168:171], v[216:219], v[30:33]
	v_mfma_f32_16x16x32_bf16 v[22:25], v[176:179], v[216:219], v[22:25]
	v_mfma_f32_16x16x32_bf16 v[14:17], v[168:171], v[224:227], v[14:17]
	v_mfma_f32_16x16x32_bf16 v[6:9], v[176:179], v[224:227], v[6:9]
	v_mfma_f32_16x16x32_bf16 v[58:61], v[180:183], v[196:199], v[58:61]
	v_mfma_f32_16x16x32_bf16 v[50:53], v[188:191], v[196:199], v[50:53]
	v_mfma_f32_16x16x32_bf16 v[42:45], v[180:183], v[204:207], v[42:45]
	v_mfma_f32_16x16x32_bf16 v[34:37], v[188:191], v[204:207], v[34:37]
	v_mfma_f32_16x16x32_bf16 v[26:29], v[180:183], v[212:215], v[26:29]
	v_mfma_f32_16x16x32_bf16 v[18:21], v[188:191], v[212:215], v[18:21]
	v_mfma_f32_16x16x32_bf16 v[10:13], v[180:183], v[220:223], v[10:13]
	v_mfma_f32_16x16x32_bf16 v[2:5], v[188:191], v[220:223], v[2:5]
	v_mfma_f32_16x16x32_bf16 v[58:61], v[184:187], v[200:203], v[58:61]
	v_mfma_f32_16x16x32_bf16 v[50:53], v[192:195], v[200:203], v[50:53]
	v_mfma_f32_16x16x32_bf16 v[42:45], v[184:187], v[208:211], v[42:45]
	v_mfma_f32_16x16x32_bf16 v[34:37], v[192:195], v[208:211], v[34:37]
	v_mfma_f32_16x16x32_bf16 v[26:29], v[184:187], v[216:219], v[26:29]
	v_mfma_f32_16x16x32_bf16 v[18:21], v[192:195], v[216:219], v[18:21]
	v_mfma_f32_16x16x32_bf16 v[10:13], v[184:187], v[224:227], v[10:13]
	v_mfma_f32_16x16x32_bf16 v[2:5], v[192:195], v[224:227], v[2:5]
	s_barrier
	s_setprio 0
	s_mov_b32 s5, s29
	s_add_u32 s88, s88, 0x100
	s_addc_u32 s89, s89, 0
	s_add_u32 s86, s86, 0x100
	s_addc_u32 s87, s87, 0
	s_cmp_ge_i32 s29, s101
	s_cbranch_scc1 .Lmy_kexit_9
.LBB0_1763:
	s_add_u32 s98, s86, 0xfffc0080
	s_addc_u32 s99, s87, -1
	s_cmp_eq_u32 s5, s100
	s_cselect_b64 s[94:95], s[90:91], s[98:99]
	s_cselect_b64 s[96:97], s[92:93], s[88:89]
	s_add_i32 s29, s5, 2
	s_add_i32 m0, s47, 0xc000
	ds_read_b128 v[164:167], v230
	global_load_lds_dwordx4 v144, s[86:87]
	s_add_i32 m0, s47, 0xe000
	ds_read_b128 v[168:171], v234
	global_load_lds_dwordx4 v142, s[86:87]
	ds_read_b128 v[172:175], v230 offset:2048
	ds_read_b128 v[176:179], v234 offset:2048
	ds_read_b128 v[180:183], v231
	ds_read_b128 v[184:187], v235
	ds_read_b128 v[188:191], v231 offset:2048
	ds_read_b128 v[192:195], v235 offset:2048
	ds_read_b128 v[196:199], v160
	ds_read_b128 v[200:203], v238
	ds_read_b128 v[204:207], v160 offset:2048
	ds_read_b128 v[208:211], v238 offset:2048
	ds_read_b128 v[212:215], v160 offset:4096
	ds_read_b128 v[216:219], v238 offset:4096
	ds_read_b128 v[220:223], v160 offset:6144
	ds_read_b128 v[224:227], v238 offset:6144
	s_waitcnt vmcnt(8)
	s_waitcnt lgkmcnt(0)
	s_setprio 1
	s_barrier
	v_mfma_f32_16x16x32_bf16 v[122:125], v[164:167], v[196:199], v[122:125]
	v_mfma_f32_16x16x32_bf16 v[118:121], v[172:175], v[196:199], v[118:121]
	v_mfma_f32_16x16x32_bf16 v[110:113], v[164:167], v[204:207], v[110:113]
	v_mfma_f32_16x16x32_bf16 v[102:105], v[172:175], v[204:207], v[102:105]
	v_mfma_f32_16x16x32_bf16 v[94:97], v[164:167], v[212:215], v[94:97]
	v_mfma_f32_16x16x32_bf16 v[86:89], v[172:175], v[212:215], v[86:89]
	v_mfma_f32_16x16x32_bf16 v[78:81], v[164:167], v[220:223], v[78:81]
	v_mfma_f32_16x16x32_bf16 v[70:73], v[172:175], v[220:223], v[70:73]
	v_mfma_f32_16x16x32_bf16 v[122:125], v[168:171], v[200:203], v[122:125]
	v_mfma_f32_16x16x32_bf16 v[118:121], v[176:179], v[200:203], v[118:121]
	v_mfma_f32_16x16x32_bf16 v[110:113], v[168:171], v[208:211], v[110:113]
	v_mfma_f32_16x16x32_bf16 v[102:105], v[176:179], v[208:211], v[102:105]
	v_mfma_f32_16x16x32_bf16 v[94:97], v[168:171], v[216:219], v[94:97]
	v_mfma_f32_16x16x32_bf16 v[86:89], v[176:179], v[216:219], v[86:89]
	v_mfma_f32_16x16x32_bf16 v[78:81], v[168:171], v[224:227], v[78:81]
	v_mfma_f32_16x16x32_bf16 v[70:73], v[176:179], v[224:227], v[70:73]
	v_mfma_f32_16x16x32_bf16 v[126:129], v[180:183], v[196:199], v[126:129]
	v_mfma_f32_16x16x32_bf16 v[114:117], v[188:191], v[196:199], v[114:117]
	v_mfma_f32_16x16x32_bf16 v[106:109], v[180:183], v[204:207], v[106:109]
	v_mfma_f32_16x16x32_bf16 v[98:101], v[188:191], v[204:207], v[98:101]
	v_mfma_f32_16x16x32_bf16 v[90:93], v[180:183], v[212:215], v[90:93]
	v_mfma_f32_16x16x32_bf16 v[82:85], v[188:191], v[212:215], v[82:85]
	v_mfma_f32_16x16x32_bf16 v[74:77], v[180:183], v[220:223], v[74:77]
	v_mfma_f32_16x16x32_bf16 v[66:69], v[188:191], v[220:223], v[66:69]
	v_mfma_f32_16x16x32_bf16 v[126:129], v[184:187], v[200:203], v[126:129]
	v_mfma_f32_16x16x32_bf16 v[114:117], v[192:195], v[200:203], v[114:117]
	v_mfma_f32_16x16x32_bf16 v[106:109], v[184:187], v[208:211], v[106:109]
	v_mfma_f32_16x16x32_bf16 v[98:101], v[192:195], v[208:211], v[98:101]
	v_mfma_f32_16x16x32_bf16 v[90:93], v[184:187], v[216:219], v[90:93]
	v_mfma_f32_16x16x32_bf16 v[82:85], v[192:195], v[216:219], v[82:85]
	v_mfma_f32_16x16x32_bf16 v[74:77], v[184:187], v[224:227], v[74:77]
	v_mfma_f32_16x16x32_bf16 v[66:69], v[192:195], v[224:227], v[66:69]
	s_barrier
	s_setprio 0
	s_add_u32 s98, s96, 0x40000
	s_addc_u32 s99, s97, 0
	s_add_i32 s5, s74, s23
	s_mov_b32 m0, s5
	ds_read_b128 v[196:199], v160 offset:16384
	global_load_lds_dwordx4 v132, s[96:97]
	s_add_i32 m0, s5, 0x2000
	s_add_i32 s5, s75, s23
	global_load_lds_dwordx4 v136, s[96:97]
	s_mov_b32 m0, s5
	ds_read_b128 v[200:203], v238 offset:16384
	global_load_lds_dwordx4 v132, s[98:99]
	s_add_i32 m0, s5, 0x2000
	ds_read_b128 v[204:207], v160 offset:18432
	global_load_lds_dwordx4 v136, s[98:99]
	s_mov_b32 m0, s47
	ds_read_b128 v[208:211], v238 offset:18432
	global_load_lds_dwordx4 v130, s[94:95]
	s_mov_b32 m0, s56
	ds_read_b128 v[212:215], v160 offset:20480
	global_load_lds_dwordx4 v134, s[94:95]
	ds_read_b128 v[216:219], v238 offset:20480
	ds_read_b128 v[220:223], v160 offset:22528
	ds_read_b128 v[224:227], v238 offset:22528
	s_waitcnt vmcnt(8)
	s_waitcnt lgkmcnt(0)
	s_setprio 1
	s_barrier
	v_mfma_f32_16x16x32_bf16 v[62:65], v[164:167], v[196:199], v[62:65]
	v_mfma_f32_16x16x32_bf16 v[54:57], v[172:175], v[196:199], v[54:57]
	v_mfma_f32_16x16x32_bf16 v[46:49], v[164:167], v[204:207], v[46:49]
	v_mfma_f32_16x16x32_bf16 v[38:41], v[172:175], v[204:207], v[38:41]
	v_mfma_f32_16x16x32_bf16 v[30:33], v[164:167], v[212:215], v[30:33]
	v_mfma_f32_16x16x32_bf16 v[22:25], v[172:175], v[212:215], v[22:25]
	v_mfma_f32_16x16x32_bf16 v[14:17], v[164:167], v[220:223], v[14:17]
	v_mfma_f32_16x16x32_bf16 v[6:9], v[172:175], v[220:223], v[6:9]
	v_mfma_f32_16x16x32_bf16 v[62:65], v[168:171], v[200:203], v[62:65]
	v_mfma_f32_16x16x32_bf16 v[54:57], v[176:179], v[200:203], v[54:57]
	v_mfma_f32_16x16x32_bf16 v[46:49], v[168:171], v[208:211], v[46:49]
	v_mfma_f32_16x16x32_bf16 v[38:41], v[176:179], v[208:211], v[38:41]
	v_mfma_f32_16x16x32_bf16 v[30:33], v[168:171], v[216:219], v[30:33]
	v_mfma_f32_16x16x32_bf16 v[22:25], v[176:179], v[216:219], v[22:25]
	v_mfma_f32_16x16x32_bf16 v[14:17], v[168:171], v[224:227], v[14:17]
	v_mfma_f32_16x16x32_bf16 v[6:9], v[176:179], v[224:227], v[6:9]
	v_mfma_f32_16x16x32_bf16 v[58:61], v[180:183], v[196:199], v[58:61]
	v_mfma_f32_16x16x32_bf16 v[50:53], v[188:191], v[196:199], v[50:53]
	v_mfma_f32_16x16x32_bf16 v[42:45], v[180:183], v[204:207], v[42:45]
	v_mfma_f32_16x16x32_bf16 v[34:37], v[188:191], v[204:207], v[34:37]
	v_mfma_f32_16x16x32_bf16 v[26:29], v[180:183], v[212:215], v[26:29]
	v_mfma_f32_16x16x32_bf16 v[18:21], v[188:191], v[212:215], v[18:21]
	v_mfma_f32_16x16x32_bf16 v[10:13], v[180:183], v[220:223], v[10:13]
	v_mfma_f32_16x16x32_bf16 v[2:5], v[188:191], v[220:223], v[2:5]
	v_mfma_f32_16x16x32_bf16 v[58:61], v[184:187], v[200:203], v[58:61]
	v_mfma_f32_16x16x32_bf16 v[50:53], v[192:195], v[200:203], v[50:53]
	v_mfma_f32_16x16x32_bf16 v[42:45], v[184:187], v[208:211], v[42:45]
	v_mfma_f32_16x16x32_bf16 v[34:37], v[192:195], v[208:211], v[34:37]
	v_mfma_f32_16x16x32_bf16 v[26:29], v[184:187], v[216:219], v[26:29]
	v_mfma_f32_16x16x32_bf16 v[18:21], v[192:195], v[216:219], v[18:21]
	v_mfma_f32_16x16x32_bf16 v[10:13], v[184:187], v[224:227], v[10:13]
	v_mfma_f32_16x16x32_bf16 v[2:5], v[192:195], v[224:227], v[2:5]
	s_barrier
	s_setprio 0
	s_add_u32 s98, s94, 0x40000
	s_addc_u32 s99, s95, 0
	s_add_i32 s5, 0, 0x18000
	s_add_i32 s45, 0, 0x1c000
	s_mov_b32 m0, s57
	ds_read_b128 v[164:167], v232
	global_load_lds_dwordx4 v130, s[98:99]
	s_mov_b32 m0, s58
	ds_read_b128 v[168:171], v236
	global_load_lds_dwordx4 v134, s[98:99]
	ds_read_b128 v[172:175], v232 offset:2048
	ds_read_b128 v[176:179], v236 offset:2048
	ds_read_b128 v[180:183], v233
	ds_read_b128 v[184:187], v237
	ds_read_b128 v[188:191], v233 offset:2048
	ds_read_b128 v[192:195], v237 offset:2048
	ds_read_b128 v[196:199], v160 offset:32768
	ds_read_b128 v[200:203], v238 offset:32768
	ds_read_b128 v[204:207], v160 offset:34816
	ds_read_b128 v[208:211], v238 offset:34816
	ds_read_b128 v[212:215], v160 offset:36864
	ds_read_b128 v[216:219], v238 offset:36864
	ds_read_b128 v[220:223], v160 offset:38912
	ds_read_b128 v[224:227], v238 offset:38912
	s_waitcnt vmcnt(8)
	s_waitcnt lgkmcnt(0)
	s_setprio 1
	s_barrier
	v_mfma_f32_16x16x32_bf16 v[122:125], v[164:167], v[196:199], v[122:125]
	v_mfma_f32_16x16x32_bf16 v[118:121], v[172:175], v[196:199], v[118:121]
	v_mfma_f32_16x16x32_bf16 v[110:113], v[164:167], v[204:207], v[110:113]
	v_mfma_f32_16x16x32_bf16 v[102:105], v[172:175], v[204:207], v[102:105]
	v_mfma_f32_16x16x32_bf16 v[94:97], v[164:167], v[212:215], v[94:97]
	v_mfma_f32_16x16x32_bf16 v[86:89], v[172:175], v[212:215], v[86:89]
	v_mfma_f32_16x16x32_bf16 v[78:81], v[164:167], v[220:223], v[78:81]
	v_mfma_f32_16x16x32_bf16 v[70:73], v[172:175], v[220:223], v[70:73]
	v_mfma_f32_16x16x32_bf16 v[122:125], v[168:171], v[200:203], v[122:125]
	v_mfma_f32_16x16x32_bf16 v[118:121], v[176:179], v[200:203], v[118:121]
	v_mfma_f32_16x16x32_bf16 v[110:113], v[168:171], v[208:211], v[110:113]
	v_mfma_f32_16x16x32_bf16 v[102:105], v[176:179], v[208:211], v[102:105]
	v_mfma_f32_16x16x32_bf16 v[94:97], v[168:171], v[216:219], v[94:97]
	v_mfma_f32_16x16x32_bf16 v[86:89], v[176:179], v[216:219], v[86:89]
	v_mfma_f32_16x16x32_bf16 v[78:81], v[168:171], v[224:227], v[78:81]
	v_mfma_f32_16x16x32_bf16 v[70:73], v[176:179], v[224:227], v[70:73]
	v_mfma_f32_16x16x32_bf16 v[126:129], v[180:183], v[196:199], v[126:129]
	v_mfma_f32_16x16x32_bf16 v[114:117], v[188:191], v[196:199], v[114:117]
	v_mfma_f32_16x16x32_bf16 v[106:109], v[180:183], v[204:207], v[106:109]
	v_mfma_f32_16x16x32_bf16 v[98:101], v[188:191], v[204:207], v[98:101]
	v_mfma_f32_16x16x32_bf16 v[90:93], v[180:183], v[212:215], v[90:93]
	v_mfma_f32_16x16x32_bf16 v[82:85], v[188:191], v[212:215], v[82:85]
	v_mfma_f32_16x16x32_bf16 v[74:77], v[180:183], v[220:223], v[74:77]
	v_mfma_f32_16x16x32_bf16 v[66:69], v[188:191], v[220:223], v[66:69]
	v_mfma_f32_16x16x32_bf16 v[126:129], v[184:187], v[200:203], v[126:129]
	v_mfma_f32_16x16x32_bf16 v[114:117], v[192:195], v[200:203], v[114:117]
	v_mfma_f32_16x16x32_bf16 v[106:109], v[184:187], v[208:211], v[106:109]
	v_mfma_f32_16x16x32_bf16 v[98:101], v[192:195], v[208:211], v[98:101]
	v_mfma_f32_16x16x32_bf16 v[90:93], v[184:187], v[216:219], v[90:93]
	v_mfma_f32_16x16x32_bf16 v[82:85], v[192:195], v[216:219], v[82:85]
	v_mfma_f32_16x16x32_bf16 v[74:77], v[184:187], v[224:227], v[74:77]
	v_mfma_f32_16x16x32_bf16 v[66:69], v[192:195], v[224:227], v[66:69]
	s_barrier
	s_setprio 0
	s_add_u32 s96, s96, 0x80
	s_addc_u32 s97, s97, 0
	s_add_u32 s98, s96, 0x40000
	s_addc_u32 s99, s97, 0
	s_add_u32 s94, s94, 0x80
	s_addc_u32 s95, s95, 0
	s_add_i32 s5, s5, s23
	s_mov_b32 m0, s5
	ds_read_b128 v[196:199], v160 offset:49152
	global_load_lds_dwordx4 v132, s[96:97]
	s_add_i32 m0, s5, 0x2000
	s_add_i32 s5, s45, s23
	global_load_lds_dwordx4 v136, s[96:97]
	s_mov_b32 m0, s5
	ds_read_b128 v[200:203], v238 offset:49152
	global_load_lds_dwordx4 v132, s[98:99]
	s_add_i32 m0, s5, 0x2000
	ds_read_b128 v[204:207], v160 offset:51200
	global_load_lds_dwordx4 v136, s[98:99]
	s_mov_b32 m0, s64
	ds_read_b128 v[208:211], v238 offset:51200
	global_load_lds_dwordx4 v130, s[94:95]
	s_mov_b32 m0, s65
	ds_read_b128 v[212:215], v160 offset:53248
	global_load_lds_dwordx4 v134, s[94:95]
	ds_read_b128 v[216:219], v238 offset:53248
	ds_read_b128 v[220:223], v160 offset:55296
	ds_read_b128 v[224:227], v238 offset:55296
	s_waitcnt vmcnt(8)
	s_waitcnt lgkmcnt(0)
	s_setprio 1
	s_barrier
	v_mfma_f32_16x16x32_bf16 v[62:65], v[164:167], v[196:199], v[62:65]
	v_mfma_f32_16x16x32_bf16 v[54:57], v[172:175], v[196:199], v[54:57]
	v_mfma_f32_16x16x32_bf16 v[46:49], v[164:167], v[204:207], v[46:49]
	v_mfma_f32_16x16x32_bf16 v[38:41], v[172:175], v[204:207], v[38:41]
	v_mfma_f32_16x16x32_bf16 v[30:33], v[164:167], v[212:215], v[30:33]
	v_mfma_f32_16x16x32_bf16 v[22:25], v[172:175], v[212:215], v[22:25]
	v_mfma_f32_16x16x32_bf16 v[14:17], v[164:167], v[220:223], v[14:17]
	v_mfma_f32_16x16x32_bf16 v[6:9], v[172:175], v[220:223], v[6:9]
	v_mfma_f32_16x16x32_bf16 v[62:65], v[168:171], v[200:203], v[62:65]
	v_mfma_f32_16x16x32_bf16 v[54:57], v[176:179], v[200:203], v[54:57]
	v_mfma_f32_16x16x32_bf16 v[46:49], v[168:171], v[208:211], v[46:49]
	v_mfma_f32_16x16x32_bf16 v[38:41], v[176:179], v[208:211], v[38:41]
	v_mfma_f32_16x16x32_bf16 v[30:33], v[168:171], v[216:219], v[30:33]
	v_mfma_f32_16x16x32_bf16 v[22:25], v[176:179], v[216:219], v[22:25]
	v_mfma_f32_16x16x32_bf16 v[14:17], v[168:171], v[224:227], v[14:17]
	v_mfma_f32_16x16x32_bf16 v[6:9], v[176:179], v[224:227], v[6:9]
	v_mfma_f32_16x16x32_bf16 v[58:61], v[180:183], v[196:199], v[58:61]
	v_mfma_f32_16x16x32_bf16 v[50:53], v[188:191], v[196:199], v[50:53]
	v_mfma_f32_16x16x32_bf16 v[42:45], v[180:183], v[204:207], v[42:45]
	v_mfma_f32_16x16x32_bf16 v[34:37], v[188:191], v[204:207], v[34:37]
	v_mfma_f32_16x16x32_bf16 v[26:29], v[180:183], v[212:215], v[26:29]
	v_mfma_f32_16x16x32_bf16 v[18:21], v[188:191], v[212:215], v[18:21]
	v_mfma_f32_16x16x32_bf16 v[10:13], v[180:183], v[220:223], v[10:13]
	v_mfma_f32_16x16x32_bf16 v[2:5], v[188:191], v[220:223], v[2:5]
	v_mfma_f32_16x16x32_bf16 v[58:61], v[184:187], v[200:203], v[58:61]
	v_mfma_f32_16x16x32_bf16 v[50:53], v[192:195], v[200:203], v[50:53]
	v_mfma_f32_16x16x32_bf16 v[42:45], v[184:187], v[208:211], v[42:45]
	v_mfma_f32_16x16x32_bf16 v[34:37], v[192:195], v[208:211], v[34:37]
	v_mfma_f32_16x16x32_bf16 v[26:29], v[184:187], v[216:219], v[26:29]
	v_mfma_f32_16x16x32_bf16 v[18:21], v[192:195], v[216:219], v[18:21]
	v_mfma_f32_16x16x32_bf16 v[10:13], v[184:187], v[224:227], v[10:13]
	v_mfma_f32_16x16x32_bf16 v[2:5], v[192:195], v[224:227], v[2:5]
	s_barrier
	s_setprio 0
	s_mov_b32 s5, s29
	s_add_u32 s88, s88, 0x100
	s_addc_u32 s89, s89, 0
	s_add_u32 s86, s86, 0x100
	s_addc_u32 s87, s87, 0
	s_cmp_ge_i32 s29, s101
	s_cbranch_scc0 .LBB0_1763

.LBB0_1935:
	v_ashrrev_i32_e32 v7, 31, v14
	v_lshrrev_b32_e32 v7, 26, v7
	v_add_u32_e32 v7, v14, v7
	v_ashrrev_i32_e32 v15, 6, v7
	v_bfe_i32 v7, v14, 27, 1
	v_lshlrev_b32_e32 v6, 4, v14
	v_lshrrev_b32_e32 v7, 22, v7
	v_add_u32_e32 v7, v6, v7
	v_and_b32_e32 v7, 0xfffffc00, v7
	v_sub_u32_e32 v7, v6, v7
	v_lshrrev_b32_e32 v8, 4, v7
	v_bitop3_b32 v8, v8, v7, 32 bitop3:0x6c
	v_ashrrev_i32_e32 v7, 31, v7
	v_lshrrev_b32_e32 v7, 26, v7
	v_add_u32_e32 v7, v8, v7
	v_ashrrev_i32_e32 v16, 6, v7
	v_lshlrev_b32_e32 v9, 3, v15
	v_mul_i32_i24_e32 v10, 64, v16
	v_and_b32_e32 v9, -16, v9
	v_sub_u32_e32 v8, v8, v10
	v_mov_b32_e32 v10, 1
	v_add_u32_e32 v7, v16, v9
	v_lshlrev_b32_e32 v9, 5, v15
	v_ashrrev_i16_sdwa v8, v10, sext(v8) dst_sel:DWORD dst_unused:UNUSED_PAD src0_sel:DWORD src1_sel:BYTE_0
	v_and_b32_e32 v9, 32, v9
	v_bfe_i32 v17, v8, 0, 16
	v_and_b32_e32 v12, 3, v16
	s_mov_b32 s1, 0x1fffe0
	v_add_lshl_u32 v9, v9, v17, 1
	v_add_u32_e32 v6, 0x2000, v6
	v_lshlrev_b32_e32 v8, 1, v7
	v_lshrrev_b32_e32 v11, 2, v7
	v_and_or_b32 v12, v7, s1, v12
	v_lshl_add_u32 v130, v7, 11, v9
	v_ashrrev_i32_e32 v7, 31, v6
	v_lshrrev_b32_e32 v7, 22, v7
	v_add_u32_e32 v7, v6, v7
	v_ashrrev_i32_e32 v18, 10, v7
	v_mul_i32_i24_e32 v7, 0x400, v18
	v_sub_u32_e32 v6, v6, v7
	v_and_b32_e32 v8, 24, v8
	v_and_b32_e32 v11, 4, v11
	v_lshrrev_b32_e32 v7, 4, v6
	v_or3_b32 v8, v12, v11, v8
	v_bitop3_b32 v6, v7, v6, 32 bitop3:0x6c
	v_lshl_add_u32 v132, v8, 11, v9
	v_ashrrev_i32_e32 v8, 31, v6
	v_lshrrev_b32_e32 v8, 26, v8
	v_add_u32_e32 v8, v6, v8
	v_lshlrev_b32_e32 v7, 3, v18
	v_ashrrev_i32_e32 v19, 6, v8
	v_and_b32_e32 v8, 0xc0, v8
	v_and_b32_e32 v7, -16, v7
	v_sub_u32_e32 v6, v6, v8
	s_ashr_i32 s0, s10, 6
	v_add_u32_e32 v7, v19, v7
	v_ashrrev_i16_sdwa v6, v10, sext(v6) dst_sel:DWORD dst_unused:UNUSED_PAD src0_sel:DWORD src1_sel:BYTE_0
	v_lshlrev_b32_e32 v9, 5, v18
	v_bfe_i32 v20, v6, 0, 16
	v_lshlrev_b32_e32 v6, 1, v7
	v_lshrrev_b32_e32 v8, 2, v7
	v_and_b32_e32 v10, 3, v19
	s_lshl_b32 s25, s0, 10
	v_and_b32_e32 v9, 32, v9
	v_and_b32_e32 v6, 24, v6
	v_and_b32_e32 v8, 4, v8
	v_and_or_b32 v10, v7, s1, v10
	s_add_i32 s49, s25, 0
	v_or3_b32 v6, v10, v8, v6
	v_add_lshl_u32 v8, v9, v20, 1
	s_add_i32 m0, s49, 0x10000
	v_readfirstlane_b32 s8, v4
	v_readfirstlane_b32 s9, v5
	v_lshl_add_u32 v136, v6, 11, v8
	v_lshl_add_u32 v134, v7, 11, v8
	s_add_i32 s58, s49, 0x2000
	s_add_i32 s59, s49, 0x4000
	s_add_i32 s60, s49, 0x6000
	v_lshrrev_b32_e32 v242, 6, v1
	v_and_b32_e32 v243, 63, v1
	v_lshlrev_b32_e32 v245, 4, v243
	v_lshrrev_b32_e32 v244, 5, v243
	v_lshlrev_b32_e32 v244, 5, v244
	v_xor_b32_e32 v245, v245, v244
	v_lshrrev_b32_e32 v244, 1, v242
	v_lshlrev_b32_e32 v244, 4, v244
	v_lshrrev_b32_e32 v243, 6, v245
	v_add_u32_e32 v244, v244, v243
	v_and_b32_e32 v245, 63, v245
	v_and_b32_e32 v242, 1, v242
	v_lshl_add_u32 v245, v242, 6, v245
	v_mul_u32_u24_e32 v244, 0x800, v244
	v_add_u32_e32 v240, v244, v245
	v_lshrrev_b32_e32 v242, 6, v1
	v_and_b32_e32 v243, 63, v1
	v_lshrrev_b32_e32 v244, 3, v243
	v_lshl_add_u32 v244, v242, 3, v244
	v_lshrrev_b32_e32 v245, 4, v243
	v_and_b32_e32 v245, 3, v245
	v_lshlrev_b32_e32 v245, 1, v245
	v_and_b32_e32 v243, 7, v243
	v_xor_b32_e32 v245, v243, v245
	v_lshlrev_b32_e32 v245, 4, v245
	v_mul_u32_u24_e32 v244, 0x800, v244
	v_add_u32_e32 v241, v244, v245
	v_sub_u32_e32 v130, v130, v240
	v_add_u32_e32 v130, v130, v241
	v_lshrrev_b32_e32 v242, 6, v1
	v_and_b32_e32 v243, 63, v1
	v_lshlrev_b32_e32 v245, 4, v243
	v_lshrrev_b32_e32 v244, 5, v243
	v_lshlrev_b32_e32 v244, 5, v244
	v_xor_b32_e32 v245, v245, v244
	v_add_u32_e32 v242, 8, v242
	v_lshrrev_b32_e32 v244, 1, v242
	v_lshlrev_b32_e32 v244, 4, v244
	v_lshrrev_b32_e32 v243, 6, v245
	v_add_u32_e32 v244, v244, v243
	v_and_b32_e32 v245, 63, v245
	v_and_b32_e32 v242, 1, v242
	v_lshl_add_u32 v245, v242, 6, v245
	v_mul_u32_u24_e32 v244, 0x800, v244
	v_add_u32_e32 v240, v244, v245
	v_lshrrev_b32_e32 v242, 6, v1
	v_and_b32_e32 v243, 63, v1
	v_lshrrev_b32_e32 v244, 3, v243
	v_lshl_add_u32 v244, v242, 3, v244
	v_add_u32_e32 v244, 64, v244
	v_lshrrev_b32_e32 v245, 4, v243
	v_and_b32_e32 v245, 3, v245
	v_lshlrev_b32_e32 v245, 1, v245
	v_and_b32_e32 v243, 7, v243
	v_xor_b32_e32 v245, v243, v245
	v_lshlrev_b32_e32 v245, 4, v245
	v_mul_u32_u24_e32 v244, 0x800, v244
	v_add_u32_e32 v241, v244, v245
	v_sub_u32_e32 v134, v134, v240
	v_add_u32_e32 v134, v134, v241
	v_lshrrev_b32_e32 v242, 6, v1
	v_and_b32_e32 v243, 63, v1
	v_lshlrev_b32_e32 v245, 4, v243
	v_lshrrev_b32_e32 v244, 5, v243
	v_lshlrev_b32_e32 v244, 5, v244
	v_xor_b32_e32 v245, v245, v244
	v_lshrrev_b32_e32 v244, 1, v242
	v_lshlrev_b32_e32 v244, 4, v244
	v_lshrrev_b32_e32 v243, 6, v245
	v_add_u32_e32 v244, v244, v243
	v_and_b32_e32 v245, 63, v245
	v_and_b32_e32 v242, 1, v242
	v_lshl_add_u32 v245, v242, 6, v245
	v_and_b32_e32 v242, 31, v244
	v_sub_u32_e32 v244, v244, v242
	v_and_b32_e32 v243, 3, v242
	v_add_u32_e32 v244, v244, v243
	v_lshrrev_b32_e32 v243, 4, v242
	v_lshl_add_u32 v244, v243, 2, v244
	v_and_b32_e32 v243, 15, v242
	v_lshrrev_b32_e32 v243, 2, v243
	v_lshl_add_u32 v244, v243, 3, v244
	v_mul_u32_u24_e32 v244, 0x800, v244
	v_add_u32_e32 v240, v244, v245
	v_lshrrev_b32_e32 v242, 6, v1
	v_and_b32_e32 v243, 63, v1
	v_lshrrev_b32_e32 v244, 3, v243
	v_lshl_add_u32 v244, v242, 3, v244
	v_lshrrev_b32_e32 v245, 4, v243
	v_and_b32_e32 v245, 3, v245
	v_lshlrev_b32_e32 v245, 1, v245
	v_and_b32_e32 v243, 7, v243
	v_xor_b32_e32 v245, v243, v245
	v_lshlrev_b32_e32 v245, 4, v245
	v_and_b32_e32 v242, 31, v244
	v_sub_u32_e32 v244, v244, v242
	v_and_b32_e32 v243, 3, v242
	v_add_u32_e32 v244, v244, v243
	v_lshrrev_b32_e32 v243, 4, v242
	v_lshl_add_u32 v244, v243, 2, v244
	v_and_b32_e32 v243, 15, v242
	v_lshrrev_b32_e32 v243, 2, v243
	v_lshl_add_u32 v244, v243, 3, v244
	v_mul_u32_u24_e32 v244, 0x800, v244
	v_add_u32_e32 v241, v244, v245
	v_sub_u32_e32 v132, v132, v240
	v_add_u32_e32 v132, v132, v241
	v_lshrrev_b32_e32 v242, 6, v1
	v_and_b32_e32 v243, 63, v1
	v_lshlrev_b32_e32 v245, 4, v243
	v_lshrrev_b32_e32 v244, 5, v243
	v_lshlrev_b32_e32 v244, 5, v244
	v_xor_b32_e32 v245, v245, v244
	v_add_u32_e32 v242, 8, v242
	v_lshrrev_b32_e32 v244, 1, v242
	v_lshlrev_b32_e32 v244, 4, v244
	v_lshrrev_b32_e32 v243, 6, v245
	v_add_u32_e32 v244, v244, v243
	v_and_b32_e32 v245, 63, v245
	v_and_b32_e32 v242, 1, v242
	v_lshl_add_u32 v245, v242, 6, v245
	v_and_b32_e32 v242, 31, v244
	v_sub_u32_e32 v244, v244, v242
	v_and_b32_e32 v243, 3, v242
	v_add_u32_e32 v244, v244, v243
	v_lshrrev_b32_e32 v243, 4, v242
	v_lshl_add_u32 v244, v243, 2, v244
	v_and_b32_e32 v243, 15, v242
	v_lshrrev_b32_e32 v243, 2, v243
	v_lshl_add_u32 v244, v243, 3, v244
	v_mul_u32_u24_e32 v244, 0x800, v244
	v_add_u32_e32 v240, v244, v245
	v_lshrrev_b32_e32 v242, 6, v1
	v_and_b32_e32 v243, 63, v1
	v_lshrrev_b32_e32 v244, 3, v243
	v_lshl_add_u32 v244, v242, 3, v244
	v_add_u32_e32 v244, 64, v244
	v_lshrrev_b32_e32 v245, 4, v243
	v_and_b32_e32 v245, 3, v245
	v_lshlrev_b32_e32 v245, 1, v245
	v_and_b32_e32 v243, 7, v243
	v_xor_b32_e32 v245, v243, v245
	v_lshlrev_b32_e32 v245, 4, v245
	v_and_b32_e32 v242, 31, v244
	v_sub_u32_e32 v244, v244, v242
	v_and_b32_e32 v243, 3, v242
	v_add_u32_e32 v244, v244, v243
	v_lshrrev_b32_e32 v243, 4, v242
	v_lshl_add_u32 v244, v243, 2, v244
	v_and_b32_e32 v243, 15, v242
	v_lshrrev_b32_e32 v243, 2, v243
	v_lshl_add_u32 v244, v243, 3, v244
	v_mul_u32_u24_e32 v244, 0x800, v244
	v_add_u32_e32 v241, v244, v245
	v_sub_u32_e32 v136, v136, v240
	v_add_u32_e32 v136, v136, v241
	global_load_lds_dwordx4 v132, s[8:9]
	s_add_i32 m0, s49, 0x12000
	s_ashr_i32 s1, s10, 8
	global_load_lds_dwordx4 v136, s[8:9]
	s_mov_b64 s[8:9], 0x40000
	v_lshl_add_u64 v[6:7], v[4:5], 0, s[8:9]
	s_add_i32 m0, s49, 0x14000
	v_readfirstlane_b32 s12, v6
	v_readfirstlane_b32 s13, v7
	v_lshl_add_u64 v[6:7], v[2:3], 0, s[8:9]
	v_mov_b32_e32 v139, 0
	v_mov_b32_e32 v133, v139
	v_mov_b32_e32 v137, v139
	v_mov_b32_e32 v131, v139
	global_load_lds_dwordx4 v132, s[12:13]
	s_add_i32 m0, s49, 0x16000
	v_mov_b32_e32 v135, v139
	global_load_lds_dwordx4 v136, s[12:13]
	v_readfirstlane_b32 s12, v2
	v_readfirstlane_b32 s13, v3
	s_mov_b32 m0, s49
	s_cmp_eq_u32 s1, 1
	s_mov_b32 s11, 0
	v_lshl_add_u64 v[12:13], v[4:5], 0, v[132:133]
	v_lshl_add_u64 v[10:11], v[4:5], 0, v[136:137]
	global_load_lds_dwordx4 v130, s[12:13]
	s_mov_b32 m0, s58
	v_lshl_add_u64 v[8:9], v[2:3], 0, v[134:135]
	global_load_lds_dwordx4 v134, s[12:13]
	v_readfirstlane_b32 s12, v6
	v_readfirstlane_b32 s13, v7
	s_mov_b32 m0, s59
	v_lshl_add_u64 v[6:7], v[2:3], 0, v[130:131]
	s_nop 2
	global_load_lds_dwordx4 v130, s[12:13]
	s_mov_b32 m0, s60
	s_nop 0
	global_load_lds_dwordx4 v134, s[12:13]
	s_cselect_b64 s[12:13], -1, 0
	s_cmp_lg_u32 s1, 1
	s_cbranch_scc1 .LBB0_1937
	s_barrier
.LBB0_1937:
	s_mov_b64 s[14:15], 0x80
	s_add_i32 m0, s49, 0x18000
	v_lshl_add_u64 v[12:13], v[12:13], 0, s[14:15]
	s_waitcnt vmcnt(2)
	s_barrier
	global_load_lds_dwordx4 v[12:13], off
	v_lshl_add_u64 v[10:11], v[10:11], 0, s[14:15]
	s_add_i32 m0, s49, 0x1a000
	s_add_i32 s61, s49, 0x8000
	global_load_lds_dwordx4 v[10:11], off
	v_lshl_add_u64 v[6:7], v[6:7], 0, s[14:15]
	s_mov_b32 m0, s61
	s_add_i32 s62, s49, 0xa000
	global_load_lds_dwordx4 v[6:7], off
	v_lshl_add_u64 v[6:7], v[8:9], 0, s[14:15]
	s_mov_b32 m0, s62
	s_mov_b64 s[16:17], 0x40080
	global_load_lds_dwordx4 v[6:7], off
	v_lshl_add_u64 v[6:7], v[4:5], 0, s[16:17]
	s_add_i32 m0, s49, 0x1c000
	v_lshl_add_u64 v[8:9], v[6:7], 0, v[132:133]
	global_load_lds_dwordx4 v[8:9], off
	v_lshl_add_u64 v[6:7], v[6:7], 0, v[136:137]
	s_add_i32 m0, s49, 0x1e000
	v_and_b32_e32 v140, 15, v14
	global_load_lds_dwordx4 v[6:7], off
	v_bfe_u32 v6, v14, 4, 2
	v_lshlrev_b32_e32 v7, 4, v6
	v_lshlrev_b32_e32 v9, 2, v14
	s_and_b32 s5, s0, 3
	s_lshl_b32 s63, s1, 6
	v_lshl_or_b32 v8, v140, 6, v7
	s_lshl_b32 s1, s1, 13
	v_and_b32_e32 v9, 32, v9
	v_bitop3_b32 v10, v8, s1, v9 bitop3:0xde
	s_lshl_b32 s64, s5, 5
	s_lshl_b32 s1, s5, 12
	s_cmpk_lt_u32 s10, 0x100
	s_cselect_b64 s[18:19], -1, 0
	s_lshl_b32 s0, s0, 6
	v_bitop3_b32 v141, v8, s1, v9 bitop3:0xde
	v_and_or_b32 v158, s0, 64, v7
	v_cmp_eq_u32_e64 s[0:1], 0, v6
	v_lshl_or_b32 v159, v6, 3, s64
	v_lshlrev_b32_e32 v6, 14, v18
	v_and_b32_e32 v6, 0xffff8000, v6
	v_lshl_add_u32 v6, v19, 11, v6
	v_and_b32_e32 v7, 1, v18
	v_lshl_or_b32 v6, v7, 6, v6
	v_lshl_add_u32 v142, v20, 1, v6
	v_lshlrev_b32_e32 v6, 14, v15
	v_and_b32_e32 v6, 0xffff8000, v6
	v_lshl_add_u32 v6, v16, 11, v6
	v_and_b32_e32 v7, 1, v15
	s_waitcnt vmcnt(6)
	v_lshl_or_b32 v6, v7, 6, v6
	s_add_i32 s72, 0, 0x10000
	v_lshl_add_u32 v144, v17, 1, v6
	s_mov_b32 s22, 0xfffc0080
	s_add_i32 s76, s72, s25
	v_mbcnt_lo_u32_b32 v6, -1, 0
	s_lshl_b32 s10, s5, 2
	v_mov_b32_e32 v143, v139
	v_mov_b32_e32 v145, v139
	s_movk_i32 s65, 0x161
	s_add_i32 s66, 0, 0x20020
	s_add_i32 s67, 0, 0x20018
	s_add_i32 s70, 0, 0x2002c
	s_add_i32 s71, 0, 0x20000
	s_mov_b64 s[20:21], 0x100
	s_mov_b32 s23, -1
	s_add_i32 s73, 0, 0x14000
	v_add_u32_e32 v160, 0, v10
	s_add_i32 s74, s49, 0xc000
	s_add_i32 s75, s49, 0xe000
	s_add_i32 s77, s76, 0x2000
	s_add_i32 s78, 0, 0x20010
	s_add_i32 s79, 0, 0x20024
	s_movk_i32 s80, 0x7fff
	s_mov_b32 s24, 0xbfb8aa3b
	v_mbcnt_hi_u32_b32 v161, -1, v6
	s_mov_b32 s81, s11
	v_mov_b64_e32 v[148:149], v[4:5]
	v_mov_b64_e32 v[146:147], v[2:3]
	s_barrier
	v_lshrrev_b32_e32 v242, 6, v1
	v_and_b32_e32 v243, 63, v1
	v_lshlrev_b32_e32 v245, 4, v243
	v_lshrrev_b32_e32 v244, 5, v243
	v_lshlrev_b32_e32 v244, 5, v244
	v_xor_b32_e32 v245, v245, v244
	v_lshrrev_b32_e32 v244, 1, v242
	v_lshlrev_b32_e32 v244, 4, v244
	v_lshrrev_b32_e32 v243, 6, v245
	v_add_u32_e32 v244, v244, v243
	v_and_b32_e32 v245, 63, v245
	v_and_b32_e32 v242, 1, v242
	v_lshl_add_u32 v245, v242, 6, v245
	v_mul_u32_u24_e32 v244, 0x800, v244
	v_add_u32_e32 v240, v244, v245
	v_lshrrev_b32_e32 v242, 6, v1
	v_and_b32_e32 v243, 63, v1
	v_lshrrev_b32_e32 v244, 3, v243
	v_lshl_add_u32 v244, v242, 3, v244
	v_lshrrev_b32_e32 v245, 4, v243
	v_and_b32_e32 v245, 3, v245
	v_lshlrev_b32_e32 v245, 1, v245
	v_and_b32_e32 v243, 7, v243
	v_xor_b32_e32 v245, v243, v245
	v_lshlrev_b32_e32 v245, 4, v245
	v_mul_u32_u24_e32 v244, 0x800, v244
	v_add_u32_e32 v241, v244, v245
	v_sub_u32_e32 v144, v144, v240
	v_add_u32_e32 v144, v144, v241
	v_lshrrev_b32_e32 v242, 6, v1
	v_and_b32_e32 v243, 63, v1
	v_lshlrev_b32_e32 v245, 4, v243
	v_lshrrev_b32_e32 v244, 5, v243
	v_lshlrev_b32_e32 v244, 5, v244
	v_xor_b32_e32 v245, v245, v244
	v_add_u32_e32 v242, 8, v242
	v_lshrrev_b32_e32 v244, 1, v242
	v_lshlrev_b32_e32 v244, 4, v244
	v_lshrrev_b32_e32 v243, 6, v245
	v_add_u32_e32 v244, v244, v243
	v_and_b32_e32 v245, 63, v245
	v_and_b32_e32 v242, 1, v242
	v_lshl_add_u32 v245, v242, 6, v245
	v_mul_u32_u24_e32 v244, 0x800, v244
	v_add_u32_e32 v240, v244, v245
	v_lshrrev_b32_e32 v242, 6, v1
	v_and_b32_e32 v243, 63, v1
	v_lshrrev_b32_e32 v244, 3, v243
	v_lshl_add_u32 v244, v242, 3, v244
	v_add_u32_e32 v244, 64, v244
	v_lshrrev_b32_e32 v245, 4, v243
	v_and_b32_e32 v245, 3, v245
	v_lshlrev_b32_e32 v245, 1, v245
	v_and_b32_e32 v243, 7, v243
	v_xor_b32_e32 v245, v243, v245
	v_lshlrev_b32_e32 v245, 4, v245
	v_mul_u32_u24_e32 v244, 0x800, v244
	v_add_u32_e32 v241, v244, v245
	v_sub_u32_e32 v142, v142, v240
	v_add_u32_e32 v142, v142, v241
	v_and_b32_e32 v240, 63, v1
	v_and_b32_e32 v241, 15, v240
	v_lshrrev_b32_e32 v242, 4, v240
	v_lshlrev_b32_e32 v243, 6, v241
	v_lshl_add_u32 v243, v242, 4, v243
	v_lshrrev_b32_e32 v244, 3, v241
	v_lshlrev_b32_e32 v245, 5, v244
	v_xor_b32_e32 v243, v243, v245
	v_sub_u32_e32 v160, v160, v243
	v_lshlrev_b32_e32 v244, 10, v244
	v_and_b32_e32 v245, 7, v241
	v_lshl_add_u32 v244, v245, 7, v244
	v_add_u32_e32 v160, v160, v244
	v_lshrrev_b32_e32 v245, 1, v245
	v_lshlrev_b32_e32 v245, 1, v245
	v_add_u32_e32 v244, 4, v242
	v_xor_b32_e32 v244, v244, v245
	v_lshl_add_u32 v238, v244, 4, v160
	v_xor_b32_e32 v244, v242, v245
	v_lshl_add_u32 v160, v244, 4, v160
	v_and_b32_e32 v240, 63, v1
	v_and_b32_e32 v241, 15, v240
	v_lshrrev_b32_e32 v242, 4, v240
	v_lshlrev_b32_e32 v243, 6, v241
	v_lshl_add_u32 v243, v242, 4, v243
	v_lshrrev_b32_e32 v244, 3, v241
	v_lshlrev_b32_e32 v245, 5, v244
	v_xor_b32_e32 v243, v243, v245
	v_sub_u32_e32 v141, v141, v243
	v_lshlrev_b32_e32 v244, 10, v244
	v_and_b32_e32 v245, 7, v241
	v_lshl_add_u32 v244, v245, 7, v244
	v_add_u32_e32 v141, v141, v244
	v_lshrrev_b32_e32 v245, 1, v245
	v_lshlrev_b32_e32 v245, 1, v245
	v_add_u32_e32 v244, 4, v242
	v_xor_b32_e32 v244, v244, v245
	v_lshl_add_u32 v239, v244, 4, v141
	v_xor_b32_e32 v244, v242, v245
	v_lshl_add_u32 v141, v244, 4, v141
	s_branch .LBB0_1940

.Lmy_nb_10:
	s_nop 0
	v_readfirstlane_b32 s86, v152
	v_readfirstlane_b32 s87, v153
	v_readfirstlane_b32 s88, v150
	v_readfirstlane_b32 s89, v151
	v_readfirstlane_b32 s90, v146
	v_readfirstlane_b32 s91, v147
	v_readfirstlane_b32 s92, v148
	v_readfirstlane_b32 s93, v149
	v_readfirstlane_b32 s100, v154
	v_readfirstlane_b32 s101, v138
	v_add_u32_e32 v230, s72, v141
	v_add_u32_e32 v234, s72, v239
	v_add_u32_e32 v231, s73, v141
	v_add_u32_e32 v235, s73, v239
	v_add_u32_e32 v232, 0x18000, v141
	v_add_u32_e32 v236, 0x18000, v239
	v_add_u32_e32 v233, 0x1c000, v141
	v_add_u32_e32 v237, 0x1c000, v239
	s_add_u32 s98, s86, 0xfffc0080
	s_addc_u32 s99, s87, -1
	s_cmp_eq_u32 s5, s100
	s_cselect_b64 s[94:95], s[90:91], s[98:99]
	s_cselect_b64 s[96:97], s[92:93], s[88:89]
	s_add_i32 s45, s5, 2
	s_mov_b32 m0, s74
	ds_read_b128 v[164:167], v230
	global_load_lds_dwordx4 v144, s[86:87]
	s_mov_b32 m0, s75
	ds_read_b128 v[168:171], v234
	global_load_lds_dwordx4 v142, s[86:87]
	ds_read_b128 v[172:175], v230 offset:2048
	ds_read_b128 v[176:179], v234 offset:2048
	ds_read_b128 v[180:183], v231
	ds_read_b128 v[184:187], v235
	ds_read_b128 v[188:191], v231 offset:2048
	ds_read_b128 v[192:195], v235 offset:2048
	ds_read_b128 v[196:199], v160
	ds_read_b128 v[200:203], v238
	ds_read_b128 v[204:207], v160 offset:2048
	ds_read_b128 v[208:211], v238 offset:2048
	ds_read_b128 v[212:215], v160 offset:4096
	ds_read_b128 v[216:219], v238 offset:4096
	ds_read_b128 v[220:223], v160 offset:6144
	ds_read_b128 v[224:227], v238 offset:6144
	s_waitcnt vmcnt(8)
	s_waitcnt lgkmcnt(0)
	s_setprio 1
	s_barrier
	v_mfma_f32_16x16x32_bf16 v[122:125], v[164:167], v[196:199], 0
	v_mfma_f32_16x16x32_bf16 v[118:121], v[172:175], v[196:199], 0
	v_mfma_f32_16x16x32_bf16 v[110:113], v[164:167], v[204:207], 0
	v_mfma_f32_16x16x32_bf16 v[102:105], v[172:175], v[204:207], 0
	v_mfma_f32_16x16x32_bf16 v[94:97], v[164:167], v[212:215], 0
	v_mfma_f32_16x16x32_bf16 v[86:89], v[172:175], v[212:215], 0
	v_mfma_f32_16x16x32_bf16 v[78:81], v[164:167], v[220:223], 0
	v_mfma_f32_16x16x32_bf16 v[70:73], v[172:175], v[220:223], 0
	v_mfma_f32_16x16x32_bf16 v[122:125], v[168:171], v[200:203], v[122:125]
	v_mfma_f32_16x16x32_bf16 v[118:121], v[176:179], v[200:203], v[118:121]
	v_mfma_f32_16x16x32_bf16 v[110:113], v[168:171], v[208:211], v[110:113]
	v_mfma_f32_16x16x32_bf16 v[102:105], v[176:179], v[208:211], v[102:105]
	v_mfma_f32_16x16x32_bf16 v[94:97], v[168:171], v[216:219], v[94:97]
	v_mfma_f32_16x16x32_bf16 v[86:89], v[176:179], v[216:219], v[86:89]
	v_mfma_f32_16x16x32_bf16 v[78:81], v[168:171], v[224:227], v[78:81]
	v_mfma_f32_16x16x32_bf16 v[70:73], v[176:179], v[224:227], v[70:73]
	v_mfma_f32_16x16x32_bf16 v[126:129], v[180:183], v[196:199], 0
	v_mfma_f32_16x16x32_bf16 v[114:117], v[188:191], v[196:199], 0
	v_mfma_f32_16x16x32_bf16 v[106:109], v[180:183], v[204:207], 0
	v_mfma_f32_16x16x32_bf16 v[98:101], v[188:191], v[204:207], 0
	v_mfma_f32_16x16x32_bf16 v[90:93], v[180:183], v[212:215], 0
	v_mfma_f32_16x16x32_bf16 v[82:85], v[188:191], v[212:215], 0
	v_mfma_f32_16x16x32_bf16 v[74:77], v[180:183], v[220:223], 0
	v_mfma_f32_16x16x32_bf16 v[66:69], v[188:191], v[220:223], 0
	v_mfma_f32_16x16x32_bf16 v[126:129], v[184:187], v[200:203], v[126:129]
	v_mfma_f32_16x16x32_bf16 v[114:117], v[192:195], v[200:203], v[114:117]
	v_mfma_f32_16x16x32_bf16 v[106:109], v[184:187], v[208:211], v[106:109]
	v_mfma_f32_16x16x32_bf16 v[98:101], v[192:195], v[208:211], v[98:101]
	v_mfma_f32_16x16x32_bf16 v[90:93], v[184:187], v[216:219], v[90:93]
	v_mfma_f32_16x16x32_bf16 v[82:85], v[192:195], v[216:219], v[82:85]
	v_mfma_f32_16x16x32_bf16 v[74:77], v[184:187], v[224:227], v[74:77]
	v_mfma_f32_16x16x32_bf16 v[66:69], v[192:195], v[224:227], v[66:69]
	s_barrier
	s_setprio 0
	s_add_u32 s98, s96, 0x40000
	s_addc_u32 s99, s97, 0
	s_mov_b32 m0, s76
	ds_read_b128 v[196:199], v160 offset:16384
	global_load_lds_dwordx4 v132, s[96:97]
	s_mov_b32 m0, s77
	s_add_i32 s5, s73, s25
	global_load_lds_dwordx4 v136, s[96:97]
	s_mov_b32 m0, s5
	ds_read_b128 v[200:203], v238 offset:16384
	global_load_lds_dwordx4 v132, s[98:99]
	s_add_i32 m0, s5, 0x2000
	ds_read_b128 v[204:207], v160 offset:18432
	global_load_lds_dwordx4 v136, s[98:99]
	s_mov_b32 m0, s49
	ds_read_b128 v[208:211], v238 offset:18432
	global_load_lds_dwordx4 v130, s[94:95]
	s_mov_b32 m0, s58
	ds_read_b128 v[212:215], v160 offset:20480
	global_load_lds_dwordx4 v134, s[94:95]
	ds_read_b128 v[216:219], v238 offset:20480
	ds_read_b128 v[220:223], v160 offset:22528
	ds_read_b128 v[224:227], v238 offset:22528
	s_waitcnt vmcnt(8)
	s_waitcnt lgkmcnt(0)
	s_setprio 1
	s_barrier
	v_mfma_f32_16x16x32_bf16 v[62:65], v[164:167], v[196:199], 0
	v_mfma_f32_16x16x32_bf16 v[54:57], v[172:175], v[196:199], 0
	v_mfma_f32_16x16x32_bf16 v[46:49], v[164:167], v[204:207], 0
	v_mfma_f32_16x16x32_bf16 v[38:41], v[172:175], v[204:207], 0
	v_mfma_f32_16x16x32_bf16 v[30:33], v[164:167], v[212:215], 0
	v_mfma_f32_16x16x32_bf16 v[22:25], v[172:175], v[212:215], 0
	v_mfma_f32_16x16x32_bf16 v[14:17], v[164:167], v[220:223], 0
	v_mfma_f32_16x16x32_bf16 v[6:9], v[172:175], v[220:223], 0
	v_mfma_f32_16x16x32_bf16 v[62:65], v[168:171], v[200:203], v[62:65]
	v_mfma_f32_16x16x32_bf16 v[54:57], v[176:179], v[200:203], v[54:57]
	v_mfma_f32_16x16x32_bf16 v[46:49], v[168:171], v[208:211], v[46:49]
	v_mfma_f32_16x16x32_bf16 v[38:41], v[176:179], v[208:211], v[38:41]
	v_mfma_f32_16x16x32_bf16 v[30:33], v[168:171], v[216:219], v[30:33]
	v_mfma_f32_16x16x32_bf16 v[22:25], v[176:179], v[216:219], v[22:25]
	v_mfma_f32_16x16x32_bf16 v[14:17], v[168:171], v[224:227], v[14:17]
	v_mfma_f32_16x16x32_bf16 v[6:9], v[176:179], v[224:227], v[6:9]
	v_mfma_f32_16x16x32_bf16 v[58:61], v[180:183], v[196:199], 0
	v_mfma_f32_16x16x32_bf16 v[50:53], v[188:191], v[196:199], 0
	v_mfma_f32_16x16x32_bf16 v[42:45], v[180:183], v[204:207], 0
	v_mfma_f32_16x16x32_bf16 v[34:37], v[188:191], v[204:207], 0
	v_mfma_f32_16x16x32_bf16 v[26:29], v[180:183], v[212:215], 0
	v_mfma_f32_16x16x32_bf16 v[18:21], v[188:191], v[212:215], 0
	v_mfma_f32_16x16x32_bf16 v[10:13], v[180:183], v[220:223], 0
	v_mfma_f32_16x16x32_bf16 v[2:5], v[188:191], v[220:223], 0
	v_mfma_f32_16x16x32_bf16 v[58:61], v[184:187], v[200:203], v[58:61]
	v_mfma_f32_16x16x32_bf16 v[50:53], v[192:195], v[200:203], v[50:53]
	v_mfma_f32_16x16x32_bf16 v[42:45], v[184:187], v[208:211], v[42:45]
	v_mfma_f32_16x16x32_bf16 v[34:37], v[192:195], v[208:211], v[34:37]
	v_mfma_f32_16x16x32_bf16 v[26:29], v[184:187], v[216:219], v[26:29]
	v_mfma_f32_16x16x32_bf16 v[18:21], v[192:195], v[216:219], v[18:21]
	v_mfma_f32_16x16x32_bf16 v[10:13], v[184:187], v[224:227], v[10:13]
	v_mfma_f32_16x16x32_bf16 v[2:5], v[192:195], v[224:227], v[2:5]
	s_barrier
	s_setprio 0
	s_add_u32 s98, s94, 0x40000
	s_addc_u32 s99, s95, 0
	s_add_i32 s5, 0, 0x18000
	s_add_i32 s47, 0, 0x1c000
	s_mov_b32 m0, s59
	ds_read_b128 v[164:167], v232
	global_load_lds_dwordx4 v130, s[98:99]
	s_mov_b32 m0, s60
	ds_read_b128 v[168:171], v236
	global_load_lds_dwordx4 v134, s[98:99]
	ds_read_b128 v[172:175], v232 offset:2048
	ds_read_b128 v[176:179], v236 offset:2048
	ds_read_b128 v[180:183], v233
	ds_read_b128 v[184:187], v237
	ds_read_b128 v[188:191], v233 offset:2048
	ds_read_b128 v[192:195], v237 offset:2048
	ds_read_b128 v[196:199], v160 offset:32768
	ds_read_b128 v[200:203], v238 offset:32768
	ds_read_b128 v[204:207], v160 offset:34816
	ds_read_b128 v[208:211], v238 offset:34816
	ds_read_b128 v[212:215], v160 offset:36864
	ds_read_b128 v[216:219], v238 offset:36864
	ds_read_b128 v[220:223], v160 offset:38912
	ds_read_b128 v[224:227], v238 offset:38912
	s_waitcnt vmcnt(8)
	s_waitcnt lgkmcnt(0)
	s_setprio 1
	s_barrier
	v_mfma_f32_16x16x32_bf16 v[122:125], v[164:167], v[196:199], v[122:125]
	v_mfma_f32_16x16x32_bf16 v[118:121], v[172:175], v[196:199], v[118:121]
	v_mfma_f32_16x16x32_bf16 v[110:113], v[164:167], v[204:207], v[110:113]
	v_mfma_f32_16x16x32_bf16 v[102:105], v[172:175], v[204:207], v[102:105]
	v_mfma_f32_16x16x32_bf16 v[94:97], v[164:167], v[212:215], v[94:97]
	v_mfma_f32_16x16x32_bf16 v[86:89], v[172:175], v[212:215], v[86:89]
	v_mfma_f32_16x16x32_bf16 v[78:81], v[164:167], v[220:223], v[78:81]
	v_mfma_f32_16x16x32_bf16 v[70:73], v[172:175], v[220:223], v[70:73]
	v_mfma_f32_16x16x32_bf16 v[122:125], v[168:171], v[200:203], v[122:125]
	v_mfma_f32_16x16x32_bf16 v[118:121], v[176:179], v[200:203], v[118:121]
	v_mfma_f32_16x16x32_bf16 v[110:113], v[168:171], v[208:211], v[110:113]
	v_mfma_f32_16x16x32_bf16 v[102:105], v[176:179], v[208:211], v[102:105]
	v_mfma_f32_16x16x32_bf16 v[94:97], v[168:171], v[216:219], v[94:97]
	v_mfma_f32_16x16x32_bf16 v[86:89], v[176:179], v[216:219], v[86:89]
	v_mfma_f32_16x16x32_bf16 v[78:81], v[168:171], v[224:227], v[78:81]
	v_mfma_f32_16x16x32_bf16 v[70:73], v[176:179], v[224:227], v[70:73]
	v_mfma_f32_16x16x32_bf16 v[126:129], v[180:183], v[196:199], v[126:129]
	v_mfma_f32_16x16x32_bf16 v[114:117], v[188:191], v[196:199], v[114:117]
	v_mfma_f32_16x16x32_bf16 v[106:109], v[180:183], v[204:207], v[106:109]
	v_mfma_f32_16x16x32_bf16 v[98:101], v[188:191], v[204:207], v[98:101]
	v_mfma_f32_16x16x32_bf16 v[90:93], v[180:183], v[212:215], v[90:93]
	v_mfma_f32_16x16x32_bf16 v[82:85], v[188:191], v[212:215], v[82:85]
	v_mfma_f32_16x16x32_bf16 v[74:77], v[180:183], v[220:223], v[74:77]
	v_mfma_f32_16x16x32_bf16 v[66:69], v[188:191], v[220:223], v[66:69]
	v_mfma_f32_16x16x32_bf16 v[126:129], v[184:187], v[200:203], v[126:129]
	v_mfma_f32_16x16x32_bf16 v[114:117], v[192:195], v[200:203], v[114:117]
	v_mfma_f32_16x16x32_bf16 v[106:109], v[184:187], v[208:211], v[106:109]
	v_mfma_f32_16x16x32_bf16 v[98:101], v[192:195], v[208:211], v[98:101]
	v_mfma_f32_16x16x32_bf16 v[90:93], v[184:187], v[216:219], v[90:93]
	v_mfma_f32_16x16x32_bf16 v[82:85], v[192:195], v[216:219], v[82:85]
	v_mfma_f32_16x16x32_bf16 v[74:77], v[184:187], v[224:227], v[74:77]
	v_mfma_f32_16x16x32_bf16 v[66:69], v[192:195], v[224:227], v[66:69]
	s_barrier
	s_setprio 0
	s_add_u32 s96, s96, 0x80
	s_addc_u32 s97, s97, 0
	s_add_u32 s98, s96, 0x40000
	s_addc_u32 s99, s97, 0
	s_add_u32 s94, s94, 0x80
	s_addc_u32 s95, s95, 0
	s_add_i32 s5, s5, s25
	s_mov_b32 m0, s5
	ds_read_b128 v[196:199], v160 offset:49152
	global_load_lds_dwordx4 v132, s[96:97]
	s_add_i32 m0, s5, 0x2000
	s_add_i32 s5, s47, s25
	global_load_lds_dwordx4 v136, s[96:97]
	s_mov_b32 m0, s5
	ds_read_b128 v[200:203], v238 offset:49152
	global_load_lds_dwordx4 v132, s[98:99]
	s_add_i32 m0, s5, 0x2000
	ds_read_b128 v[204:207], v160 offset:51200
	global_load_lds_dwordx4 v136, s[98:99]
	s_mov_b32 m0, s61
	ds_read_b128 v[208:211], v238 offset:51200
	global_load_lds_dwordx4 v130, s[94:95]
	s_mov_b32 m0, s62
	ds_read_b128 v[212:215], v160 offset:53248
	global_load_lds_dwordx4 v134, s[94:95]
	ds_read_b128 v[216:219], v238 offset:53248
	ds_read_b128 v[220:223], v160 offset:55296
	ds_read_b128 v[224:227], v238 offset:55296
	s_waitcnt vmcnt(8)
	s_waitcnt lgkmcnt(0)
	s_setprio 1
	s_barrier
	v_mfma_f32_16x16x32_bf16 v[62:65], v[164:167], v[196:199], v[62:65]
	v_mfma_f32_16x16x32_bf16 v[54:57], v[172:175], v[196:199], v[54:57]
	v_mfma_f32_16x16x32_bf16 v[46:49], v[164:167], v[204:207], v[46:49]
	v_mfma_f32_16x16x32_bf16 v[38:41], v[172:175], v[204:207], v[38:41]
	v_mfma_f32_16x16x32_bf16 v[30:33], v[164:167], v[212:215], v[30:33]
	v_mfma_f32_16x16x32_bf16 v[22:25], v[172:175], v[212:215], v[22:25]
	v_mfma_f32_16x16x32_bf16 v[14:17], v[164:167], v[220:223], v[14:17]
	v_mfma_f32_16x16x32_bf16 v[6:9], v[172:175], v[220:223], v[6:9]
	v_mfma_f32_16x16x32_bf16 v[62:65], v[168:171], v[200:203], v[62:65]
	v_mfma_f32_16x16x32_bf16 v[54:57], v[176:179], v[200:203], v[54:57]
	v_mfma_f32_16x16x32_bf16 v[46:49], v[168:171], v[208:211], v[46:49]
	v_mfma_f32_16x16x32_bf16 v[38:41], v[176:179], v[208:211], v[38:41]
	v_mfma_f32_16x16x32_bf16 v[30:33], v[168:171], v[216:219], v[30:33]
	v_mfma_f32_16x16x32_bf16 v[22:25], v[176:179], v[216:219], v[22:25]
	v_mfma_f32_16x16x32_bf16 v[14:17], v[168:171], v[224:227], v[14:17]
	v_mfma_f32_16x16x32_bf16 v[6:9], v[176:179], v[224:227], v[6:9]
	v_mfma_f32_16x16x32_bf16 v[58:61], v[180:183], v[196:199], v[58:61]
	v_mfma_f32_16x16x32_bf16 v[50:53], v[188:191], v[196:199], v[50:53]
	v_mfma_f32_16x16x32_bf16 v[42:45], v[180:183], v[204:207], v[42:45]
	v_mfma_f32_16x16x32_bf16 v[34:37], v[188:191], v[204:207], v[34:37]
	v_mfma_f32_16x16x32_bf16 v[26:29], v[180:183], v[212:215], v[26:29]
	v_mfma_f32_16x16x32_bf16 v[18:21], v[188:191], v[212:215], v[18:21]
	v_mfma_f32_16x16x32_bf16 v[10:13], v[180:183], v[220:223], v[10:13]
	v_mfma_f32_16x16x32_bf16 v[2:5], v[188:191], v[220:223], v[2:5]
	v_mfma_f32_16x16x32_bf16 v[58:61], v[184:187], v[200:203], v[58:61]
	v_mfma_f32_16x16x32_bf16 v[50:53], v[192:195], v[200:203], v[50:53]
	v_mfma_f32_16x16x32_bf16 v[42:45], v[184:187], v[208:211], v[42:45]
	v_mfma_f32_16x16x32_bf16 v[34:37], v[192:195], v[208:211], v[34:37]
	v_mfma_f32_16x16x32_bf16 v[26:29], v[184:187], v[216:219], v[26:29]
	v_mfma_f32_16x16x32_bf16 v[18:21], v[192:195], v[216:219], v[18:21]
	v_mfma_f32_16x16x32_bf16 v[10:13], v[184:187], v[224:227], v[10:13]
	v_mfma_f32_16x16x32_bf16 v[2:5], v[192:195], v[224:227], v[2:5]
	s_barrier
	s_setprio 0
	s_mov_b32 s5, s45
	s_add_u32 s88, s88, 0x100
	s_addc_u32 s89, s89, 0
	s_add_u32 s86, s86, 0x100
	s_addc_u32 s87, s87, 0
	s_cmp_ge_i32 s45, s101
	s_cbranch_scc1 .Lmy_kexit_10
.LBB0_1944:
	s_add_u32 s98, s86, 0xfffc0080
	s_addc_u32 s99, s87, -1
	s_cmp_eq_u32 s5, s100
	s_cselect_b64 s[94:95], s[90:91], s[98:99]
	s_cselect_b64 s[96:97], s[92:93], s[88:89]
	s_add_i32 s45, s5, 2
	s_mov_b32 m0, s74
	ds_read_b128 v[164:167], v230
	global_load_lds_dwordx4 v144, s[86:87]
	s_mov_b32 m0, s75
	ds_read_b128 v[168:171], v234
	global_load_lds_dwordx4 v142, s[86:87]
	ds_read_b128 v[172:175], v230 offset:2048
	ds_read_b128 v[176:179], v234 offset:2048
	ds_read_b128 v[180:183], v231
	ds_read_b128 v[184:187], v235
	ds_read_b128 v[188:191], v231 offset:2048
	ds_read_b128 v[192:195], v235 offset:2048
	ds_read_b128 v[196:199], v160
	ds_read_b128 v[200:203], v238
	ds_read_b128 v[204:207], v160 offset:2048
	ds_read_b128 v[208:211], v238 offset:2048
	ds_read_b128 v[212:215], v160 offset:4096
	ds_read_b128 v[216:219], v238 offset:4096
	ds_read_b128 v[220:223], v160 offset:6144
	ds_read_b128 v[224:227], v238 offset:6144
	s_waitcnt vmcnt(8)
	s_waitcnt lgkmcnt(0)
	s_setprio 1
	s_barrier
	v_mfma_f32_16x16x32_bf16 v[122:125], v[164:167], v[196:199], v[122:125]
	v_mfma_f32_16x16x32_bf16 v[118:121], v[172:175], v[196:199], v[118:121]
	v_mfma_f32_16x16x32_bf16 v[110:113], v[164:167], v[204:207], v[110:113]
	v_mfma_f32_16x16x32_bf16 v[102:105], v[172:175], v[204:207], v[102:105]
	v_mfma_f32_16x16x32_bf16 v[94:97], v[164:167], v[212:215], v[94:97]
	v_mfma_f32_16x16x32_bf16 v[86:89], v[172:175], v[212:215], v[86:89]
	v_mfma_f32_16x16x32_bf16 v[78:81], v[164:167], v[220:223], v[78:81]
	v_mfma_f32_16x16x32_bf16 v[70:73], v[172:175], v[220:223], v[70:73]
	v_mfma_f32_16x16x32_bf16 v[122:125], v[168:171], v[200:203], v[122:125]
	v_mfma_f32_16x16x32_bf16 v[118:121], v[176:179], v[200:203], v[118:121]
	v_mfma_f32_16x16x32_bf16 v[110:113], v[168:171], v[208:211], v[110:113]
	v_mfma_f32_16x16x32_bf16 v[102:105], v[176:179], v[208:211], v[102:105]
	v_mfma_f32_16x16x32_bf16 v[94:97], v[168:171], v[216:219], v[94:97]
	v_mfma_f32_16x16x32_bf16 v[86:89], v[176:179], v[216:219], v[86:89]
	v_mfma_f32_16x16x32_bf16 v[78:81], v[168:171], v[224:227], v[78:81]
	v_mfma_f32_16x16x32_bf16 v[70:73], v[176:179], v[224:227], v[70:73]
	v_mfma_f32_16x16x32_bf16 v[126:129], v[180:183], v[196:199], v[126:129]
	v_mfma_f32_16x16x32_bf16 v[114:117], v[188:191], v[196:199], v[114:117]
	v_mfma_f32_16x16x32_bf16 v[106:109], v[180:183], v[204:207], v[106:109]
	v_mfma_f32_16x16x32_bf16 v[98:101], v[188:191], v[204:207], v[98:101]
	v_mfma_f32_16x16x32_bf16 v[90:93], v[180:183], v[212:215], v[90:93]
	v_mfma_f32_16x16x32_bf16 v[82:85], v[188:191], v[212:215], v[82:85]
	v_mfma_f32_16x16x32_bf16 v[74:77], v[180:183], v[220:223], v[74:77]
	v_mfma_f32_16x16x32_bf16 v[66:69], v[188:191], v[220:223], v[66:69]
	v_mfma_f32_16x16x32_bf16 v[126:129], v[184:187], v[200:203], v[126:129]
	v_mfma_f32_16x16x32_bf16 v[114:117], v[192:195], v[200:203], v[114:117]
	v_mfma_f32_16x16x32_bf16 v[106:109], v[184:187], v[208:211], v[106:109]
	v_mfma_f32_16x16x32_bf16 v[98:101], v[192:195], v[208:211], v[98:101]
	v_mfma_f32_16x16x32_bf16 v[90:93], v[184:187], v[216:219], v[90:93]
	v_mfma_f32_16x16x32_bf16 v[82:85], v[192:195], v[216:219], v[82:85]
	v_mfma_f32_16x16x32_bf16 v[74:77], v[184:187], v[224:227], v[74:77]
	v_mfma_f32_16x16x32_bf16 v[66:69], v[192:195], v[224:227], v[66:69]
	s_barrier
	s_setprio 0
	s_add_u32 s98, s96, 0x40000
	s_addc_u32 s99, s97, 0
	s_mov_b32 m0, s76
	ds_read_b128 v[196:199], v160 offset:16384
	global_load_lds_dwordx4 v132, s[96:97]
	s_mov_b32 m0, s77
	s_add_i32 s5, s73, s25
	global_load_lds_dwordx4 v136, s[96:97]
	s_mov_b32 m0, s5
	ds_read_b128 v[200:203], v238 offset:16384
	global_load_lds_dwordx4 v132, s[98:99]
	s_add_i32 m0, s5, 0x2000
	ds_read_b128 v[204:207], v160 offset:18432
	global_load_lds_dwordx4 v136, s[98:99]
	s_mov_b32 m0, s49
	ds_read_b128 v[208:211], v238 offset:18432
	global_load_lds_dwordx4 v130, s[94:95]
	s_mov_b32 m0, s58
	ds_read_b128 v[212:215], v160 offset:20480
	global_load_lds_dwordx4 v134, s[94:95]
	ds_read_b128 v[216:219], v238 offset:20480
	ds_read_b128 v[220:223], v160 offset:22528
	ds_read_b128 v[224:227], v238 offset:22528
	s_waitcnt vmcnt(8)
	s_waitcnt lgkmcnt(0)
	s_setprio 1
	s_barrier
	v_mfma_f32_16x16x32_bf16 v[62:65], v[164:167], v[196:199], v[62:65]
	v_mfma_f32_16x16x32_bf16 v[54:57], v[172:175], v[196:199], v[54:57]
	v_mfma_f32_16x16x32_bf16 v[46:49], v[164:167], v[204:207], v[46:49]
	v_mfma_f32_16x16x32_bf16 v[38:41], v[172:175], v[204:207], v[38:41]
	v_mfma_f32_16x16x32_bf16 v[30:33], v[164:167], v[212:215], v[30:33]
	v_mfma_f32_16x16x32_bf16 v[22:25], v[172:175], v[212:215], v[22:25]
	v_mfma_f32_16x16x32_bf16 v[14:17], v[164:167], v[220:223], v[14:17]
	v_mfma_f32_16x16x32_bf16 v[6:9], v[172:175], v[220:223], v[6:9]
	v_mfma_f32_16x16x32_bf16 v[62:65], v[168:171], v[200:203], v[62:65]
	v_mfma_f32_16x16x32_bf16 v[54:57], v[176:179], v[200:203], v[54:57]
	v_mfma_f32_16x16x32_bf16 v[46:49], v[168:171], v[208:211], v[46:49]
	v_mfma_f32_16x16x32_bf16 v[38:41], v[176:179], v[208:211], v[38:41]
	v_mfma_f32_16x16x32_bf16 v[30:33], v[168:171], v[216:219], v[30:33]
	v_mfma_f32_16x16x32_bf16 v[22:25], v[176:179], v[216:219], v[22:25]
	v_mfma_f32_16x16x32_bf16 v[14:17], v[168:171], v[224:227], v[14:17]
	v_mfma_f32_16x16x32_bf16 v[6:9], v[176:179], v[224:227], v[6:9]
	v_mfma_f32_16x16x32_bf16 v[58:61], v[180:183], v[196:199], v[58:61]
	v_mfma_f32_16x16x32_bf16 v[50:53], v[188:191], v[196:199], v[50:53]
	v_mfma_f32_16x16x32_bf16 v[42:45], v[180:183], v[204:207], v[42:45]
	v_mfma_f32_16x16x32_bf16 v[34:37], v[188:191], v[204:207], v[34:37]
	v_mfma_f32_16x16x32_bf16 v[26:29], v[180:183], v[212:215], v[26:29]
	v_mfma_f32_16x16x32_bf16 v[18:21], v[188:191], v[212:215], v[18:21]
	v_mfma_f32_16x16x32_bf16 v[10:13], v[180:183], v[220:223], v[10:13]
	v_mfma_f32_16x16x32_bf16 v[2:5], v[188:191], v[220:223], v[2:5]
	v_mfma_f32_16x16x32_bf16 v[58:61], v[184:187], v[200:203], v[58:61]
	v_mfma_f32_16x16x32_bf16 v[50:53], v[192:195], v[200:203], v[50:53]
	v_mfma_f32_16x16x32_bf16 v[42:45], v[184:187], v[208:211], v[42:45]
	v_mfma_f32_16x16x32_bf16 v[34:37], v[192:195], v[208:211], v[34:37]
	v_mfma_f32_16x16x32_bf16 v[26:29], v[184:187], v[216:219], v[26:29]
	v_mfma_f32_16x16x32_bf16 v[18:21], v[192:195], v[216:219], v[18:21]
	v_mfma_f32_16x16x32_bf16 v[10:13], v[184:187], v[224:227], v[10:13]
	v_mfma_f32_16x16x32_bf16 v[2:5], v[192:195], v[224:227], v[2:5]
	s_barrier
	s_setprio 0
	s_add_u32 s98, s94, 0x40000
	s_addc_u32 s99, s95, 0
	s_add_i32 s5, 0, 0x18000
	s_add_i32 s47, 0, 0x1c000
	s_mov_b32 m0, s59
	ds_read_b128 v[164:167], v232
	global_load_lds_dwordx4 v130, s[98:99]
	s_mov_b32 m0, s60
	ds_read_b128 v[168:171], v236
	global_load_lds_dwordx4 v134, s[98:99]
	ds_read_b128 v[172:175], v232 offset:2048
	ds_read_b128 v[176:179], v236 offset:2048
	ds_read_b128 v[180:183], v233
	ds_read_b128 v[184:187], v237
	ds_read_b128 v[188:191], v233 offset:2048
	ds_read_b128 v[192:195], v237 offset:2048
	ds_read_b128 v[196:199], v160 offset:32768
	ds_read_b128 v[200:203], v238 offset:32768
	ds_read_b128 v[204:207], v160 offset:34816
	ds_read_b128 v[208:211], v238 offset:34816
	ds_read_b128 v[212:215], v160 offset:36864
	ds_read_b128 v[216:219], v238 offset:36864
	ds_read_b128 v[220:223], v160 offset:38912
	ds_read_b128 v[224:227], v238 offset:38912
	s_waitcnt vmcnt(8)
	s_waitcnt lgkmcnt(0)
	s_setprio 1
	s_barrier
	v_mfma_f32_16x16x32_bf16 v[122:125], v[164:167], v[196:199], v[122:125]
	v_mfma_f32_16x16x32_bf16 v[118:121], v[172:175], v[196:199], v[118:121]
	v_mfma_f32_16x16x32_bf16 v[110:113], v[164:167], v[204:207], v[110:113]
	v_mfma_f32_16x16x32_bf16 v[102:105], v[172:175], v[204:207], v[102:105]
	v_mfma_f32_16x16x32_bf16 v[94:97], v[164:167], v[212:215], v[94:97]
	v_mfma_f32_16x16x32_bf16 v[86:89], v[172:175], v[212:215], v[86:89]
	v_mfma_f32_16x16x32_bf16 v[78:81], v[164:167], v[220:223], v[78:81]
	v_mfma_f32_16x16x32_bf16 v[70:73], v[172:175], v[220:223], v[70:73]
	v_mfma_f32_16x16x32_bf16 v[122:125], v[168:171], v[200:203], v[122:125]
	v_mfma_f32_16x16x32_bf16 v[118:121], v[176:179], v[200:203], v[118:121]
	v_mfma_f32_16x16x32_bf16 v[110:113], v[168:171], v[208:211], v[110:113]
	v_mfma_f32_16x16x32_bf16 v[102:105], v[176:179], v[208:211], v[102:105]
	v_mfma_f32_16x16x32_bf16 v[94:97], v[168:171], v[216:219], v[94:97]
	v_mfma_f32_16x16x32_bf16 v[86:89], v[176:179], v[216:219], v[86:89]
	v_mfma_f32_16x16x32_bf16 v[78:81], v[168:171], v[224:227], v[78:81]
	v_mfma_f32_16x16x32_bf16 v[70:73], v[176:179], v[224:227], v[70:73]
	v_mfma_f32_16x16x32_bf16 v[126:129], v[180:183], v[196:199], v[126:129]
	v_mfma_f32_16x16x32_bf16 v[114:117], v[188:191], v[196:199], v[114:117]
	v_mfma_f32_16x16x32_bf16 v[106:109], v[180:183], v[204:207], v[106:109]
	v_mfma_f32_16x16x32_bf16 v[98:101], v[188:191], v[204:207], v[98:101]
	v_mfma_f32_16x16x32_bf16 v[90:93], v[180:183], v[212:215], v[90:93]
	v_mfma_f32_16x16x32_bf16 v[82:85], v[188:191], v[212:215], v[82:85]
	v_mfma_f32_16x16x32_bf16 v[74:77], v[180:183], v[220:223], v[74:77]
	v_mfma_f32_16x16x32_bf16 v[66:69], v[188:191], v[220:223], v[66:69]
	v_mfma_f32_16x16x32_bf16 v[126:129], v[184:187], v[200:203], v[126:129]
	v_mfma_f32_16x16x32_bf16 v[114:117], v[192:195], v[200:203], v[114:117]
	v_mfma_f32_16x16x32_bf16 v[106:109], v[184:187], v[208:211], v[106:109]
	v_mfma_f32_16x16x32_bf16 v[98:101], v[192:195], v[208:211], v[98:101]
	v_mfma_f32_16x16x32_bf16 v[90:93], v[184:187], v[216:219], v[90:93]
	v_mfma_f32_16x16x32_bf16 v[82:85], v[192:195], v[216:219], v[82:85]
	v_mfma_f32_16x16x32_bf16 v[74:77], v[184:187], v[224:227], v[74:77]
	v_mfma_f32_16x16x32_bf16 v[66:69], v[192:195], v[224:227], v[66:69]
	s_barrier
	s_setprio 0
	s_add_u32 s96, s96, 0x80
	s_addc_u32 s97, s97, 0
	s_add_u32 s98, s96, 0x40000
	s_addc_u32 s99, s97, 0
	s_add_u32 s94, s94, 0x80
	s_addc_u32 s95, s95, 0
	s_add_i32 s5, s5, s25
	s_mov_b32 m0, s5
	ds_read_b128 v[196:199], v160 offset:49152
	global_load_lds_dwordx4 v132, s[96:97]
	s_add_i32 m0, s5, 0x2000
	s_add_i32 s5, s47, s25
	global_load_lds_dwordx4 v136, s[96:97]
	s_mov_b32 m0, s5
	ds_read_b128 v[200:203], v238 offset:49152
	global_load_lds_dwordx4 v132, s[98:99]
	s_add_i32 m0, s5, 0x2000
	ds_read_b128 v[204:207], v160 offset:51200
	global_load_lds_dwordx4 v136, s[98:99]
	s_mov_b32 m0, s61
	ds_read_b128 v[208:211], v238 offset:51200
	global_load_lds_dwordx4 v130, s[94:95]
	s_mov_b32 m0, s62
	ds_read_b128 v[212:215], v160 offset:53248
	global_load_lds_dwordx4 v134, s[94:95]
	ds_read_b128 v[216:219], v238 offset:53248
	ds_read_b128 v[220:223], v160 offset:55296
	ds_read_b128 v[224:227], v238 offset:55296
	s_waitcnt vmcnt(8)
	s_waitcnt lgkmcnt(0)
	s_setprio 1
	s_barrier
	v_mfma_f32_16x16x32_bf16 v[62:65], v[164:167], v[196:199], v[62:65]
	v_mfma_f32_16x16x32_bf16 v[54:57], v[172:175], v[196:199], v[54:57]
	v_mfma_f32_16x16x32_bf16 v[46:49], v[164:167], v[204:207], v[46:49]
	v_mfma_f32_16x16x32_bf16 v[38:41], v[172:175], v[204:207], v[38:41]
	v_mfma_f32_16x16x32_bf16 v[30:33], v[164:167], v[212:215], v[30:33]
	v_mfma_f32_16x16x32_bf16 v[22:25], v[172:175], v[212:215], v[22:25]
	v_mfma_f32_16x16x32_bf16 v[14:17], v[164:167], v[220:223], v[14:17]
	v_mfma_f32_16x16x32_bf16 v[6:9], v[172:175], v[220:223], v[6:9]
	v_mfma_f32_16x16x32_bf16 v[62:65], v[168:171], v[200:203], v[62:65]
	v_mfma_f32_16x16x32_bf16 v[54:57], v[176:179], v[200:203], v[54:57]
	v_mfma_f32_16x16x32_bf16 v[46:49], v[168:171], v[208:211], v[46:49]
	v_mfma_f32_16x16x32_bf16 v[38:41], v[176:179], v[208:211], v[38:41]
	v_mfma_f32_16x16x32_bf16 v[30:33], v[168:171], v[216:219], v[30:33]
	v_mfma_f32_16x16x32_bf16 v[22:25], v[176:179], v[216:219], v[22:25]
	v_mfma_f32_16x16x32_bf16 v[14:17], v[168:171], v[224:227], v[14:17]
	v_mfma_f32_16x16x32_bf16 v[6:9], v[176:179], v[224:227], v[6:9]
	v_mfma_f32_16x16x32_bf16 v[58:61], v[180:183], v[196:199], v[58:61]
	v_mfma_f32_16x16x32_bf16 v[50:53], v[188:191], v[196:199], v[50:53]
	v_mfma_f32_16x16x32_bf16 v[42:45], v[180:183], v[204:207], v[42:45]
	v_mfma_f32_16x16x32_bf16 v[34:37], v[188:191], v[204:207], v[34:37]
	v_mfma_f32_16x16x32_bf16 v[26:29], v[180:183], v[212:215], v[26:29]
	v_mfma_f32_16x16x32_bf16 v[18:21], v[188:191], v[212:215], v[18:21]
	v_mfma_f32_16x16x32_bf16 v[10:13], v[180:183], v[220:223], v[10:13]
	v_mfma_f32_16x16x32_bf16 v[2:5], v[188:191], v[220:223], v[2:5]
	v_mfma_f32_16x16x32_bf16 v[58:61], v[184:187], v[200:203], v[58:61]
	v_mfma_f32_16x16x32_bf16 v[50:53], v[192:195], v[200:203], v[50:53]
	v_mfma_f32_16x16x32_bf16 v[42:45], v[184:187], v[208:211], v[42:45]
	v_mfma_f32_16x16x32_bf16 v[34:37], v[192:195], v[208:211], v[34:37]
	v_mfma_f32_16x16x32_bf16 v[26:29], v[184:187], v[216:219], v[26:29]
	v_mfma_f32_16x16x32_bf16 v[18:21], v[192:195], v[216:219], v[18:21]
	v_mfma_f32_16x16x32_bf16 v[10:13], v[184:187], v[224:227], v[10:13]
	v_mfma_f32_16x16x32_bf16 v[2:5], v[192:195], v[224:227], v[2:5]
	s_barrier
	s_setprio 0
	s_mov_b32 s5, s45
	s_add_u32 s88, s88, 0x100
	s_addc_u32 s89, s89, 0
	s_add_u32 s86, s86, 0x100
	s_addc_u32 s87, s87, 0
	s_cmp_ge_i32 s45, s101
	s_cbranch_scc0 .LBB0_1944

.LBB0_2062:
	v_ashrrev_i32_e32 v5, 31, v12
	v_lshrrev_b32_e32 v5, 26, v5
	v_add_u32_e32 v5, v12, v5
	v_ashrrev_i32_e32 v13, 6, v5
	v_bfe_i32 v5, v12, 27, 1
	v_lshlrev_b32_e32 v4, 4, v12
	v_lshrrev_b32_e32 v5, 22, v5
	v_add_u32_e32 v5, v4, v5
	v_and_b32_e32 v5, 0xfffffc00, v5
	v_sub_u32_e32 v5, v4, v5
	v_lshrrev_b32_e32 v6, 4, v5
	v_bitop3_b32 v6, v6, v5, 32 bitop3:0x6c
	v_ashrrev_i32_e32 v5, 31, v5
	v_lshrrev_b32_e32 v5, 26, v5
	v_lshlrev_b32_e32 v7, 3, v13
	v_add_u32_e32 v5, v6, v5
	v_and_b32_e32 v7, -16, v7
	v_ashrrev_i32_e32 v14, 6, v5
	v_add_u32_e32 v5, v14, v7
	v_lshlrev_b32_e32 v7, 5, v13
	v_and_b32_e32 v15, 32, v7
	v_mul_i32_i24_e32 v7, 64, v14
	v_sub_u32_e32 v6, v6, v7
	v_mov_b32_e32 v7, 1
	v_ashrrev_i16_sdwa v6, v7, sext(v6) dst_sel:DWORD dst_unused:UNUSED_PAD src0_sel:DWORD src1_sel:BYTE_0
	v_lshlrev_b32_e32 v8, 1, v5
	v_lshrrev_b32_e32 v9, 2, v5
	v_and_b32_e32 v10, 3, v14
	s_mov_b32 s1, 0xffffe0
	v_bfe_i32 v16, v6, 0, 16
	v_and_b32_e32 v8, 24, v8
	v_and_b32_e32 v9, 4, v9
	v_and_or_b32 v10, v5, s1, v10
	s_movk_i32 s5, 0xb00
	v_add_u32_e32 v6, v15, v16
	v_or3_b32 v8, v10, v9, v8
	v_mul_lo_u32 v5, v5, s5
	v_add_lshl_u32 v130, v6, v5, 1
	v_mul_u32_u24_e32 v5, 0xb00, v8
	v_add_u32_e32 v4, 0x2000, v4
	v_add_lshl_u32 v132, v5, v6, 1
	v_ashrrev_i32_e32 v5, 31, v4
	v_lshrrev_b32_e32 v5, 22, v5
	v_add_u32_e32 v5, v4, v5
	v_ashrrev_i32_e32 v17, 10, v5
	v_mul_i32_i24_e32 v5, 0x400, v17
	v_sub_u32_e32 v4, v4, v5
	v_lshrrev_b32_e32 v5, 4, v4
	v_bitop3_b32 v4, v5, v4, 32 bitop3:0x6c
	v_ashrrev_i32_e32 v6, 31, v4
	v_lshrrev_b32_e32 v6, 26, v6
	v_lshlrev_b32_e32 v5, 3, v17
	v_add_u32_e32 v6, v4, v6
	v_and_b32_e32 v5, -16, v5
	v_ashrrev_i32_e32 v19, 6, v6
	v_and_b32_e32 v6, 0xc0, v6
	v_add_u32_e32 v5, v19, v5
	v_lshlrev_b32_e32 v8, 5, v17
	v_sub_u32_e32 v4, v4, v6
	s_ashr_i32 s0, s4, 6
	v_and_b32_e32 v18, 32, v8
	v_ashrrev_i16_sdwa v4, v7, sext(v4) dst_sel:DWORD dst_unused:UNUSED_PAD src0_sel:DWORD src1_sel:BYTE_0
	v_lshlrev_b32_e32 v6, 1, v5
	v_lshrrev_b32_e32 v7, 2, v5
	v_and_b32_e32 v8, 3, v19
	v_bfe_i32 v20, v4, 0, 16
	v_and_b32_e32 v6, 24, v6
	v_and_b32_e32 v7, 4, v7
	v_and_or_b32 v8, v5, s1, v8
	s_lshl_b32 s21, s0, 10
	v_add_u32_e32 v4, v18, v20
	v_or3_b32 v6, v8, v7, v6
	v_mul_lo_u32 v5, v5, s5
	s_add_i32 s44, s21, 0
	v_add_lshl_u32 v134, v4, v5, 1
	v_mul_u32_u24_e32 v5, 0xb00, v6
	s_add_i32 m0, s44, 0x10000
	v_readfirstlane_b32 s8, v2
	v_readfirstlane_b32 s9, v3
	v_add_lshl_u32 v136, v5, v4, 1
	s_add_i32 s45, s44, 0x2000
	s_add_i32 s46, s44, 0x4000
	s_add_i32 s47, s44, 0x6000
	s_ashr_i32 s1, s4, 8
	v_lshrrev_b32_e32 v242, 6, v1
	v_and_b32_e32 v243, 63, v1
	v_lshlrev_b32_e32 v245, 4, v243
	v_lshrrev_b32_e32 v244, 5, v243
	v_lshlrev_b32_e32 v244, 5, v244
	v_xor_b32_e32 v245, v245, v244
	v_lshrrev_b32_e32 v244, 1, v242
	v_lshlrev_b32_e32 v244, 4, v244
	v_lshrrev_b32_e32 v243, 6, v245
	v_add_u32_e32 v244, v244, v243
	v_and_b32_e32 v245, 63, v245
	v_and_b32_e32 v242, 1, v242
	v_lshl_add_u32 v245, v242, 6, v245
	v_mul_u32_u24_e32 v244, 0x1600, v244
	v_add_u32_e32 v240, v244, v245
	v_lshrrev_b32_e32 v242, 6, v1
	v_and_b32_e32 v243, 63, v1
	v_lshrrev_b32_e32 v244, 3, v243
	v_lshl_add_u32 v244, v242, 3, v244
	v_lshrrev_b32_e32 v245, 4, v243
	v_and_b32_e32 v245, 3, v245
	v_lshlrev_b32_e32 v245, 1, v245
	v_and_b32_e32 v243, 7, v243
	v_xor_b32_e32 v245, v243, v245
	v_lshlrev_b32_e32 v245, 4, v245
	v_mul_u32_u24_e32 v244, 0x1600, v244
	v_add_u32_e32 v241, v244, v245
	v_sub_u32_e32 v130, v130, v240
	v_add_u32_e32 v130, v130, v241
	v_lshrrev_b32_e32 v242, 6, v1
	v_and_b32_e32 v243, 63, v1
	v_lshlrev_b32_e32 v245, 4, v243
	v_lshrrev_b32_e32 v244, 5, v243
	v_lshlrev_b32_e32 v244, 5, v244
	v_xor_b32_e32 v245, v245, v244
	v_add_u32_e32 v242, 8, v242
	v_lshrrev_b32_e32 v244, 1, v242
	v_lshlrev_b32_e32 v244, 4, v244
	v_lshrrev_b32_e32 v243, 6, v245
	v_add_u32_e32 v244, v244, v243
	v_and_b32_e32 v245, 63, v245
	v_and_b32_e32 v242, 1, v242
	v_lshl_add_u32 v245, v242, 6, v245
	v_mul_u32_u24_e32 v244, 0x1600, v244
	v_add_u32_e32 v240, v244, v245
	v_lshrrev_b32_e32 v242, 6, v1
	v_and_b32_e32 v243, 63, v1
	v_lshrrev_b32_e32 v244, 3, v243
	v_lshl_add_u32 v244, v242, 3, v244
	v_add_u32_e32 v244, 64, v244
	v_lshrrev_b32_e32 v245, 4, v243
	v_and_b32_e32 v245, 3, v245
	v_lshlrev_b32_e32 v245, 1, v245
	v_and_b32_e32 v243, 7, v243
	v_xor_b32_e32 v245, v243, v245
	v_lshlrev_b32_e32 v245, 4, v245
	v_mul_u32_u24_e32 v244, 0x1600, v244
	v_add_u32_e32 v241, v244, v245
	v_sub_u32_e32 v134, v134, v240
	v_add_u32_e32 v134, v134, v241
	v_lshrrev_b32_e32 v242, 6, v1
	v_and_b32_e32 v243, 63, v1
	v_lshlrev_b32_e32 v245, 4, v243
	v_lshrrev_b32_e32 v244, 5, v243
	v_lshlrev_b32_e32 v244, 5, v244
	v_xor_b32_e32 v245, v245, v244
	v_lshrrev_b32_e32 v244, 1, v242
	v_lshlrev_b32_e32 v244, 4, v244
	v_lshrrev_b32_e32 v243, 6, v245
	v_add_u32_e32 v244, v244, v243
	v_and_b32_e32 v245, 63, v245
	v_and_b32_e32 v242, 1, v242
	v_lshl_add_u32 v245, v242, 6, v245
	v_and_b32_e32 v242, 31, v244
	v_sub_u32_e32 v244, v244, v242
	v_and_b32_e32 v243, 3, v242
	v_add_u32_e32 v244, v244, v243
	v_lshrrev_b32_e32 v243, 4, v242
	v_lshl_add_u32 v244, v243, 2, v244
	v_and_b32_e32 v243, 15, v242
	v_lshrrev_b32_e32 v243, 2, v243
	v_lshl_add_u32 v244, v243, 3, v244
	v_mul_u32_u24_e32 v244, 0x1600, v244
	v_add_u32_e32 v240, v244, v245
	v_lshrrev_b32_e32 v242, 6, v1
	v_and_b32_e32 v243, 63, v1
	v_lshrrev_b32_e32 v244, 3, v243
	v_lshl_add_u32 v244, v242, 3, v244
	v_lshrrev_b32_e32 v245, 4, v243
	v_and_b32_e32 v245, 3, v245
	v_lshlrev_b32_e32 v245, 1, v245
	v_and_b32_e32 v243, 7, v243
	v_xor_b32_e32 v245, v243, v245
	v_lshlrev_b32_e32 v245, 4, v245
	v_and_b32_e32 v242, 31, v244
	v_sub_u32_e32 v244, v244, v242
	v_and_b32_e32 v243, 3, v242
	v_add_u32_e32 v244, v244, v243
	v_lshrrev_b32_e32 v243, 4, v242
	v_lshl_add_u32 v244, v243, 2, v244
	v_and_b32_e32 v243, 15, v242
	v_lshrrev_b32_e32 v243, 2, v243
	v_lshl_add_u32 v244, v243, 3, v244
	v_mul_u32_u24_e32 v244, 0x1600, v244
	v_add_u32_e32 v241, v244, v245
	v_sub_u32_e32 v132, v132, v240
	v_add_u32_e32 v132, v132, v241
	v_lshrrev_b32_e32 v242, 6, v1
	v_and_b32_e32 v243, 63, v1
	v_lshlrev_b32_e32 v245, 4, v243
	v_lshrrev_b32_e32 v244, 5, v243
	v_lshlrev_b32_e32 v244, 5, v244
	v_xor_b32_e32 v245, v245, v244
	v_add_u32_e32 v242, 8, v242
	v_lshrrev_b32_e32 v244, 1, v242
	v_lshlrev_b32_e32 v244, 4, v244
	v_lshrrev_b32_e32 v243, 6, v245
	v_add_u32_e32 v244, v244, v243
	v_and_b32_e32 v245, 63, v245
	v_and_b32_e32 v242, 1, v242
	v_lshl_add_u32 v245, v242, 6, v245
	v_and_b32_e32 v242, 31, v244
	v_sub_u32_e32 v244, v244, v242
	v_and_b32_e32 v243, 3, v242
	v_add_u32_e32 v244, v244, v243
	v_lshrrev_b32_e32 v243, 4, v242
	v_lshl_add_u32 v244, v243, 2, v244
	v_and_b32_e32 v243, 15, v242
	v_lshrrev_b32_e32 v243, 2, v243
	v_lshl_add_u32 v244, v243, 3, v244
	v_mul_u32_u24_e32 v244, 0x1600, v244
	v_add_u32_e32 v240, v244, v245
	v_lshrrev_b32_e32 v242, 6, v1
	v_and_b32_e32 v243, 63, v1
	v_lshrrev_b32_e32 v244, 3, v243
	v_lshl_add_u32 v244, v242, 3, v244
	v_add_u32_e32 v244, 64, v244
	v_lshrrev_b32_e32 v245, 4, v243
	v_and_b32_e32 v245, 3, v245
	v_lshlrev_b32_e32 v245, 1, v245
	v_and_b32_e32 v243, 7, v243
	v_xor_b32_e32 v245, v243, v245
	v_lshlrev_b32_e32 v245, 4, v245
	v_and_b32_e32 v242, 31, v244
	v_sub_u32_e32 v244, v244, v242
	v_and_b32_e32 v243, 3, v242
	v_add_u32_e32 v244, v244, v243
	v_lshrrev_b32_e32 v243, 4, v242
	v_lshl_add_u32 v244, v243, 2, v244
	v_and_b32_e32 v243, 15, v242
	v_lshrrev_b32_e32 v243, 2, v243
	v_lshl_add_u32 v244, v243, 3, v244
	v_mul_u32_u24_e32 v244, 0x1600, v244
	v_add_u32_e32 v241, v244, v245
	v_sub_u32_e32 v136, v136, v240
	v_add_u32_e32 v136, v136, v241
	global_load_lds_dwordx4 v132, s[8:9]
	s_add_i32 m0, s44, 0x12000
	v_mov_b32_e32 v139, 0
	global_load_lds_dwordx4 v136, s[8:9]
	s_mov_b64 s[8:9], 0xb0000
	v_lshl_add_u64 v[4:5], v[2:3], 0, s[8:9]
	s_add_i32 m0, s44, 0x14000
	v_readfirstlane_b32 s10, v4
	v_readfirstlane_b32 s11, v5
	v_lshl_add_u64 v[4:5], v[150:151], 0, s[8:9]
	v_mov_b32_e32 v133, v139
	v_mov_b32_e32 v137, v139
	v_mov_b32_e32 v131, v139
	v_mov_b32_e32 v135, v139
	global_load_lds_dwordx4 v132, s[10:11]
	s_add_i32 m0, s44, 0x16000
	s_cmp_eq_u32 s1, 1
	global_load_lds_dwordx4 v136, s[10:11]
	v_readfirstlane_b32 s10, v150
	v_readfirstlane_b32 s11, v151
	s_mov_b32 m0, s44
	s_mov_b32 s48, 0
	v_lshl_add_u64 v[10:11], v[2:3], 0, v[132:133]
	v_lshl_add_u64 v[8:9], v[2:3], 0, v[136:137]
	v_lshl_add_u64 v[6:7], v[150:151], 0, v[134:135]
	global_load_lds_dwordx4 v130, s[10:11]
	s_mov_b32 m0, s45
	s_nop 0
	global_load_lds_dwordx4 v134, s[10:11]
	v_readfirstlane_b32 s10, v4
	v_readfirstlane_b32 s11, v5
	s_mov_b32 m0, s46
	v_lshl_add_u64 v[4:5], v[150:151], 0, v[130:131]
	s_nop 2
	global_load_lds_dwordx4 v130, s[10:11]
	s_mov_b32 m0, s47
	s_nop 0
	global_load_lds_dwordx4 v134, s[10:11]
	s_cselect_b64 s[10:11], -1, 0
	s_cmp_lg_u32 s1, 1
	s_cbranch_scc1 .LBB0_2064
	s_barrier
.LBB0_2064:
	s_and_b32 s18, s0, 3
	s_lshl_b32 s49, s1, 6
	s_lshl_b32 s1, s1, 13
	s_lshl_b32 s50, s18, 5
	s_lshl_b32 s16, s18, 12
	s_add_u32 s51, s38, 0x51a2000
	s_mov_b64 s[12:13], 0x80
	s_addc_u32 s56, s39, 0
	s_add_i32 m0, s44, 0x18000
	v_lshl_add_u64 v[10:11], v[10:11], 0, s[12:13]
	s_waitcnt vmcnt(2)
	s_barrier
	global_load_lds_dwordx4 v[10:11], off
	v_lshl_add_u64 v[8:9], v[8:9], 0, s[12:13]
	s_add_i32 m0, s44, 0x1a000
	s_add_i32 s57, s44, 0x8000
	global_load_lds_dwordx4 v[8:9], off
	v_lshl_add_u64 v[4:5], v[4:5], 0, s[12:13]
	s_mov_b32 m0, s57
	s_add_i32 s58, s44, 0xa000
	global_load_lds_dwordx4 v[4:5], off
	v_lshl_add_u64 v[4:5], v[6:7], 0, s[12:13]
	s_mov_b32 m0, s58
	s_mov_b64 s[14:15], 0xb0080
	global_load_lds_dwordx4 v[4:5], off
	v_lshl_add_u64 v[4:5], v[2:3], 0, s[14:15]
	s_add_i32 m0, s44, 0x1c000
	v_lshl_add_u64 v[6:7], v[4:5], 0, v[132:133]
	global_load_lds_dwordx4 v[6:7], off
	v_lshl_add_u64 v[4:5], v[4:5], 0, v[136:137]
	s_add_i32 m0, s44, 0x1e000
	v_and_b32_e32 v140, 15, v12
	global_load_lds_dwordx4 v[4:5], off
	v_bfe_u32 v4, v12, 4, 2
	v_lshlrev_b32_e32 v5, 4, v4
	v_lshlrev_b32_e32 v7, 2, v12
	v_lshl_or_b32 v6, v140, 6, v5
	v_and_b32_e32 v7, 32, v7
	s_cmpk_lt_u32 s4, 0x100
	v_bitop3_b32 v141, v6, s16, v7 bitop3:0xde
	s_cselect_b64 s[16:17], -1, 0
	s_lshl_b32 s0, s0, 6
	s_lshl_b32 s4, s18, 2
	v_bitop3_b32 v8, v6, s1, v7 bitop3:0xde
	v_and_or_b32 v158, s0, 64, v5
	v_cmp_eq_u32_e64 s[0:1], 0, v4
	s_add_u32 s59, s51, s4
	v_lshl_or_b32 v159, v4, 3, s50
	v_lshrrev_b32_e32 v5, 1, v17
	v_mul_lo_u32 v4, v19, s5
	s_mov_b32 s4, 0xb000
	v_mad_u64_u32 v[4:5], s[18:19], v5, s4, v[4:5]
	v_or_b32_e32 v4, v4, v18
	v_add_lshl_u32 v138, v4, v20, 1
	v_lshrrev_b32_e32 v5, 1, v13
	v_mul_lo_u32 v4, v14, s5
	v_mad_u64_u32 v[4:5], s[4:5], v5, s4, v[4:5]
	s_waitcnt vmcnt(6)
	v_or_b32_e32 v4, v4, v15
	v_lshl_add_u64 v[142:143], v[138:139], 0, s[14:15]
	v_add_lshl_u32 v138, v4, v16, 1
	v_mbcnt_lo_u32_b32 v4, -1, 0
	s_addc_u32 s60, s56, 0
	v_lshl_add_u64 v[144:145], v[138:139], 0, s[14:15]
	s_add_i32 s61, 0, 0x20020
	s_add_i32 s62, 0, 0x20018
	s_add_i32 s63, 0, 0x2002c
	s_add_i32 s64, 0, 0x20000
	s_mov_b64 s[18:19], 0x100
	s_add_i32 s65, 0, 0x10000
	s_add_i32 s66, 0, 0x14000
	v_add_u32_e32 v160, 0, v8
	s_add_i32 s67, 0, 0x20010
	s_add_i32 s70, 0, 0x20024
	s_movk_i32 s71, 0x7fff
	s_mov_b32 s20, 0xbfb8aa3b
	v_mbcnt_hi_u32_b32 v161, -1, v4
	v_mov_b64_e32 v[146:147], v[150:151]
	v_mov_b64_e32 v[148:149], v[2:3]
	s_barrier
	v_lshrrev_b32_e32 v242, 6, v1
	v_and_b32_e32 v243, 63, v1
	v_lshlrev_b32_e32 v245, 4, v243
	v_lshrrev_b32_e32 v244, 5, v243
	v_lshlrev_b32_e32 v244, 5, v244
	v_xor_b32_e32 v245, v245, v244
	v_lshrrev_b32_e32 v244, 1, v242
	v_lshlrev_b32_e32 v244, 4, v244
	v_lshrrev_b32_e32 v243, 6, v245
	v_add_u32_e32 v244, v244, v243
	v_and_b32_e32 v245, 63, v245
	v_and_b32_e32 v242, 1, v242
	v_lshl_add_u32 v245, v242, 6, v245
	v_mul_u32_u24_e32 v244, 0x1600, v244
	v_add_u32_e32 v240, v244, v245
	v_lshrrev_b32_e32 v242, 6, v1
	v_and_b32_e32 v243, 63, v1
	v_lshrrev_b32_e32 v244, 3, v243
	v_lshl_add_u32 v244, v242, 3, v244
	v_lshrrev_b32_e32 v245, 4, v243
	v_and_b32_e32 v245, 3, v245
	v_lshlrev_b32_e32 v245, 1, v245
	v_and_b32_e32 v243, 7, v243
	v_xor_b32_e32 v245, v243, v245
	v_lshlrev_b32_e32 v245, 4, v245
	v_mul_u32_u24_e32 v244, 0x1600, v244
	v_add_u32_e32 v241, v244, v245
	v_sub_u32_e32 v144, v144, v240
	v_add_u32_e32 v144, v144, v241
	v_lshrrev_b32_e32 v242, 6, v1
	v_and_b32_e32 v243, 63, v1
	v_lshlrev_b32_e32 v245, 4, v243
	v_lshrrev_b32_e32 v244, 5, v243
	v_lshlrev_b32_e32 v244, 5, v244
	v_xor_b32_e32 v245, v245, v244
	v_add_u32_e32 v242, 8, v242
	v_lshrrev_b32_e32 v244, 1, v242
	v_lshlrev_b32_e32 v244, 4, v244
	v_lshrrev_b32_e32 v243, 6, v245
	v_add_u32_e32 v244, v244, v243
	v_and_b32_e32 v245, 63, v245
	v_and_b32_e32 v242, 1, v242
	v_lshl_add_u32 v245, v242, 6, v245
	v_mul_u32_u24_e32 v244, 0x1600, v244
	v_add_u32_e32 v240, v244, v245
	v_lshrrev_b32_e32 v242, 6, v1
	v_and_b32_e32 v243, 63, v1
	v_lshrrev_b32_e32 v244, 3, v243
	v_lshl_add_u32 v244, v242, 3, v244
	v_add_u32_e32 v244, 64, v244
	v_lshrrev_b32_e32 v245, 4, v243
	v_and_b32_e32 v245, 3, v245
	v_lshlrev_b32_e32 v245, 1, v245
	v_and_b32_e32 v243, 7, v243
	v_xor_b32_e32 v245, v243, v245
	v_lshlrev_b32_e32 v245, 4, v245
	v_mul_u32_u24_e32 v244, 0x1600, v244
	v_add_u32_e32 v241, v244, v245
	v_sub_u32_e32 v142, v142, v240
	v_add_u32_e32 v142, v142, v241
	v_and_b32_e32 v240, 63, v1
	v_and_b32_e32 v241, 15, v240
	v_lshrrev_b32_e32 v242, 4, v240
	v_lshlrev_b32_e32 v243, 6, v241
	v_lshl_add_u32 v243, v242, 4, v243
	v_lshrrev_b32_e32 v244, 3, v241
	v_lshlrev_b32_e32 v245, 5, v244
	v_xor_b32_e32 v243, v243, v245
	v_sub_u32_e32 v160, v160, v243
	v_lshlrev_b32_e32 v244, 10, v244
	v_and_b32_e32 v245, 7, v241
	v_lshl_add_u32 v244, v245, 7, v244
	v_add_u32_e32 v160, v160, v244
	v_lshrrev_b32_e32 v245, 1, v245
	v_lshlrev_b32_e32 v245, 1, v245
	v_add_u32_e32 v244, 4, v242
	v_xor_b32_e32 v244, v244, v245
	v_lshl_add_u32 v238, v244, 4, v160
	v_xor_b32_e32 v244, v242, v245
	v_lshl_add_u32 v160, v244, 4, v160
	v_and_b32_e32 v240, 63, v1
	v_and_b32_e32 v241, 15, v240
	v_lshrrev_b32_e32 v242, 4, v240
	v_lshlrev_b32_e32 v243, 6, v241
	v_lshl_add_u32 v243, v242, 4, v243
	v_lshrrev_b32_e32 v244, 3, v241
	v_lshlrev_b32_e32 v245, 5, v244
	v_xor_b32_e32 v243, v243, v245
	v_sub_u32_e32 v141, v141, v243
	v_lshlrev_b32_e32 v244, 10, v244
	v_and_b32_e32 v245, 7, v241
	v_lshl_add_u32 v244, v245, 7, v244
	v_add_u32_e32 v141, v141, v244
	v_lshrrev_b32_e32 v245, 1, v245
	v_lshlrev_b32_e32 v245, 1, v245
	v_add_u32_e32 v244, 4, v242
	v_xor_b32_e32 v244, v244, v245
	v_lshl_add_u32 v239, v244, 4, v141
	v_xor_b32_e32 v244, v242, v245
	v_lshl_add_u32 v141, v244, 4, v141
	s_branch .LBB0_2067

.Lmy_nb_11:
	s_nop 0
	v_readfirstlane_b32 s86, v150
	v_readfirstlane_b32 s87, v151
	v_readfirstlane_b32 s88, v152
	v_readfirstlane_b32 s89, v153
	v_readfirstlane_b32 s90, v146
	v_readfirstlane_b32 s91, v147
	v_readfirstlane_b32 s92, v148
	v_readfirstlane_b32 s93, v149
	v_readfirstlane_b32 s100, v138
	v_readfirstlane_b32 s101, v156
	v_add_u32_e32 v230, s65, v141
	v_add_u32_e32 v234, s65, v239
	v_add_u32_e32 v231, s66, v141
	v_add_u32_e32 v235, s66, v239
	v_add_u32_e32 v232, 0x18000, v141
	v_add_u32_e32 v236, 0x18000, v239
	v_add_u32_e32 v233, 0x1c000, v141
	v_add_u32_e32 v237, 0x1c000, v239
	s_add_u32 s98, s86, 0x100
	s_addc_u32 s99, s87, 0
	s_cmp_eq_u32 s4, s100
	s_cselect_b64 s[94:95], s[90:91], s[98:99]
	s_cselect_b64 s[96:97], s[92:93], s[88:89]
	s_add_i32 s5, s4, 2
	s_add_i32 m0, s44, 0xc000
	ds_read_b128 v[164:167], v230
	global_load_lds_dwordx4 v144, s[86:87]
	s_add_i32 m0, s44, 0xe000
	ds_read_b128 v[168:171], v234
	global_load_lds_dwordx4 v142, s[86:87]
	ds_read_b128 v[172:175], v230 offset:2048
	ds_read_b128 v[176:179], v234 offset:2048
	ds_read_b128 v[180:183], v231
	ds_read_b128 v[184:187], v235
	ds_read_b128 v[188:191], v231 offset:2048
	ds_read_b128 v[192:195], v235 offset:2048
	ds_read_b128 v[196:199], v160
	ds_read_b128 v[200:203], v238
	ds_read_b128 v[204:207], v160 offset:2048
	ds_read_b128 v[208:211], v238 offset:2048
	ds_read_b128 v[212:215], v160 offset:4096
	ds_read_b128 v[216:219], v238 offset:4096
	ds_read_b128 v[220:223], v160 offset:6144
	ds_read_b128 v[224:227], v238 offset:6144
	s_waitcnt vmcnt(8)
	s_waitcnt lgkmcnt(0)
	s_setprio 1
	s_barrier
	v_mfma_f32_16x16x32_bf16 v[122:125], v[164:167], v[196:199], 0
	v_mfma_f32_16x16x32_bf16 v[118:121], v[172:175], v[196:199], 0
	v_mfma_f32_16x16x32_bf16 v[110:113], v[164:167], v[204:207], 0
	v_mfma_f32_16x16x32_bf16 v[102:105], v[172:175], v[204:207], 0
	v_mfma_f32_16x16x32_bf16 v[94:97], v[164:167], v[212:215], 0
	v_mfma_f32_16x16x32_bf16 v[86:89], v[172:175], v[212:215], 0
	v_mfma_f32_16x16x32_bf16 v[78:81], v[164:167], v[220:223], 0
	v_mfma_f32_16x16x32_bf16 v[70:73], v[172:175], v[220:223], 0
	v_mfma_f32_16x16x32_bf16 v[122:125], v[168:171], v[200:203], v[122:125]
	v_mfma_f32_16x16x32_bf16 v[118:121], v[176:179], v[200:203], v[118:121]
	v_mfma_f32_16x16x32_bf16 v[110:113], v[168:171], v[208:211], v[110:113]
	v_mfma_f32_16x16x32_bf16 v[102:105], v[176:179], v[208:211], v[102:105]
	v_mfma_f32_16x16x32_bf16 v[94:97], v[168:171], v[216:219], v[94:97]
	v_mfma_f32_16x16x32_bf16 v[86:89], v[176:179], v[216:219], v[86:89]
	v_mfma_f32_16x16x32_bf16 v[78:81], v[168:171], v[224:227], v[78:81]
	v_mfma_f32_16x16x32_bf16 v[70:73], v[176:179], v[224:227], v[70:73]
	v_mfma_f32_16x16x32_bf16 v[126:129], v[180:183], v[196:199], 0
	v_mfma_f32_16x16x32_bf16 v[114:117], v[188:191], v[196:199], 0
	v_mfma_f32_16x16x32_bf16 v[106:109], v[180:183], v[204:207], 0
	v_mfma_f32_16x16x32_bf16 v[98:101], v[188:191], v[204:207], 0
	v_mfma_f32_16x16x32_bf16 v[90:93], v[180:183], v[212:215], 0
	v_mfma_f32_16x16x32_bf16 v[82:85], v[188:191], v[212:215], 0
	v_mfma_f32_16x16x32_bf16 v[74:77], v[180:183], v[220:223], 0
	v_mfma_f32_16x16x32_bf16 v[66:69], v[188:191], v[220:223], 0
	v_mfma_f32_16x16x32_bf16 v[126:129], v[184:187], v[200:203], v[126:129]
	v_mfma_f32_16x16x32_bf16 v[114:117], v[192:195], v[200:203], v[114:117]
	v_mfma_f32_16x16x32_bf16 v[106:109], v[184:187], v[208:211], v[106:109]
	v_mfma_f32_16x16x32_bf16 v[98:101], v[192:195], v[208:211], v[98:101]
	v_mfma_f32_16x16x32_bf16 v[90:93], v[184:187], v[216:219], v[90:93]
	v_mfma_f32_16x16x32_bf16 v[82:85], v[192:195], v[216:219], v[82:85]
	v_mfma_f32_16x16x32_bf16 v[74:77], v[184:187], v[224:227], v[74:77]
	v_mfma_f32_16x16x32_bf16 v[66:69], v[192:195], v[224:227], v[66:69]
	s_barrier
	s_setprio 0
	s_add_u32 s98, s96, 0xb0000
	s_addc_u32 s99, s97, 0
	s_add_i32 s4, s65, s21
	s_mov_b32 m0, s4
	ds_read_b128 v[196:199], v160 offset:16384
	global_load_lds_dwordx4 v132, s[96:97]
	s_add_i32 m0, s4, 0x2000
	s_add_i32 s4, s66, s21
	global_load_lds_dwordx4 v136, s[96:97]
	s_mov_b32 m0, s4
	ds_read_b128 v[200:203], v238 offset:16384
	global_load_lds_dwordx4 v132, s[98:99]
	s_add_i32 m0, s4, 0x2000
	ds_read_b128 v[204:207], v160 offset:18432
	global_load_lds_dwordx4 v136, s[98:99]
	s_mov_b32 m0, s44
	ds_read_b128 v[208:211], v238 offset:18432
	global_load_lds_dwordx4 v130, s[94:95]
	s_mov_b32 m0, s45
	ds_read_b128 v[212:215], v160 offset:20480
	global_load_lds_dwordx4 v134, s[94:95]
	ds_read_b128 v[216:219], v238 offset:20480
	ds_read_b128 v[220:223], v160 offset:22528
	ds_read_b128 v[224:227], v238 offset:22528
	s_waitcnt vmcnt(8)
	s_waitcnt lgkmcnt(0)
	s_setprio 1
	s_barrier
	v_mfma_f32_16x16x32_bf16 v[62:65], v[164:167], v[196:199], 0
	v_mfma_f32_16x16x32_bf16 v[54:57], v[172:175], v[196:199], 0
	v_mfma_f32_16x16x32_bf16 v[46:49], v[164:167], v[204:207], 0
	v_mfma_f32_16x16x32_bf16 v[38:41], v[172:175], v[204:207], 0
	v_mfma_f32_16x16x32_bf16 v[30:33], v[164:167], v[212:215], 0
	v_mfma_f32_16x16x32_bf16 v[22:25], v[172:175], v[212:215], 0
	v_mfma_f32_16x16x32_bf16 v[14:17], v[164:167], v[220:223], 0
	v_mfma_f32_16x16x32_bf16 v[6:9], v[172:175], v[220:223], 0
	v_mfma_f32_16x16x32_bf16 v[62:65], v[168:171], v[200:203], v[62:65]
	v_mfma_f32_16x16x32_bf16 v[54:57], v[176:179], v[200:203], v[54:57]
	v_mfma_f32_16x16x32_bf16 v[46:49], v[168:171], v[208:211], v[46:49]
	v_mfma_f32_16x16x32_bf16 v[38:41], v[176:179], v[208:211], v[38:41]
	v_mfma_f32_16x16x32_bf16 v[30:33], v[168:171], v[216:219], v[30:33]
	v_mfma_f32_16x16x32_bf16 v[22:25], v[176:179], v[216:219], v[22:25]
	v_mfma_f32_16x16x32_bf16 v[14:17], v[168:171], v[224:227], v[14:17]
	v_mfma_f32_16x16x32_bf16 v[6:9], v[176:179], v[224:227], v[6:9]
	v_mfma_f32_16x16x32_bf16 v[58:61], v[180:183], v[196:199], 0
	v_mfma_f32_16x16x32_bf16 v[50:53], v[188:191], v[196:199], 0
	v_mfma_f32_16x16x32_bf16 v[42:45], v[180:183], v[204:207], 0
	v_mfma_f32_16x16x32_bf16 v[34:37], v[188:191], v[204:207], 0
	v_mfma_f32_16x16x32_bf16 v[26:29], v[180:183], v[212:215], 0
	v_mfma_f32_16x16x32_bf16 v[18:21], v[188:191], v[212:215], 0
	v_mfma_f32_16x16x32_bf16 v[10:13], v[180:183], v[220:223], 0
	v_mfma_f32_16x16x32_bf16 v[2:5], v[188:191], v[220:223], 0
	v_mfma_f32_16x16x32_bf16 v[58:61], v[184:187], v[200:203], v[58:61]
	v_mfma_f32_16x16x32_bf16 v[50:53], v[192:195], v[200:203], v[50:53]
	v_mfma_f32_16x16x32_bf16 v[42:45], v[184:187], v[208:211], v[42:45]
	v_mfma_f32_16x16x32_bf16 v[34:37], v[192:195], v[208:211], v[34:37]
	v_mfma_f32_16x16x32_bf16 v[26:29], v[184:187], v[216:219], v[26:29]
	v_mfma_f32_16x16x32_bf16 v[18:21], v[192:195], v[216:219], v[18:21]
	v_mfma_f32_16x16x32_bf16 v[10:13], v[184:187], v[224:227], v[10:13]
	v_mfma_f32_16x16x32_bf16 v[2:5], v[192:195], v[224:227], v[2:5]
	s_barrier
	s_setprio 0
	s_add_u32 s98, s94, 0xb0000
	s_addc_u32 s99, s95, 0
	s_add_i32 s4, 0, 0x18000
	s_add_i32 s25, 0, 0x1c000
	s_mov_b32 m0, s46
	ds_read_b128 v[164:167], v232
	global_load_lds_dwordx4 v130, s[98:99]
	s_mov_b32 m0, s47
	ds_read_b128 v[168:171], v236
	global_load_lds_dwordx4 v134, s[98:99]
	ds_read_b128 v[172:175], v232 offset:2048
	ds_read_b128 v[176:179], v236 offset:2048
	ds_read_b128 v[180:183], v233
	ds_read_b128 v[184:187], v237
	ds_read_b128 v[188:191], v233 offset:2048
	ds_read_b128 v[192:195], v237 offset:2048
	ds_read_b128 v[196:199], v160 offset:32768
	ds_read_b128 v[200:203], v238 offset:32768
	ds_read_b128 v[204:207], v160 offset:34816
	ds_read_b128 v[208:211], v238 offset:34816
	ds_read_b128 v[212:215], v160 offset:36864
	ds_read_b128 v[216:219], v238 offset:36864
	ds_read_b128 v[220:223], v160 offset:38912
	ds_read_b128 v[224:227], v238 offset:38912
	s_waitcnt vmcnt(8)
	s_waitcnt lgkmcnt(0)
	s_setprio 1
	s_barrier
	v_mfma_f32_16x16x32_bf16 v[122:125], v[164:167], v[196:199], v[122:125]
	v_mfma_f32_16x16x32_bf16 v[118:121], v[172:175], v[196:199], v[118:121]
	v_mfma_f32_16x16x32_bf16 v[110:113], v[164:167], v[204:207], v[110:113]
	v_mfma_f32_16x16x32_bf16 v[102:105], v[172:175], v[204:207], v[102:105]
	v_mfma_f32_16x16x32_bf16 v[94:97], v[164:167], v[212:215], v[94:97]
	v_mfma_f32_16x16x32_bf16 v[86:89], v[172:175], v[212:215], v[86:89]
	v_mfma_f32_16x16x32_bf16 v[78:81], v[164:167], v[220:223], v[78:81]
	v_mfma_f32_16x16x32_bf16 v[70:73], v[172:175], v[220:223], v[70:73]
	v_mfma_f32_16x16x32_bf16 v[122:125], v[168:171], v[200:203], v[122:125]
	v_mfma_f32_16x16x32_bf16 v[118:121], v[176:179], v[200:203], v[118:121]
	v_mfma_f32_16x16x32_bf16 v[110:113], v[168:171], v[208:211], v[110:113]
	v_mfma_f32_16x16x32_bf16 v[102:105], v[176:179], v[208:211], v[102:105]
	v_mfma_f32_16x16x32_bf16 v[94:97], v[168:171], v[216:219], v[94:97]
	v_mfma_f32_16x16x32_bf16 v[86:89], v[176:179], v[216:219], v[86:89]
	v_mfma_f32_16x16x32_bf16 v[78:81], v[168:171], v[224:227], v[78:81]
	v_mfma_f32_16x16x32_bf16 v[70:73], v[176:179], v[224:227], v[70:73]
	v_mfma_f32_16x16x32_bf16 v[126:129], v[180:183], v[196:199], v[126:129]
	v_mfma_f32_16x16x32_bf16 v[114:117], v[188:191], v[196:199], v[114:117]
	v_mfma_f32_16x16x32_bf16 v[106:109], v[180:183], v[204:207], v[106:109]
	v_mfma_f32_16x16x32_bf16 v[98:101], v[188:191], v[204:207], v[98:101]
	v_mfma_f32_16x16x32_bf16 v[90:93], v[180:183], v[212:215], v[90:93]
	v_mfma_f32_16x16x32_bf16 v[82:85], v[188:191], v[212:215], v[82:85]
	v_mfma_f32_16x16x32_bf16 v[74:77], v[180:183], v[220:223], v[74:77]
	v_mfma_f32_16x16x32_bf16 v[66:69], v[188:191], v[220:223], v[66:69]
	v_mfma_f32_16x16x32_bf16 v[126:129], v[184:187], v[200:203], v[126:129]
	v_mfma_f32_16x16x32_bf16 v[114:117], v[192:195], v[200:203], v[114:117]
	v_mfma_f32_16x16x32_bf16 v[106:109], v[184:187], v[208:211], v[106:109]
	v_mfma_f32_16x16x32_bf16 v[98:101], v[192:195], v[208:211], v[98:101]
	v_mfma_f32_16x16x32_bf16 v[90:93], v[184:187], v[216:219], v[90:93]
	v_mfma_f32_16x16x32_bf16 v[82:85], v[192:195], v[216:219], v[82:85]
	v_mfma_f32_16x16x32_bf16 v[74:77], v[184:187], v[224:227], v[74:77]
	v_mfma_f32_16x16x32_bf16 v[66:69], v[192:195], v[224:227], v[66:69]
	s_barrier
	s_setprio 0
	s_add_u32 s96, s96, 0x80
	s_addc_u32 s97, s97, 0
	s_add_u32 s98, s96, 0xb0000
	s_addc_u32 s99, s97, 0
	s_add_u32 s94, s94, 0x80
	s_addc_u32 s95, s95, 0
	s_add_i32 s4, s4, s21
	s_mov_b32 m0, s4
	ds_read_b128 v[196:199], v160 offset:49152
	global_load_lds_dwordx4 v132, s[96:97]
	s_add_i32 m0, s4, 0x2000
	s_add_i32 s4, s25, s21
	global_load_lds_dwordx4 v136, s[96:97]
	s_mov_b32 m0, s4
	ds_read_b128 v[200:203], v238 offset:49152
	global_load_lds_dwordx4 v132, s[98:99]
	s_add_i32 m0, s4, 0x2000
	ds_read_b128 v[204:207], v160 offset:51200
	global_load_lds_dwordx4 v136, s[98:99]
	s_mov_b32 m0, s57
	ds_read_b128 v[208:211], v238 offset:51200
	global_load_lds_dwordx4 v130, s[94:95]
	s_mov_b32 m0, s58
	ds_read_b128 v[212:215], v160 offset:53248
	global_load_lds_dwordx4 v134, s[94:95]
	ds_read_b128 v[216:219], v238 offset:53248
	ds_read_b128 v[220:223], v160 offset:55296
	ds_read_b128 v[224:227], v238 offset:55296
	s_waitcnt vmcnt(8)
	s_waitcnt lgkmcnt(0)
	s_setprio 1
	s_barrier
	v_mfma_f32_16x16x32_bf16 v[62:65], v[164:167], v[196:199], v[62:65]
	v_mfma_f32_16x16x32_bf16 v[54:57], v[172:175], v[196:199], v[54:57]
	v_mfma_f32_16x16x32_bf16 v[46:49], v[164:167], v[204:207], v[46:49]
	v_mfma_f32_16x16x32_bf16 v[38:41], v[172:175], v[204:207], v[38:41]
	v_mfma_f32_16x16x32_bf16 v[30:33], v[164:167], v[212:215], v[30:33]
	v_mfma_f32_16x16x32_bf16 v[22:25], v[172:175], v[212:215], v[22:25]
	v_mfma_f32_16x16x32_bf16 v[14:17], v[164:167], v[220:223], v[14:17]
	v_mfma_f32_16x16x32_bf16 v[6:9], v[172:175], v[220:223], v[6:9]
	v_mfma_f32_16x16x32_bf16 v[62:65], v[168:171], v[200:203], v[62:65]
	v_mfma_f32_16x16x32_bf16 v[54:57], v[176:179], v[200:203], v[54:57]
	v_mfma_f32_16x16x32_bf16 v[46:49], v[168:171], v[208:211], v[46:49]
	v_mfma_f32_16x16x32_bf16 v[38:41], v[176:179], v[208:211], v[38:41]
	v_mfma_f32_16x16x32_bf16 v[30:33], v[168:171], v[216:219], v[30:33]
	v_mfma_f32_16x16x32_bf16 v[22:25], v[176:179], v[216:219], v[22:25]
	v_mfma_f32_16x16x32_bf16 v[14:17], v[168:171], v[224:227], v[14:17]
	v_mfma_f32_16x16x32_bf16 v[6:9], v[176:179], v[224:227], v[6:9]
	v_mfma_f32_16x16x32_bf16 v[58:61], v[180:183], v[196:199], v[58:61]
	v_mfma_f32_16x16x32_bf16 v[50:53], v[188:191], v[196:199], v[50:53]
	v_mfma_f32_16x16x32_bf16 v[42:45], v[180:183], v[204:207], v[42:45]
	v_mfma_f32_16x16x32_bf16 v[34:37], v[188:191], v[204:207], v[34:37]
	v_mfma_f32_16x16x32_bf16 v[26:29], v[180:183], v[212:215], v[26:29]
	v_mfma_f32_16x16x32_bf16 v[18:21], v[188:191], v[212:215], v[18:21]
	v_mfma_f32_16x16x32_bf16 v[10:13], v[180:183], v[220:223], v[10:13]
	v_mfma_f32_16x16x32_bf16 v[2:5], v[188:191], v[220:223], v[2:5]
	v_mfma_f32_16x16x32_bf16 v[58:61], v[184:187], v[200:203], v[58:61]
	v_mfma_f32_16x16x32_bf16 v[50:53], v[192:195], v[200:203], v[50:53]
	v_mfma_f32_16x16x32_bf16 v[42:45], v[184:187], v[208:211], v[42:45]
	v_mfma_f32_16x16x32_bf16 v[34:37], v[192:195], v[208:211], v[34:37]
	v_mfma_f32_16x16x32_bf16 v[26:29], v[184:187], v[216:219], v[26:29]
	v_mfma_f32_16x16x32_bf16 v[18:21], v[192:195], v[216:219], v[18:21]
	v_mfma_f32_16x16x32_bf16 v[10:13], v[184:187], v[224:227], v[10:13]
	v_mfma_f32_16x16x32_bf16 v[2:5], v[192:195], v[224:227], v[2:5]
	s_barrier
	s_setprio 0
	s_mov_b32 s4, s5
	s_add_u32 s88, s88, 0x100
	s_addc_u32 s89, s89, 0
	s_add_u32 s86, s86, 0x100
	s_addc_u32 s87, s87, 0
	s_cmp_ge_i32 s5, s101
	s_cbranch_scc1 .Lmy_kexit_11
.LBB0_2075:
	s_add_u32 s98, s86, 0x100
	s_addc_u32 s99, s87, 0
	s_cmp_eq_u32 s4, s100
	s_cselect_b64 s[94:95], s[90:91], s[98:99]
	s_cselect_b64 s[96:97], s[92:93], s[88:89]
	s_add_i32 s5, s4, 2
	s_add_i32 m0, s44, 0xc000
	ds_read_b128 v[164:167], v230
	global_load_lds_dwordx4 v144, s[86:87]
	s_add_i32 m0, s44, 0xe000
	ds_read_b128 v[168:171], v234
	global_load_lds_dwordx4 v142, s[86:87]
	ds_read_b128 v[172:175], v230 offset:2048
	ds_read_b128 v[176:179], v234 offset:2048
	ds_read_b128 v[180:183], v231
	ds_read_b128 v[184:187], v235
	ds_read_b128 v[188:191], v231 offset:2048
	ds_read_b128 v[192:195], v235 offset:2048
	ds_read_b128 v[196:199], v160
	ds_read_b128 v[200:203], v238
	ds_read_b128 v[204:207], v160 offset:2048
	ds_read_b128 v[208:211], v238 offset:2048
	ds_read_b128 v[212:215], v160 offset:4096
	ds_read_b128 v[216:219], v238 offset:4096
	ds_read_b128 v[220:223], v160 offset:6144
	ds_read_b128 v[224:227], v238 offset:6144
	s_waitcnt vmcnt(8)
	s_waitcnt lgkmcnt(0)
	s_setprio 1
	s_barrier
	v_mfma_f32_16x16x32_bf16 v[122:125], v[164:167], v[196:199], v[122:125]
	v_mfma_f32_16x16x32_bf16 v[118:121], v[172:175], v[196:199], v[118:121]
	v_mfma_f32_16x16x32_bf16 v[110:113], v[164:167], v[204:207], v[110:113]
	v_mfma_f32_16x16x32_bf16 v[102:105], v[172:175], v[204:207], v[102:105]
	v_mfma_f32_16x16x32_bf16 v[94:97], v[164:167], v[212:215], v[94:97]
	v_mfma_f32_16x16x32_bf16 v[86:89], v[172:175], v[212:215], v[86:89]
	v_mfma_f32_16x16x32_bf16 v[78:81], v[164:167], v[220:223], v[78:81]
	v_mfma_f32_16x16x32_bf16 v[70:73], v[172:175], v[220:223], v[70:73]
	v_mfma_f32_16x16x32_bf16 v[122:125], v[168:171], v[200:203], v[122:125]
	v_mfma_f32_16x16x32_bf16 v[118:121], v[176:179], v[200:203], v[118:121]
	v_mfma_f32_16x16x32_bf16 v[110:113], v[168:171], v[208:211], v[110:113]
	v_mfma_f32_16x16x32_bf16 v[102:105], v[176:179], v[208:211], v[102:105]
	v_mfma_f32_16x16x32_bf16 v[94:97], v[168:171], v[216:219], v[94:97]
	v_mfma_f32_16x16x32_bf16 v[86:89], v[176:179], v[216:219], v[86:89]
	v_mfma_f32_16x16x32_bf16 v[78:81], v[168:171], v[224:227], v[78:81]
	v_mfma_f32_16x16x32_bf16 v[70:73], v[176:179], v[224:227], v[70:73]
	v_mfma_f32_16x16x32_bf16 v[126:129], v[180:183], v[196:199], v[126:129]
	v_mfma_f32_16x16x32_bf16 v[114:117], v[188:191], v[196:199], v[114:117]
	v_mfma_f32_16x16x32_bf16 v[106:109], v[180:183], v[204:207], v[106:109]
	v_mfma_f32_16x16x32_bf16 v[98:101], v[188:191], v[204:207], v[98:101]
	v_mfma_f32_16x16x32_bf16 v[90:93], v[180:183], v[212:215], v[90:93]
	v_mfma_f32_16x16x32_bf16 v[82:85], v[188:191], v[212:215], v[82:85]
	v_mfma_f32_16x16x32_bf16 v[74:77], v[180:183], v[220:223], v[74:77]
	v_mfma_f32_16x16x32_bf16 v[66:69], v[188:191], v[220:223], v[66:69]
	v_mfma_f32_16x16x32_bf16 v[126:129], v[184:187], v[200:203], v[126:129]
	v_mfma_f32_16x16x32_bf16 v[114:117], v[192:195], v[200:203], v[114:117]
	v_mfma_f32_16x16x32_bf16 v[106:109], v[184:187], v[208:211], v[106:109]
	v_mfma_f32_16x16x32_bf16 v[98:101], v[192:195], v[208:211], v[98:101]
	v_mfma_f32_16x16x32_bf16 v[90:93], v[184:187], v[216:219], v[90:93]
	v_mfma_f32_16x16x32_bf16 v[82:85], v[192:195], v[216:219], v[82:85]
	v_mfma_f32_16x16x32_bf16 v[74:77], v[184:187], v[224:227], v[74:77]
	v_mfma_f32_16x16x32_bf16 v[66:69], v[192:195], v[224:227], v[66:69]
	s_barrier
	s_setprio 0
	s_add_u32 s98, s96, 0xb0000
	s_addc_u32 s99, s97, 0
	s_add_i32 s4, s65, s21
	s_mov_b32 m0, s4
	ds_read_b128 v[196:199], v160 offset:16384
	global_load_lds_dwordx4 v132, s[96:97]
	s_add_i32 m0, s4, 0x2000
	s_add_i32 s4, s66, s21
	global_load_lds_dwordx4 v136, s[96:97]
	s_mov_b32 m0, s4
	ds_read_b128 v[200:203], v238 offset:16384
	global_load_lds_dwordx4 v132, s[98:99]
	s_add_i32 m0, s4, 0x2000
	ds_read_b128 v[204:207], v160 offset:18432
	global_load_lds_dwordx4 v136, s[98:99]
	s_mov_b32 m0, s44
	ds_read_b128 v[208:211], v238 offset:18432
	global_load_lds_dwordx4 v130, s[94:95]
	s_mov_b32 m0, s45
	ds_read_b128 v[212:215], v160 offset:20480
	global_load_lds_dwordx4 v134, s[94:95]
	ds_read_b128 v[216:219], v238 offset:20480
	ds_read_b128 v[220:223], v160 offset:22528
	ds_read_b128 v[224:227], v238 offset:22528
	s_waitcnt vmcnt(8)
	s_waitcnt lgkmcnt(0)
	s_setprio 1
	s_barrier
	v_mfma_f32_16x16x32_bf16 v[62:65], v[164:167], v[196:199], v[62:65]
	v_mfma_f32_16x16x32_bf16 v[54:57], v[172:175], v[196:199], v[54:57]
	v_mfma_f32_16x16x32_bf16 v[46:49], v[164:167], v[204:207], v[46:49]
	v_mfma_f32_16x16x32_bf16 v[38:41], v[172:175], v[204:207], v[38:41]
	v_mfma_f32_16x16x32_bf16 v[30:33], v[164:167], v[212:215], v[30:33]
	v_mfma_f32_16x16x32_bf16 v[22:25], v[172:175], v[212:215], v[22:25]
	v_mfma_f32_16x16x32_bf16 v[14:17], v[164:167], v[220:223], v[14:17]
	v_mfma_f32_16x16x32_bf16 v[6:9], v[172:175], v[220:223], v[6:9]
	v_mfma_f32_16x16x32_bf16 v[62:65], v[168:171], v[200:203], v[62:65]
	v_mfma_f32_16x16x32_bf16 v[54:57], v[176:179], v[200:203], v[54:57]
	v_mfma_f32_16x16x32_bf16 v[46:49], v[168:171], v[208:211], v[46:49]
	v_mfma_f32_16x16x32_bf16 v[38:41], v[176:179], v[208:211], v[38:41]
	v_mfma_f32_16x16x32_bf16 v[30:33], v[168:171], v[216:219], v[30:33]
	v_mfma_f32_16x16x32_bf16 v[22:25], v[176:179], v[216:219], v[22:25]
	v_mfma_f32_16x16x32_bf16 v[14:17], v[168:171], v[224:227], v[14:17]
	v_mfma_f32_16x16x32_bf16 v[6:9], v[176:179], v[224:227], v[6:9]
	v_mfma_f32_16x16x32_bf16 v[58:61], v[180:183], v[196:199], v[58:61]
	v_mfma_f32_16x16x32_bf16 v[50:53], v[188:191], v[196:199], v[50:53]
	v_mfma_f32_16x16x32_bf16 v[42:45], v[180:183], v[204:207], v[42:45]
	v_mfma_f32_16x16x32_bf16 v[34:37], v[188:191], v[204:207], v[34:37]
	v_mfma_f32_16x16x32_bf16 v[26:29], v[180:183], v[212:215], v[26:29]
	v_mfma_f32_16x16x32_bf16 v[18:21], v[188:191], v[212:215], v[18:21]
	v_mfma_f32_16x16x32_bf16 v[10:13], v[180:183], v[220:223], v[10:13]
	v_mfma_f32_16x16x32_bf16 v[2:5], v[188:191], v[220:223], v[2:5]
	v_mfma_f32_16x16x32_bf16 v[58:61], v[184:187], v[200:203], v[58:61]
	v_mfma_f32_16x16x32_bf16 v[50:53], v[192:195], v[200:203], v[50:53]
	v_mfma_f32_16x16x32_bf16 v[42:45], v[184:187], v[208:211], v[42:45]
	v_mfma_f32_16x16x32_bf16 v[34:37], v[192:195], v[208:211], v[34:37]
	v_mfma_f32_16x16x32_bf16 v[26:29], v[184:187], v[216:219], v[26:29]
	v_mfma_f32_16x16x32_bf16 v[18:21], v[192:195], v[216:219], v[18:21]
	v_mfma_f32_16x16x32_bf16 v[10:13], v[184:187], v[224:227], v[10:13]
	v_mfma_f32_16x16x32_bf16 v[2:5], v[192:195], v[224:227], v[2:5]
	s_barrier
	s_setprio 0
	s_add_u32 s98, s94, 0xb0000
	s_addc_u32 s99, s95, 0
	s_add_i32 s4, 0, 0x18000
	s_add_i32 s25, 0, 0x1c000
	s_mov_b32 m0, s46
	ds_read_b128 v[164:167], v232
	global_load_lds_dwordx4 v130, s[98:99]
	s_mov_b32 m0, s47
	ds_read_b128 v[168:171], v236
	global_load_lds_dwordx4 v134, s[98:99]
	ds_read_b128 v[172:175], v232 offset:2048
	ds_read_b128 v[176:179], v236 offset:2048
	ds_read_b128 v[180:183], v233
	ds_read_b128 v[184:187], v237
	ds_read_b128 v[188:191], v233 offset:2048
	ds_read_b128 v[192:195], v237 offset:2048
	ds_read_b128 v[196:199], v160 offset:32768
	ds_read_b128 v[200:203], v238 offset:32768
	ds_read_b128 v[204:207], v160 offset:34816
	ds_read_b128 v[208:211], v238 offset:34816
	ds_read_b128 v[212:215], v160 offset:36864
	ds_read_b128 v[216:219], v238 offset:36864
	ds_read_b128 v[220:223], v160 offset:38912
	ds_read_b128 v[224:227], v238 offset:38912
	s_waitcnt vmcnt(8)
	s_waitcnt lgkmcnt(0)
	s_setprio 1
	s_barrier
	v_mfma_f32_16x16x32_bf16 v[122:125], v[164:167], v[196:199], v[122:125]
	v_mfma_f32_16x16x32_bf16 v[118:121], v[172:175], v[196:199], v[118:121]
	v_mfma_f32_16x16x32_bf16 v[110:113], v[164:167], v[204:207], v[110:113]
	v_mfma_f32_16x16x32_bf16 v[102:105], v[172:175], v[204:207], v[102:105]
	v_mfma_f32_16x16x32_bf16 v[94:97], v[164:167], v[212:215], v[94:97]
	v_mfma_f32_16x16x32_bf16 v[86:89], v[172:175], v[212:215], v[86:89]
	v_mfma_f32_16x16x32_bf16 v[78:81], v[164:167], v[220:223], v[78:81]
	v_mfma_f32_16x16x32_bf16 v[70:73], v[172:175], v[220:223], v[70:73]
	v_mfma_f32_16x16x32_bf16 v[122:125], v[168:171], v[200:203], v[122:125]
	v_mfma_f32_16x16x32_bf16 v[118:121], v[176:179], v[200:203], v[118:121]
	v_mfma_f32_16x16x32_bf16 v[110:113], v[168:171], v[208:211], v[110:113]
	v_mfma_f32_16x16x32_bf16 v[102:105], v[176:179], v[208:211], v[102:105]
	v_mfma_f32_16x16x32_bf16 v[94:97], v[168:171], v[216:219], v[94:97]
	v_mfma_f32_16x16x32_bf16 v[86:89], v[176:179], v[216:219], v[86:89]
	v_mfma_f32_16x16x32_bf16 v[78:81], v[168:171], v[224:227], v[78:81]
	v_mfma_f32_16x16x32_bf16 v[70:73], v[176:179], v[224:227], v[70:73]
	v_mfma_f32_16x16x32_bf16 v[126:129], v[180:183], v[196:199], v[126:129]
	v_mfma_f32_16x16x32_bf16 v[114:117], v[188:191], v[196:199], v[114:117]
	v_mfma_f32_16x16x32_bf16 v[106:109], v[180:183], v[204:207], v[106:109]
	v_mfma_f32_16x16x32_bf16 v[98:101], v[188:191], v[204:207], v[98:101]
	v_mfma_f32_16x16x32_bf16 v[90:93], v[180:183], v[212:215], v[90:93]
	v_mfma_f32_16x16x32_bf16 v[82:85], v[188:191], v[212:215], v[82:85]
	v_mfma_f32_16x16x32_bf16 v[74:77], v[180:183], v[220:223], v[74:77]
	v_mfma_f32_16x16x32_bf16 v[66:69], v[188:191], v[220:223], v[66:69]
	v_mfma_f32_16x16x32_bf16 v[126:129], v[184:187], v[200:203], v[126:129]
	v_mfma_f32_16x16x32_bf16 v[114:117], v[192:195], v[200:203], v[114:117]
	v_mfma_f32_16x16x32_bf16 v[106:109], v[184:187], v[208:211], v[106:109]
	v_mfma_f32_16x16x32_bf16 v[98:101], v[192:195], v[208:211], v[98:101]
	v_mfma_f32_16x16x32_bf16 v[90:93], v[184:187], v[216:219], v[90:93]
	v_mfma_f32_16x16x32_bf16 v[82:85], v[192:195], v[216:219], v[82:85]
	v_mfma_f32_16x16x32_bf16 v[74:77], v[184:187], v[224:227], v[74:77]
	v_mfma_f32_16x16x32_bf16 v[66:69], v[192:195], v[224:227], v[66:69]
	s_barrier
	s_setprio 0
	s_add_u32 s96, s96, 0x80
	s_addc_u32 s97, s97, 0
	s_add_u32 s98, s96, 0xb0000
	s_addc_u32 s99, s97, 0
	s_add_u32 s94, s94, 0x80
	s_addc_u32 s95, s95, 0
	s_add_i32 s4, s4, s21
	s_mov_b32 m0, s4
	ds_read_b128 v[196:199], v160 offset:49152
	global_load_lds_dwordx4 v132, s[96:97]
	s_add_i32 m0, s4, 0x2000
	s_add_i32 s4, s25, s21
	global_load_lds_dwordx4 v136, s[96:97]
	s_mov_b32 m0, s4
	ds_read_b128 v[200:203], v238 offset:49152
	global_load_lds_dwordx4 v132, s[98:99]
	s_add_i32 m0, s4, 0x2000
	ds_read_b128 v[204:207], v160 offset:51200
	global_load_lds_dwordx4 v136, s[98:99]
	s_mov_b32 m0, s57
	ds_read_b128 v[208:211], v238 offset:51200
	global_load_lds_dwordx4 v130, s[94:95]
	s_mov_b32 m0, s58
	ds_read_b128 v[212:215], v160 offset:53248
	global_load_lds_dwordx4 v134, s[94:95]
	ds_read_b128 v[216:219], v238 offset:53248
	ds_read_b128 v[220:223], v160 offset:55296
	ds_read_b128 v[224:227], v238 offset:55296
	s_waitcnt vmcnt(8)
	s_waitcnt lgkmcnt(0)
	s_setprio 1
	s_barrier
	v_mfma_f32_16x16x32_bf16 v[62:65], v[164:167], v[196:199], v[62:65]
	v_mfma_f32_16x16x32_bf16 v[54:57], v[172:175], v[196:199], v[54:57]
	v_mfma_f32_16x16x32_bf16 v[46:49], v[164:167], v[204:207], v[46:49]
	v_mfma_f32_16x16x32_bf16 v[38:41], v[172:175], v[204:207], v[38:41]
	v_mfma_f32_16x16x32_bf16 v[30:33], v[164:167], v[212:215], v[30:33]
	v_mfma_f32_16x16x32_bf16 v[22:25], v[172:175], v[212:215], v[22:25]
	v_mfma_f32_16x16x32_bf16 v[14:17], v[164:167], v[220:223], v[14:17]
	v_mfma_f32_16x16x32_bf16 v[6:9], v[172:175], v[220:223], v[6:9]
	v_mfma_f32_16x16x32_bf16 v[62:65], v[168:171], v[200:203], v[62:65]
	v_mfma_f32_16x16x32_bf16 v[54:57], v[176:179], v[200:203], v[54:57]
	v_mfma_f32_16x16x32_bf16 v[46:49], v[168:171], v[208:211], v[46:49]
	v_mfma_f32_16x16x32_bf16 v[38:41], v[176:179], v[208:211], v[38:41]
	v_mfma_f32_16x16x32_bf16 v[30:33], v[168:171], v[216:219], v[30:33]
	v_mfma_f32_16x16x32_bf16 v[22:25], v[176:179], v[216:219], v[22:25]
	v_mfma_f32_16x16x32_bf16 v[14:17], v[168:171], v[224:227], v[14:17]
	v_mfma_f32_16x16x32_bf16 v[6:9], v[176:179], v[224:227], v[6:9]
	v_mfma_f32_16x16x32_bf16 v[58:61], v[180:183], v[196:199], v[58:61]
	v_mfma_f32_16x16x32_bf16 v[50:53], v[188:191], v[196:199], v[50:53]
	v_mfma_f32_16x16x32_bf16 v[42:45], v[180:183], v[204:207], v[42:45]
	v_mfma_f32_16x16x32_bf16 v[34:37], v[188:191], v[204:207], v[34:37]
	v_mfma_f32_16x16x32_bf16 v[26:29], v[180:183], v[212:215], v[26:29]
	v_mfma_f32_16x16x32_bf16 v[18:21], v[188:191], v[212:215], v[18:21]
	v_mfma_f32_16x16x32_bf16 v[10:13], v[180:183], v[220:223], v[10:13]
	v_mfma_f32_16x16x32_bf16 v[2:5], v[188:191], v[220:223], v[2:5]
	v_mfma_f32_16x16x32_bf16 v[58:61], v[184:187], v[200:203], v[58:61]
	v_mfma_f32_16x16x32_bf16 v[50:53], v[192:195], v[200:203], v[50:53]
	v_mfma_f32_16x16x32_bf16 v[42:45], v[184:187], v[208:211], v[42:45]
	v_mfma_f32_16x16x32_bf16 v[34:37], v[192:195], v[208:211], v[34:37]
	v_mfma_f32_16x16x32_bf16 v[26:29], v[184:187], v[216:219], v[26:29]
	v_mfma_f32_16x16x32_bf16 v[18:21], v[192:195], v[216:219], v[18:21]
	v_mfma_f32_16x16x32_bf16 v[10:13], v[184:187], v[224:227], v[10:13]
	v_mfma_f32_16x16x32_bf16 v[2:5], v[192:195], v[224:227], v[2:5]
	s_barrier
	s_setprio 0
	s_mov_b32 s4, s5
	s_add_u32 s88, s88, 0x100
	s_addc_u32 s89, s89, 0
	s_add_u32 s86, s86, 0x100
	s_addc_u32 s87, s87, 0
	s_cmp_ge_i32 s5, s101
	s_cbranch_scc0 .LBB0_2075

	.amdhsa_kernel _Z10fwd_kernel4Args
		.amdhsa_group_segment_fixed_size 0
		.amdhsa_private_segment_fixed_size 0
		.amdhsa_kernarg_size 448
		.amdhsa_user_sgpr_count 2
		.amdhsa_user_sgpr_dispatch_ptr 0
		.amdhsa_user_sgpr_queue_ptr 0
		.amdhsa_user_sgpr_kernarg_segment_ptr 1
		.amdhsa_user_sgpr_dispatch_id 0
		.amdhsa_user_sgpr_kernarg_preload_length 0
		.amdhsa_user_sgpr_kernarg_preload_offset 0
		.amdhsa_user_sgpr_private_segment_size 0
		.amdhsa_uses_dynamic_stack 0
		.amdhsa_enable_private_segment 0
		.amdhsa_system_sgpr_workgroup_id_x 1
		.amdhsa_system_sgpr_workgroup_id_y 0
		.amdhsa_system_sgpr_workgroup_id_z 0
		.amdhsa_system_sgpr_workgroup_info 0
		.amdhsa_system_vgpr_workitem_id 2
		.amdhsa_next_free_vgpr 256
		.amdhsa_next_free_sgpr 102
		.amdhsa_accum_offset 256
		.amdhsa_reserve_vcc 1
		.amdhsa_float_round_mode_32 0
		.amdhsa_float_round_mode_16_64 0
		.amdhsa_float_denorm_mode_32 3
		.amdhsa_float_denorm_mode_16_64 3
		.amdhsa_dx10_clamp 1
		.amdhsa_ieee_mode 1
		.amdhsa_fp16_overflow 0
		.amdhsa_tg_split 0
		.amdhsa_exception_fp_ieee_invalid_op 0
		.amdhsa_exception_fp_denorm_src 0
		.amdhsa_exception_fp_ieee_div_zero 0
		.amdhsa_exception_fp_ieee_overflow 0
		.amdhsa_exception_fp_ieee_underflow 0
		.amdhsa_exception_fp_ieee_inexact 0
		.amdhsa_exception_int_div_zero 0
	.end_amdhsa_kernel

amdhsa.kernels:
  - .agpr_count:     0
    .args:
      - .offset:         0
        .size:           192
        .value_kind:     by_value
      - .offset:         192
        .size:           4
        .value_kind:     hidden_block_count_x
      - .offset:         196
        .size:           4
        .value_kind:     hidden_block_count_y
      - .offset:         200
        .size:           4
        .value_kind:     hidden_block_count_z
      - .offset:         204
        .size:           2
        .value_kind:     hidden_group_size_x
      - .offset:         206
        .size:           2
        .value_kind:     hidden_group_size_y
      - .offset:         208
        .size:           2
        .value_kind:     hidden_group_size_z
      - .offset:         210
        .size:           2
        .value_kind:     hidden_remainder_x
      - .offset:         212
        .size:           2
        .value_kind:     hidden_remainder_y
      - .offset:         214
        .size:           2
        .value_kind:     hidden_remainder_z
      - .offset:         232
        .size:           8
        .value_kind:     hidden_global_offset_x
      - .offset:         240
        .size:           8
        .value_kind:     hidden_global_offset_y
      - .offset:         248
        .size:           8
        .value_kind:     hidden_global_offset_z
      - .offset:         256
        .size:           2
        .value_kind:     hidden_grid_dims
      - .offset:         280
        .size:           8
        .value_kind:     hidden_multigrid_sync_arg
      - .offset:         312
        .size:           4
        .value_kind:     hidden_dynamic_lds_size
    .group_segment_fixed_size: 0
    .kernarg_segment_align: 8
    .kernarg_segment_size: 448
    .language:       OpenCL C
    .language_version:
      - 2
      - 0
    .max_flat_workgroup_size: 512
    .name:           _Z10fwd_kernel4Args
    .private_segment_fixed_size: 0
    .sgpr_count:     108
    .sgpr_spill_count: 0
    .symbol:         _Z10fwd_kernel4Args.kd
    .uniform_work_group_size: 1
    .uses_dynamic_stack: false
    .vgpr_count:     256
    .vgpr_spill_count: 0
    .wavefront_size: 64
